# streaming hints extended: y0/y1 row loads in P6/P11 also non-temporal
# baseline (speedup 1.0000x reference)
; __device__ __forceinline__ float bf_lo(unsigned w) { return __uint_as_float(w << 16); }
; __device__ __forceinline__ float bf_hi(unsigned w) { return __uint_as_float(w & 0xffff0000u); }
; #define FRESH() int gtid; do { int t_ = threadIdx.x; asm volatile("" : "+v"(t_)); F.tid = t_; F.lane = t_ & 63; gtid = blockIdx.x * (NWAVES * 64) + t_; (void)gtid; } while (0)
; __global__ void __launch_bounds__(NWAVES * 64, 2) mk_fwd(Args args) {
;     ...
;     if (IN(6)) { FRESH();
;         for (int row0 = F.gw * 3; row0 < MT; row0 += F.NGW * 3) {
;             f32x4 v[3][8]; u32x2 yw[3][8];
; #pragma unroll
;             for (int q = 0; q < 3; ++q) { const int row = row0 + q; const float* src = row < ML ? x + (size_t)row * DM : ctx + (size_t)(row - ML) * DM; load_row_f32(src, F.lane, v[q]);
;                 const bf16_t* yr = Y + (size_t)row * DM;
; #pragma unroll
;                 for (int j = 0; j < 8; ++j) yw[q][j] = *(const u32x2*)(yr + 4 * F.lane + 256 * j); }
; #pragma unroll
;             for (int q = 0; q < 3; ++q) { const int row = row0 + q; const bool lat = row < ML; const int r = lat ? row / SEQ : 8;
;                 float sy = 0.f;
; #pragma unroll
;                 for (int j = 0; j < 8; ++j) { const float a = bf_lo(yw[q][j].x), b = bf_hi(yw[q][j].x), c2 = bf_lo(yw[q][j].y), d = bf_hi(yw[q][j].y); sy += (a * a + b * b) + (c2 * c2 + d * d); }
;                 const float rsy = __builtin_amdgcn_rsqf(wave_sum(sy) * (1.f / DM) + EPS);
;                 const float* m0 = mod + (size_t)r * 6144;
; #pragma unroll
;                 for (int j = 0; j < 8; ++j) { const int col = 4 * F.lane + 256 * j; const f32x4 gt = *(const f32x4*)(m0 + 2 * DM + col), pn = *(const f32x4*)(post_norm + col);
;                     const f32x4 y4 = (f32x4){bf_lo(yw[q][j].x), bf_hi(yw[q][j].x), bf_lo(yw[q][j].y), bf_hi(yw[q][j].y)};
.LBB0_716:
	s_cmp_lt_i32 s86, 7
	s_cselect_b64 s[4:5], -1, 0
	s_and_b64 s[0:1], s[4:5], s[0:1]
	s_andn2_b64 vcc, exec, s[0:1]
	s_cbranch_vccnz .LBB0_778
	s_cmpk_lg_i32 s63, 0x100
	s_cbranch_scc1 .Lp6_generic
	v_and_b32_e32 v194, 63, v198
	v_lshlrev_b32_e32 v192, 4, v194
	v_add_u32_e32 v193, 0x1000, v192
	v_lshlrev_b32_e32 v194, 3, v194
	v_mov_b32_e32 v195, 0x358637bd
	s_mul_i32 s6, s33, 9
	s_mov_b32 s7, -1
	s_add_i32 s0, s6, 0
	s_cmp_lt_u32 s0, 0x4000
	s_cselect_b32 s10, s68, s72
	s_cselect_b32 s11, s69, s73
	s_cselect_b32 s1, 0, 0x4000
	s_sub_i32 s1, s0, s1
	s_lshl_b32 s1, s1, 13
	s_add_u32 s10, s10, s1
	s_addc_u32 s11, s11, 0
	s_add_i32 s0, s6, 0
	s_lshl_b32 s1, s0, 12
	s_add_u32 s22, s84, s1
	s_addc_u32 s23, s85, 0
	s_add_u32 s22, s22, 0x11800000
	s_addc_u32 s23, s23, 0
	global_load_dwordx4 v[0:3], v192, s[10:11] offset:0 nt
	global_load_dwordx4 v[4:7], v192, s[10:11] offset:1024 nt
	global_load_dwordx4 v[8:11], v192, s[10:11] offset:2048 nt
	global_load_dwordx4 v[12:15], v192, s[10:11] offset:3072 nt
	global_load_dwordx4 v[16:19], v193, s[10:11] offset:0 nt
	global_load_dwordx4 v[20:23], v193, s[10:11] offset:1024 nt
	global_load_dwordx4 v[24:27], v193, s[10:11] offset:2048 nt
	global_load_dwordx4 v[28:31], v193, s[10:11] offset:3072 nt
	global_load_dwordx2 v[32:33], v194, s[22:23] offset:0 nt
	global_load_dwordx2 v[34:35], v194, s[22:23] offset:512 nt
	global_load_dwordx2 v[36:37], v194, s[22:23] offset:1024 nt
	global_load_dwordx2 v[38:39], v194, s[22:23] offset:1536 nt
	global_load_dwordx2 v[40:41], v194, s[22:23] offset:2048 nt
	global_load_dwordx2 v[42:43], v194, s[22:23] offset:2560 nt
	global_load_dwordx2 v[44:45], v194, s[22:23] offset:3072 nt
	global_load_dwordx2 v[46:47], v194, s[22:23] offset:3584 nt
	s_add_i32 s0, s6, 1
	s_cmp_lt_u32 s0, 0x4000
	s_cselect_b32 s10, s68, s72
	s_cselect_b32 s11, s69, s73
	s_cselect_b32 s1, 0, 0x4000
	s_sub_i32 s1, s0, s1
	s_lshl_b32 s1, s1, 13
	s_add_u32 s10, s10, s1
	s_addc_u32 s11, s11, 0
	s_add_i32 s0, s6, 1
	s_lshl_b32 s1, s0, 12
	s_add_u32 s22, s84, s1
	s_addc_u32 s23, s85, 0
	s_add_u32 s22, s22, 0x11800000
	s_addc_u32 s23, s23, 0
	global_load_dwordx4 v[48:51], v192, s[10:11] offset:0 nt
	global_load_dwordx4 v[52:55], v192, s[10:11] offset:1024 nt
	global_load_dwordx4 v[56:59], v192, s[10:11] offset:2048 nt
	global_load_dwordx4 v[60:63], v192, s[10:11] offset:3072 nt
	global_load_dwordx4 v[64:67], v193, s[10:11] offset:0 nt
	global_load_dwordx4 v[68:71], v193, s[10:11] offset:1024 nt
	global_load_dwordx4 v[72:75], v193, s[10:11] offset:2048 nt
	global_load_dwordx4 v[76:79], v193, s[10:11] offset:3072 nt
	global_load_dwordx2 v[80:81], v194, s[22:23] offset:0 nt
	global_load_dwordx2 v[82:83], v194, s[22:23] offset:512 nt
	global_load_dwordx2 v[84:85], v194, s[22:23] offset:1024 nt
	global_load_dwordx2 v[86:87], v194, s[22:23] offset:1536 nt
	global_load_dwordx2 v[88:89], v194, s[22:23] offset:2048 nt
	global_load_dwordx2 v[90:91], v194, s[22:23] offset:2560 nt
	global_load_dwordx2 v[92:93], v194, s[22:23] offset:3072 nt
	global_load_dwordx2 v[94:95], v194, s[22:23] offset:3584 nt
	s_add_i32 s0, s6, 0
	s_add_i32 s0, s6, 0
	s_lshr_b32 s8, s0, 11
	s_cmp_lt_u32 s0, 0x4000
	s_cselect_b32 s8, s8, 8
	s_cmp_eq_u32 s8, s7
	s_cbranch_scc1 .Lp6_np0
	s_mov_b32 s7, s8
	s_add_i32 s1, s8, 9
	s_mul_i32 s1, s1, 0x6000
	s_add_u32 s44, s84, s1
	s_addc_u32 s45, s85, 0
	s_add_u32 s44, s44, 0x2000
	s_addc_u32 s45, s45, 0
	s_add_i32 s1, s8, 9
	s_mul_i32 s1, s1, 0x6000
	s_add_u32 s36, s84, s1
	s_addc_u32 s37, s85, 0
	s_add_u32 s38, s80, 0x2000
	s_addc_u32 s39, s81, 0
	s_mul_i32 s1, s8, 0x6000
	s_add_u32 s34, s84, s1
	s_addc_u32 s35, s85, 0
	s_add_u32 s34, s34, 0x4000
	s_addc_u32 s35, s35, 0
	global_load_dwordx4 v[96:99], v192, s[34:35] offset:0
	global_load_dwordx4 v[200:203], v192, s[82:83] offset:0
	global_load_dwordx4 v[100:103], v192, s[34:35] offset:1024
	global_load_dwordx4 v[204:207], v192, s[82:83] offset:1024
	global_load_dwordx4 v[104:107], v192, s[34:35] offset:2048
	global_load_dwordx4 v[208:211], v192, s[82:83] offset:2048
	global_load_dwordx4 v[108:111], v192, s[34:35] offset:3072
	global_load_dwordx4 v[212:215], v192, s[82:83] offset:3072
	s_waitcnt vmcnt(0)
	v_mul_f32_e32 v96, v96, v200
	v_mul_f32_e32 v97, v97, v201
	v_mul_f32_e32 v98, v98, v202
	v_mul_f32_e32 v99, v99, v203
	v_mul_f32_e32 v100, v100, v204
	v_mul_f32_e32 v101, v101, v205
	v_mul_f32_e32 v102, v102, v206
	v_mul_f32_e32 v103, v103, v207
	v_mul_f32_e32 v104, v104, v208
	v_mul_f32_e32 v105, v105, v209
	v_mul_f32_e32 v106, v106, v210
	v_mul_f32_e32 v107, v107, v211
	v_mul_f32_e32 v108, v108, v212
	v_mul_f32_e32 v109, v109, v213
	v_mul_f32_e32 v110, v110, v214
	v_mul_f32_e32 v111, v111, v215
	global_load_dwordx4 v[128:131], v192, s[38:39] offset:0
	global_load_dwordx4 v[200:203], v192, s[44:45] offset:0
	global_load_dwordx4 v[160:163], v192, s[36:37] offset:0
	global_load_dwordx4 v[132:135], v192, s[38:39] offset:1024
	global_load_dwordx4 v[204:207], v192, s[44:45] offset:1024
	global_load_dwordx4 v[164:167], v192, s[36:37] offset:1024
	global_load_dwordx4 v[136:139], v192, s[38:39] offset:2048
	global_load_dwordx4 v[208:211], v192, s[44:45] offset:2048
	global_load_dwordx4 v[168:171], v192, s[36:37] offset:2048
	global_load_dwordx4 v[140:143], v192, s[38:39] offset:3072
	global_load_dwordx4 v[212:215], v192, s[44:45] offset:3072
	global_load_dwordx4 v[172:175], v192, s[36:37] offset:3072
	s_waitcnt vmcnt(0)
; __device__ __forceinline__ void modulate_store(const f32x4 (&v)[8], float rstd, const float* pn, const float* modr, bf16_t* orow, int lane) {
;     ...
;     for (int j = 0; j < 8; ++j) { const int col = 4 * lane + 256 * j;
;         const f32x4 g = *(const f32x4*)(pn + col), sh = *(const f32x4*)(modr + col), sc = *(const f32x4*)(modr + DM + col);
;         const f32x4 hh = v[j] * rstd * g * (sc + 1.f) + sh;
; __global__ void __launch_bounds__(NWAVES * 64, 2) mk_fwd(Args args) {
;     ...
;                 const float* m0 = mod + (size_t)r * 6144;
; #pragma unroll
;                 for (int j = 0; j < 8; ++j) { const int col = 4 * F.lane + 256 * j; const f32x4 gt = *(const f32x4*)(m0 + 2 * DM + col), pn = *(const f32x4*)(post_norm + col);
	v_add_f32_e32 v200, 1.0, v200
	v_add_f32_e32 v201, 1.0, v201
	v_add_f32_e32 v202, 1.0, v202
	v_add_f32_e32 v203, 1.0, v203
	v_mul_f32_e32 v128, v128, v200
	v_mul_f32_e32 v129, v129, v201
	v_mul_f32_e32 v130, v130, v202
	v_mul_f32_e32 v131, v131, v203
	v_add_f32_e32 v204, 1.0, v204
	v_add_f32_e32 v205, 1.0, v205
	v_add_f32_e32 v206, 1.0, v206
	v_add_f32_e32 v207, 1.0, v207
	v_mul_f32_e32 v132, v132, v204
	v_mul_f32_e32 v133, v133, v205
	v_mul_f32_e32 v134, v134, v206
	v_mul_f32_e32 v135, v135, v207
	v_add_f32_e32 v208, 1.0, v208
	v_add_f32_e32 v209, 1.0, v209
	v_add_f32_e32 v210, 1.0, v210
	v_add_f32_e32 v211, 1.0, v211
	v_mul_f32_e32 v136, v136, v208
	v_mul_f32_e32 v137, v137, v209
	v_mul_f32_e32 v138, v138, v210
	v_mul_f32_e32 v139, v139, v211
	v_add_f32_e32 v212, 1.0, v212
	v_add_f32_e32 v213, 1.0, v213
	v_add_f32_e32 v214, 1.0, v214
	v_add_f32_e32 v215, 1.0, v215
	v_mul_f32_e32 v140, v140, v212
	v_mul_f32_e32 v141, v141, v213
	v_mul_f32_e32 v142, v142, v214
	v_mul_f32_e32 v143, v143, v215
	global_load_dwordx4 v[112:115], v193, s[34:35] offset:0
	global_load_dwordx4 v[200:203], v193, s[82:83] offset:0
	global_load_dwordx4 v[116:119], v193, s[34:35] offset:1024
	global_load_dwordx4 v[204:207], v193, s[82:83] offset:1024
	global_load_dwordx4 v[120:123], v193, s[34:35] offset:2048
	global_load_dwordx4 v[208:211], v193, s[82:83] offset:2048
	global_load_dwordx4 v[124:127], v193, s[34:35] offset:3072
	global_load_dwordx4 v[212:215], v193, s[82:83] offset:3072
	s_waitcnt vmcnt(0)
	v_mul_f32_e32 v112, v112, v200
	v_mul_f32_e32 v113, v113, v201
	v_mul_f32_e32 v114, v114, v202
	v_mul_f32_e32 v115, v115, v203
	v_mul_f32_e32 v116, v116, v204
	v_mul_f32_e32 v117, v117, v205
	v_mul_f32_e32 v118, v118, v206
	v_mul_f32_e32 v119, v119, v207
	v_mul_f32_e32 v120, v120, v208
	v_mul_f32_e32 v121, v121, v209
	v_mul_f32_e32 v122, v122, v210
	v_mul_f32_e32 v123, v123, v211
	v_mul_f32_e32 v124, v124, v212
	v_mul_f32_e32 v125, v125, v213
	v_mul_f32_e32 v126, v126, v214
	v_mul_f32_e32 v127, v127, v215
	global_load_dwordx4 v[144:147], v193, s[38:39] offset:0
	global_load_dwordx4 v[200:203], v193, s[44:45] offset:0
	global_load_dwordx4 v[176:179], v193, s[36:37] offset:0
	global_load_dwordx4 v[148:151], v193, s[38:39] offset:1024
	global_load_dwordx4 v[204:207], v193, s[44:45] offset:1024
	global_load_dwordx4 v[180:183], v193, s[36:37] offset:1024
	global_load_dwordx4 v[152:155], v193, s[38:39] offset:2048
	global_load_dwordx4 v[208:211], v193, s[44:45] offset:2048
	global_load_dwordx4 v[184:187], v193, s[36:37] offset:2048
	global_load_dwordx4 v[156:159], v193, s[38:39] offset:3072
	global_load_dwordx4 v[212:215], v193, s[44:45] offset:3072
	global_load_dwordx4 v[188:191], v193, s[36:37] offset:3072
	s_waitcnt vmcnt(0)
	v_add_f32_e32 v200, 1.0, v200
	v_add_f32_e32 v201, 1.0, v201
	v_add_f32_e32 v202, 1.0, v202
	v_add_f32_e32 v203, 1.0, v203
	v_mul_f32_e32 v144, v144, v200
	v_mul_f32_e32 v145, v145, v201
	v_mul_f32_e32 v146, v146, v202
	v_mul_f32_e32 v147, v147, v203
	v_add_f32_e32 v204, 1.0, v204
	v_add_f32_e32 v205, 1.0, v205
	v_add_f32_e32 v206, 1.0, v206
	v_add_f32_e32 v207, 1.0, v207
	v_mul_f32_e32 v148, v148, v204
	v_mul_f32_e32 v149, v149, v205
	v_mul_f32_e32 v150, v150, v206
	v_mul_f32_e32 v151, v151, v207
	v_add_f32_e32 v208, 1.0, v208
	v_add_f32_e32 v209, 1.0, v209
	v_add_f32_e32 v210, 1.0, v210
	v_add_f32_e32 v211, 1.0, v211
	v_mul_f32_e32 v152, v152, v208
	v_mul_f32_e32 v153, v153, v209
	v_mul_f32_e32 v154, v154, v210
	v_mul_f32_e32 v155, v155, v211
	v_add_f32_e32 v212, 1.0, v212
	v_add_f32_e32 v213, 1.0, v213
	v_add_f32_e32 v214, 1.0, v214
	v_add_f32_e32 v215, 1.0, v215
	v_mul_f32_e32 v156, v156, v212
	v_mul_f32_e32 v157, v157, v213
	v_mul_f32_e32 v158, v158, v214
	v_mul_f32_e32 v159, v159, v215
.Lp6_np0:
	s_waitcnt vmcnt(16)
	v_lshlrev_b32_e32 v216, 16, v32
	v_and_b32_e32 v217, 0xffff0000, v32
	v_lshlrev_b32_e32 v218, 16, v33
	v_and_b32_e32 v219, 0xffff0000, v33
	v_mul_f32_e32 v222, v216, v216
	v_mul_f32_e32 v223, v217, v217
	v_fmac_f32_e32 v222, v218, v218
	v_fmac_f32_e32 v223, v219, v219
	v_lshlrev_b32_e32 v216, 16, v34
	v_and_b32_e32 v217, 0xffff0000, v34
	v_lshlrev_b32_e32 v218, 16, v35
	v_and_b32_e32 v219, 0xffff0000, v35
	v_fmac_f32_e32 v222, v216, v216
	v_fmac_f32_e32 v223, v217, v217
	v_fmac_f32_e32 v222, v218, v218
	v_fmac_f32_e32 v223, v219, v219
	v_lshlrev_b32_e32 v216, 16, v36
	v_and_b32_e32 v217, 0xffff0000, v36
	v_lshlrev_b32_e32 v218, 16, v37
	v_and_b32_e32 v219, 0xffff0000, v37
	v_fmac_f32_e32 v222, v216, v216
	v_fmac_f32_e32 v223, v217, v217
	v_fmac_f32_e32 v222, v218, v218
	v_fmac_f32_e32 v223, v219, v219
	v_lshlrev_b32_e32 v216, 16, v38
	v_and_b32_e32 v217, 0xffff0000, v38
	v_lshlrev_b32_e32 v218, 16, v39
	v_and_b32_e32 v219, 0xffff0000, v39
	v_fmac_f32_e32 v222, v216, v216
	v_fmac_f32_e32 v223, v217, v217
	v_fmac_f32_e32 v222, v218, v218
	v_fmac_f32_e32 v223, v219, v219
	v_lshlrev_b32_e32 v216, 16, v40
	v_and_b32_e32 v217, 0xffff0000, v40
	v_lshlrev_b32_e32 v218, 16, v41
	v_and_b32_e32 v219, 0xffff0000, v41
	v_fmac_f32_e32 v222, v216, v216
	v_fmac_f32_e32 v223, v217, v217
	v_fmac_f32_e32 v222, v218, v218
	v_fmac_f32_e32 v223, v219, v219
	v_lshlrev_b32_e32 v216, 16, v42
	v_and_b32_e32 v217, 0xffff0000, v42
	v_lshlrev_b32_e32 v218, 16, v43
	v_and_b32_e32 v219, 0xffff0000, v43
	v_fmac_f32_e32 v222, v216, v216
	v_fmac_f32_e32 v223, v217, v217
	v_fmac_f32_e32 v222, v218, v218
	v_fmac_f32_e32 v223, v219, v219
	v_lshlrev_b32_e32 v216, 16, v44
	v_and_b32_e32 v217, 0xffff0000, v44
	v_lshlrev_b32_e32 v218, 16, v45
	v_and_b32_e32 v219, 0xffff0000, v45
	v_fmac_f32_e32 v222, v216, v216
	v_fmac_f32_e32 v223, v217, v217
	v_fmac_f32_e32 v222, v218, v218
; __device__ __forceinline__ float bf_lo(unsigned w) { return __uint_as_float(w << 16); }
; __device__ __forceinline__ float bf_hi(unsigned w) { return __uint_as_float(w & 0xffff0000u); }
; __global__ void __launch_bounds__(NWAVES * 64, 2) mk_fwd(Args args) {
;     ...
;                 for (int j = 0; j < 8; ++j) { const float a = bf_lo(yw[q][j].x), b = bf_hi(yw[q][j].x), c2 = bf_lo(yw[q][j].y), d = bf_hi(yw[q][j].y); sy += (a * a + b * b) + (c2 * c2 + d * d); }
;                 const float rsy = __builtin_amdgcn_rsqf(wave_sum(sy) * (1.f / DM) + EPS);
;                 const float* m0 = mod + (size_t)r * 6144;
; #pragma unroll
;                 for (int j = 0; j < 8; ++j) { const int col = 4 * F.lane + 256 * j; const f32x4 gt = *(const f32x4*)(m0 + 2 * DM + col), pn = *(const f32x4*)(post_norm + col);
;                     const f32x4 y4 = (f32x4){bf_lo(yw[q][j].x), bf_hi(yw[q][j].x), bf_lo(yw[q][j].y), bf_hi(yw[q][j].y)};
;                     v[q][j] = v[q][j] + gt * (y4 * rsy * pn);
;                     if (lat) *(f32x4*)(args.out + (size_t)row * DM + col) = v[q][j]; }
;                 const float rstd = __builtin_amdgcn_rsqf(sumsq8(v[q]) * (1.f / DM) + EPS);
	v_fmac_f32_e32 v223, v219, v219
	v_lshlrev_b32_e32 v216, 16, v46
	v_and_b32_e32 v217, 0xffff0000, v46
	v_lshlrev_b32_e32 v218, 16, v47
	v_and_b32_e32 v219, 0xffff0000, v47
	v_fmac_f32_e32 v222, v216, v216
	v_fmac_f32_e32 v223, v217, v217
	v_fmac_f32_e32 v222, v218, v218
	v_fmac_f32_e32 v223, v219, v219
	v_add_f32_e32 v222, v222, v223
	s_nop 1
	v_add_f32_dpp v224, v222, v222 quad_perm:[1,0,3,2] row_mask:0xf bank_mask:0xf
	s_nop 1
	v_add_f32_dpp v224, v224, v224 quad_perm:[2,3,0,1] row_mask:0xf bank_mask:0xf
	s_nop 1
	v_add_f32_dpp v224, v224, v224 row_half_mirror row_mask:0xf bank_mask:0xf
	s_nop 1
	v_add_f32_dpp v224, v224, v224 row_mirror row_mask:0xf bank_mask:0xf
	s_nop 1
	v_readlane_b32 s40, v224, 0
	v_readlane_b32 s41, v224, 16
	v_readlane_b32 s42, v224, 32
	v_readlane_b32 s43, v224, 48
	s_nop 1
	v_mov_b32_e32 v225, s40
	v_add_f32_e32 v225, s41, v225
	v_add_f32_e32 v225, s42, v225
	v_add_f32_e32 v225, s43, v225
	v_fmamk_f32 v225, v225, 0x3a000000, v195
	v_rsq_f32_e32 v225, v225
	s_nop 0
	v_lshlrev_b32_e32 v216, 16, v32
	v_and_b32_e32 v217, 0xffff0000, v32
	v_lshlrev_b32_e32 v218, 16, v33
	v_and_b32_e32 v219, 0xffff0000, v33
	v_mul_f32_e32 v216, v225, v216
	v_mul_f32_e32 v217, v225, v217
	v_mul_f32_e32 v218, v225, v218
	v_mul_f32_e32 v219, v225, v219
	v_fmac_f32_e32 v0, v96, v216
	v_fmac_f32_e32 v1, v97, v217
	v_fmac_f32_e32 v2, v98, v218
	v_fmac_f32_e32 v3, v99, v219
	v_lshlrev_b32_e32 v216, 16, v34
	v_and_b32_e32 v217, 0xffff0000, v34
	v_lshlrev_b32_e32 v218, 16, v35
	v_and_b32_e32 v219, 0xffff0000, v35
	v_mul_f32_e32 v216, v225, v216
	v_mul_f32_e32 v217, v225, v217
	v_mul_f32_e32 v218, v225, v218
	v_mul_f32_e32 v219, v225, v219
	v_fmac_f32_e32 v4, v100, v216
	v_fmac_f32_e32 v5, v101, v217
	v_fmac_f32_e32 v6, v102, v218
	v_fmac_f32_e32 v7, v103, v219
	v_lshlrev_b32_e32 v216, 16, v36
	v_and_b32_e32 v217, 0xffff0000, v36
	v_lshlrev_b32_e32 v218, 16, v37
	v_and_b32_e32 v219, 0xffff0000, v37
	v_mul_f32_e32 v216, v225, v216
	v_mul_f32_e32 v217, v225, v217
	v_mul_f32_e32 v218, v225, v218
	v_mul_f32_e32 v219, v225, v219
	v_fmac_f32_e32 v8, v104, v216
	v_fmac_f32_e32 v9, v105, v217
	v_fmac_f32_e32 v10, v106, v218
	v_fmac_f32_e32 v11, v107, v219
	v_lshlrev_b32_e32 v216, 16, v38
	v_and_b32_e32 v217, 0xffff0000, v38
	v_lshlrev_b32_e32 v218, 16, v39
	v_and_b32_e32 v219, 0xffff0000, v39
	v_mul_f32_e32 v216, v225, v216
	v_mul_f32_e32 v217, v225, v217
	v_mul_f32_e32 v218, v225, v218
	v_mul_f32_e32 v219, v225, v219
	v_fmac_f32_e32 v12, v108, v216
	v_fmac_f32_e32 v13, v109, v217
	v_fmac_f32_e32 v14, v110, v218
	v_fmac_f32_e32 v15, v111, v219
	v_lshlrev_b32_e32 v216, 16, v40
	v_and_b32_e32 v217, 0xffff0000, v40
	v_lshlrev_b32_e32 v218, 16, v41
	v_and_b32_e32 v219, 0xffff0000, v41
	v_mul_f32_e32 v216, v225, v216
	v_mul_f32_e32 v217, v225, v217
	v_mul_f32_e32 v218, v225, v218
	v_mul_f32_e32 v219, v225, v219
	v_fmac_f32_e32 v16, v112, v216
	v_fmac_f32_e32 v17, v113, v217
	v_fmac_f32_e32 v18, v114, v218
	v_fmac_f32_e32 v19, v115, v219
	v_lshlrev_b32_e32 v216, 16, v42
	v_and_b32_e32 v217, 0xffff0000, v42
	v_lshlrev_b32_e32 v218, 16, v43
	v_and_b32_e32 v219, 0xffff0000, v43
	v_mul_f32_e32 v216, v225, v216
	v_mul_f32_e32 v217, v225, v217
	v_mul_f32_e32 v218, v225, v218
	v_mul_f32_e32 v219, v225, v219
	v_fmac_f32_e32 v20, v116, v216
	v_fmac_f32_e32 v21, v117, v217
	v_fmac_f32_e32 v22, v118, v218
	v_fmac_f32_e32 v23, v119, v219
	v_lshlrev_b32_e32 v216, 16, v44
	v_and_b32_e32 v217, 0xffff0000, v44
	v_lshlrev_b32_e32 v218, 16, v45
	v_and_b32_e32 v219, 0xffff0000, v45
	v_mul_f32_e32 v216, v225, v216
	v_mul_f32_e32 v217, v225, v217
	v_mul_f32_e32 v218, v225, v218
	v_mul_f32_e32 v219, v225, v219
	v_fmac_f32_e32 v24, v120, v216
	v_fmac_f32_e32 v25, v121, v217
	v_fmac_f32_e32 v26, v122, v218
	v_fmac_f32_e32 v27, v123, v219
	v_lshlrev_b32_e32 v216, 16, v46
	v_and_b32_e32 v217, 0xffff0000, v46
	v_lshlrev_b32_e32 v218, 16, v47
	v_and_b32_e32 v219, 0xffff0000, v47
	v_mul_f32_e32 v216, v225, v216
	v_mul_f32_e32 v217, v225, v217
	v_mul_f32_e32 v218, v225, v218
	v_mul_f32_e32 v219, v225, v219
	v_fmac_f32_e32 v28, v124, v216
	v_fmac_f32_e32 v29, v125, v217
	v_fmac_f32_e32 v30, v126, v218
	v_fmac_f32_e32 v31, v127, v219
	v_mul_f32_e32 v222, v0, v0
	v_mul_f32_e32 v223, v1, v1
	v_fmac_f32_e32 v222, v2, v2
	v_fmac_f32_e32 v223, v3, v3
	v_fmac_f32_e32 v222, v4, v4
	v_fmac_f32_e32 v223, v5, v5
	v_fmac_f32_e32 v222, v6, v6
	v_fmac_f32_e32 v223, v7, v7
	v_fmac_f32_e32 v222, v8, v8
	v_fmac_f32_e32 v223, v9, v9
	v_fmac_f32_e32 v222, v10, v10
	v_fmac_f32_e32 v223, v11, v11
	v_fmac_f32_e32 v222, v12, v12
	v_fmac_f32_e32 v223, v13, v13
	v_fmac_f32_e32 v222, v14, v14
	v_fmac_f32_e32 v223, v15, v15
	v_fmac_f32_e32 v222, v16, v16
	v_fmac_f32_e32 v223, v17, v17
	v_fmac_f32_e32 v222, v18, v18
	v_fmac_f32_e32 v223, v19, v19
	v_fmac_f32_e32 v222, v20, v20
	v_fmac_f32_e32 v223, v21, v21
	v_fmac_f32_e32 v222, v22, v22
	v_fmac_f32_e32 v223, v23, v23
	v_fmac_f32_e32 v222, v24, v24
	v_fmac_f32_e32 v223, v25, v25
	v_fmac_f32_e32 v222, v26, v26
	v_fmac_f32_e32 v223, v27, v27
	v_fmac_f32_e32 v222, v28, v28
	v_fmac_f32_e32 v223, v29, v29
	v_fmac_f32_e32 v222, v30, v30
	v_fmac_f32_e32 v223, v31, v31
	v_add_f32_e32 v222, v222, v223
	s_nop 1
	v_add_f32_dpp v224, v222, v222 quad_perm:[1,0,3,2] row_mask:0xf bank_mask:0xf
	s_nop 1
	v_add_f32_dpp v224, v224, v224 quad_perm:[2,3,0,1] row_mask:0xf bank_mask:0xf
	s_nop 1
	v_add_f32_dpp v224, v224, v224 row_half_mirror row_mask:0xf bank_mask:0xf
	s_nop 1
	v_add_f32_dpp v224, v224, v224 row_mirror row_mask:0xf bank_mask:0xf
	s_nop 1
	v_readlane_b32 s40, v224, 0
	v_readlane_b32 s41, v224, 16
	v_readlane_b32 s42, v224, 32
	v_readlane_b32 s43, v224, 48
	s_nop 1
; __device__ __forceinline__ unsigned cvt_pk_bf16(float lo, float hi) { unsigned r; asm volatile("v_cvt_pk_bf16_f32 %0, %1, %2" : "=v"(r) : "v"(lo), "v"(hi)); return r; }
; __device__ __forceinline__ void modulate_store(const f32x4 (&v)[8], float rstd, const float* pn, const float* modr, bf16_t* orow, int lane) {
; #pragma unroll
;     for (int j = 0; j < 8; ++j) { const int col = 4 * lane + 256 * j;
;         const f32x4 g = *(const f32x4*)(pn + col), sh = *(const f32x4*)(modr + col), sc = *(const f32x4*)(modr + DM + col);
;         const f32x4 hh = v[j] * rstd * g * (sc + 1.f) + sh;
;         u32x2 w; w.x = cvt_pk_bf16(hh[0], hh[1]); w.y = cvt_pk_bf16(hh[2], hh[3]);
;         *(u32x2*)(orow + col) = w; }
; }
; __global__ void __launch_bounds__(NWAVES * 64, 2) mk_fwd(Args args) {
;     ...
;             f32x4 v[3][8]; u32x2 yw[3][8];
; #pragma unroll
;             for (int q = 0; q < 3; ++q) { const int row = row0 + q; const float* src = row < ML ? x + (size_t)row * DM : ctx + (size_t)(row - ML) * DM; load_row_f32(src, F.lane, v[q]);
;                 const bf16_t* yr = Y + (size_t)row * DM;
; #pragma unroll
;                 for (int j = 0; j < 8; ++j) yw[q][j] = *(const u32x2*)(yr + 4 * F.lane + 256 * j); }
	v_mov_b32_e32 v225, s40
	v_add_f32_e32 v225, s41, v225
	v_add_f32_e32 v225, s42, v225
	v_add_f32_e32 v225, s43, v225
	v_fmamk_f32 v225, v225, 0x3a000000, v195
	v_rsq_f32_e32 v225, v225
	s_nop 0
	s_add_i32 s0, s6, 0
	s_lshl_b32 s1, s0, 12
	s_add_u32 s26, s84, s1
	s_addc_u32 s27, s85, 0
	s_add_u32 s26, s26, 0x4000000
	s_addc_u32 s27, s27, 0
	v_mul_f32_e32 v216, v225, v0
	v_mul_f32_e32 v217, v225, v1
	v_mul_f32_e32 v218, v225, v2
	v_mul_f32_e32 v219, v225, v3
	v_fma_f32 v216, v216, v128, v160
	v_fma_f32 v217, v217, v129, v161
	v_fma_f32 v218, v218, v130, v162
	v_fma_f32 v219, v219, v131, v163
	v_cvt_pk_bf16_f32 v196, v216, v217
	v_cvt_pk_bf16_f32 v197, v218, v219
	global_store_dwordx2 v194, v[196:197], s[26:27] offset:0
	v_mul_f32_e32 v216, v225, v4
	v_mul_f32_e32 v217, v225, v5
	v_mul_f32_e32 v218, v225, v6
	v_mul_f32_e32 v219, v225, v7
	v_fma_f32 v216, v216, v132, v164
	v_fma_f32 v217, v217, v133, v165
	v_fma_f32 v218, v218, v134, v166
	v_fma_f32 v219, v219, v135, v167
	v_cvt_pk_bf16_f32 v220, v216, v217
	v_cvt_pk_bf16_f32 v221, v218, v219
	global_store_dwordx2 v194, v[220:221], s[26:27] offset:512
	v_mul_f32_e32 v216, v225, v8
	v_mul_f32_e32 v217, v225, v9
	v_mul_f32_e32 v218, v225, v10
	v_mul_f32_e32 v219, v225, v11
	v_fma_f32 v216, v216, v136, v168
	v_fma_f32 v217, v217, v137, v169
	v_fma_f32 v218, v218, v138, v170
	v_fma_f32 v219, v219, v139, v171
	v_cvt_pk_bf16_f32 v196, v216, v217
	v_cvt_pk_bf16_f32 v197, v218, v219
	global_store_dwordx2 v194, v[196:197], s[26:27] offset:1024
	v_mul_f32_e32 v216, v225, v12
	v_mul_f32_e32 v217, v225, v13
	v_mul_f32_e32 v218, v225, v14
	v_mul_f32_e32 v219, v225, v15
	v_fma_f32 v216, v216, v140, v172
	v_fma_f32 v217, v217, v141, v173
	v_fma_f32 v218, v218, v142, v174
	v_fma_f32 v219, v219, v143, v175
	v_cvt_pk_bf16_f32 v220, v216, v217
	v_cvt_pk_bf16_f32 v221, v218, v219
	global_store_dwordx2 v194, v[220:221], s[26:27] offset:1536
	v_mul_f32_e32 v216, v225, v16
	v_mul_f32_e32 v217, v225, v17
	v_mul_f32_e32 v218, v225, v18
	v_mul_f32_e32 v219, v225, v19
	v_fma_f32 v216, v216, v144, v176
	v_fma_f32 v217, v217, v145, v177
	v_fma_f32 v218, v218, v146, v178
	v_fma_f32 v219, v219, v147, v179
	v_cvt_pk_bf16_f32 v196, v216, v217
	v_cvt_pk_bf16_f32 v197, v218, v219
	global_store_dwordx2 v194, v[196:197], s[26:27] offset:2048
	v_mul_f32_e32 v216, v225, v20
	v_mul_f32_e32 v217, v225, v21
	v_mul_f32_e32 v218, v225, v22
	v_mul_f32_e32 v219, v225, v23
	v_fma_f32 v216, v216, v148, v180
	v_fma_f32 v217, v217, v149, v181
	v_fma_f32 v218, v218, v150, v182
	v_fma_f32 v219, v219, v151, v183
	v_cvt_pk_bf16_f32 v220, v216, v217
	v_cvt_pk_bf16_f32 v221, v218, v219
	global_store_dwordx2 v194, v[220:221], s[26:27] offset:2560
	v_mul_f32_e32 v216, v225, v24
	v_mul_f32_e32 v217, v225, v25
	v_mul_f32_e32 v218, v225, v26
	v_mul_f32_e32 v219, v225, v27
	v_fma_f32 v216, v216, v152, v184
	v_fma_f32 v217, v217, v153, v185
	v_fma_f32 v218, v218, v154, v186
	v_fma_f32 v219, v219, v155, v187
	v_cvt_pk_bf16_f32 v196, v216, v217
	v_cvt_pk_bf16_f32 v197, v218, v219
	global_store_dwordx2 v194, v[196:197], s[26:27] offset:3072
	v_mul_f32_e32 v216, v225, v28
	v_mul_f32_e32 v217, v225, v29
	v_mul_f32_e32 v218, v225, v30
	v_mul_f32_e32 v219, v225, v31
	v_fma_f32 v216, v216, v156, v188
	v_fma_f32 v217, v217, v157, v189
	v_fma_f32 v218, v218, v158, v190
	v_fma_f32 v219, v219, v159, v191
	v_cvt_pk_bf16_f32 v220, v216, v217
	v_cvt_pk_bf16_f32 v221, v218, v219
	global_store_dwordx2 v194, v[220:221], s[26:27] offset:3584
	s_add_i32 s0, s6, 2
	s_cmp_lt_u32 s0, 0x4000
	s_cselect_b32 s10, s68, s72
	s_cselect_b32 s11, s69, s73
	s_cselect_b32 s1, 0, 0x4000
	s_sub_i32 s1, s0, s1
	s_lshl_b32 s1, s1, 13
	s_add_u32 s10, s10, s1
	s_addc_u32 s11, s11, 0
	s_add_i32 s0, s6, 2
	s_lshl_b32 s1, s0, 12
	s_add_u32 s22, s84, s1
	s_addc_u32 s23, s85, 0
	s_add_u32 s22, s22, 0x11800000
	s_addc_u32 s23, s23, 0
	global_load_dwordx4 v[0:3], v192, s[10:11] offset:0 nt
	global_load_dwordx4 v[4:7], v192, s[10:11] offset:1024 nt
	global_load_dwordx4 v[8:11], v192, s[10:11] offset:2048 nt
	global_load_dwordx4 v[12:15], v192, s[10:11] offset:3072 nt
	global_load_dwordx4 v[16:19], v193, s[10:11] offset:0 nt
	global_load_dwordx4 v[20:23], v193, s[10:11] offset:1024 nt
	global_load_dwordx4 v[24:27], v193, s[10:11] offset:2048 nt
	global_load_dwordx4 v[28:31], v193, s[10:11] offset:3072 nt
	global_load_dwordx2 v[32:33], v194, s[22:23] offset:0 nt
	global_load_dwordx2 v[34:35], v194, s[22:23] offset:512 nt
	global_load_dwordx2 v[36:37], v194, s[22:23] offset:1024 nt
	global_load_dwordx2 v[38:39], v194, s[22:23] offset:1536 nt
	global_load_dwordx2 v[40:41], v194, s[22:23] offset:2048 nt
	global_load_dwordx2 v[42:43], v194, s[22:23] offset:2560 nt
	global_load_dwordx2 v[44:45], v194, s[22:23] offset:3072 nt
	global_load_dwordx2 v[46:47], v194, s[22:23] offset:3584 nt
	s_add_i32 s0, s6, 1
	s_add_i32 s0, s6, 1
	s_lshr_b32 s8, s0, 11
	s_cmp_lt_u32 s0, 0x4000
	s_cselect_b32 s8, s8, 8
	s_cmp_eq_u32 s8, s7
	s_cbranch_scc1 .Lp6_np1
; __device__ __forceinline__ void modulate_store(const f32x4 (&v)[8], float rstd, const float* pn, const float* modr, bf16_t* orow, int lane) {
;     ...
;     for (int j = 0; j < 8; ++j) { const int col = 4 * lane + 256 * j;
;         const f32x4 g = *(const f32x4*)(pn + col), sh = *(const f32x4*)(modr + col), sc = *(const f32x4*)(modr + DM + col);
;         const f32x4 hh = v[j] * rstd * g * (sc + 1.f) + sh;
; __global__ void __launch_bounds__(NWAVES * 64, 2) mk_fwd(Args args) {
;     ...
;                 const float* m0 = mod + (size_t)r * 6144;
; #pragma unroll
;                 for (int j = 0; j < 8; ++j) { const int col = 4 * F.lane + 256 * j; const f32x4 gt = *(const f32x4*)(m0 + 2 * DM + col), pn = *(const f32x4*)(post_norm + col);
	s_mov_b32 s7, s8
	s_add_i32 s1, s8, 9
	s_mul_i32 s1, s1, 0x6000
	s_add_u32 s44, s84, s1
	s_addc_u32 s45, s85, 0
	s_add_u32 s44, s44, 0x2000
	s_addc_u32 s45, s45, 0
	s_add_i32 s1, s8, 9
	s_mul_i32 s1, s1, 0x6000
	s_add_u32 s36, s84, s1
	s_addc_u32 s37, s85, 0
	s_add_u32 s38, s80, 0x2000
	s_addc_u32 s39, s81, 0
	s_mul_i32 s1, s8, 0x6000
	s_add_u32 s34, s84, s1
	s_addc_u32 s35, s85, 0
	s_add_u32 s34, s34, 0x4000
	s_addc_u32 s35, s35, 0
	global_load_dwordx4 v[96:99], v192, s[34:35] offset:0
	global_load_dwordx4 v[200:203], v192, s[82:83] offset:0
	global_load_dwordx4 v[100:103], v192, s[34:35] offset:1024
	global_load_dwordx4 v[204:207], v192, s[82:83] offset:1024
	global_load_dwordx4 v[104:107], v192, s[34:35] offset:2048
	global_load_dwordx4 v[208:211], v192, s[82:83] offset:2048
	global_load_dwordx4 v[108:111], v192, s[34:35] offset:3072
	global_load_dwordx4 v[212:215], v192, s[82:83] offset:3072
	s_waitcnt vmcnt(0)
	v_mul_f32_e32 v96, v96, v200
	v_mul_f32_e32 v97, v97, v201
	v_mul_f32_e32 v98, v98, v202
	v_mul_f32_e32 v99, v99, v203
	v_mul_f32_e32 v100, v100, v204
	v_mul_f32_e32 v101, v101, v205
	v_mul_f32_e32 v102, v102, v206
	v_mul_f32_e32 v103, v103, v207
	v_mul_f32_e32 v104, v104, v208
	v_mul_f32_e32 v105, v105, v209
	v_mul_f32_e32 v106, v106, v210
	v_mul_f32_e32 v107, v107, v211
	v_mul_f32_e32 v108, v108, v212
	v_mul_f32_e32 v109, v109, v213
	v_mul_f32_e32 v110, v110, v214
	v_mul_f32_e32 v111, v111, v215
	global_load_dwordx4 v[128:131], v192, s[38:39] offset:0
	global_load_dwordx4 v[200:203], v192, s[44:45] offset:0
	global_load_dwordx4 v[160:163], v192, s[36:37] offset:0
	global_load_dwordx4 v[132:135], v192, s[38:39] offset:1024
	global_load_dwordx4 v[204:207], v192, s[44:45] offset:1024
	global_load_dwordx4 v[164:167], v192, s[36:37] offset:1024
	global_load_dwordx4 v[136:139], v192, s[38:39] offset:2048
	global_load_dwordx4 v[208:211], v192, s[44:45] offset:2048
	global_load_dwordx4 v[168:171], v192, s[36:37] offset:2048
	global_load_dwordx4 v[140:143], v192, s[38:39] offset:3072
	global_load_dwordx4 v[212:215], v192, s[44:45] offset:3072
	global_load_dwordx4 v[172:175], v192, s[36:37] offset:3072
	s_waitcnt vmcnt(0)
	v_add_f32_e32 v200, 1.0, v200
	v_add_f32_e32 v201, 1.0, v201
	v_add_f32_e32 v202, 1.0, v202
	v_add_f32_e32 v203, 1.0, v203
	v_mul_f32_e32 v128, v128, v200
	v_mul_f32_e32 v129, v129, v201
	v_mul_f32_e32 v130, v130, v202
	v_mul_f32_e32 v131, v131, v203
	v_add_f32_e32 v204, 1.0, v204
	v_add_f32_e32 v205, 1.0, v205
	v_add_f32_e32 v206, 1.0, v206
	v_add_f32_e32 v207, 1.0, v207
	v_mul_f32_e32 v132, v132, v204
	v_mul_f32_e32 v133, v133, v205
	v_mul_f32_e32 v134, v134, v206
	v_mul_f32_e32 v135, v135, v207
	v_add_f32_e32 v208, 1.0, v208
	v_add_f32_e32 v209, 1.0, v209
	v_add_f32_e32 v210, 1.0, v210
	v_add_f32_e32 v211, 1.0, v211
	v_mul_f32_e32 v136, v136, v208
	v_mul_f32_e32 v137, v137, v209
	v_mul_f32_e32 v138, v138, v210
	v_mul_f32_e32 v139, v139, v211
	v_add_f32_e32 v212, 1.0, v212
	v_add_f32_e32 v213, 1.0, v213
	v_add_f32_e32 v214, 1.0, v214
	v_add_f32_e32 v215, 1.0, v215
	v_mul_f32_e32 v140, v140, v212
	v_mul_f32_e32 v141, v141, v213
	v_mul_f32_e32 v142, v142, v214
	v_mul_f32_e32 v143, v143, v215
	global_load_dwordx4 v[112:115], v193, s[34:35] offset:0
	global_load_dwordx4 v[200:203], v193, s[82:83] offset:0
	global_load_dwordx4 v[116:119], v193, s[34:35] offset:1024
	global_load_dwordx4 v[204:207], v193, s[82:83] offset:1024
	global_load_dwordx4 v[120:123], v193, s[34:35] offset:2048
	global_load_dwordx4 v[208:211], v193, s[82:83] offset:2048
	global_load_dwordx4 v[124:127], v193, s[34:35] offset:3072
	global_load_dwordx4 v[212:215], v193, s[82:83] offset:3072
	s_waitcnt vmcnt(0)
	v_mul_f32_e32 v112, v112, v200
	v_mul_f32_e32 v113, v113, v201
	v_mul_f32_e32 v114, v114, v202
	v_mul_f32_e32 v115, v115, v203
	v_mul_f32_e32 v116, v116, v204
	v_mul_f32_e32 v117, v117, v205
	v_mul_f32_e32 v118, v118, v206
	v_mul_f32_e32 v119, v119, v207
	v_mul_f32_e32 v120, v120, v208
	v_mul_f32_e32 v121, v121, v209
	v_mul_f32_e32 v122, v122, v210
	v_mul_f32_e32 v123, v123, v211
	v_mul_f32_e32 v124, v124, v212
	v_mul_f32_e32 v125, v125, v213
	v_mul_f32_e32 v126, v126, v214
	v_mul_f32_e32 v127, v127, v215
	global_load_dwordx4 v[144:147], v193, s[38:39] offset:0
	global_load_dwordx4 v[200:203], v193, s[44:45] offset:0
	global_load_dwordx4 v[176:179], v193, s[36:37] offset:0
	global_load_dwordx4 v[148:151], v193, s[38:39] offset:1024
	global_load_dwordx4 v[204:207], v193, s[44:45] offset:1024
	global_load_dwordx4 v[180:183], v193, s[36:37] offset:1024
	global_load_dwordx4 v[152:155], v193, s[38:39] offset:2048
	global_load_dwordx4 v[208:211], v193, s[44:45] offset:2048
	global_load_dwordx4 v[184:187], v193, s[36:37] offset:2048
	global_load_dwordx4 v[156:159], v193, s[38:39] offset:3072
	global_load_dwordx4 v[212:215], v193, s[44:45] offset:3072
	global_load_dwordx4 v[188:191], v193, s[36:37] offset:3072
	s_waitcnt vmcnt(0)
	v_add_f32_e32 v200, 1.0, v200
	v_add_f32_e32 v201, 1.0, v201
	v_add_f32_e32 v202, 1.0, v202
	v_add_f32_e32 v203, 1.0, v203
	v_mul_f32_e32 v144, v144, v200
	v_mul_f32_e32 v145, v145, v201
	v_mul_f32_e32 v146, v146, v202
	v_mul_f32_e32 v147, v147, v203
	v_add_f32_e32 v204, 1.0, v204
	v_add_f32_e32 v205, 1.0, v205
	v_add_f32_e32 v206, 1.0, v206
	v_add_f32_e32 v207, 1.0, v207
	v_mul_f32_e32 v148, v148, v204
	v_mul_f32_e32 v149, v149, v205
	v_mul_f32_e32 v150, v150, v206
	v_mul_f32_e32 v151, v151, v207
	v_add_f32_e32 v208, 1.0, v208
	v_add_f32_e32 v209, 1.0, v209
	v_add_f32_e32 v210, 1.0, v210
	v_add_f32_e32 v211, 1.0, v211
	v_mul_f32_e32 v152, v152, v208
	v_mul_f32_e32 v153, v153, v209
	v_mul_f32_e32 v154, v154, v210
	v_mul_f32_e32 v155, v155, v211
	v_add_f32_e32 v212, 1.0, v212
	v_add_f32_e32 v213, 1.0, v213
	v_add_f32_e32 v214, 1.0, v214
	v_add_f32_e32 v215, 1.0, v215
	v_mul_f32_e32 v156, v156, v212
	v_mul_f32_e32 v157, v157, v213
	v_mul_f32_e32 v158, v158, v214
	v_mul_f32_e32 v159, v159, v215
; __device__ __forceinline__ float bf_lo(unsigned w) { return __uint_as_float(w << 16); }
; __device__ __forceinline__ float bf_hi(unsigned w) { return __uint_as_float(w & 0xffff0000u); }
; __global__ void __launch_bounds__(NWAVES * 64, 2) mk_fwd(Args args) {
;     ...
;             for (int q = 0; q < 3; ++q) { const int row = row0 + q; const bool lat = row < ML; const int r = lat ? row / SEQ : 8;
;                 float sy = 0.f;
; #pragma unroll
;                 for (int j = 0; j < 8; ++j) { const float a = bf_lo(yw[q][j].x), b = bf_hi(yw[q][j].x), c2 = bf_lo(yw[q][j].y), d = bf_hi(yw[q][j].y); sy += (a * a + b * b) + (c2 * c2 + d * d); }
;                 const float rsy = __builtin_amdgcn_rsqf(wave_sum(sy) * (1.f / DM) + EPS);
;                 const float* m0 = mod + (size_t)r * 6144;
; #pragma unroll
;                 for (int j = 0; j < 8; ++j) { const int col = 4 * F.lane + 256 * j; const f32x4 gt = *(const f32x4*)(m0 + 2 * DM + col), pn = *(const f32x4*)(post_norm + col);
;                     const f32x4 y4 = (f32x4){bf_lo(yw[q][j].x), bf_hi(yw[q][j].x), bf_lo(yw[q][j].y), bf_hi(yw[q][j].y)};
;                     v[q][j] = v[q][j] + gt * (y4 * rsy * pn);
.Lp6_np1:
	s_waitcnt vmcnt(24)
	v_lshlrev_b32_e32 v216, 16, v80
	v_and_b32_e32 v217, 0xffff0000, v80
	v_lshlrev_b32_e32 v218, 16, v81
	v_and_b32_e32 v219, 0xffff0000, v81
	v_mul_f32_e32 v222, v216, v216
	v_mul_f32_e32 v223, v217, v217
	v_fmac_f32_e32 v222, v218, v218
	v_fmac_f32_e32 v223, v219, v219
	v_lshlrev_b32_e32 v216, 16, v82
	v_and_b32_e32 v217, 0xffff0000, v82
	v_lshlrev_b32_e32 v218, 16, v83
	v_and_b32_e32 v219, 0xffff0000, v83
	v_fmac_f32_e32 v222, v216, v216
	v_fmac_f32_e32 v223, v217, v217
	v_fmac_f32_e32 v222, v218, v218
	v_fmac_f32_e32 v223, v219, v219
	v_lshlrev_b32_e32 v216, 16, v84
	v_and_b32_e32 v217, 0xffff0000, v84
	v_lshlrev_b32_e32 v218, 16, v85
	v_and_b32_e32 v219, 0xffff0000, v85
	v_fmac_f32_e32 v222, v216, v216
	v_fmac_f32_e32 v223, v217, v217
	v_fmac_f32_e32 v222, v218, v218
	v_fmac_f32_e32 v223, v219, v219
	v_lshlrev_b32_e32 v216, 16, v86
	v_and_b32_e32 v217, 0xffff0000, v86
	v_lshlrev_b32_e32 v218, 16, v87
	v_and_b32_e32 v219, 0xffff0000, v87
	v_fmac_f32_e32 v222, v216, v216
	v_fmac_f32_e32 v223, v217, v217
	v_fmac_f32_e32 v222, v218, v218
	v_fmac_f32_e32 v223, v219, v219
	v_lshlrev_b32_e32 v216, 16, v88
	v_and_b32_e32 v217, 0xffff0000, v88
	v_lshlrev_b32_e32 v218, 16, v89
	v_and_b32_e32 v219, 0xffff0000, v89
	v_fmac_f32_e32 v222, v216, v216
	v_fmac_f32_e32 v223, v217, v217
	v_fmac_f32_e32 v222, v218, v218
	v_fmac_f32_e32 v223, v219, v219
	v_lshlrev_b32_e32 v216, 16, v90
	v_and_b32_e32 v217, 0xffff0000, v90
	v_lshlrev_b32_e32 v218, 16, v91
	v_and_b32_e32 v219, 0xffff0000, v91
	v_fmac_f32_e32 v222, v216, v216
	v_fmac_f32_e32 v223, v217, v217
	v_fmac_f32_e32 v222, v218, v218
	v_fmac_f32_e32 v223, v219, v219
	v_lshlrev_b32_e32 v216, 16, v92
	v_and_b32_e32 v217, 0xffff0000, v92
	v_lshlrev_b32_e32 v218, 16, v93
	v_and_b32_e32 v219, 0xffff0000, v93
	v_fmac_f32_e32 v222, v216, v216
	v_fmac_f32_e32 v223, v217, v217
	v_fmac_f32_e32 v222, v218, v218
	v_fmac_f32_e32 v223, v219, v219
	v_lshlrev_b32_e32 v216, 16, v94
	v_and_b32_e32 v217, 0xffff0000, v94
	v_lshlrev_b32_e32 v218, 16, v95
	v_and_b32_e32 v219, 0xffff0000, v95
	v_fmac_f32_e32 v222, v216, v216
	v_fmac_f32_e32 v223, v217, v217
	v_fmac_f32_e32 v222, v218, v218
	v_fmac_f32_e32 v223, v219, v219
	v_add_f32_e32 v222, v222, v223
	s_nop 1
	v_add_f32_dpp v224, v222, v222 quad_perm:[1,0,3,2] row_mask:0xf bank_mask:0xf
	s_nop 1
	v_add_f32_dpp v224, v224, v224 quad_perm:[2,3,0,1] row_mask:0xf bank_mask:0xf
	s_nop 1
	v_add_f32_dpp v224, v224, v224 row_half_mirror row_mask:0xf bank_mask:0xf
	s_nop 1
	v_add_f32_dpp v224, v224, v224 row_mirror row_mask:0xf bank_mask:0xf
	s_nop 1
	v_readlane_b32 s40, v224, 0
	v_readlane_b32 s41, v224, 16
	v_readlane_b32 s42, v224, 32
	v_readlane_b32 s43, v224, 48
	s_nop 1
	v_mov_b32_e32 v225, s40
	v_add_f32_e32 v225, s41, v225
	v_add_f32_e32 v225, s42, v225
	v_add_f32_e32 v225, s43, v225
	v_fmamk_f32 v225, v225, 0x3a000000, v195
	v_rsq_f32_e32 v225, v225
	s_nop 0
	v_lshlrev_b32_e32 v216, 16, v80
	v_and_b32_e32 v217, 0xffff0000, v80
	v_lshlrev_b32_e32 v218, 16, v81
	v_and_b32_e32 v219, 0xffff0000, v81
	v_mul_f32_e32 v216, v225, v216
	v_mul_f32_e32 v217, v225, v217
	v_mul_f32_e32 v218, v225, v218
	v_mul_f32_e32 v219, v225, v219
	v_fmac_f32_e32 v48, v96, v216
	v_fmac_f32_e32 v49, v97, v217
	v_fmac_f32_e32 v50, v98, v218
	v_fmac_f32_e32 v51, v99, v219
	v_lshlrev_b32_e32 v216, 16, v82
	v_and_b32_e32 v217, 0xffff0000, v82
	v_lshlrev_b32_e32 v218, 16, v83
	v_and_b32_e32 v219, 0xffff0000, v83
	v_mul_f32_e32 v216, v225, v216
	v_mul_f32_e32 v217, v225, v217
	v_mul_f32_e32 v218, v225, v218
	v_mul_f32_e32 v219, v225, v219
	v_fmac_f32_e32 v52, v100, v216
	v_fmac_f32_e32 v53, v101, v217
	v_fmac_f32_e32 v54, v102, v218
	v_fmac_f32_e32 v55, v103, v219
	v_lshlrev_b32_e32 v216, 16, v84
	v_and_b32_e32 v217, 0xffff0000, v84
	v_lshlrev_b32_e32 v218, 16, v85
	v_and_b32_e32 v219, 0xffff0000, v85
	v_mul_f32_e32 v216, v225, v216
	v_mul_f32_e32 v217, v225, v217
	v_mul_f32_e32 v218, v225, v218
	v_mul_f32_e32 v219, v225, v219
	v_fmac_f32_e32 v56, v104, v216
	v_fmac_f32_e32 v57, v105, v217
	v_fmac_f32_e32 v58, v106, v218
	v_fmac_f32_e32 v59, v107, v219
	v_lshlrev_b32_e32 v216, 16, v86
	v_and_b32_e32 v217, 0xffff0000, v86
	v_lshlrev_b32_e32 v218, 16, v87
	v_and_b32_e32 v219, 0xffff0000, v87
	v_mul_f32_e32 v216, v225, v216
	v_mul_f32_e32 v217, v225, v217
	v_mul_f32_e32 v218, v225, v218
	v_mul_f32_e32 v219, v225, v219
	v_fmac_f32_e32 v60, v108, v216
	v_fmac_f32_e32 v61, v109, v217
	v_fmac_f32_e32 v62, v110, v218
	v_fmac_f32_e32 v63, v111, v219
	v_lshlrev_b32_e32 v216, 16, v88
	v_and_b32_e32 v217, 0xffff0000, v88
	v_lshlrev_b32_e32 v218, 16, v89
	v_and_b32_e32 v219, 0xffff0000, v89
	v_mul_f32_e32 v216, v225, v216
	v_mul_f32_e32 v217, v225, v217
	v_mul_f32_e32 v218, v225, v218
	v_mul_f32_e32 v219, v225, v219
	v_fmac_f32_e32 v64, v112, v216
	v_fmac_f32_e32 v65, v113, v217
	v_fmac_f32_e32 v66, v114, v218
	v_fmac_f32_e32 v67, v115, v219
	v_lshlrev_b32_e32 v216, 16, v90
	v_and_b32_e32 v217, 0xffff0000, v90
	v_lshlrev_b32_e32 v218, 16, v91
	v_and_b32_e32 v219, 0xffff0000, v91
	v_mul_f32_e32 v216, v225, v216
	v_mul_f32_e32 v217, v225, v217
	v_mul_f32_e32 v218, v225, v218
	v_mul_f32_e32 v219, v225, v219
	v_fmac_f32_e32 v68, v116, v216
	v_fmac_f32_e32 v69, v117, v217
	v_fmac_f32_e32 v70, v118, v218
	v_fmac_f32_e32 v71, v119, v219
	v_lshlrev_b32_e32 v216, 16, v92
	v_and_b32_e32 v217, 0xffff0000, v92
	v_lshlrev_b32_e32 v218, 16, v93
	v_and_b32_e32 v219, 0xffff0000, v93
	v_mul_f32_e32 v216, v225, v216
	v_mul_f32_e32 v217, v225, v217
	v_mul_f32_e32 v218, v225, v218
	v_mul_f32_e32 v219, v225, v219
	v_fmac_f32_e32 v72, v120, v216
	v_fmac_f32_e32 v73, v121, v217
	v_fmac_f32_e32 v74, v122, v218
; __device__ __forceinline__ unsigned cvt_pk_bf16(float lo, float hi) { unsigned r; asm volatile("v_cvt_pk_bf16_f32 %0, %1, %2" : "=v"(r) : "v"(lo), "v"(hi)); return r; }
; __device__ __forceinline__ void modulate_store(const f32x4 (&v)[8], float rstd, const float* pn, const float* modr, bf16_t* orow, int lane) {
; #pragma unroll
;     for (int j = 0; j < 8; ++j) { const int col = 4 * lane + 256 * j;
;         const f32x4 g = *(const f32x4*)(pn + col), sh = *(const f32x4*)(modr + col), sc = *(const f32x4*)(modr + DM + col);
;         const f32x4 hh = v[j] * rstd * g * (sc + 1.f) + sh;
;         u32x2 w; w.x = cvt_pk_bf16(hh[0], hh[1]); w.y = cvt_pk_bf16(hh[2], hh[3]);
;         *(u32x2*)(orow + col) = w; }
; }
; __global__ void __launch_bounds__(NWAVES * 64, 2) mk_fwd(Args args) {
;     ...
;                 const float rstd = __builtin_amdgcn_rsqf(sumsq8(v[q]) * (1.f / DM) + EPS);
;                 modulate_store(v[q], rstd, pre_norm + DM, mod + (size_t)(9 + r) * 6144, H + (size_t)row * DM, F.lane); }
	v_fmac_f32_e32 v75, v123, v219
	v_lshlrev_b32_e32 v216, 16, v94
	v_and_b32_e32 v217, 0xffff0000, v94
	v_lshlrev_b32_e32 v218, 16, v95
	v_and_b32_e32 v219, 0xffff0000, v95
	v_mul_f32_e32 v216, v225, v216
	v_mul_f32_e32 v217, v225, v217
	v_mul_f32_e32 v218, v225, v218
	v_mul_f32_e32 v219, v225, v219
	v_fmac_f32_e32 v76, v124, v216
	v_fmac_f32_e32 v77, v125, v217
	v_fmac_f32_e32 v78, v126, v218
	v_fmac_f32_e32 v79, v127, v219
	v_mul_f32_e32 v222, v48, v48
	v_mul_f32_e32 v223, v49, v49
	v_fmac_f32_e32 v222, v50, v50
	v_fmac_f32_e32 v223, v51, v51
	v_fmac_f32_e32 v222, v52, v52
	v_fmac_f32_e32 v223, v53, v53
	v_fmac_f32_e32 v222, v54, v54
	v_fmac_f32_e32 v223, v55, v55
	v_fmac_f32_e32 v222, v56, v56
	v_fmac_f32_e32 v223, v57, v57
	v_fmac_f32_e32 v222, v58, v58
	v_fmac_f32_e32 v223, v59, v59
	v_fmac_f32_e32 v222, v60, v60
	v_fmac_f32_e32 v223, v61, v61
	v_fmac_f32_e32 v222, v62, v62
	v_fmac_f32_e32 v223, v63, v63
	v_fmac_f32_e32 v222, v64, v64
	v_fmac_f32_e32 v223, v65, v65
	v_fmac_f32_e32 v222, v66, v66
	v_fmac_f32_e32 v223, v67, v67
	v_fmac_f32_e32 v222, v68, v68
	v_fmac_f32_e32 v223, v69, v69
	v_fmac_f32_e32 v222, v70, v70
	v_fmac_f32_e32 v223, v71, v71
	v_fmac_f32_e32 v222, v72, v72
	v_fmac_f32_e32 v223, v73, v73
	v_fmac_f32_e32 v222, v74, v74
	v_fmac_f32_e32 v223, v75, v75
	v_fmac_f32_e32 v222, v76, v76
	v_fmac_f32_e32 v223, v77, v77
	v_fmac_f32_e32 v222, v78, v78
	v_fmac_f32_e32 v223, v79, v79
	v_add_f32_e32 v222, v222, v223
	s_nop 1
	v_add_f32_dpp v224, v222, v222 quad_perm:[1,0,3,2] row_mask:0xf bank_mask:0xf
	s_nop 1
	v_add_f32_dpp v224, v224, v224 quad_perm:[2,3,0,1] row_mask:0xf bank_mask:0xf
	s_nop 1
	v_add_f32_dpp v224, v224, v224 row_half_mirror row_mask:0xf bank_mask:0xf
	s_nop 1
	v_add_f32_dpp v224, v224, v224 row_mirror row_mask:0xf bank_mask:0xf
	s_nop 1
	v_readlane_b32 s40, v224, 0
	v_readlane_b32 s41, v224, 16
	v_readlane_b32 s42, v224, 32
	v_readlane_b32 s43, v224, 48
	s_nop 1
	v_mov_b32_e32 v225, s40
	v_add_f32_e32 v225, s41, v225
	v_add_f32_e32 v225, s42, v225
	v_add_f32_e32 v225, s43, v225
	v_fmamk_f32 v225, v225, 0x3a000000, v195
	v_rsq_f32_e32 v225, v225
	s_nop 0
	s_add_i32 s0, s6, 1
	s_lshl_b32 s1, s0, 12
	s_add_u32 s26, s84, s1
	s_addc_u32 s27, s85, 0
	s_add_u32 s26, s26, 0x4000000
	s_addc_u32 s27, s27, 0
	v_mul_f32_e32 v216, v225, v48
	v_mul_f32_e32 v217, v225, v49
	v_mul_f32_e32 v218, v225, v50
	v_mul_f32_e32 v219, v225, v51
	v_fma_f32 v216, v216, v128, v160
	v_fma_f32 v217, v217, v129, v161
	v_fma_f32 v218, v218, v130, v162
	v_fma_f32 v219, v219, v131, v163
	v_cvt_pk_bf16_f32 v196, v216, v217
	v_cvt_pk_bf16_f32 v197, v218, v219
	global_store_dwordx2 v194, v[196:197], s[26:27] offset:0
	v_mul_f32_e32 v216, v225, v52
	v_mul_f32_e32 v217, v225, v53
	v_mul_f32_e32 v218, v225, v54
	v_mul_f32_e32 v219, v225, v55
	v_fma_f32 v216, v216, v132, v164
	v_fma_f32 v217, v217, v133, v165
	v_fma_f32 v218, v218, v134, v166
	v_fma_f32 v219, v219, v135, v167
	v_cvt_pk_bf16_f32 v220, v216, v217
	v_cvt_pk_bf16_f32 v221, v218, v219
	global_store_dwordx2 v194, v[220:221], s[26:27] offset:512
	v_mul_f32_e32 v216, v225, v56
	v_mul_f32_e32 v217, v225, v57
	v_mul_f32_e32 v218, v225, v58
	v_mul_f32_e32 v219, v225, v59
	v_fma_f32 v216, v216, v136, v168
	v_fma_f32 v217, v217, v137, v169
	v_fma_f32 v218, v218, v138, v170
	v_fma_f32 v219, v219, v139, v171
	v_cvt_pk_bf16_f32 v196, v216, v217
	v_cvt_pk_bf16_f32 v197, v218, v219
	global_store_dwordx2 v194, v[196:197], s[26:27] offset:1024
	v_mul_f32_e32 v216, v225, v60
	v_mul_f32_e32 v217, v225, v61
	v_mul_f32_e32 v218, v225, v62
	v_mul_f32_e32 v219, v225, v63
	v_fma_f32 v216, v216, v140, v172
	v_fma_f32 v217, v217, v141, v173
	v_fma_f32 v218, v218, v142, v174
	v_fma_f32 v219, v219, v143, v175
	v_cvt_pk_bf16_f32 v220, v216, v217
	v_cvt_pk_bf16_f32 v221, v218, v219
	global_store_dwordx2 v194, v[220:221], s[26:27] offset:1536
	v_mul_f32_e32 v216, v225, v64
	v_mul_f32_e32 v217, v225, v65
	v_mul_f32_e32 v218, v225, v66
	v_mul_f32_e32 v219, v225, v67
	v_fma_f32 v216, v216, v144, v176
	v_fma_f32 v217, v217, v145, v177
	v_fma_f32 v218, v218, v146, v178
	v_fma_f32 v219, v219, v147, v179
	v_cvt_pk_bf16_f32 v196, v216, v217
	v_cvt_pk_bf16_f32 v197, v218, v219
	global_store_dwordx2 v194, v[196:197], s[26:27] offset:2048
	v_mul_f32_e32 v216, v225, v68
	v_mul_f32_e32 v217, v225, v69
	v_mul_f32_e32 v218, v225, v70
	v_mul_f32_e32 v219, v225, v71
	v_fma_f32 v216, v216, v148, v180
	v_fma_f32 v217, v217, v149, v181
	v_fma_f32 v218, v218, v150, v182
	v_fma_f32 v219, v219, v151, v183
	v_cvt_pk_bf16_f32 v220, v216, v217
	v_cvt_pk_bf16_f32 v221, v218, v219
	global_store_dwordx2 v194, v[220:221], s[26:27] offset:2560
	v_mul_f32_e32 v216, v225, v72
	v_mul_f32_e32 v217, v225, v73
	v_mul_f32_e32 v218, v225, v74
	v_mul_f32_e32 v219, v225, v75
	v_fma_f32 v216, v216, v152, v184
	v_fma_f32 v217, v217, v153, v185
	v_fma_f32 v218, v218, v154, v186
	v_fma_f32 v219, v219, v155, v187
	v_cvt_pk_bf16_f32 v196, v216, v217
	v_cvt_pk_bf16_f32 v197, v218, v219
	global_store_dwordx2 v194, v[196:197], s[26:27] offset:3072
	v_mul_f32_e32 v216, v225, v76
	v_mul_f32_e32 v217, v225, v77
	v_mul_f32_e32 v218, v225, v78
	v_mul_f32_e32 v219, v225, v79
	v_fma_f32 v216, v216, v156, v188
	v_fma_f32 v217, v217, v157, v189
	v_fma_f32 v218, v218, v158, v190
	v_fma_f32 v219, v219, v159, v191
	v_cvt_pk_bf16_f32 v220, v216, v217
	v_cvt_pk_bf16_f32 v221, v218, v219
	global_store_dwordx2 v194, v[220:221], s[26:27] offset:3584
	s_add_i32 s0, s6, 3
	s_cmp_lt_u32 s0, 0x4000
	s_cselect_b32 s10, s68, s72
	s_cselect_b32 s11, s69, s73
	s_cselect_b32 s1, 0, 0x4000
	s_sub_i32 s1, s0, s1
	s_lshl_b32 s1, s1, 13
	s_add_u32 s10, s10, s1
	s_addc_u32 s11, s11, 0
	s_add_i32 s0, s6, 3
	s_lshl_b32 s1, s0, 12
	s_add_u32 s22, s84, s1
	s_addc_u32 s23, s85, 0
	s_add_u32 s22, s22, 0x11800000
	s_addc_u32 s23, s23, 0
	global_load_dwordx4 v[48:51], v192, s[10:11] offset:0 nt
	global_load_dwordx4 v[52:55], v192, s[10:11] offset:1024 nt
	global_load_dwordx4 v[56:59], v192, s[10:11] offset:2048 nt
	global_load_dwordx4 v[60:63], v192, s[10:11] offset:3072 nt
	global_load_dwordx4 v[64:67], v193, s[10:11] offset:0 nt
	global_load_dwordx4 v[68:71], v193, s[10:11] offset:1024 nt
	global_load_dwordx4 v[72:75], v193, s[10:11] offset:2048 nt
	global_load_dwordx4 v[76:79], v193, s[10:11] offset:3072 nt
	global_load_dwordx2 v[80:81], v194, s[22:23] offset:0 nt
	global_load_dwordx2 v[82:83], v194, s[22:23] offset:512 nt
	global_load_dwordx2 v[84:85], v194, s[22:23] offset:1024 nt
	global_load_dwordx2 v[86:87], v194, s[22:23] offset:1536 nt
	global_load_dwordx2 v[88:89], v194, s[22:23] offset:2048 nt
	global_load_dwordx2 v[90:91], v194, s[22:23] offset:2560 nt
	global_load_dwordx2 v[92:93], v194, s[22:23] offset:3072 nt
	global_load_dwordx2 v[94:95], v194, s[22:23] offset:3584 nt
	s_add_i32 s0, s6, 2
	s_add_i32 s0, s6, 2
	s_lshr_b32 s8, s0, 11
	s_cmp_lt_u32 s0, 0x4000
	s_cselect_b32 s8, s8, 8
	s_cmp_eq_u32 s8, s7
	s_cbranch_scc1 .Lp6_np2
; __device__ __forceinline__ void modulate_store(const f32x4 (&v)[8], float rstd, const float* pn, const float* modr, bf16_t* orow, int lane) {
;     ...
;     for (int j = 0; j < 8; ++j) { const int col = 4 * lane + 256 * j;
;         const f32x4 g = *(const f32x4*)(pn + col), sh = *(const f32x4*)(modr + col), sc = *(const f32x4*)(modr + DM + col);
;         const f32x4 hh = v[j] * rstd * g * (sc + 1.f) + sh;
; __global__ void __launch_bounds__(NWAVES * 64, 2) mk_fwd(Args args) {
;     ...
;                 const float* m0 = mod + (size_t)r * 6144;
; #pragma unroll
;                 for (int j = 0; j < 8; ++j) { const int col = 4 * F.lane + 256 * j; const f32x4 gt = *(const f32x4*)(m0 + 2 * DM + col), pn = *(const f32x4*)(post_norm + col);
	s_mov_b32 s7, s8
	s_add_i32 s1, s8, 9
	s_mul_i32 s1, s1, 0x6000
	s_add_u32 s44, s84, s1
	s_addc_u32 s45, s85, 0
	s_add_u32 s44, s44, 0x2000
	s_addc_u32 s45, s45, 0
	s_add_i32 s1, s8, 9
	s_mul_i32 s1, s1, 0x6000
	s_add_u32 s36, s84, s1
	s_addc_u32 s37, s85, 0
	s_add_u32 s38, s80, 0x2000
	s_addc_u32 s39, s81, 0
	s_mul_i32 s1, s8, 0x6000
	s_add_u32 s34, s84, s1
	s_addc_u32 s35, s85, 0
	s_add_u32 s34, s34, 0x4000
	s_addc_u32 s35, s35, 0
	global_load_dwordx4 v[96:99], v192, s[34:35] offset:0
	global_load_dwordx4 v[200:203], v192, s[82:83] offset:0
	global_load_dwordx4 v[100:103], v192, s[34:35] offset:1024
	global_load_dwordx4 v[204:207], v192, s[82:83] offset:1024
	global_load_dwordx4 v[104:107], v192, s[34:35] offset:2048
	global_load_dwordx4 v[208:211], v192, s[82:83] offset:2048
	global_load_dwordx4 v[108:111], v192, s[34:35] offset:3072
	global_load_dwordx4 v[212:215], v192, s[82:83] offset:3072
	s_waitcnt vmcnt(0)
	v_mul_f32_e32 v96, v96, v200
	v_mul_f32_e32 v97, v97, v201
	v_mul_f32_e32 v98, v98, v202
	v_mul_f32_e32 v99, v99, v203
	v_mul_f32_e32 v100, v100, v204
	v_mul_f32_e32 v101, v101, v205
	v_mul_f32_e32 v102, v102, v206
	v_mul_f32_e32 v103, v103, v207
	v_mul_f32_e32 v104, v104, v208
	v_mul_f32_e32 v105, v105, v209
	v_mul_f32_e32 v106, v106, v210
	v_mul_f32_e32 v107, v107, v211
	v_mul_f32_e32 v108, v108, v212
	v_mul_f32_e32 v109, v109, v213
	v_mul_f32_e32 v110, v110, v214
	v_mul_f32_e32 v111, v111, v215
	global_load_dwordx4 v[128:131], v192, s[38:39] offset:0
	global_load_dwordx4 v[200:203], v192, s[44:45] offset:0
	global_load_dwordx4 v[160:163], v192, s[36:37] offset:0
	global_load_dwordx4 v[132:135], v192, s[38:39] offset:1024
	global_load_dwordx4 v[204:207], v192, s[44:45] offset:1024
	global_load_dwordx4 v[164:167], v192, s[36:37] offset:1024
	global_load_dwordx4 v[136:139], v192, s[38:39] offset:2048
	global_load_dwordx4 v[208:211], v192, s[44:45] offset:2048
	global_load_dwordx4 v[168:171], v192, s[36:37] offset:2048
	global_load_dwordx4 v[140:143], v192, s[38:39] offset:3072
	global_load_dwordx4 v[212:215], v192, s[44:45] offset:3072
	global_load_dwordx4 v[172:175], v192, s[36:37] offset:3072
	s_waitcnt vmcnt(0)
	v_add_f32_e32 v200, 1.0, v200
	v_add_f32_e32 v201, 1.0, v201
	v_add_f32_e32 v202, 1.0, v202
	v_add_f32_e32 v203, 1.0, v203
	v_mul_f32_e32 v128, v128, v200
	v_mul_f32_e32 v129, v129, v201
	v_mul_f32_e32 v130, v130, v202
	v_mul_f32_e32 v131, v131, v203
	v_add_f32_e32 v204, 1.0, v204
	v_add_f32_e32 v205, 1.0, v205
	v_add_f32_e32 v206, 1.0, v206
	v_add_f32_e32 v207, 1.0, v207
	v_mul_f32_e32 v132, v132, v204
	v_mul_f32_e32 v133, v133, v205
	v_mul_f32_e32 v134, v134, v206
	v_mul_f32_e32 v135, v135, v207
	v_add_f32_e32 v208, 1.0, v208
	v_add_f32_e32 v209, 1.0, v209
	v_add_f32_e32 v210, 1.0, v210
	v_add_f32_e32 v211, 1.0, v211
	v_mul_f32_e32 v136, v136, v208
	v_mul_f32_e32 v137, v137, v209
	v_mul_f32_e32 v138, v138, v210
	v_mul_f32_e32 v139, v139, v211
	v_add_f32_e32 v212, 1.0, v212
	v_add_f32_e32 v213, 1.0, v213
	v_add_f32_e32 v214, 1.0, v214
	v_add_f32_e32 v215, 1.0, v215
	v_mul_f32_e32 v140, v140, v212
	v_mul_f32_e32 v141, v141, v213
	v_mul_f32_e32 v142, v142, v214
	v_mul_f32_e32 v143, v143, v215
	global_load_dwordx4 v[112:115], v193, s[34:35] offset:0
	global_load_dwordx4 v[200:203], v193, s[82:83] offset:0
	global_load_dwordx4 v[116:119], v193, s[34:35] offset:1024
	global_load_dwordx4 v[204:207], v193, s[82:83] offset:1024
	global_load_dwordx4 v[120:123], v193, s[34:35] offset:2048
	global_load_dwordx4 v[208:211], v193, s[82:83] offset:2048
	global_load_dwordx4 v[124:127], v193, s[34:35] offset:3072
	global_load_dwordx4 v[212:215], v193, s[82:83] offset:3072
	s_waitcnt vmcnt(0)
	v_mul_f32_e32 v112, v112, v200
	v_mul_f32_e32 v113, v113, v201
	v_mul_f32_e32 v114, v114, v202
	v_mul_f32_e32 v115, v115, v203
	v_mul_f32_e32 v116, v116, v204
	v_mul_f32_e32 v117, v117, v205
	v_mul_f32_e32 v118, v118, v206
	v_mul_f32_e32 v119, v119, v207
	v_mul_f32_e32 v120, v120, v208
	v_mul_f32_e32 v121, v121, v209
	v_mul_f32_e32 v122, v122, v210
	v_mul_f32_e32 v123, v123, v211
	v_mul_f32_e32 v124, v124, v212
	v_mul_f32_e32 v125, v125, v213
	v_mul_f32_e32 v126, v126, v214
	v_mul_f32_e32 v127, v127, v215
	global_load_dwordx4 v[144:147], v193, s[38:39] offset:0
	global_load_dwordx4 v[200:203], v193, s[44:45] offset:0
	global_load_dwordx4 v[176:179], v193, s[36:37] offset:0
	global_load_dwordx4 v[148:151], v193, s[38:39] offset:1024
	global_load_dwordx4 v[204:207], v193, s[44:45] offset:1024
	global_load_dwordx4 v[180:183], v193, s[36:37] offset:1024
	global_load_dwordx4 v[152:155], v193, s[38:39] offset:2048
	global_load_dwordx4 v[208:211], v193, s[44:45] offset:2048
	global_load_dwordx4 v[184:187], v193, s[36:37] offset:2048
	global_load_dwordx4 v[156:159], v193, s[38:39] offset:3072
	global_load_dwordx4 v[212:215], v193, s[44:45] offset:3072
	global_load_dwordx4 v[188:191], v193, s[36:37] offset:3072
	s_waitcnt vmcnt(0)
	v_add_f32_e32 v200, 1.0, v200
	v_add_f32_e32 v201, 1.0, v201
	v_add_f32_e32 v202, 1.0, v202
	v_add_f32_e32 v203, 1.0, v203
	v_mul_f32_e32 v144, v144, v200
	v_mul_f32_e32 v145, v145, v201
	v_mul_f32_e32 v146, v146, v202
	v_mul_f32_e32 v147, v147, v203
	v_add_f32_e32 v204, 1.0, v204
	v_add_f32_e32 v205, 1.0, v205
	v_add_f32_e32 v206, 1.0, v206
	v_add_f32_e32 v207, 1.0, v207
	v_mul_f32_e32 v148, v148, v204
	v_mul_f32_e32 v149, v149, v205
	v_mul_f32_e32 v150, v150, v206
	v_mul_f32_e32 v151, v151, v207
	v_add_f32_e32 v208, 1.0, v208
	v_add_f32_e32 v209, 1.0, v209
	v_add_f32_e32 v210, 1.0, v210
	v_add_f32_e32 v211, 1.0, v211
	v_mul_f32_e32 v152, v152, v208
	v_mul_f32_e32 v153, v153, v209
	v_mul_f32_e32 v154, v154, v210
	v_mul_f32_e32 v155, v155, v211
	v_add_f32_e32 v212, 1.0, v212
	v_add_f32_e32 v213, 1.0, v213
	v_add_f32_e32 v214, 1.0, v214
	v_add_f32_e32 v215, 1.0, v215
	v_mul_f32_e32 v156, v156, v212
	v_mul_f32_e32 v157, v157, v213
	v_mul_f32_e32 v158, v158, v214
	v_mul_f32_e32 v159, v159, v215
; __device__ __forceinline__ float bf_lo(unsigned w) { return __uint_as_float(w << 16); }
; __device__ __forceinline__ float bf_hi(unsigned w) { return __uint_as_float(w & 0xffff0000u); }
; __global__ void __launch_bounds__(NWAVES * 64, 2) mk_fwd(Args args) {
;     ...
;             for (int q = 0; q < 3; ++q) { const int row = row0 + q; const bool lat = row < ML; const int r = lat ? row / SEQ : 8;
;                 float sy = 0.f;
; #pragma unroll
;                 for (int j = 0; j < 8; ++j) { const float a = bf_lo(yw[q][j].x), b = bf_hi(yw[q][j].x), c2 = bf_lo(yw[q][j].y), d = bf_hi(yw[q][j].y); sy += (a * a + b * b) + (c2 * c2 + d * d); }
;                 const float rsy = __builtin_amdgcn_rsqf(wave_sum(sy) * (1.f / DM) + EPS);
;                 const float* m0 = mod + (size_t)r * 6144;
; #pragma unroll
;                 for (int j = 0; j < 8; ++j) { const int col = 4 * F.lane + 256 * j; const f32x4 gt = *(const f32x4*)(m0 + 2 * DM + col), pn = *(const f32x4*)(post_norm + col);
;                     const f32x4 y4 = (f32x4){bf_lo(yw[q][j].x), bf_hi(yw[q][j].x), bf_lo(yw[q][j].y), bf_hi(yw[q][j].y)};
;                     v[q][j] = v[q][j] + gt * (y4 * rsy * pn);
.Lp6_np2:
	s_waitcnt vmcnt(24)
	v_lshlrev_b32_e32 v216, 16, v32
	v_and_b32_e32 v217, 0xffff0000, v32
	v_lshlrev_b32_e32 v218, 16, v33
	v_and_b32_e32 v219, 0xffff0000, v33
	v_mul_f32_e32 v222, v216, v216
	v_mul_f32_e32 v223, v217, v217
	v_fmac_f32_e32 v222, v218, v218
	v_fmac_f32_e32 v223, v219, v219
	v_lshlrev_b32_e32 v216, 16, v34
	v_and_b32_e32 v217, 0xffff0000, v34
	v_lshlrev_b32_e32 v218, 16, v35
	v_and_b32_e32 v219, 0xffff0000, v35
	v_fmac_f32_e32 v222, v216, v216
	v_fmac_f32_e32 v223, v217, v217
	v_fmac_f32_e32 v222, v218, v218
	v_fmac_f32_e32 v223, v219, v219
	v_lshlrev_b32_e32 v216, 16, v36
	v_and_b32_e32 v217, 0xffff0000, v36
	v_lshlrev_b32_e32 v218, 16, v37
	v_and_b32_e32 v219, 0xffff0000, v37
	v_fmac_f32_e32 v222, v216, v216
	v_fmac_f32_e32 v223, v217, v217
	v_fmac_f32_e32 v222, v218, v218
	v_fmac_f32_e32 v223, v219, v219
	v_lshlrev_b32_e32 v216, 16, v38
	v_and_b32_e32 v217, 0xffff0000, v38
	v_lshlrev_b32_e32 v218, 16, v39
	v_and_b32_e32 v219, 0xffff0000, v39
	v_fmac_f32_e32 v222, v216, v216
	v_fmac_f32_e32 v223, v217, v217
	v_fmac_f32_e32 v222, v218, v218
	v_fmac_f32_e32 v223, v219, v219
	v_lshlrev_b32_e32 v216, 16, v40
	v_and_b32_e32 v217, 0xffff0000, v40
	v_lshlrev_b32_e32 v218, 16, v41
	v_and_b32_e32 v219, 0xffff0000, v41
	v_fmac_f32_e32 v222, v216, v216
	v_fmac_f32_e32 v223, v217, v217
	v_fmac_f32_e32 v222, v218, v218
	v_fmac_f32_e32 v223, v219, v219
	v_lshlrev_b32_e32 v216, 16, v42
	v_and_b32_e32 v217, 0xffff0000, v42
	v_lshlrev_b32_e32 v218, 16, v43
	v_and_b32_e32 v219, 0xffff0000, v43
	v_fmac_f32_e32 v222, v216, v216
	v_fmac_f32_e32 v223, v217, v217
	v_fmac_f32_e32 v222, v218, v218
	v_fmac_f32_e32 v223, v219, v219
	v_lshlrev_b32_e32 v216, 16, v44
	v_and_b32_e32 v217, 0xffff0000, v44
	v_lshlrev_b32_e32 v218, 16, v45
	v_and_b32_e32 v219, 0xffff0000, v45
	v_fmac_f32_e32 v222, v216, v216
	v_fmac_f32_e32 v223, v217, v217
	v_fmac_f32_e32 v222, v218, v218
	v_fmac_f32_e32 v223, v219, v219
	v_lshlrev_b32_e32 v216, 16, v46
	v_and_b32_e32 v217, 0xffff0000, v46
	v_lshlrev_b32_e32 v218, 16, v47
	v_and_b32_e32 v219, 0xffff0000, v47
	v_fmac_f32_e32 v222, v216, v216
	v_fmac_f32_e32 v223, v217, v217
	v_fmac_f32_e32 v222, v218, v218
	v_fmac_f32_e32 v223, v219, v219
	v_add_f32_e32 v222, v222, v223
	s_nop 1
	v_add_f32_dpp v224, v222, v222 quad_perm:[1,0,3,2] row_mask:0xf bank_mask:0xf
	s_nop 1
	v_add_f32_dpp v224, v224, v224 quad_perm:[2,3,0,1] row_mask:0xf bank_mask:0xf
	s_nop 1
	v_add_f32_dpp v224, v224, v224 row_half_mirror row_mask:0xf bank_mask:0xf
	s_nop 1
	v_add_f32_dpp v224, v224, v224 row_mirror row_mask:0xf bank_mask:0xf
	s_nop 1
	v_readlane_b32 s40, v224, 0
	v_readlane_b32 s41, v224, 16
	v_readlane_b32 s42, v224, 32
	v_readlane_b32 s43, v224, 48
	s_nop 1
	v_mov_b32_e32 v225, s40
	v_add_f32_e32 v225, s41, v225
	v_add_f32_e32 v225, s42, v225
	v_add_f32_e32 v225, s43, v225
	v_fmamk_f32 v225, v225, 0x3a000000, v195
	v_rsq_f32_e32 v225, v225
	s_nop 0
	v_lshlrev_b32_e32 v216, 16, v32
	v_and_b32_e32 v217, 0xffff0000, v32
	v_lshlrev_b32_e32 v218, 16, v33
	v_and_b32_e32 v219, 0xffff0000, v33
	v_mul_f32_e32 v216, v225, v216
	v_mul_f32_e32 v217, v225, v217
	v_mul_f32_e32 v218, v225, v218
	v_mul_f32_e32 v219, v225, v219
	v_fmac_f32_e32 v0, v96, v216
	v_fmac_f32_e32 v1, v97, v217
	v_fmac_f32_e32 v2, v98, v218
	v_fmac_f32_e32 v3, v99, v219
	v_lshlrev_b32_e32 v216, 16, v34
	v_and_b32_e32 v217, 0xffff0000, v34
	v_lshlrev_b32_e32 v218, 16, v35
	v_and_b32_e32 v219, 0xffff0000, v35
	v_mul_f32_e32 v216, v225, v216
	v_mul_f32_e32 v217, v225, v217
	v_mul_f32_e32 v218, v225, v218
	v_mul_f32_e32 v219, v225, v219
	v_fmac_f32_e32 v4, v100, v216
	v_fmac_f32_e32 v5, v101, v217
	v_fmac_f32_e32 v6, v102, v218
	v_fmac_f32_e32 v7, v103, v219
	v_lshlrev_b32_e32 v216, 16, v36
	v_and_b32_e32 v217, 0xffff0000, v36
	v_lshlrev_b32_e32 v218, 16, v37
	v_and_b32_e32 v219, 0xffff0000, v37
	v_mul_f32_e32 v216, v225, v216
	v_mul_f32_e32 v217, v225, v217
	v_mul_f32_e32 v218, v225, v218
	v_mul_f32_e32 v219, v225, v219
	v_fmac_f32_e32 v8, v104, v216
	v_fmac_f32_e32 v9, v105, v217
	v_fmac_f32_e32 v10, v106, v218
	v_fmac_f32_e32 v11, v107, v219
	v_lshlrev_b32_e32 v216, 16, v38
	v_and_b32_e32 v217, 0xffff0000, v38
	v_lshlrev_b32_e32 v218, 16, v39
	v_and_b32_e32 v219, 0xffff0000, v39
	v_mul_f32_e32 v216, v225, v216
	v_mul_f32_e32 v217, v225, v217
	v_mul_f32_e32 v218, v225, v218
	v_mul_f32_e32 v219, v225, v219
	v_fmac_f32_e32 v12, v108, v216
	v_fmac_f32_e32 v13, v109, v217
	v_fmac_f32_e32 v14, v110, v218
	v_fmac_f32_e32 v15, v111, v219
	v_lshlrev_b32_e32 v216, 16, v40
	v_and_b32_e32 v217, 0xffff0000, v40
	v_lshlrev_b32_e32 v218, 16, v41
	v_and_b32_e32 v219, 0xffff0000, v41
	v_mul_f32_e32 v216, v225, v216
	v_mul_f32_e32 v217, v225, v217
	v_mul_f32_e32 v218, v225, v218
	v_mul_f32_e32 v219, v225, v219
	v_fmac_f32_e32 v16, v112, v216
	v_fmac_f32_e32 v17, v113, v217
	v_fmac_f32_e32 v18, v114, v218
	v_fmac_f32_e32 v19, v115, v219
	v_lshlrev_b32_e32 v216, 16, v42
	v_and_b32_e32 v217, 0xffff0000, v42
	v_lshlrev_b32_e32 v218, 16, v43
	v_and_b32_e32 v219, 0xffff0000, v43
	v_mul_f32_e32 v216, v225, v216
	v_mul_f32_e32 v217, v225, v217
	v_mul_f32_e32 v218, v225, v218
	v_mul_f32_e32 v219, v225, v219
	v_fmac_f32_e32 v20, v116, v216
	v_fmac_f32_e32 v21, v117, v217
	v_fmac_f32_e32 v22, v118, v218
	v_fmac_f32_e32 v23, v119, v219
	v_lshlrev_b32_e32 v216, 16, v44
	v_and_b32_e32 v217, 0xffff0000, v44
	v_lshlrev_b32_e32 v218, 16, v45
	v_and_b32_e32 v219, 0xffff0000, v45
	v_mul_f32_e32 v216, v225, v216
	v_mul_f32_e32 v217, v225, v217
	v_mul_f32_e32 v218, v225, v218
	v_mul_f32_e32 v219, v225, v219
	v_fmac_f32_e32 v24, v120, v216
	v_fmac_f32_e32 v25, v121, v217
	v_fmac_f32_e32 v26, v122, v218
; __device__ __forceinline__ unsigned cvt_pk_bf16(float lo, float hi) { unsigned r; asm volatile("v_cvt_pk_bf16_f32 %0, %1, %2" : "=v"(r) : "v"(lo), "v"(hi)); return r; }
; __device__ __forceinline__ void modulate_store(const f32x4 (&v)[8], float rstd, const float* pn, const float* modr, bf16_t* orow, int lane) {
; #pragma unroll
;     for (int j = 0; j < 8; ++j) { const int col = 4 * lane + 256 * j;
;         const f32x4 g = *(const f32x4*)(pn + col), sh = *(const f32x4*)(modr + col), sc = *(const f32x4*)(modr + DM + col);
;         const f32x4 hh = v[j] * rstd * g * (sc + 1.f) + sh;
;         u32x2 w; w.x = cvt_pk_bf16(hh[0], hh[1]); w.y = cvt_pk_bf16(hh[2], hh[3]);
;         *(u32x2*)(orow + col) = w; }
; }
; __global__ void __launch_bounds__(NWAVES * 64, 2) mk_fwd(Args args) {
;     ...
;                 const float rstd = __builtin_amdgcn_rsqf(sumsq8(v[q]) * (1.f / DM) + EPS);
;                 modulate_store(v[q], rstd, pre_norm + DM, mod + (size_t)(9 + r) * 6144, H + (size_t)row * DM, F.lane); }
	v_fmac_f32_e32 v27, v123, v219
	v_lshlrev_b32_e32 v216, 16, v46
	v_and_b32_e32 v217, 0xffff0000, v46
	v_lshlrev_b32_e32 v218, 16, v47
	v_and_b32_e32 v219, 0xffff0000, v47
	v_mul_f32_e32 v216, v225, v216
	v_mul_f32_e32 v217, v225, v217
	v_mul_f32_e32 v218, v225, v218
	v_mul_f32_e32 v219, v225, v219
	v_fmac_f32_e32 v28, v124, v216
	v_fmac_f32_e32 v29, v125, v217
	v_fmac_f32_e32 v30, v126, v218
	v_fmac_f32_e32 v31, v127, v219
	v_mul_f32_e32 v222, v0, v0
	v_mul_f32_e32 v223, v1, v1
	v_fmac_f32_e32 v222, v2, v2
	v_fmac_f32_e32 v223, v3, v3
	v_fmac_f32_e32 v222, v4, v4
	v_fmac_f32_e32 v223, v5, v5
	v_fmac_f32_e32 v222, v6, v6
	v_fmac_f32_e32 v223, v7, v7
	v_fmac_f32_e32 v222, v8, v8
	v_fmac_f32_e32 v223, v9, v9
	v_fmac_f32_e32 v222, v10, v10
	v_fmac_f32_e32 v223, v11, v11
	v_fmac_f32_e32 v222, v12, v12
	v_fmac_f32_e32 v223, v13, v13
	v_fmac_f32_e32 v222, v14, v14
	v_fmac_f32_e32 v223, v15, v15
	v_fmac_f32_e32 v222, v16, v16
	v_fmac_f32_e32 v223, v17, v17
	v_fmac_f32_e32 v222, v18, v18
	v_fmac_f32_e32 v223, v19, v19
	v_fmac_f32_e32 v222, v20, v20
	v_fmac_f32_e32 v223, v21, v21
	v_fmac_f32_e32 v222, v22, v22
	v_fmac_f32_e32 v223, v23, v23
	v_fmac_f32_e32 v222, v24, v24
	v_fmac_f32_e32 v223, v25, v25
	v_fmac_f32_e32 v222, v26, v26
	v_fmac_f32_e32 v223, v27, v27
	v_fmac_f32_e32 v222, v28, v28
	v_fmac_f32_e32 v223, v29, v29
	v_fmac_f32_e32 v222, v30, v30
	v_fmac_f32_e32 v223, v31, v31
	v_add_f32_e32 v222, v222, v223
	s_nop 1
	v_add_f32_dpp v224, v222, v222 quad_perm:[1,0,3,2] row_mask:0xf bank_mask:0xf
	s_nop 1
	v_add_f32_dpp v224, v224, v224 quad_perm:[2,3,0,1] row_mask:0xf bank_mask:0xf
	s_nop 1
	v_add_f32_dpp v224, v224, v224 row_half_mirror row_mask:0xf bank_mask:0xf
	s_nop 1
	v_add_f32_dpp v224, v224, v224 row_mirror row_mask:0xf bank_mask:0xf
	s_nop 1
	v_readlane_b32 s40, v224, 0
	v_readlane_b32 s41, v224, 16
	v_readlane_b32 s42, v224, 32
	v_readlane_b32 s43, v224, 48
	s_nop 1
	v_mov_b32_e32 v225, s40
	v_add_f32_e32 v225, s41, v225
	v_add_f32_e32 v225, s42, v225
	v_add_f32_e32 v225, s43, v225
	v_fmamk_f32 v225, v225, 0x3a000000, v195
	v_rsq_f32_e32 v225, v225
	s_nop 0
	s_add_i32 s0, s6, 2
	s_lshl_b32 s1, s0, 12
	s_add_u32 s26, s84, s1
	s_addc_u32 s27, s85, 0
	s_add_u32 s26, s26, 0x4000000
	s_addc_u32 s27, s27, 0
	v_mul_f32_e32 v216, v225, v0
	v_mul_f32_e32 v217, v225, v1
	v_mul_f32_e32 v218, v225, v2
	v_mul_f32_e32 v219, v225, v3
	v_fma_f32 v216, v216, v128, v160
	v_fma_f32 v217, v217, v129, v161
	v_fma_f32 v218, v218, v130, v162
	v_fma_f32 v219, v219, v131, v163
	v_cvt_pk_bf16_f32 v196, v216, v217
	v_cvt_pk_bf16_f32 v197, v218, v219
	global_store_dwordx2 v194, v[196:197], s[26:27] offset:0
	v_mul_f32_e32 v216, v225, v4
	v_mul_f32_e32 v217, v225, v5
	v_mul_f32_e32 v218, v225, v6
	v_mul_f32_e32 v219, v225, v7
	v_fma_f32 v216, v216, v132, v164
	v_fma_f32 v217, v217, v133, v165
	v_fma_f32 v218, v218, v134, v166
	v_fma_f32 v219, v219, v135, v167
	v_cvt_pk_bf16_f32 v220, v216, v217
	v_cvt_pk_bf16_f32 v221, v218, v219
	global_store_dwordx2 v194, v[220:221], s[26:27] offset:512
	v_mul_f32_e32 v216, v225, v8
	v_mul_f32_e32 v217, v225, v9
	v_mul_f32_e32 v218, v225, v10
	v_mul_f32_e32 v219, v225, v11
	v_fma_f32 v216, v216, v136, v168
	v_fma_f32 v217, v217, v137, v169
	v_fma_f32 v218, v218, v138, v170
	v_fma_f32 v219, v219, v139, v171
	v_cvt_pk_bf16_f32 v196, v216, v217
	v_cvt_pk_bf16_f32 v197, v218, v219
	global_store_dwordx2 v194, v[196:197], s[26:27] offset:1024
	v_mul_f32_e32 v216, v225, v12
	v_mul_f32_e32 v217, v225, v13
	v_mul_f32_e32 v218, v225, v14
	v_mul_f32_e32 v219, v225, v15
	v_fma_f32 v216, v216, v140, v172
	v_fma_f32 v217, v217, v141, v173
	v_fma_f32 v218, v218, v142, v174
	v_fma_f32 v219, v219, v143, v175
	v_cvt_pk_bf16_f32 v220, v216, v217
	v_cvt_pk_bf16_f32 v221, v218, v219
	global_store_dwordx2 v194, v[220:221], s[26:27] offset:1536
	v_mul_f32_e32 v216, v225, v16
	v_mul_f32_e32 v217, v225, v17
	v_mul_f32_e32 v218, v225, v18
	v_mul_f32_e32 v219, v225, v19
	v_fma_f32 v216, v216, v144, v176
	v_fma_f32 v217, v217, v145, v177
	v_fma_f32 v218, v218, v146, v178
	v_fma_f32 v219, v219, v147, v179
	v_cvt_pk_bf16_f32 v196, v216, v217
	v_cvt_pk_bf16_f32 v197, v218, v219
	global_store_dwordx2 v194, v[196:197], s[26:27] offset:2048
	v_mul_f32_e32 v216, v225, v20
	v_mul_f32_e32 v217, v225, v21
	v_mul_f32_e32 v218, v225, v22
	v_mul_f32_e32 v219, v225, v23
	v_fma_f32 v216, v216, v148, v180
	v_fma_f32 v217, v217, v149, v181
	v_fma_f32 v218, v218, v150, v182
	v_fma_f32 v219, v219, v151, v183
	v_cvt_pk_bf16_f32 v220, v216, v217
	v_cvt_pk_bf16_f32 v221, v218, v219
	global_store_dwordx2 v194, v[220:221], s[26:27] offset:2560
	v_mul_f32_e32 v216, v225, v24
	v_mul_f32_e32 v217, v225, v25
	v_mul_f32_e32 v218, v225, v26
	v_mul_f32_e32 v219, v225, v27
	v_fma_f32 v216, v216, v152, v184
	v_fma_f32 v217, v217, v153, v185
	v_fma_f32 v218, v218, v154, v186
	v_fma_f32 v219, v219, v155, v187
	v_cvt_pk_bf16_f32 v196, v216, v217
	v_cvt_pk_bf16_f32 v197, v218, v219
	global_store_dwordx2 v194, v[196:197], s[26:27] offset:3072
	v_mul_f32_e32 v216, v225, v28
	v_mul_f32_e32 v217, v225, v29
	v_mul_f32_e32 v218, v225, v30
	v_mul_f32_e32 v219, v225, v31
	v_fma_f32 v216, v216, v156, v188
	v_fma_f32 v217, v217, v157, v189
	v_fma_f32 v218, v218, v158, v190
	v_fma_f32 v219, v219, v159, v191
	v_cvt_pk_bf16_f32 v220, v216, v217
	v_cvt_pk_bf16_f32 v221, v218, v219
	global_store_dwordx2 v194, v[220:221], s[26:27] offset:3584
	s_add_i32 s0, s6, 4
	s_cmp_lt_u32 s0, 0x4000
	s_cselect_b32 s10, s68, s72
	s_cselect_b32 s11, s69, s73
	s_cselect_b32 s1, 0, 0x4000
	s_sub_i32 s1, s0, s1
	s_lshl_b32 s1, s1, 13
	s_add_u32 s10, s10, s1
	s_addc_u32 s11, s11, 0
	s_add_i32 s0, s6, 4
	s_lshl_b32 s1, s0, 12
	s_add_u32 s22, s84, s1
	s_addc_u32 s23, s85, 0
	s_add_u32 s22, s22, 0x11800000
	s_addc_u32 s23, s23, 0
	global_load_dwordx4 v[0:3], v192, s[10:11] offset:0 nt
	global_load_dwordx4 v[4:7], v192, s[10:11] offset:1024 nt
	global_load_dwordx4 v[8:11], v192, s[10:11] offset:2048 nt
	global_load_dwordx4 v[12:15], v192, s[10:11] offset:3072 nt
	global_load_dwordx4 v[16:19], v193, s[10:11] offset:0 nt
	global_load_dwordx4 v[20:23], v193, s[10:11] offset:1024 nt
	global_load_dwordx4 v[24:27], v193, s[10:11] offset:2048 nt
	global_load_dwordx4 v[28:31], v193, s[10:11] offset:3072 nt
	global_load_dwordx2 v[32:33], v194, s[22:23] offset:0 nt
	global_load_dwordx2 v[34:35], v194, s[22:23] offset:512 nt
	global_load_dwordx2 v[36:37], v194, s[22:23] offset:1024 nt
	global_load_dwordx2 v[38:39], v194, s[22:23] offset:1536 nt
	global_load_dwordx2 v[40:41], v194, s[22:23] offset:2048 nt
	global_load_dwordx2 v[42:43], v194, s[22:23] offset:2560 nt
	global_load_dwordx2 v[44:45], v194, s[22:23] offset:3072 nt
	global_load_dwordx2 v[46:47], v194, s[22:23] offset:3584 nt
	s_add_i32 s0, s6, 3
	s_add_i32 s0, s6, 3
	s_lshr_b32 s8, s0, 11
	s_cmp_lt_u32 s0, 0x4000
	s_cselect_b32 s8, s8, 8
	s_cmp_eq_u32 s8, s7
	s_cbranch_scc1 .Lp6_np3
; __device__ __forceinline__ void modulate_store(const f32x4 (&v)[8], float rstd, const float* pn, const float* modr, bf16_t* orow, int lane) {
;     ...
;     for (int j = 0; j < 8; ++j) { const int col = 4 * lane + 256 * j;
;         const f32x4 g = *(const f32x4*)(pn + col), sh = *(const f32x4*)(modr + col), sc = *(const f32x4*)(modr + DM + col);
;         const f32x4 hh = v[j] * rstd * g * (sc + 1.f) + sh;
; __global__ void __launch_bounds__(NWAVES * 64, 2) mk_fwd(Args args) {
;     ...
;                 const float* m0 = mod + (size_t)r * 6144;
; #pragma unroll
;                 for (int j = 0; j < 8; ++j) { const int col = 4 * F.lane + 256 * j; const f32x4 gt = *(const f32x4*)(m0 + 2 * DM + col), pn = *(const f32x4*)(post_norm + col);
	s_mov_b32 s7, s8
	s_add_i32 s1, s8, 9
	s_mul_i32 s1, s1, 0x6000
	s_add_u32 s44, s84, s1
	s_addc_u32 s45, s85, 0
	s_add_u32 s44, s44, 0x2000
	s_addc_u32 s45, s45, 0
	s_add_i32 s1, s8, 9
	s_mul_i32 s1, s1, 0x6000
	s_add_u32 s36, s84, s1
	s_addc_u32 s37, s85, 0
	s_add_u32 s38, s80, 0x2000
	s_addc_u32 s39, s81, 0
	s_mul_i32 s1, s8, 0x6000
	s_add_u32 s34, s84, s1
	s_addc_u32 s35, s85, 0
	s_add_u32 s34, s34, 0x4000
	s_addc_u32 s35, s35, 0
	global_load_dwordx4 v[96:99], v192, s[34:35] offset:0
	global_load_dwordx4 v[200:203], v192, s[82:83] offset:0
	global_load_dwordx4 v[100:103], v192, s[34:35] offset:1024
	global_load_dwordx4 v[204:207], v192, s[82:83] offset:1024
	global_load_dwordx4 v[104:107], v192, s[34:35] offset:2048
	global_load_dwordx4 v[208:211], v192, s[82:83] offset:2048
	global_load_dwordx4 v[108:111], v192, s[34:35] offset:3072
	global_load_dwordx4 v[212:215], v192, s[82:83] offset:3072
	s_waitcnt vmcnt(0)
	v_mul_f32_e32 v96, v96, v200
	v_mul_f32_e32 v97, v97, v201
	v_mul_f32_e32 v98, v98, v202
	v_mul_f32_e32 v99, v99, v203
	v_mul_f32_e32 v100, v100, v204
	v_mul_f32_e32 v101, v101, v205
	v_mul_f32_e32 v102, v102, v206
	v_mul_f32_e32 v103, v103, v207
	v_mul_f32_e32 v104, v104, v208
	v_mul_f32_e32 v105, v105, v209
	v_mul_f32_e32 v106, v106, v210
	v_mul_f32_e32 v107, v107, v211
	v_mul_f32_e32 v108, v108, v212
	v_mul_f32_e32 v109, v109, v213
	v_mul_f32_e32 v110, v110, v214
	v_mul_f32_e32 v111, v111, v215
	global_load_dwordx4 v[128:131], v192, s[38:39] offset:0
	global_load_dwordx4 v[200:203], v192, s[44:45] offset:0
	global_load_dwordx4 v[160:163], v192, s[36:37] offset:0
	global_load_dwordx4 v[132:135], v192, s[38:39] offset:1024
	global_load_dwordx4 v[204:207], v192, s[44:45] offset:1024
	global_load_dwordx4 v[164:167], v192, s[36:37] offset:1024
	global_load_dwordx4 v[136:139], v192, s[38:39] offset:2048
	global_load_dwordx4 v[208:211], v192, s[44:45] offset:2048
	global_load_dwordx4 v[168:171], v192, s[36:37] offset:2048
	global_load_dwordx4 v[140:143], v192, s[38:39] offset:3072
	global_load_dwordx4 v[212:215], v192, s[44:45] offset:3072
	global_load_dwordx4 v[172:175], v192, s[36:37] offset:3072
	s_waitcnt vmcnt(0)
	v_add_f32_e32 v200, 1.0, v200
	v_add_f32_e32 v201, 1.0, v201
	v_add_f32_e32 v202, 1.0, v202
	v_add_f32_e32 v203, 1.0, v203
	v_mul_f32_e32 v128, v128, v200
	v_mul_f32_e32 v129, v129, v201
	v_mul_f32_e32 v130, v130, v202
	v_mul_f32_e32 v131, v131, v203
	v_add_f32_e32 v204, 1.0, v204
	v_add_f32_e32 v205, 1.0, v205
	v_add_f32_e32 v206, 1.0, v206
	v_add_f32_e32 v207, 1.0, v207
	v_mul_f32_e32 v132, v132, v204
	v_mul_f32_e32 v133, v133, v205
	v_mul_f32_e32 v134, v134, v206
	v_mul_f32_e32 v135, v135, v207
	v_add_f32_e32 v208, 1.0, v208
	v_add_f32_e32 v209, 1.0, v209
	v_add_f32_e32 v210, 1.0, v210
	v_add_f32_e32 v211, 1.0, v211
	v_mul_f32_e32 v136, v136, v208
	v_mul_f32_e32 v137, v137, v209
	v_mul_f32_e32 v138, v138, v210
	v_mul_f32_e32 v139, v139, v211
	v_add_f32_e32 v212, 1.0, v212
	v_add_f32_e32 v213, 1.0, v213
	v_add_f32_e32 v214, 1.0, v214
	v_add_f32_e32 v215, 1.0, v215
	v_mul_f32_e32 v140, v140, v212
	v_mul_f32_e32 v141, v141, v213
	v_mul_f32_e32 v142, v142, v214
	v_mul_f32_e32 v143, v143, v215
	global_load_dwordx4 v[112:115], v193, s[34:35] offset:0
	global_load_dwordx4 v[200:203], v193, s[82:83] offset:0
	global_load_dwordx4 v[116:119], v193, s[34:35] offset:1024
	global_load_dwordx4 v[204:207], v193, s[82:83] offset:1024
	global_load_dwordx4 v[120:123], v193, s[34:35] offset:2048
	global_load_dwordx4 v[208:211], v193, s[82:83] offset:2048
	global_load_dwordx4 v[124:127], v193, s[34:35] offset:3072
	global_load_dwordx4 v[212:215], v193, s[82:83] offset:3072
	s_waitcnt vmcnt(0)
	v_mul_f32_e32 v112, v112, v200
	v_mul_f32_e32 v113, v113, v201
	v_mul_f32_e32 v114, v114, v202
	v_mul_f32_e32 v115, v115, v203
	v_mul_f32_e32 v116, v116, v204
	v_mul_f32_e32 v117, v117, v205
	v_mul_f32_e32 v118, v118, v206
	v_mul_f32_e32 v119, v119, v207
	v_mul_f32_e32 v120, v120, v208
	v_mul_f32_e32 v121, v121, v209
	v_mul_f32_e32 v122, v122, v210
	v_mul_f32_e32 v123, v123, v211
	v_mul_f32_e32 v124, v124, v212
	v_mul_f32_e32 v125, v125, v213
	v_mul_f32_e32 v126, v126, v214
	v_mul_f32_e32 v127, v127, v215
	global_load_dwordx4 v[144:147], v193, s[38:39] offset:0
	global_load_dwordx4 v[200:203], v193, s[44:45] offset:0
	global_load_dwordx4 v[176:179], v193, s[36:37] offset:0
	global_load_dwordx4 v[148:151], v193, s[38:39] offset:1024
	global_load_dwordx4 v[204:207], v193, s[44:45] offset:1024
	global_load_dwordx4 v[180:183], v193, s[36:37] offset:1024
	global_load_dwordx4 v[152:155], v193, s[38:39] offset:2048
	global_load_dwordx4 v[208:211], v193, s[44:45] offset:2048
	global_load_dwordx4 v[184:187], v193, s[36:37] offset:2048
	global_load_dwordx4 v[156:159], v193, s[38:39] offset:3072
	global_load_dwordx4 v[212:215], v193, s[44:45] offset:3072
	global_load_dwordx4 v[188:191], v193, s[36:37] offset:3072
	s_waitcnt vmcnt(0)
	v_add_f32_e32 v200, 1.0, v200
	v_add_f32_e32 v201, 1.0, v201
	v_add_f32_e32 v202, 1.0, v202
	v_add_f32_e32 v203, 1.0, v203
	v_mul_f32_e32 v144, v144, v200
	v_mul_f32_e32 v145, v145, v201
	v_mul_f32_e32 v146, v146, v202
	v_mul_f32_e32 v147, v147, v203
	v_add_f32_e32 v204, 1.0, v204
	v_add_f32_e32 v205, 1.0, v205
	v_add_f32_e32 v206, 1.0, v206
	v_add_f32_e32 v207, 1.0, v207
	v_mul_f32_e32 v148, v148, v204
	v_mul_f32_e32 v149, v149, v205
	v_mul_f32_e32 v150, v150, v206
	v_mul_f32_e32 v151, v151, v207
	v_add_f32_e32 v208, 1.0, v208
	v_add_f32_e32 v209, 1.0, v209
	v_add_f32_e32 v210, 1.0, v210
	v_add_f32_e32 v211, 1.0, v211
	v_mul_f32_e32 v152, v152, v208
	v_mul_f32_e32 v153, v153, v209
	v_mul_f32_e32 v154, v154, v210
	v_mul_f32_e32 v155, v155, v211
	v_add_f32_e32 v212, 1.0, v212
	v_add_f32_e32 v213, 1.0, v213
	v_add_f32_e32 v214, 1.0, v214
	v_add_f32_e32 v215, 1.0, v215
	v_mul_f32_e32 v156, v156, v212
	v_mul_f32_e32 v157, v157, v213
	v_mul_f32_e32 v158, v158, v214
	v_mul_f32_e32 v159, v159, v215
; __device__ __forceinline__ float bf_lo(unsigned w) { return __uint_as_float(w << 16); }
; __device__ __forceinline__ float bf_hi(unsigned w) { return __uint_as_float(w & 0xffff0000u); }
; __global__ void __launch_bounds__(NWAVES * 64, 2) mk_fwd(Args args) {
;     ...
;             for (int q = 0; q < 3; ++q) { const int row = row0 + q; const bool lat = row < ML; const int r = lat ? row / SEQ : 8;
;                 float sy = 0.f;
; #pragma unroll
;                 for (int j = 0; j < 8; ++j) { const float a = bf_lo(yw[q][j].x), b = bf_hi(yw[q][j].x), c2 = bf_lo(yw[q][j].y), d = bf_hi(yw[q][j].y); sy += (a * a + b * b) + (c2 * c2 + d * d); }
;                 const float rsy = __builtin_amdgcn_rsqf(wave_sum(sy) * (1.f / DM) + EPS);
;                 const float* m0 = mod + (size_t)r * 6144;
; #pragma unroll
;                 for (int j = 0; j < 8; ++j) { const int col = 4 * F.lane + 256 * j; const f32x4 gt = *(const f32x4*)(m0 + 2 * DM + col), pn = *(const f32x4*)(post_norm + col);
;                     const f32x4 y4 = (f32x4){bf_lo(yw[q][j].x), bf_hi(yw[q][j].x), bf_lo(yw[q][j].y), bf_hi(yw[q][j].y)};
;                     v[q][j] = v[q][j] + gt * (y4 * rsy * pn);
.Lp6_np3:
	s_waitcnt vmcnt(24)
	v_lshlrev_b32_e32 v216, 16, v80
	v_and_b32_e32 v217, 0xffff0000, v80
	v_lshlrev_b32_e32 v218, 16, v81
	v_and_b32_e32 v219, 0xffff0000, v81
	v_mul_f32_e32 v222, v216, v216
	v_mul_f32_e32 v223, v217, v217
	v_fmac_f32_e32 v222, v218, v218
	v_fmac_f32_e32 v223, v219, v219
	v_lshlrev_b32_e32 v216, 16, v82
	v_and_b32_e32 v217, 0xffff0000, v82
	v_lshlrev_b32_e32 v218, 16, v83
	v_and_b32_e32 v219, 0xffff0000, v83
	v_fmac_f32_e32 v222, v216, v216
	v_fmac_f32_e32 v223, v217, v217
	v_fmac_f32_e32 v222, v218, v218
	v_fmac_f32_e32 v223, v219, v219
	v_lshlrev_b32_e32 v216, 16, v84
	v_and_b32_e32 v217, 0xffff0000, v84
	v_lshlrev_b32_e32 v218, 16, v85
	v_and_b32_e32 v219, 0xffff0000, v85
	v_fmac_f32_e32 v222, v216, v216
	v_fmac_f32_e32 v223, v217, v217
	v_fmac_f32_e32 v222, v218, v218
	v_fmac_f32_e32 v223, v219, v219
	v_lshlrev_b32_e32 v216, 16, v86
	v_and_b32_e32 v217, 0xffff0000, v86
	v_lshlrev_b32_e32 v218, 16, v87
	v_and_b32_e32 v219, 0xffff0000, v87
	v_fmac_f32_e32 v222, v216, v216
	v_fmac_f32_e32 v223, v217, v217
	v_fmac_f32_e32 v222, v218, v218
	v_fmac_f32_e32 v223, v219, v219
	v_lshlrev_b32_e32 v216, 16, v88
	v_and_b32_e32 v217, 0xffff0000, v88
	v_lshlrev_b32_e32 v218, 16, v89
	v_and_b32_e32 v219, 0xffff0000, v89
	v_fmac_f32_e32 v222, v216, v216
	v_fmac_f32_e32 v223, v217, v217
	v_fmac_f32_e32 v222, v218, v218
	v_fmac_f32_e32 v223, v219, v219
	v_lshlrev_b32_e32 v216, 16, v90
	v_and_b32_e32 v217, 0xffff0000, v90
	v_lshlrev_b32_e32 v218, 16, v91
	v_and_b32_e32 v219, 0xffff0000, v91
	v_fmac_f32_e32 v222, v216, v216
	v_fmac_f32_e32 v223, v217, v217
	v_fmac_f32_e32 v222, v218, v218
	v_fmac_f32_e32 v223, v219, v219
	v_lshlrev_b32_e32 v216, 16, v92
	v_and_b32_e32 v217, 0xffff0000, v92
	v_lshlrev_b32_e32 v218, 16, v93
	v_and_b32_e32 v219, 0xffff0000, v93
	v_fmac_f32_e32 v222, v216, v216
	v_fmac_f32_e32 v223, v217, v217
	v_fmac_f32_e32 v222, v218, v218
	v_fmac_f32_e32 v223, v219, v219
	v_lshlrev_b32_e32 v216, 16, v94
	v_and_b32_e32 v217, 0xffff0000, v94
	v_lshlrev_b32_e32 v218, 16, v95
	v_and_b32_e32 v219, 0xffff0000, v95
	v_fmac_f32_e32 v222, v216, v216
	v_fmac_f32_e32 v223, v217, v217
	v_fmac_f32_e32 v222, v218, v218
	v_fmac_f32_e32 v223, v219, v219
	v_add_f32_e32 v222, v222, v223
	s_nop 1
	v_add_f32_dpp v224, v222, v222 quad_perm:[1,0,3,2] row_mask:0xf bank_mask:0xf
	s_nop 1
	v_add_f32_dpp v224, v224, v224 quad_perm:[2,3,0,1] row_mask:0xf bank_mask:0xf
	s_nop 1
	v_add_f32_dpp v224, v224, v224 row_half_mirror row_mask:0xf bank_mask:0xf
	s_nop 1
	v_add_f32_dpp v224, v224, v224 row_mirror row_mask:0xf bank_mask:0xf
	s_nop 1
	v_readlane_b32 s40, v224, 0
	v_readlane_b32 s41, v224, 16
	v_readlane_b32 s42, v224, 32
	v_readlane_b32 s43, v224, 48
	s_nop 1
	v_mov_b32_e32 v225, s40
	v_add_f32_e32 v225, s41, v225
	v_add_f32_e32 v225, s42, v225
	v_add_f32_e32 v225, s43, v225
	v_fmamk_f32 v225, v225, 0x3a000000, v195
	v_rsq_f32_e32 v225, v225
	s_nop 0
	v_lshlrev_b32_e32 v216, 16, v80
	v_and_b32_e32 v217, 0xffff0000, v80
	v_lshlrev_b32_e32 v218, 16, v81
	v_and_b32_e32 v219, 0xffff0000, v81
	v_mul_f32_e32 v216, v225, v216
	v_mul_f32_e32 v217, v225, v217
	v_mul_f32_e32 v218, v225, v218
	v_mul_f32_e32 v219, v225, v219
	v_fmac_f32_e32 v48, v96, v216
	v_fmac_f32_e32 v49, v97, v217
	v_fmac_f32_e32 v50, v98, v218
	v_fmac_f32_e32 v51, v99, v219
	v_lshlrev_b32_e32 v216, 16, v82
	v_and_b32_e32 v217, 0xffff0000, v82
	v_lshlrev_b32_e32 v218, 16, v83
	v_and_b32_e32 v219, 0xffff0000, v83
	v_mul_f32_e32 v216, v225, v216
	v_mul_f32_e32 v217, v225, v217
	v_mul_f32_e32 v218, v225, v218
	v_mul_f32_e32 v219, v225, v219
	v_fmac_f32_e32 v52, v100, v216
	v_fmac_f32_e32 v53, v101, v217
	v_fmac_f32_e32 v54, v102, v218
	v_fmac_f32_e32 v55, v103, v219
	v_lshlrev_b32_e32 v216, 16, v84
	v_and_b32_e32 v217, 0xffff0000, v84
	v_lshlrev_b32_e32 v218, 16, v85
	v_and_b32_e32 v219, 0xffff0000, v85
	v_mul_f32_e32 v216, v225, v216
	v_mul_f32_e32 v217, v225, v217
	v_mul_f32_e32 v218, v225, v218
	v_mul_f32_e32 v219, v225, v219
	v_fmac_f32_e32 v56, v104, v216
	v_fmac_f32_e32 v57, v105, v217
	v_fmac_f32_e32 v58, v106, v218
	v_fmac_f32_e32 v59, v107, v219
	v_lshlrev_b32_e32 v216, 16, v86
	v_and_b32_e32 v217, 0xffff0000, v86
	v_lshlrev_b32_e32 v218, 16, v87
	v_and_b32_e32 v219, 0xffff0000, v87
	v_mul_f32_e32 v216, v225, v216
	v_mul_f32_e32 v217, v225, v217
	v_mul_f32_e32 v218, v225, v218
	v_mul_f32_e32 v219, v225, v219
	v_fmac_f32_e32 v60, v108, v216
	v_fmac_f32_e32 v61, v109, v217
	v_fmac_f32_e32 v62, v110, v218
	v_fmac_f32_e32 v63, v111, v219
	v_lshlrev_b32_e32 v216, 16, v88
	v_and_b32_e32 v217, 0xffff0000, v88
	v_lshlrev_b32_e32 v218, 16, v89
	v_and_b32_e32 v219, 0xffff0000, v89
	v_mul_f32_e32 v216, v225, v216
	v_mul_f32_e32 v217, v225, v217
	v_mul_f32_e32 v218, v225, v218
	v_mul_f32_e32 v219, v225, v219
	v_fmac_f32_e32 v64, v112, v216
	v_fmac_f32_e32 v65, v113, v217
	v_fmac_f32_e32 v66, v114, v218
	v_fmac_f32_e32 v67, v115, v219
	v_lshlrev_b32_e32 v216, 16, v90
	v_and_b32_e32 v217, 0xffff0000, v90
	v_lshlrev_b32_e32 v218, 16, v91
	v_and_b32_e32 v219, 0xffff0000, v91
	v_mul_f32_e32 v216, v225, v216
	v_mul_f32_e32 v217, v225, v217
	v_mul_f32_e32 v218, v225, v218
	v_mul_f32_e32 v219, v225, v219
	v_fmac_f32_e32 v68, v116, v216
	v_fmac_f32_e32 v69, v117, v217
	v_fmac_f32_e32 v70, v118, v218
	v_fmac_f32_e32 v71, v119, v219
	v_lshlrev_b32_e32 v216, 16, v92
	v_and_b32_e32 v217, 0xffff0000, v92
	v_lshlrev_b32_e32 v218, 16, v93
	v_and_b32_e32 v219, 0xffff0000, v93
	v_mul_f32_e32 v216, v225, v216
	v_mul_f32_e32 v217, v225, v217
	v_mul_f32_e32 v218, v225, v218
	v_mul_f32_e32 v219, v225, v219
	v_fmac_f32_e32 v72, v120, v216
	v_fmac_f32_e32 v73, v121, v217
	v_fmac_f32_e32 v74, v122, v218
; __device__ __forceinline__ unsigned cvt_pk_bf16(float lo, float hi) { unsigned r; asm volatile("v_cvt_pk_bf16_f32 %0, %1, %2" : "=v"(r) : "v"(lo), "v"(hi)); return r; }
; __device__ __forceinline__ void modulate_store(const f32x4 (&v)[8], float rstd, const float* pn, const float* modr, bf16_t* orow, int lane) {
; #pragma unroll
;     for (int j = 0; j < 8; ++j) { const int col = 4 * lane + 256 * j;
;         const f32x4 g = *(const f32x4*)(pn + col), sh = *(const f32x4*)(modr + col), sc = *(const f32x4*)(modr + DM + col);
;         const f32x4 hh = v[j] * rstd * g * (sc + 1.f) + sh;
;         u32x2 w; w.x = cvt_pk_bf16(hh[0], hh[1]); w.y = cvt_pk_bf16(hh[2], hh[3]);
;         *(u32x2*)(orow + col) = w; }
; }
; __global__ void __launch_bounds__(NWAVES * 64, 2) mk_fwd(Args args) {
;     ...
;                 const float rstd = __builtin_amdgcn_rsqf(sumsq8(v[q]) * (1.f / DM) + EPS);
;                 modulate_store(v[q], rstd, pre_norm + DM, mod + (size_t)(9 + r) * 6144, H + (size_t)row * DM, F.lane); }
	v_fmac_f32_e32 v75, v123, v219
	v_lshlrev_b32_e32 v216, 16, v94
	v_and_b32_e32 v217, 0xffff0000, v94
	v_lshlrev_b32_e32 v218, 16, v95
	v_and_b32_e32 v219, 0xffff0000, v95
	v_mul_f32_e32 v216, v225, v216
	v_mul_f32_e32 v217, v225, v217
	v_mul_f32_e32 v218, v225, v218
	v_mul_f32_e32 v219, v225, v219
	v_fmac_f32_e32 v76, v124, v216
	v_fmac_f32_e32 v77, v125, v217
	v_fmac_f32_e32 v78, v126, v218
	v_fmac_f32_e32 v79, v127, v219
	v_mul_f32_e32 v222, v48, v48
	v_mul_f32_e32 v223, v49, v49
	v_fmac_f32_e32 v222, v50, v50
	v_fmac_f32_e32 v223, v51, v51
	v_fmac_f32_e32 v222, v52, v52
	v_fmac_f32_e32 v223, v53, v53
	v_fmac_f32_e32 v222, v54, v54
	v_fmac_f32_e32 v223, v55, v55
	v_fmac_f32_e32 v222, v56, v56
	v_fmac_f32_e32 v223, v57, v57
	v_fmac_f32_e32 v222, v58, v58
	v_fmac_f32_e32 v223, v59, v59
	v_fmac_f32_e32 v222, v60, v60
	v_fmac_f32_e32 v223, v61, v61
	v_fmac_f32_e32 v222, v62, v62
	v_fmac_f32_e32 v223, v63, v63
	v_fmac_f32_e32 v222, v64, v64
	v_fmac_f32_e32 v223, v65, v65
	v_fmac_f32_e32 v222, v66, v66
	v_fmac_f32_e32 v223, v67, v67
	v_fmac_f32_e32 v222, v68, v68
	v_fmac_f32_e32 v223, v69, v69
	v_fmac_f32_e32 v222, v70, v70
	v_fmac_f32_e32 v223, v71, v71
	v_fmac_f32_e32 v222, v72, v72
	v_fmac_f32_e32 v223, v73, v73
	v_fmac_f32_e32 v222, v74, v74
	v_fmac_f32_e32 v223, v75, v75
	v_fmac_f32_e32 v222, v76, v76
	v_fmac_f32_e32 v223, v77, v77
	v_fmac_f32_e32 v222, v78, v78
	v_fmac_f32_e32 v223, v79, v79
	v_add_f32_e32 v222, v222, v223
	s_nop 1
	v_add_f32_dpp v224, v222, v222 quad_perm:[1,0,3,2] row_mask:0xf bank_mask:0xf
	s_nop 1
	v_add_f32_dpp v224, v224, v224 quad_perm:[2,3,0,1] row_mask:0xf bank_mask:0xf
	s_nop 1
	v_add_f32_dpp v224, v224, v224 row_half_mirror row_mask:0xf bank_mask:0xf
	s_nop 1
	v_add_f32_dpp v224, v224, v224 row_mirror row_mask:0xf bank_mask:0xf
	s_nop 1
	v_readlane_b32 s40, v224, 0
	v_readlane_b32 s41, v224, 16
	v_readlane_b32 s42, v224, 32
	v_readlane_b32 s43, v224, 48
	s_nop 1
	v_mov_b32_e32 v225, s40
	v_add_f32_e32 v225, s41, v225
	v_add_f32_e32 v225, s42, v225
	v_add_f32_e32 v225, s43, v225
	v_fmamk_f32 v225, v225, 0x3a000000, v195
	v_rsq_f32_e32 v225, v225
	s_nop 0
	s_add_i32 s0, s6, 3
	s_lshl_b32 s1, s0, 12
	s_add_u32 s26, s84, s1
	s_addc_u32 s27, s85, 0
	s_add_u32 s26, s26, 0x4000000
	s_addc_u32 s27, s27, 0
	v_mul_f32_e32 v216, v225, v48
	v_mul_f32_e32 v217, v225, v49
	v_mul_f32_e32 v218, v225, v50
	v_mul_f32_e32 v219, v225, v51
	v_fma_f32 v216, v216, v128, v160
	v_fma_f32 v217, v217, v129, v161
	v_fma_f32 v218, v218, v130, v162
	v_fma_f32 v219, v219, v131, v163
	v_cvt_pk_bf16_f32 v196, v216, v217
	v_cvt_pk_bf16_f32 v197, v218, v219
	global_store_dwordx2 v194, v[196:197], s[26:27] offset:0
	v_mul_f32_e32 v216, v225, v52
	v_mul_f32_e32 v217, v225, v53
	v_mul_f32_e32 v218, v225, v54
	v_mul_f32_e32 v219, v225, v55
	v_fma_f32 v216, v216, v132, v164
	v_fma_f32 v217, v217, v133, v165
	v_fma_f32 v218, v218, v134, v166
	v_fma_f32 v219, v219, v135, v167
	v_cvt_pk_bf16_f32 v220, v216, v217
	v_cvt_pk_bf16_f32 v221, v218, v219
	global_store_dwordx2 v194, v[220:221], s[26:27] offset:512
	v_mul_f32_e32 v216, v225, v56
	v_mul_f32_e32 v217, v225, v57
	v_mul_f32_e32 v218, v225, v58
	v_mul_f32_e32 v219, v225, v59
	v_fma_f32 v216, v216, v136, v168
	v_fma_f32 v217, v217, v137, v169
	v_fma_f32 v218, v218, v138, v170
	v_fma_f32 v219, v219, v139, v171
	v_cvt_pk_bf16_f32 v196, v216, v217
	v_cvt_pk_bf16_f32 v197, v218, v219
	global_store_dwordx2 v194, v[196:197], s[26:27] offset:1024
	v_mul_f32_e32 v216, v225, v60
	v_mul_f32_e32 v217, v225, v61
	v_mul_f32_e32 v218, v225, v62
	v_mul_f32_e32 v219, v225, v63
	v_fma_f32 v216, v216, v140, v172
	v_fma_f32 v217, v217, v141, v173
	v_fma_f32 v218, v218, v142, v174
	v_fma_f32 v219, v219, v143, v175
	v_cvt_pk_bf16_f32 v220, v216, v217
	v_cvt_pk_bf16_f32 v221, v218, v219
	global_store_dwordx2 v194, v[220:221], s[26:27] offset:1536
	v_mul_f32_e32 v216, v225, v64
	v_mul_f32_e32 v217, v225, v65
	v_mul_f32_e32 v218, v225, v66
	v_mul_f32_e32 v219, v225, v67
	v_fma_f32 v216, v216, v144, v176
	v_fma_f32 v217, v217, v145, v177
	v_fma_f32 v218, v218, v146, v178
	v_fma_f32 v219, v219, v147, v179
	v_cvt_pk_bf16_f32 v196, v216, v217
	v_cvt_pk_bf16_f32 v197, v218, v219
	global_store_dwordx2 v194, v[196:197], s[26:27] offset:2048
	v_mul_f32_e32 v216, v225, v68
	v_mul_f32_e32 v217, v225, v69
	v_mul_f32_e32 v218, v225, v70
	v_mul_f32_e32 v219, v225, v71
	v_fma_f32 v216, v216, v148, v180
	v_fma_f32 v217, v217, v149, v181
	v_fma_f32 v218, v218, v150, v182
	v_fma_f32 v219, v219, v151, v183
	v_cvt_pk_bf16_f32 v220, v216, v217
	v_cvt_pk_bf16_f32 v221, v218, v219
	global_store_dwordx2 v194, v[220:221], s[26:27] offset:2560
	v_mul_f32_e32 v216, v225, v72
	v_mul_f32_e32 v217, v225, v73
	v_mul_f32_e32 v218, v225, v74
	v_mul_f32_e32 v219, v225, v75
	v_fma_f32 v216, v216, v152, v184
	v_fma_f32 v217, v217, v153, v185
	v_fma_f32 v218, v218, v154, v186
	v_fma_f32 v219, v219, v155, v187
	v_cvt_pk_bf16_f32 v196, v216, v217
	v_cvt_pk_bf16_f32 v197, v218, v219
	global_store_dwordx2 v194, v[196:197], s[26:27] offset:3072
	v_mul_f32_e32 v216, v225, v76
	v_mul_f32_e32 v217, v225, v77
	v_mul_f32_e32 v218, v225, v78
	v_mul_f32_e32 v219, v225, v79
	v_fma_f32 v216, v216, v156, v188
	v_fma_f32 v217, v217, v157, v189
	v_fma_f32 v218, v218, v158, v190
	v_fma_f32 v219, v219, v159, v191
	v_cvt_pk_bf16_f32 v220, v216, v217
	v_cvt_pk_bf16_f32 v221, v218, v219
	global_store_dwordx2 v194, v[220:221], s[26:27] offset:3584
	s_add_i32 s0, s6, 5
	s_cmp_lt_u32 s0, 0x4000
	s_cselect_b32 s10, s68, s72
	s_cselect_b32 s11, s69, s73
	s_cselect_b32 s1, 0, 0x4000
	s_sub_i32 s1, s0, s1
	s_lshl_b32 s1, s1, 13
	s_add_u32 s10, s10, s1
	s_addc_u32 s11, s11, 0
	s_add_i32 s0, s6, 5
	s_lshl_b32 s1, s0, 12
	s_add_u32 s22, s84, s1
	s_addc_u32 s23, s85, 0
	s_add_u32 s22, s22, 0x11800000
	s_addc_u32 s23, s23, 0
	global_load_dwordx4 v[48:51], v192, s[10:11] offset:0 nt
	global_load_dwordx4 v[52:55], v192, s[10:11] offset:1024 nt
	global_load_dwordx4 v[56:59], v192, s[10:11] offset:2048 nt
	global_load_dwordx4 v[60:63], v192, s[10:11] offset:3072 nt
	global_load_dwordx4 v[64:67], v193, s[10:11] offset:0 nt
	global_load_dwordx4 v[68:71], v193, s[10:11] offset:1024 nt
	global_load_dwordx4 v[72:75], v193, s[10:11] offset:2048 nt
	global_load_dwordx4 v[76:79], v193, s[10:11] offset:3072 nt
	global_load_dwordx2 v[80:81], v194, s[22:23] offset:0 nt
	global_load_dwordx2 v[82:83], v194, s[22:23] offset:512 nt
	global_load_dwordx2 v[84:85], v194, s[22:23] offset:1024 nt
	global_load_dwordx2 v[86:87], v194, s[22:23] offset:1536 nt
	global_load_dwordx2 v[88:89], v194, s[22:23] offset:2048 nt
	global_load_dwordx2 v[90:91], v194, s[22:23] offset:2560 nt
	global_load_dwordx2 v[92:93], v194, s[22:23] offset:3072 nt
	global_load_dwordx2 v[94:95], v194, s[22:23] offset:3584 nt
	s_add_i32 s0, s6, 4
	s_add_i32 s0, s6, 4
	s_lshr_b32 s8, s0, 11
	s_cmp_lt_u32 s0, 0x4000
	s_cselect_b32 s8, s8, 8
	s_cmp_eq_u32 s8, s7
	s_cbranch_scc1 .Lp6_np4
; __device__ __forceinline__ void modulate_store(const f32x4 (&v)[8], float rstd, const float* pn, const float* modr, bf16_t* orow, int lane) {
;     ...
;     for (int j = 0; j < 8; ++j) { const int col = 4 * lane + 256 * j;
;         const f32x4 g = *(const f32x4*)(pn + col), sh = *(const f32x4*)(modr + col), sc = *(const f32x4*)(modr + DM + col);
;         const f32x4 hh = v[j] * rstd * g * (sc + 1.f) + sh;
; __global__ void __launch_bounds__(NWAVES * 64, 2) mk_fwd(Args args) {
;     ...
;                 const float* m0 = mod + (size_t)r * 6144;
; #pragma unroll
;                 for (int j = 0; j < 8; ++j) { const int col = 4 * F.lane + 256 * j; const f32x4 gt = *(const f32x4*)(m0 + 2 * DM + col), pn = *(const f32x4*)(post_norm + col);
	s_mov_b32 s7, s8
	s_add_i32 s1, s8, 9
	s_mul_i32 s1, s1, 0x6000
	s_add_u32 s44, s84, s1
	s_addc_u32 s45, s85, 0
	s_add_u32 s44, s44, 0x2000
	s_addc_u32 s45, s45, 0
	s_add_i32 s1, s8, 9
	s_mul_i32 s1, s1, 0x6000
	s_add_u32 s36, s84, s1
	s_addc_u32 s37, s85, 0
	s_add_u32 s38, s80, 0x2000
	s_addc_u32 s39, s81, 0
	s_mul_i32 s1, s8, 0x6000
	s_add_u32 s34, s84, s1
	s_addc_u32 s35, s85, 0
	s_add_u32 s34, s34, 0x4000
	s_addc_u32 s35, s35, 0
	global_load_dwordx4 v[96:99], v192, s[34:35] offset:0
	global_load_dwordx4 v[200:203], v192, s[82:83] offset:0
	global_load_dwordx4 v[100:103], v192, s[34:35] offset:1024
	global_load_dwordx4 v[204:207], v192, s[82:83] offset:1024
	global_load_dwordx4 v[104:107], v192, s[34:35] offset:2048
	global_load_dwordx4 v[208:211], v192, s[82:83] offset:2048
	global_load_dwordx4 v[108:111], v192, s[34:35] offset:3072
	global_load_dwordx4 v[212:215], v192, s[82:83] offset:3072
	s_waitcnt vmcnt(0)
	v_mul_f32_e32 v96, v96, v200
	v_mul_f32_e32 v97, v97, v201
	v_mul_f32_e32 v98, v98, v202
	v_mul_f32_e32 v99, v99, v203
	v_mul_f32_e32 v100, v100, v204
	v_mul_f32_e32 v101, v101, v205
	v_mul_f32_e32 v102, v102, v206
	v_mul_f32_e32 v103, v103, v207
	v_mul_f32_e32 v104, v104, v208
	v_mul_f32_e32 v105, v105, v209
	v_mul_f32_e32 v106, v106, v210
	v_mul_f32_e32 v107, v107, v211
	v_mul_f32_e32 v108, v108, v212
	v_mul_f32_e32 v109, v109, v213
	v_mul_f32_e32 v110, v110, v214
	v_mul_f32_e32 v111, v111, v215
	global_load_dwordx4 v[128:131], v192, s[38:39] offset:0
	global_load_dwordx4 v[200:203], v192, s[44:45] offset:0
	global_load_dwordx4 v[160:163], v192, s[36:37] offset:0
	global_load_dwordx4 v[132:135], v192, s[38:39] offset:1024
	global_load_dwordx4 v[204:207], v192, s[44:45] offset:1024
	global_load_dwordx4 v[164:167], v192, s[36:37] offset:1024
	global_load_dwordx4 v[136:139], v192, s[38:39] offset:2048
	global_load_dwordx4 v[208:211], v192, s[44:45] offset:2048
	global_load_dwordx4 v[168:171], v192, s[36:37] offset:2048
	global_load_dwordx4 v[140:143], v192, s[38:39] offset:3072
	global_load_dwordx4 v[212:215], v192, s[44:45] offset:3072
	global_load_dwordx4 v[172:175], v192, s[36:37] offset:3072
	s_waitcnt vmcnt(0)
	v_add_f32_e32 v200, 1.0, v200
	v_add_f32_e32 v201, 1.0, v201
	v_add_f32_e32 v202, 1.0, v202
	v_add_f32_e32 v203, 1.0, v203
	v_mul_f32_e32 v128, v128, v200
	v_mul_f32_e32 v129, v129, v201
	v_mul_f32_e32 v130, v130, v202
	v_mul_f32_e32 v131, v131, v203
	v_add_f32_e32 v204, 1.0, v204
	v_add_f32_e32 v205, 1.0, v205
	v_add_f32_e32 v206, 1.0, v206
	v_add_f32_e32 v207, 1.0, v207
	v_mul_f32_e32 v132, v132, v204
	v_mul_f32_e32 v133, v133, v205
	v_mul_f32_e32 v134, v134, v206
	v_mul_f32_e32 v135, v135, v207
	v_add_f32_e32 v208, 1.0, v208
	v_add_f32_e32 v209, 1.0, v209
	v_add_f32_e32 v210, 1.0, v210
	v_add_f32_e32 v211, 1.0, v211
	v_mul_f32_e32 v136, v136, v208
	v_mul_f32_e32 v137, v137, v209
	v_mul_f32_e32 v138, v138, v210
	v_mul_f32_e32 v139, v139, v211
	v_add_f32_e32 v212, 1.0, v212
	v_add_f32_e32 v213, 1.0, v213
	v_add_f32_e32 v214, 1.0, v214
	v_add_f32_e32 v215, 1.0, v215
	v_mul_f32_e32 v140, v140, v212
	v_mul_f32_e32 v141, v141, v213
	v_mul_f32_e32 v142, v142, v214
	v_mul_f32_e32 v143, v143, v215
	global_load_dwordx4 v[112:115], v193, s[34:35] offset:0
	global_load_dwordx4 v[200:203], v193, s[82:83] offset:0
	global_load_dwordx4 v[116:119], v193, s[34:35] offset:1024
	global_load_dwordx4 v[204:207], v193, s[82:83] offset:1024
	global_load_dwordx4 v[120:123], v193, s[34:35] offset:2048
	global_load_dwordx4 v[208:211], v193, s[82:83] offset:2048
	global_load_dwordx4 v[124:127], v193, s[34:35] offset:3072
	global_load_dwordx4 v[212:215], v193, s[82:83] offset:3072
	s_waitcnt vmcnt(0)
	v_mul_f32_e32 v112, v112, v200
	v_mul_f32_e32 v113, v113, v201
	v_mul_f32_e32 v114, v114, v202
	v_mul_f32_e32 v115, v115, v203
	v_mul_f32_e32 v116, v116, v204
	v_mul_f32_e32 v117, v117, v205
	v_mul_f32_e32 v118, v118, v206
	v_mul_f32_e32 v119, v119, v207
	v_mul_f32_e32 v120, v120, v208
	v_mul_f32_e32 v121, v121, v209
	v_mul_f32_e32 v122, v122, v210
	v_mul_f32_e32 v123, v123, v211
	v_mul_f32_e32 v124, v124, v212
	v_mul_f32_e32 v125, v125, v213
	v_mul_f32_e32 v126, v126, v214
	v_mul_f32_e32 v127, v127, v215
	global_load_dwordx4 v[144:147], v193, s[38:39] offset:0
	global_load_dwordx4 v[200:203], v193, s[44:45] offset:0
	global_load_dwordx4 v[176:179], v193, s[36:37] offset:0
	global_load_dwordx4 v[148:151], v193, s[38:39] offset:1024
	global_load_dwordx4 v[204:207], v193, s[44:45] offset:1024
	global_load_dwordx4 v[180:183], v193, s[36:37] offset:1024
	global_load_dwordx4 v[152:155], v193, s[38:39] offset:2048
	global_load_dwordx4 v[208:211], v193, s[44:45] offset:2048
	global_load_dwordx4 v[184:187], v193, s[36:37] offset:2048
	global_load_dwordx4 v[156:159], v193, s[38:39] offset:3072
	global_load_dwordx4 v[212:215], v193, s[44:45] offset:3072
	global_load_dwordx4 v[188:191], v193, s[36:37] offset:3072
	s_waitcnt vmcnt(0)
	v_add_f32_e32 v200, 1.0, v200
	v_add_f32_e32 v201, 1.0, v201
	v_add_f32_e32 v202, 1.0, v202
	v_add_f32_e32 v203, 1.0, v203
	v_mul_f32_e32 v144, v144, v200
	v_mul_f32_e32 v145, v145, v201
	v_mul_f32_e32 v146, v146, v202
	v_mul_f32_e32 v147, v147, v203
	v_add_f32_e32 v204, 1.0, v204
	v_add_f32_e32 v205, 1.0, v205
	v_add_f32_e32 v206, 1.0, v206
	v_add_f32_e32 v207, 1.0, v207
	v_mul_f32_e32 v148, v148, v204
	v_mul_f32_e32 v149, v149, v205
	v_mul_f32_e32 v150, v150, v206
	v_mul_f32_e32 v151, v151, v207
	v_add_f32_e32 v208, 1.0, v208
	v_add_f32_e32 v209, 1.0, v209
	v_add_f32_e32 v210, 1.0, v210
	v_add_f32_e32 v211, 1.0, v211
	v_mul_f32_e32 v152, v152, v208
	v_mul_f32_e32 v153, v153, v209
	v_mul_f32_e32 v154, v154, v210
	v_mul_f32_e32 v155, v155, v211
	v_add_f32_e32 v212, 1.0, v212
	v_add_f32_e32 v213, 1.0, v213
	v_add_f32_e32 v214, 1.0, v214
	v_add_f32_e32 v215, 1.0, v215
	v_mul_f32_e32 v156, v156, v212
	v_mul_f32_e32 v157, v157, v213
	v_mul_f32_e32 v158, v158, v214
	v_mul_f32_e32 v159, v159, v215
; __device__ __forceinline__ float bf_lo(unsigned w) { return __uint_as_float(w << 16); }
; __device__ __forceinline__ float bf_hi(unsigned w) { return __uint_as_float(w & 0xffff0000u); }
; __global__ void __launch_bounds__(NWAVES * 64, 2) mk_fwd(Args args) {
;     ...
;             for (int q = 0; q < 3; ++q) { const int row = row0 + q; const bool lat = row < ML; const int r = lat ? row / SEQ : 8;
;                 float sy = 0.f;
; #pragma unroll
;                 for (int j = 0; j < 8; ++j) { const float a = bf_lo(yw[q][j].x), b = bf_hi(yw[q][j].x), c2 = bf_lo(yw[q][j].y), d = bf_hi(yw[q][j].y); sy += (a * a + b * b) + (c2 * c2 + d * d); }
;                 const float rsy = __builtin_amdgcn_rsqf(wave_sum(sy) * (1.f / DM) + EPS);
;                 const float* m0 = mod + (size_t)r * 6144;
; #pragma unroll
;                 for (int j = 0; j < 8; ++j) { const int col = 4 * F.lane + 256 * j; const f32x4 gt = *(const f32x4*)(m0 + 2 * DM + col), pn = *(const f32x4*)(post_norm + col);
;                     const f32x4 y4 = (f32x4){bf_lo(yw[q][j].x), bf_hi(yw[q][j].x), bf_lo(yw[q][j].y), bf_hi(yw[q][j].y)};
;                     v[q][j] = v[q][j] + gt * (y4 * rsy * pn);
.Lp6_np4:
	s_waitcnt vmcnt(24)
	v_lshlrev_b32_e32 v216, 16, v32
	v_and_b32_e32 v217, 0xffff0000, v32
	v_lshlrev_b32_e32 v218, 16, v33
	v_and_b32_e32 v219, 0xffff0000, v33
	v_mul_f32_e32 v222, v216, v216
	v_mul_f32_e32 v223, v217, v217
	v_fmac_f32_e32 v222, v218, v218
	v_fmac_f32_e32 v223, v219, v219
	v_lshlrev_b32_e32 v216, 16, v34
	v_and_b32_e32 v217, 0xffff0000, v34
	v_lshlrev_b32_e32 v218, 16, v35
	v_and_b32_e32 v219, 0xffff0000, v35
	v_fmac_f32_e32 v222, v216, v216
	v_fmac_f32_e32 v223, v217, v217
	v_fmac_f32_e32 v222, v218, v218
	v_fmac_f32_e32 v223, v219, v219
	v_lshlrev_b32_e32 v216, 16, v36
	v_and_b32_e32 v217, 0xffff0000, v36
	v_lshlrev_b32_e32 v218, 16, v37
	v_and_b32_e32 v219, 0xffff0000, v37
	v_fmac_f32_e32 v222, v216, v216
	v_fmac_f32_e32 v223, v217, v217
	v_fmac_f32_e32 v222, v218, v218
	v_fmac_f32_e32 v223, v219, v219
	v_lshlrev_b32_e32 v216, 16, v38
	v_and_b32_e32 v217, 0xffff0000, v38
	v_lshlrev_b32_e32 v218, 16, v39
	v_and_b32_e32 v219, 0xffff0000, v39
	v_fmac_f32_e32 v222, v216, v216
	v_fmac_f32_e32 v223, v217, v217
	v_fmac_f32_e32 v222, v218, v218
	v_fmac_f32_e32 v223, v219, v219
	v_lshlrev_b32_e32 v216, 16, v40
	v_and_b32_e32 v217, 0xffff0000, v40
	v_lshlrev_b32_e32 v218, 16, v41
	v_and_b32_e32 v219, 0xffff0000, v41
	v_fmac_f32_e32 v222, v216, v216
	v_fmac_f32_e32 v223, v217, v217
	v_fmac_f32_e32 v222, v218, v218
	v_fmac_f32_e32 v223, v219, v219
	v_lshlrev_b32_e32 v216, 16, v42
	v_and_b32_e32 v217, 0xffff0000, v42
	v_lshlrev_b32_e32 v218, 16, v43
	v_and_b32_e32 v219, 0xffff0000, v43
	v_fmac_f32_e32 v222, v216, v216
	v_fmac_f32_e32 v223, v217, v217
	v_fmac_f32_e32 v222, v218, v218
	v_fmac_f32_e32 v223, v219, v219
	v_lshlrev_b32_e32 v216, 16, v44
	v_and_b32_e32 v217, 0xffff0000, v44
	v_lshlrev_b32_e32 v218, 16, v45
	v_and_b32_e32 v219, 0xffff0000, v45
	v_fmac_f32_e32 v222, v216, v216
	v_fmac_f32_e32 v223, v217, v217
	v_fmac_f32_e32 v222, v218, v218
	v_fmac_f32_e32 v223, v219, v219
	v_lshlrev_b32_e32 v216, 16, v46
	v_and_b32_e32 v217, 0xffff0000, v46
	v_lshlrev_b32_e32 v218, 16, v47
	v_and_b32_e32 v219, 0xffff0000, v47
	v_fmac_f32_e32 v222, v216, v216
	v_fmac_f32_e32 v223, v217, v217
	v_fmac_f32_e32 v222, v218, v218
	v_fmac_f32_e32 v223, v219, v219
	v_add_f32_e32 v222, v222, v223
	s_nop 1
	v_add_f32_dpp v224, v222, v222 quad_perm:[1,0,3,2] row_mask:0xf bank_mask:0xf
	s_nop 1
	v_add_f32_dpp v224, v224, v224 quad_perm:[2,3,0,1] row_mask:0xf bank_mask:0xf
	s_nop 1
	v_add_f32_dpp v224, v224, v224 row_half_mirror row_mask:0xf bank_mask:0xf
	s_nop 1
	v_add_f32_dpp v224, v224, v224 row_mirror row_mask:0xf bank_mask:0xf
	s_nop 1
	v_readlane_b32 s40, v224, 0
	v_readlane_b32 s41, v224, 16
	v_readlane_b32 s42, v224, 32
	v_readlane_b32 s43, v224, 48
	s_nop 1
	v_mov_b32_e32 v225, s40
	v_add_f32_e32 v225, s41, v225
	v_add_f32_e32 v225, s42, v225
	v_add_f32_e32 v225, s43, v225
	v_fmamk_f32 v225, v225, 0x3a000000, v195
	v_rsq_f32_e32 v225, v225
	s_nop 0
	v_lshlrev_b32_e32 v216, 16, v32
	v_and_b32_e32 v217, 0xffff0000, v32
	v_lshlrev_b32_e32 v218, 16, v33
	v_and_b32_e32 v219, 0xffff0000, v33
	v_mul_f32_e32 v216, v225, v216
	v_mul_f32_e32 v217, v225, v217
	v_mul_f32_e32 v218, v225, v218
	v_mul_f32_e32 v219, v225, v219
	v_fmac_f32_e32 v0, v96, v216
	v_fmac_f32_e32 v1, v97, v217
	v_fmac_f32_e32 v2, v98, v218
	v_fmac_f32_e32 v3, v99, v219
	v_lshlrev_b32_e32 v216, 16, v34
	v_and_b32_e32 v217, 0xffff0000, v34
	v_lshlrev_b32_e32 v218, 16, v35
	v_and_b32_e32 v219, 0xffff0000, v35
	v_mul_f32_e32 v216, v225, v216
	v_mul_f32_e32 v217, v225, v217
	v_mul_f32_e32 v218, v225, v218
	v_mul_f32_e32 v219, v225, v219
	v_fmac_f32_e32 v4, v100, v216
	v_fmac_f32_e32 v5, v101, v217
	v_fmac_f32_e32 v6, v102, v218
	v_fmac_f32_e32 v7, v103, v219
	v_lshlrev_b32_e32 v216, 16, v36
	v_and_b32_e32 v217, 0xffff0000, v36
	v_lshlrev_b32_e32 v218, 16, v37
	v_and_b32_e32 v219, 0xffff0000, v37
	v_mul_f32_e32 v216, v225, v216
	v_mul_f32_e32 v217, v225, v217
	v_mul_f32_e32 v218, v225, v218
	v_mul_f32_e32 v219, v225, v219
	v_fmac_f32_e32 v8, v104, v216
	v_fmac_f32_e32 v9, v105, v217
	v_fmac_f32_e32 v10, v106, v218
	v_fmac_f32_e32 v11, v107, v219
	v_lshlrev_b32_e32 v216, 16, v38
	v_and_b32_e32 v217, 0xffff0000, v38
	v_lshlrev_b32_e32 v218, 16, v39
	v_and_b32_e32 v219, 0xffff0000, v39
	v_mul_f32_e32 v216, v225, v216
	v_mul_f32_e32 v217, v225, v217
	v_mul_f32_e32 v218, v225, v218
	v_mul_f32_e32 v219, v225, v219
	v_fmac_f32_e32 v12, v108, v216
	v_fmac_f32_e32 v13, v109, v217
	v_fmac_f32_e32 v14, v110, v218
	v_fmac_f32_e32 v15, v111, v219
	v_lshlrev_b32_e32 v216, 16, v40
	v_and_b32_e32 v217, 0xffff0000, v40
	v_lshlrev_b32_e32 v218, 16, v41
	v_and_b32_e32 v219, 0xffff0000, v41
	v_mul_f32_e32 v216, v225, v216
	v_mul_f32_e32 v217, v225, v217
	v_mul_f32_e32 v218, v225, v218
	v_mul_f32_e32 v219, v225, v219
	v_fmac_f32_e32 v16, v112, v216
	v_fmac_f32_e32 v17, v113, v217
	v_fmac_f32_e32 v18, v114, v218
	v_fmac_f32_e32 v19, v115, v219
	v_lshlrev_b32_e32 v216, 16, v42
	v_and_b32_e32 v217, 0xffff0000, v42
	v_lshlrev_b32_e32 v218, 16, v43
	v_and_b32_e32 v219, 0xffff0000, v43
	v_mul_f32_e32 v216, v225, v216
	v_mul_f32_e32 v217, v225, v217
	v_mul_f32_e32 v218, v225, v218
	v_mul_f32_e32 v219, v225, v219
	v_fmac_f32_e32 v20, v116, v216
	v_fmac_f32_e32 v21, v117, v217
	v_fmac_f32_e32 v22, v118, v218
	v_fmac_f32_e32 v23, v119, v219
	v_lshlrev_b32_e32 v216, 16, v44
	v_and_b32_e32 v217, 0xffff0000, v44
	v_lshlrev_b32_e32 v218, 16, v45
	v_and_b32_e32 v219, 0xffff0000, v45
	v_mul_f32_e32 v216, v225, v216
	v_mul_f32_e32 v217, v225, v217
	v_mul_f32_e32 v218, v225, v218
	v_mul_f32_e32 v219, v225, v219
	v_fmac_f32_e32 v24, v120, v216
	v_fmac_f32_e32 v25, v121, v217
	v_fmac_f32_e32 v26, v122, v218
; __device__ __forceinline__ unsigned cvt_pk_bf16(float lo, float hi) { unsigned r; asm volatile("v_cvt_pk_bf16_f32 %0, %1, %2" : "=v"(r) : "v"(lo), "v"(hi)); return r; }
; __device__ __forceinline__ void modulate_store(const f32x4 (&v)[8], float rstd, const float* pn, const float* modr, bf16_t* orow, int lane) {
; #pragma unroll
;     for (int j = 0; j < 8; ++j) { const int col = 4 * lane + 256 * j;
;         const f32x4 g = *(const f32x4*)(pn + col), sh = *(const f32x4*)(modr + col), sc = *(const f32x4*)(modr + DM + col);
;         const f32x4 hh = v[j] * rstd * g * (sc + 1.f) + sh;
;         u32x2 w; w.x = cvt_pk_bf16(hh[0], hh[1]); w.y = cvt_pk_bf16(hh[2], hh[3]);
;         *(u32x2*)(orow + col) = w; }
; }
; __global__ void __launch_bounds__(NWAVES * 64, 2) mk_fwd(Args args) {
;     ...
;                 const float rstd = __builtin_amdgcn_rsqf(sumsq8(v[q]) * (1.f / DM) + EPS);
;                 modulate_store(v[q], rstd, pre_norm + DM, mod + (size_t)(9 + r) * 6144, H + (size_t)row * DM, F.lane); }
	v_fmac_f32_e32 v27, v123, v219
	v_lshlrev_b32_e32 v216, 16, v46
	v_and_b32_e32 v217, 0xffff0000, v46
	v_lshlrev_b32_e32 v218, 16, v47
	v_and_b32_e32 v219, 0xffff0000, v47
	v_mul_f32_e32 v216, v225, v216
	v_mul_f32_e32 v217, v225, v217
	v_mul_f32_e32 v218, v225, v218
	v_mul_f32_e32 v219, v225, v219
	v_fmac_f32_e32 v28, v124, v216
	v_fmac_f32_e32 v29, v125, v217
	v_fmac_f32_e32 v30, v126, v218
	v_fmac_f32_e32 v31, v127, v219
	v_mul_f32_e32 v222, v0, v0
	v_mul_f32_e32 v223, v1, v1
	v_fmac_f32_e32 v222, v2, v2
	v_fmac_f32_e32 v223, v3, v3
	v_fmac_f32_e32 v222, v4, v4
	v_fmac_f32_e32 v223, v5, v5
	v_fmac_f32_e32 v222, v6, v6
	v_fmac_f32_e32 v223, v7, v7
	v_fmac_f32_e32 v222, v8, v8
	v_fmac_f32_e32 v223, v9, v9
	v_fmac_f32_e32 v222, v10, v10
	v_fmac_f32_e32 v223, v11, v11
	v_fmac_f32_e32 v222, v12, v12
	v_fmac_f32_e32 v223, v13, v13
	v_fmac_f32_e32 v222, v14, v14
	v_fmac_f32_e32 v223, v15, v15
	v_fmac_f32_e32 v222, v16, v16
	v_fmac_f32_e32 v223, v17, v17
	v_fmac_f32_e32 v222, v18, v18
	v_fmac_f32_e32 v223, v19, v19
	v_fmac_f32_e32 v222, v20, v20
	v_fmac_f32_e32 v223, v21, v21
	v_fmac_f32_e32 v222, v22, v22
	v_fmac_f32_e32 v223, v23, v23
	v_fmac_f32_e32 v222, v24, v24
	v_fmac_f32_e32 v223, v25, v25
	v_fmac_f32_e32 v222, v26, v26
	v_fmac_f32_e32 v223, v27, v27
	v_fmac_f32_e32 v222, v28, v28
	v_fmac_f32_e32 v223, v29, v29
	v_fmac_f32_e32 v222, v30, v30
	v_fmac_f32_e32 v223, v31, v31
	v_add_f32_e32 v222, v222, v223
	s_nop 1
	v_add_f32_dpp v224, v222, v222 quad_perm:[1,0,3,2] row_mask:0xf bank_mask:0xf
	s_nop 1
	v_add_f32_dpp v224, v224, v224 quad_perm:[2,3,0,1] row_mask:0xf bank_mask:0xf
	s_nop 1
	v_add_f32_dpp v224, v224, v224 row_half_mirror row_mask:0xf bank_mask:0xf
	s_nop 1
	v_add_f32_dpp v224, v224, v224 row_mirror row_mask:0xf bank_mask:0xf
	s_nop 1
	v_readlane_b32 s40, v224, 0
	v_readlane_b32 s41, v224, 16
	v_readlane_b32 s42, v224, 32
	v_readlane_b32 s43, v224, 48
	s_nop 1
	v_mov_b32_e32 v225, s40
	v_add_f32_e32 v225, s41, v225
	v_add_f32_e32 v225, s42, v225
	v_add_f32_e32 v225, s43, v225
	v_fmamk_f32 v225, v225, 0x3a000000, v195
	v_rsq_f32_e32 v225, v225
	s_nop 0
	s_add_i32 s0, s6, 4
	s_lshl_b32 s1, s0, 12
	s_add_u32 s26, s84, s1
	s_addc_u32 s27, s85, 0
	s_add_u32 s26, s26, 0x4000000
	s_addc_u32 s27, s27, 0
	v_mul_f32_e32 v216, v225, v0
	v_mul_f32_e32 v217, v225, v1
	v_mul_f32_e32 v218, v225, v2
	v_mul_f32_e32 v219, v225, v3
	v_fma_f32 v216, v216, v128, v160
	v_fma_f32 v217, v217, v129, v161
	v_fma_f32 v218, v218, v130, v162
	v_fma_f32 v219, v219, v131, v163
	v_cvt_pk_bf16_f32 v196, v216, v217
	v_cvt_pk_bf16_f32 v197, v218, v219
	global_store_dwordx2 v194, v[196:197], s[26:27] offset:0
	v_mul_f32_e32 v216, v225, v4
	v_mul_f32_e32 v217, v225, v5
	v_mul_f32_e32 v218, v225, v6
	v_mul_f32_e32 v219, v225, v7
	v_fma_f32 v216, v216, v132, v164
	v_fma_f32 v217, v217, v133, v165
	v_fma_f32 v218, v218, v134, v166
	v_fma_f32 v219, v219, v135, v167
	v_cvt_pk_bf16_f32 v220, v216, v217
	v_cvt_pk_bf16_f32 v221, v218, v219
	global_store_dwordx2 v194, v[220:221], s[26:27] offset:512
	v_mul_f32_e32 v216, v225, v8
	v_mul_f32_e32 v217, v225, v9
	v_mul_f32_e32 v218, v225, v10
	v_mul_f32_e32 v219, v225, v11
	v_fma_f32 v216, v216, v136, v168
	v_fma_f32 v217, v217, v137, v169
	v_fma_f32 v218, v218, v138, v170
	v_fma_f32 v219, v219, v139, v171
	v_cvt_pk_bf16_f32 v196, v216, v217
	v_cvt_pk_bf16_f32 v197, v218, v219
	global_store_dwordx2 v194, v[196:197], s[26:27] offset:1024
	v_mul_f32_e32 v216, v225, v12
	v_mul_f32_e32 v217, v225, v13
	v_mul_f32_e32 v218, v225, v14
	v_mul_f32_e32 v219, v225, v15
	v_fma_f32 v216, v216, v140, v172
	v_fma_f32 v217, v217, v141, v173
	v_fma_f32 v218, v218, v142, v174
	v_fma_f32 v219, v219, v143, v175
	v_cvt_pk_bf16_f32 v220, v216, v217
	v_cvt_pk_bf16_f32 v221, v218, v219
	global_store_dwordx2 v194, v[220:221], s[26:27] offset:1536
	v_mul_f32_e32 v216, v225, v16
	v_mul_f32_e32 v217, v225, v17
	v_mul_f32_e32 v218, v225, v18
	v_mul_f32_e32 v219, v225, v19
	v_fma_f32 v216, v216, v144, v176
	v_fma_f32 v217, v217, v145, v177
	v_fma_f32 v218, v218, v146, v178
	v_fma_f32 v219, v219, v147, v179
	v_cvt_pk_bf16_f32 v196, v216, v217
	v_cvt_pk_bf16_f32 v197, v218, v219
	global_store_dwordx2 v194, v[196:197], s[26:27] offset:2048
	v_mul_f32_e32 v216, v225, v20
	v_mul_f32_e32 v217, v225, v21
	v_mul_f32_e32 v218, v225, v22
	v_mul_f32_e32 v219, v225, v23
	v_fma_f32 v216, v216, v148, v180
	v_fma_f32 v217, v217, v149, v181
	v_fma_f32 v218, v218, v150, v182
	v_fma_f32 v219, v219, v151, v183
	v_cvt_pk_bf16_f32 v220, v216, v217
	v_cvt_pk_bf16_f32 v221, v218, v219
	global_store_dwordx2 v194, v[220:221], s[26:27] offset:2560
	v_mul_f32_e32 v216, v225, v24
	v_mul_f32_e32 v217, v225, v25
	v_mul_f32_e32 v218, v225, v26
	v_mul_f32_e32 v219, v225, v27
	v_fma_f32 v216, v216, v152, v184
	v_fma_f32 v217, v217, v153, v185
	v_fma_f32 v218, v218, v154, v186
	v_fma_f32 v219, v219, v155, v187
	v_cvt_pk_bf16_f32 v196, v216, v217
	v_cvt_pk_bf16_f32 v197, v218, v219
	global_store_dwordx2 v194, v[196:197], s[26:27] offset:3072
	v_mul_f32_e32 v216, v225, v28
	v_mul_f32_e32 v217, v225, v29
	v_mul_f32_e32 v218, v225, v30
	v_mul_f32_e32 v219, v225, v31
	v_fma_f32 v216, v216, v156, v188
	v_fma_f32 v217, v217, v157, v189
	v_fma_f32 v218, v218, v158, v190
	v_fma_f32 v219, v219, v159, v191
	v_cvt_pk_bf16_f32 v220, v216, v217
	v_cvt_pk_bf16_f32 v221, v218, v219
	global_store_dwordx2 v194, v[220:221], s[26:27] offset:3584
	s_add_i32 s0, s6, 6
	s_cmp_lt_u32 s0, 0x4000
	s_cselect_b32 s10, s68, s72
	s_cselect_b32 s11, s69, s73
	s_cselect_b32 s1, 0, 0x4000
	s_sub_i32 s1, s0, s1
	s_lshl_b32 s1, s1, 13
	s_add_u32 s10, s10, s1
	s_addc_u32 s11, s11, 0
	s_add_i32 s0, s6, 6
	s_lshl_b32 s1, s0, 12
	s_add_u32 s22, s84, s1
	s_addc_u32 s23, s85, 0
	s_add_u32 s22, s22, 0x11800000
	s_addc_u32 s23, s23, 0
	global_load_dwordx4 v[0:3], v192, s[10:11] offset:0 nt
	global_load_dwordx4 v[4:7], v192, s[10:11] offset:1024 nt
	global_load_dwordx4 v[8:11], v192, s[10:11] offset:2048 nt
	global_load_dwordx4 v[12:15], v192, s[10:11] offset:3072 nt
	global_load_dwordx4 v[16:19], v193, s[10:11] offset:0 nt
	global_load_dwordx4 v[20:23], v193, s[10:11] offset:1024 nt
	global_load_dwordx4 v[24:27], v193, s[10:11] offset:2048 nt
	global_load_dwordx4 v[28:31], v193, s[10:11] offset:3072 nt
	global_load_dwordx2 v[32:33], v194, s[22:23] offset:0 nt
	global_load_dwordx2 v[34:35], v194, s[22:23] offset:512 nt
	global_load_dwordx2 v[36:37], v194, s[22:23] offset:1024 nt
	global_load_dwordx2 v[38:39], v194, s[22:23] offset:1536 nt
	global_load_dwordx2 v[40:41], v194, s[22:23] offset:2048 nt
	global_load_dwordx2 v[42:43], v194, s[22:23] offset:2560 nt
	global_load_dwordx2 v[44:45], v194, s[22:23] offset:3072 nt
	global_load_dwordx2 v[46:47], v194, s[22:23] offset:3584 nt
	s_add_i32 s0, s6, 5
	s_add_i32 s0, s6, 5
	s_lshr_b32 s8, s0, 11
	s_cmp_lt_u32 s0, 0x4000
	s_cselect_b32 s8, s8, 8
	s_cmp_eq_u32 s8, s7
	s_cbranch_scc1 .Lp6_np5
; __device__ __forceinline__ void modulate_store(const f32x4 (&v)[8], float rstd, const float* pn, const float* modr, bf16_t* orow, int lane) {
;     ...
;     for (int j = 0; j < 8; ++j) { const int col = 4 * lane + 256 * j;
;         const f32x4 g = *(const f32x4*)(pn + col), sh = *(const f32x4*)(modr + col), sc = *(const f32x4*)(modr + DM + col);
;         const f32x4 hh = v[j] * rstd * g * (sc + 1.f) + sh;
; __global__ void __launch_bounds__(NWAVES * 64, 2) mk_fwd(Args args) {
;     ...
;                 const float* m0 = mod + (size_t)r * 6144;
; #pragma unroll
;                 for (int j = 0; j < 8; ++j) { const int col = 4 * F.lane + 256 * j; const f32x4 gt = *(const f32x4*)(m0 + 2 * DM + col), pn = *(const f32x4*)(post_norm + col);
	s_mov_b32 s7, s8
	s_add_i32 s1, s8, 9
	s_mul_i32 s1, s1, 0x6000
	s_add_u32 s44, s84, s1
	s_addc_u32 s45, s85, 0
	s_add_u32 s44, s44, 0x2000
	s_addc_u32 s45, s45, 0
	s_add_i32 s1, s8, 9
	s_mul_i32 s1, s1, 0x6000
	s_add_u32 s36, s84, s1
	s_addc_u32 s37, s85, 0
	s_add_u32 s38, s80, 0x2000
	s_addc_u32 s39, s81, 0
	s_mul_i32 s1, s8, 0x6000
	s_add_u32 s34, s84, s1
	s_addc_u32 s35, s85, 0
	s_add_u32 s34, s34, 0x4000
	s_addc_u32 s35, s35, 0
	global_load_dwordx4 v[96:99], v192, s[34:35] offset:0
	global_load_dwordx4 v[200:203], v192, s[82:83] offset:0
	global_load_dwordx4 v[100:103], v192, s[34:35] offset:1024
	global_load_dwordx4 v[204:207], v192, s[82:83] offset:1024
	global_load_dwordx4 v[104:107], v192, s[34:35] offset:2048
	global_load_dwordx4 v[208:211], v192, s[82:83] offset:2048
	global_load_dwordx4 v[108:111], v192, s[34:35] offset:3072
	global_load_dwordx4 v[212:215], v192, s[82:83] offset:3072
	s_waitcnt vmcnt(0)
	v_mul_f32_e32 v96, v96, v200
	v_mul_f32_e32 v97, v97, v201
	v_mul_f32_e32 v98, v98, v202
	v_mul_f32_e32 v99, v99, v203
	v_mul_f32_e32 v100, v100, v204
	v_mul_f32_e32 v101, v101, v205
	v_mul_f32_e32 v102, v102, v206
	v_mul_f32_e32 v103, v103, v207
	v_mul_f32_e32 v104, v104, v208
	v_mul_f32_e32 v105, v105, v209
	v_mul_f32_e32 v106, v106, v210
	v_mul_f32_e32 v107, v107, v211
	v_mul_f32_e32 v108, v108, v212
	v_mul_f32_e32 v109, v109, v213
	v_mul_f32_e32 v110, v110, v214
	v_mul_f32_e32 v111, v111, v215
	global_load_dwordx4 v[128:131], v192, s[38:39] offset:0
	global_load_dwordx4 v[200:203], v192, s[44:45] offset:0
	global_load_dwordx4 v[160:163], v192, s[36:37] offset:0
	global_load_dwordx4 v[132:135], v192, s[38:39] offset:1024
	global_load_dwordx4 v[204:207], v192, s[44:45] offset:1024
	global_load_dwordx4 v[164:167], v192, s[36:37] offset:1024
	global_load_dwordx4 v[136:139], v192, s[38:39] offset:2048
	global_load_dwordx4 v[208:211], v192, s[44:45] offset:2048
	global_load_dwordx4 v[168:171], v192, s[36:37] offset:2048
	global_load_dwordx4 v[140:143], v192, s[38:39] offset:3072
	global_load_dwordx4 v[212:215], v192, s[44:45] offset:3072
	global_load_dwordx4 v[172:175], v192, s[36:37] offset:3072
	s_waitcnt vmcnt(0)
	v_add_f32_e32 v200, 1.0, v200
	v_add_f32_e32 v201, 1.0, v201
	v_add_f32_e32 v202, 1.0, v202
	v_add_f32_e32 v203, 1.0, v203
	v_mul_f32_e32 v128, v128, v200
	v_mul_f32_e32 v129, v129, v201
	v_mul_f32_e32 v130, v130, v202
	v_mul_f32_e32 v131, v131, v203
	v_add_f32_e32 v204, 1.0, v204
	v_add_f32_e32 v205, 1.0, v205
	v_add_f32_e32 v206, 1.0, v206
	v_add_f32_e32 v207, 1.0, v207
	v_mul_f32_e32 v132, v132, v204
	v_mul_f32_e32 v133, v133, v205
	v_mul_f32_e32 v134, v134, v206
	v_mul_f32_e32 v135, v135, v207
	v_add_f32_e32 v208, 1.0, v208
	v_add_f32_e32 v209, 1.0, v209
	v_add_f32_e32 v210, 1.0, v210
	v_add_f32_e32 v211, 1.0, v211
	v_mul_f32_e32 v136, v136, v208
	v_mul_f32_e32 v137, v137, v209
	v_mul_f32_e32 v138, v138, v210
	v_mul_f32_e32 v139, v139, v211
	v_add_f32_e32 v212, 1.0, v212
	v_add_f32_e32 v213, 1.0, v213
	v_add_f32_e32 v214, 1.0, v214
	v_add_f32_e32 v215, 1.0, v215
	v_mul_f32_e32 v140, v140, v212
	v_mul_f32_e32 v141, v141, v213
	v_mul_f32_e32 v142, v142, v214
	v_mul_f32_e32 v143, v143, v215
	global_load_dwordx4 v[112:115], v193, s[34:35] offset:0
	global_load_dwordx4 v[200:203], v193, s[82:83] offset:0
	global_load_dwordx4 v[116:119], v193, s[34:35] offset:1024
	global_load_dwordx4 v[204:207], v193, s[82:83] offset:1024
	global_load_dwordx4 v[120:123], v193, s[34:35] offset:2048
	global_load_dwordx4 v[208:211], v193, s[82:83] offset:2048
	global_load_dwordx4 v[124:127], v193, s[34:35] offset:3072
	global_load_dwordx4 v[212:215], v193, s[82:83] offset:3072
	s_waitcnt vmcnt(0)
	v_mul_f32_e32 v112, v112, v200
	v_mul_f32_e32 v113, v113, v201
	v_mul_f32_e32 v114, v114, v202
	v_mul_f32_e32 v115, v115, v203
	v_mul_f32_e32 v116, v116, v204
	v_mul_f32_e32 v117, v117, v205
	v_mul_f32_e32 v118, v118, v206
	v_mul_f32_e32 v119, v119, v207
	v_mul_f32_e32 v120, v120, v208
	v_mul_f32_e32 v121, v121, v209
	v_mul_f32_e32 v122, v122, v210
	v_mul_f32_e32 v123, v123, v211
	v_mul_f32_e32 v124, v124, v212
	v_mul_f32_e32 v125, v125, v213
	v_mul_f32_e32 v126, v126, v214
	v_mul_f32_e32 v127, v127, v215
	global_load_dwordx4 v[144:147], v193, s[38:39] offset:0
	global_load_dwordx4 v[200:203], v193, s[44:45] offset:0
	global_load_dwordx4 v[176:179], v193, s[36:37] offset:0
	global_load_dwordx4 v[148:151], v193, s[38:39] offset:1024
	global_load_dwordx4 v[204:207], v193, s[44:45] offset:1024
	global_load_dwordx4 v[180:183], v193, s[36:37] offset:1024
	global_load_dwordx4 v[152:155], v193, s[38:39] offset:2048
	global_load_dwordx4 v[208:211], v193, s[44:45] offset:2048
	global_load_dwordx4 v[184:187], v193, s[36:37] offset:2048
	global_load_dwordx4 v[156:159], v193, s[38:39] offset:3072
	global_load_dwordx4 v[212:215], v193, s[44:45] offset:3072
	global_load_dwordx4 v[188:191], v193, s[36:37] offset:3072
	s_waitcnt vmcnt(0)
	v_add_f32_e32 v200, 1.0, v200
	v_add_f32_e32 v201, 1.0, v201
	v_add_f32_e32 v202, 1.0, v202
	v_add_f32_e32 v203, 1.0, v203
	v_mul_f32_e32 v144, v144, v200
	v_mul_f32_e32 v145, v145, v201
	v_mul_f32_e32 v146, v146, v202
	v_mul_f32_e32 v147, v147, v203
	v_add_f32_e32 v204, 1.0, v204
	v_add_f32_e32 v205, 1.0, v205
	v_add_f32_e32 v206, 1.0, v206
	v_add_f32_e32 v207, 1.0, v207
	v_mul_f32_e32 v148, v148, v204
	v_mul_f32_e32 v149, v149, v205
	v_mul_f32_e32 v150, v150, v206
	v_mul_f32_e32 v151, v151, v207
	v_add_f32_e32 v208, 1.0, v208
	v_add_f32_e32 v209, 1.0, v209
	v_add_f32_e32 v210, 1.0, v210
	v_add_f32_e32 v211, 1.0, v211
	v_mul_f32_e32 v152, v152, v208
	v_mul_f32_e32 v153, v153, v209
	v_mul_f32_e32 v154, v154, v210
	v_mul_f32_e32 v155, v155, v211
	v_add_f32_e32 v212, 1.0, v212
	v_add_f32_e32 v213, 1.0, v213
	v_add_f32_e32 v214, 1.0, v214
	v_add_f32_e32 v215, 1.0, v215
	v_mul_f32_e32 v156, v156, v212
	v_mul_f32_e32 v157, v157, v213
	v_mul_f32_e32 v158, v158, v214
	v_mul_f32_e32 v159, v159, v215
; __device__ __forceinline__ float bf_lo(unsigned w) { return __uint_as_float(w << 16); }
; __device__ __forceinline__ float bf_hi(unsigned w) { return __uint_as_float(w & 0xffff0000u); }
; __global__ void __launch_bounds__(NWAVES * 64, 2) mk_fwd(Args args) {
;     ...
;             for (int q = 0; q < 3; ++q) { const int row = row0 + q; const bool lat = row < ML; const int r = lat ? row / SEQ : 8;
;                 float sy = 0.f;
; #pragma unroll
;                 for (int j = 0; j < 8; ++j) { const float a = bf_lo(yw[q][j].x), b = bf_hi(yw[q][j].x), c2 = bf_lo(yw[q][j].y), d = bf_hi(yw[q][j].y); sy += (a * a + b * b) + (c2 * c2 + d * d); }
;                 const float rsy = __builtin_amdgcn_rsqf(wave_sum(sy) * (1.f / DM) + EPS);
;                 const float* m0 = mod + (size_t)r * 6144;
; #pragma unroll
;                 for (int j = 0; j < 8; ++j) { const int col = 4 * F.lane + 256 * j; const f32x4 gt = *(const f32x4*)(m0 + 2 * DM + col), pn = *(const f32x4*)(post_norm + col);
;                     const f32x4 y4 = (f32x4){bf_lo(yw[q][j].x), bf_hi(yw[q][j].x), bf_lo(yw[q][j].y), bf_hi(yw[q][j].y)};
;                     v[q][j] = v[q][j] + gt * (y4 * rsy * pn);
.Lp6_np5:
	s_waitcnt vmcnt(24)
	v_lshlrev_b32_e32 v216, 16, v80
	v_and_b32_e32 v217, 0xffff0000, v80
	v_lshlrev_b32_e32 v218, 16, v81
	v_and_b32_e32 v219, 0xffff0000, v81
	v_mul_f32_e32 v222, v216, v216
	v_mul_f32_e32 v223, v217, v217
	v_fmac_f32_e32 v222, v218, v218
	v_fmac_f32_e32 v223, v219, v219
	v_lshlrev_b32_e32 v216, 16, v82
	v_and_b32_e32 v217, 0xffff0000, v82
	v_lshlrev_b32_e32 v218, 16, v83
	v_and_b32_e32 v219, 0xffff0000, v83
	v_fmac_f32_e32 v222, v216, v216
	v_fmac_f32_e32 v223, v217, v217
	v_fmac_f32_e32 v222, v218, v218
	v_fmac_f32_e32 v223, v219, v219
	v_lshlrev_b32_e32 v216, 16, v84
	v_and_b32_e32 v217, 0xffff0000, v84
	v_lshlrev_b32_e32 v218, 16, v85
	v_and_b32_e32 v219, 0xffff0000, v85
	v_fmac_f32_e32 v222, v216, v216
	v_fmac_f32_e32 v223, v217, v217
	v_fmac_f32_e32 v222, v218, v218
	v_fmac_f32_e32 v223, v219, v219
	v_lshlrev_b32_e32 v216, 16, v86
	v_and_b32_e32 v217, 0xffff0000, v86
	v_lshlrev_b32_e32 v218, 16, v87
	v_and_b32_e32 v219, 0xffff0000, v87
	v_fmac_f32_e32 v222, v216, v216
	v_fmac_f32_e32 v223, v217, v217
	v_fmac_f32_e32 v222, v218, v218
	v_fmac_f32_e32 v223, v219, v219
	v_lshlrev_b32_e32 v216, 16, v88
	v_and_b32_e32 v217, 0xffff0000, v88
	v_lshlrev_b32_e32 v218, 16, v89
	v_and_b32_e32 v219, 0xffff0000, v89
	v_fmac_f32_e32 v222, v216, v216
	v_fmac_f32_e32 v223, v217, v217
	v_fmac_f32_e32 v222, v218, v218
	v_fmac_f32_e32 v223, v219, v219
	v_lshlrev_b32_e32 v216, 16, v90
	v_and_b32_e32 v217, 0xffff0000, v90
	v_lshlrev_b32_e32 v218, 16, v91
	v_and_b32_e32 v219, 0xffff0000, v91
	v_fmac_f32_e32 v222, v216, v216
	v_fmac_f32_e32 v223, v217, v217
	v_fmac_f32_e32 v222, v218, v218
	v_fmac_f32_e32 v223, v219, v219
	v_lshlrev_b32_e32 v216, 16, v92
	v_and_b32_e32 v217, 0xffff0000, v92
	v_lshlrev_b32_e32 v218, 16, v93
	v_and_b32_e32 v219, 0xffff0000, v93
	v_fmac_f32_e32 v222, v216, v216
	v_fmac_f32_e32 v223, v217, v217
	v_fmac_f32_e32 v222, v218, v218
	v_fmac_f32_e32 v223, v219, v219
	v_lshlrev_b32_e32 v216, 16, v94
	v_and_b32_e32 v217, 0xffff0000, v94
	v_lshlrev_b32_e32 v218, 16, v95
	v_and_b32_e32 v219, 0xffff0000, v95
	v_fmac_f32_e32 v222, v216, v216
	v_fmac_f32_e32 v223, v217, v217
	v_fmac_f32_e32 v222, v218, v218
	v_fmac_f32_e32 v223, v219, v219
	v_add_f32_e32 v222, v222, v223
	s_nop 1
	v_add_f32_dpp v224, v222, v222 quad_perm:[1,0,3,2] row_mask:0xf bank_mask:0xf
	s_nop 1
	v_add_f32_dpp v224, v224, v224 quad_perm:[2,3,0,1] row_mask:0xf bank_mask:0xf
	s_nop 1
	v_add_f32_dpp v224, v224, v224 row_half_mirror row_mask:0xf bank_mask:0xf
	s_nop 1
	v_add_f32_dpp v224, v224, v224 row_mirror row_mask:0xf bank_mask:0xf
	s_nop 1
	v_readlane_b32 s40, v224, 0
	v_readlane_b32 s41, v224, 16
	v_readlane_b32 s42, v224, 32
	v_readlane_b32 s43, v224, 48
	s_nop 1
	v_mov_b32_e32 v225, s40
	v_add_f32_e32 v225, s41, v225
	v_add_f32_e32 v225, s42, v225
	v_add_f32_e32 v225, s43, v225
	v_fmamk_f32 v225, v225, 0x3a000000, v195
	v_rsq_f32_e32 v225, v225
	s_nop 0
	v_lshlrev_b32_e32 v216, 16, v80
	v_and_b32_e32 v217, 0xffff0000, v80
	v_lshlrev_b32_e32 v218, 16, v81
	v_and_b32_e32 v219, 0xffff0000, v81
	v_mul_f32_e32 v216, v225, v216
	v_mul_f32_e32 v217, v225, v217
	v_mul_f32_e32 v218, v225, v218
	v_mul_f32_e32 v219, v225, v219
	v_fmac_f32_e32 v48, v96, v216
	v_fmac_f32_e32 v49, v97, v217
	v_fmac_f32_e32 v50, v98, v218
	v_fmac_f32_e32 v51, v99, v219
	v_lshlrev_b32_e32 v216, 16, v82
	v_and_b32_e32 v217, 0xffff0000, v82
	v_lshlrev_b32_e32 v218, 16, v83
	v_and_b32_e32 v219, 0xffff0000, v83
	v_mul_f32_e32 v216, v225, v216
	v_mul_f32_e32 v217, v225, v217
	v_mul_f32_e32 v218, v225, v218
	v_mul_f32_e32 v219, v225, v219
	v_fmac_f32_e32 v52, v100, v216
	v_fmac_f32_e32 v53, v101, v217
	v_fmac_f32_e32 v54, v102, v218
	v_fmac_f32_e32 v55, v103, v219
	v_lshlrev_b32_e32 v216, 16, v84
	v_and_b32_e32 v217, 0xffff0000, v84
	v_lshlrev_b32_e32 v218, 16, v85
	v_and_b32_e32 v219, 0xffff0000, v85
	v_mul_f32_e32 v216, v225, v216
	v_mul_f32_e32 v217, v225, v217
	v_mul_f32_e32 v218, v225, v218
	v_mul_f32_e32 v219, v225, v219
	v_fmac_f32_e32 v56, v104, v216
	v_fmac_f32_e32 v57, v105, v217
	v_fmac_f32_e32 v58, v106, v218
	v_fmac_f32_e32 v59, v107, v219
	v_lshlrev_b32_e32 v216, 16, v86
	v_and_b32_e32 v217, 0xffff0000, v86
	v_lshlrev_b32_e32 v218, 16, v87
	v_and_b32_e32 v219, 0xffff0000, v87
	v_mul_f32_e32 v216, v225, v216
	v_mul_f32_e32 v217, v225, v217
	v_mul_f32_e32 v218, v225, v218
	v_mul_f32_e32 v219, v225, v219
	v_fmac_f32_e32 v60, v108, v216
	v_fmac_f32_e32 v61, v109, v217
	v_fmac_f32_e32 v62, v110, v218
	v_fmac_f32_e32 v63, v111, v219
	v_lshlrev_b32_e32 v216, 16, v88
	v_and_b32_e32 v217, 0xffff0000, v88
	v_lshlrev_b32_e32 v218, 16, v89
	v_and_b32_e32 v219, 0xffff0000, v89
	v_mul_f32_e32 v216, v225, v216
	v_mul_f32_e32 v217, v225, v217
	v_mul_f32_e32 v218, v225, v218
	v_mul_f32_e32 v219, v225, v219
	v_fmac_f32_e32 v64, v112, v216
	v_fmac_f32_e32 v65, v113, v217
	v_fmac_f32_e32 v66, v114, v218
	v_fmac_f32_e32 v67, v115, v219
	v_lshlrev_b32_e32 v216, 16, v90
	v_and_b32_e32 v217, 0xffff0000, v90
	v_lshlrev_b32_e32 v218, 16, v91
	v_and_b32_e32 v219, 0xffff0000, v91
	v_mul_f32_e32 v216, v225, v216
	v_mul_f32_e32 v217, v225, v217
	v_mul_f32_e32 v218, v225, v218
	v_mul_f32_e32 v219, v225, v219
	v_fmac_f32_e32 v68, v116, v216
	v_fmac_f32_e32 v69, v117, v217
	v_fmac_f32_e32 v70, v118, v218
	v_fmac_f32_e32 v71, v119, v219
	v_lshlrev_b32_e32 v216, 16, v92
	v_and_b32_e32 v217, 0xffff0000, v92
	v_lshlrev_b32_e32 v218, 16, v93
	v_and_b32_e32 v219, 0xffff0000, v93
	v_mul_f32_e32 v216, v225, v216
	v_mul_f32_e32 v217, v225, v217
	v_mul_f32_e32 v218, v225, v218
	v_mul_f32_e32 v219, v225, v219
	v_fmac_f32_e32 v72, v120, v216
	v_fmac_f32_e32 v73, v121, v217
	v_fmac_f32_e32 v74, v122, v218
; __device__ __forceinline__ unsigned cvt_pk_bf16(float lo, float hi) { unsigned r; asm volatile("v_cvt_pk_bf16_f32 %0, %1, %2" : "=v"(r) : "v"(lo), "v"(hi)); return r; }
; __device__ __forceinline__ void modulate_store(const f32x4 (&v)[8], float rstd, const float* pn, const float* modr, bf16_t* orow, int lane) {
; #pragma unroll
;     for (int j = 0; j < 8; ++j) { const int col = 4 * lane + 256 * j;
;         const f32x4 g = *(const f32x4*)(pn + col), sh = *(const f32x4*)(modr + col), sc = *(const f32x4*)(modr + DM + col);
;         const f32x4 hh = v[j] * rstd * g * (sc + 1.f) + sh;
;         u32x2 w; w.x = cvt_pk_bf16(hh[0], hh[1]); w.y = cvt_pk_bf16(hh[2], hh[3]);
;         *(u32x2*)(orow + col) = w; }
; }
; __global__ void __launch_bounds__(NWAVES * 64, 2) mk_fwd(Args args) {
;     ...
;                 const float rstd = __builtin_amdgcn_rsqf(sumsq8(v[q]) * (1.f / DM) + EPS);
;                 modulate_store(v[q], rstd, pre_norm + DM, mod + (size_t)(9 + r) * 6144, H + (size_t)row * DM, F.lane); }
	v_fmac_f32_e32 v75, v123, v219
	v_lshlrev_b32_e32 v216, 16, v94
	v_and_b32_e32 v217, 0xffff0000, v94
	v_lshlrev_b32_e32 v218, 16, v95
	v_and_b32_e32 v219, 0xffff0000, v95
	v_mul_f32_e32 v216, v225, v216
	v_mul_f32_e32 v217, v225, v217
	v_mul_f32_e32 v218, v225, v218
	v_mul_f32_e32 v219, v225, v219
	v_fmac_f32_e32 v76, v124, v216
	v_fmac_f32_e32 v77, v125, v217
	v_fmac_f32_e32 v78, v126, v218
	v_fmac_f32_e32 v79, v127, v219
	v_mul_f32_e32 v222, v48, v48
	v_mul_f32_e32 v223, v49, v49
	v_fmac_f32_e32 v222, v50, v50
	v_fmac_f32_e32 v223, v51, v51
	v_fmac_f32_e32 v222, v52, v52
	v_fmac_f32_e32 v223, v53, v53
	v_fmac_f32_e32 v222, v54, v54
	v_fmac_f32_e32 v223, v55, v55
	v_fmac_f32_e32 v222, v56, v56
	v_fmac_f32_e32 v223, v57, v57
	v_fmac_f32_e32 v222, v58, v58
	v_fmac_f32_e32 v223, v59, v59
	v_fmac_f32_e32 v222, v60, v60
	v_fmac_f32_e32 v223, v61, v61
	v_fmac_f32_e32 v222, v62, v62
	v_fmac_f32_e32 v223, v63, v63
	v_fmac_f32_e32 v222, v64, v64
	v_fmac_f32_e32 v223, v65, v65
	v_fmac_f32_e32 v222, v66, v66
	v_fmac_f32_e32 v223, v67, v67
	v_fmac_f32_e32 v222, v68, v68
	v_fmac_f32_e32 v223, v69, v69
	v_fmac_f32_e32 v222, v70, v70
	v_fmac_f32_e32 v223, v71, v71
	v_fmac_f32_e32 v222, v72, v72
	v_fmac_f32_e32 v223, v73, v73
	v_fmac_f32_e32 v222, v74, v74
	v_fmac_f32_e32 v223, v75, v75
	v_fmac_f32_e32 v222, v76, v76
	v_fmac_f32_e32 v223, v77, v77
	v_fmac_f32_e32 v222, v78, v78
	v_fmac_f32_e32 v223, v79, v79
	v_add_f32_e32 v222, v222, v223
	s_nop 1
	v_add_f32_dpp v224, v222, v222 quad_perm:[1,0,3,2] row_mask:0xf bank_mask:0xf
	s_nop 1
	v_add_f32_dpp v224, v224, v224 quad_perm:[2,3,0,1] row_mask:0xf bank_mask:0xf
	s_nop 1
	v_add_f32_dpp v224, v224, v224 row_half_mirror row_mask:0xf bank_mask:0xf
	s_nop 1
	v_add_f32_dpp v224, v224, v224 row_mirror row_mask:0xf bank_mask:0xf
	s_nop 1
	v_readlane_b32 s40, v224, 0
	v_readlane_b32 s41, v224, 16
	v_readlane_b32 s42, v224, 32
	v_readlane_b32 s43, v224, 48
	s_nop 1
	v_mov_b32_e32 v225, s40
	v_add_f32_e32 v225, s41, v225
	v_add_f32_e32 v225, s42, v225
	v_add_f32_e32 v225, s43, v225
	v_fmamk_f32 v225, v225, 0x3a000000, v195
	v_rsq_f32_e32 v225, v225
	s_nop 0
	s_add_i32 s0, s6, 5
	s_lshl_b32 s1, s0, 12
	s_add_u32 s26, s84, s1
	s_addc_u32 s27, s85, 0
	s_add_u32 s26, s26, 0x4000000
	s_addc_u32 s27, s27, 0
	v_mul_f32_e32 v216, v225, v48
	v_mul_f32_e32 v217, v225, v49
	v_mul_f32_e32 v218, v225, v50
	v_mul_f32_e32 v219, v225, v51
	v_fma_f32 v216, v216, v128, v160
	v_fma_f32 v217, v217, v129, v161
	v_fma_f32 v218, v218, v130, v162
	v_fma_f32 v219, v219, v131, v163
	v_cvt_pk_bf16_f32 v196, v216, v217
	v_cvt_pk_bf16_f32 v197, v218, v219
	global_store_dwordx2 v194, v[196:197], s[26:27] offset:0
	v_mul_f32_e32 v216, v225, v52
	v_mul_f32_e32 v217, v225, v53
	v_mul_f32_e32 v218, v225, v54
	v_mul_f32_e32 v219, v225, v55
	v_fma_f32 v216, v216, v132, v164
	v_fma_f32 v217, v217, v133, v165
	v_fma_f32 v218, v218, v134, v166
	v_fma_f32 v219, v219, v135, v167
	v_cvt_pk_bf16_f32 v220, v216, v217
	v_cvt_pk_bf16_f32 v221, v218, v219
	global_store_dwordx2 v194, v[220:221], s[26:27] offset:512
	v_mul_f32_e32 v216, v225, v56
	v_mul_f32_e32 v217, v225, v57
	v_mul_f32_e32 v218, v225, v58
	v_mul_f32_e32 v219, v225, v59
	v_fma_f32 v216, v216, v136, v168
	v_fma_f32 v217, v217, v137, v169
	v_fma_f32 v218, v218, v138, v170
	v_fma_f32 v219, v219, v139, v171
	v_cvt_pk_bf16_f32 v196, v216, v217
	v_cvt_pk_bf16_f32 v197, v218, v219
	global_store_dwordx2 v194, v[196:197], s[26:27] offset:1024
	v_mul_f32_e32 v216, v225, v60
	v_mul_f32_e32 v217, v225, v61
	v_mul_f32_e32 v218, v225, v62
	v_mul_f32_e32 v219, v225, v63
	v_fma_f32 v216, v216, v140, v172
	v_fma_f32 v217, v217, v141, v173
	v_fma_f32 v218, v218, v142, v174
	v_fma_f32 v219, v219, v143, v175
	v_cvt_pk_bf16_f32 v220, v216, v217
	v_cvt_pk_bf16_f32 v221, v218, v219
	global_store_dwordx2 v194, v[220:221], s[26:27] offset:1536
	v_mul_f32_e32 v216, v225, v64
	v_mul_f32_e32 v217, v225, v65
	v_mul_f32_e32 v218, v225, v66
	v_mul_f32_e32 v219, v225, v67
	v_fma_f32 v216, v216, v144, v176
	v_fma_f32 v217, v217, v145, v177
	v_fma_f32 v218, v218, v146, v178
	v_fma_f32 v219, v219, v147, v179
	v_cvt_pk_bf16_f32 v196, v216, v217
	v_cvt_pk_bf16_f32 v197, v218, v219
	global_store_dwordx2 v194, v[196:197], s[26:27] offset:2048
	v_mul_f32_e32 v216, v225, v68
	v_mul_f32_e32 v217, v225, v69
	v_mul_f32_e32 v218, v225, v70
	v_mul_f32_e32 v219, v225, v71
	v_fma_f32 v216, v216, v148, v180
	v_fma_f32 v217, v217, v149, v181
	v_fma_f32 v218, v218, v150, v182
	v_fma_f32 v219, v219, v151, v183
	v_cvt_pk_bf16_f32 v220, v216, v217
	v_cvt_pk_bf16_f32 v221, v218, v219
	global_store_dwordx2 v194, v[220:221], s[26:27] offset:2560
	v_mul_f32_e32 v216, v225, v72
	v_mul_f32_e32 v217, v225, v73
	v_mul_f32_e32 v218, v225, v74
	v_mul_f32_e32 v219, v225, v75
	v_fma_f32 v216, v216, v152, v184
	v_fma_f32 v217, v217, v153, v185
	v_fma_f32 v218, v218, v154, v186
	v_fma_f32 v219, v219, v155, v187
	v_cvt_pk_bf16_f32 v196, v216, v217
	v_cvt_pk_bf16_f32 v197, v218, v219
	global_store_dwordx2 v194, v[196:197], s[26:27] offset:3072
	v_mul_f32_e32 v216, v225, v76
	v_mul_f32_e32 v217, v225, v77
	v_mul_f32_e32 v218, v225, v78
	v_mul_f32_e32 v219, v225, v79
	v_fma_f32 v216, v216, v156, v188
	v_fma_f32 v217, v217, v157, v189
	v_fma_f32 v218, v218, v158, v190
	v_fma_f32 v219, v219, v159, v191
	v_cvt_pk_bf16_f32 v220, v216, v217
	v_cvt_pk_bf16_f32 v221, v218, v219
	global_store_dwordx2 v194, v[220:221], s[26:27] offset:3584
	s_add_i32 s0, s6, 7
	s_cmp_lt_u32 s0, 0x4000
	s_cselect_b32 s10, s68, s72
	s_cselect_b32 s11, s69, s73
	s_cselect_b32 s1, 0, 0x4000
	s_sub_i32 s1, s0, s1
	s_lshl_b32 s1, s1, 13
	s_add_u32 s10, s10, s1
	s_addc_u32 s11, s11, 0
	s_add_i32 s0, s6, 7
	s_lshl_b32 s1, s0, 12
	s_add_u32 s22, s84, s1
	s_addc_u32 s23, s85, 0
	s_add_u32 s22, s22, 0x11800000
	s_addc_u32 s23, s23, 0
	global_load_dwordx4 v[48:51], v192, s[10:11] offset:0 nt
	global_load_dwordx4 v[52:55], v192, s[10:11] offset:1024 nt
	global_load_dwordx4 v[56:59], v192, s[10:11] offset:2048 nt
	global_load_dwordx4 v[60:63], v192, s[10:11] offset:3072 nt
	global_load_dwordx4 v[64:67], v193, s[10:11] offset:0 nt
	global_load_dwordx4 v[68:71], v193, s[10:11] offset:1024 nt
	global_load_dwordx4 v[72:75], v193, s[10:11] offset:2048 nt
	global_load_dwordx4 v[76:79], v193, s[10:11] offset:3072 nt
	global_load_dwordx2 v[80:81], v194, s[22:23] offset:0 nt
	global_load_dwordx2 v[82:83], v194, s[22:23] offset:512 nt
	global_load_dwordx2 v[84:85], v194, s[22:23] offset:1024 nt
	global_load_dwordx2 v[86:87], v194, s[22:23] offset:1536 nt
	global_load_dwordx2 v[88:89], v194, s[22:23] offset:2048 nt
	global_load_dwordx2 v[90:91], v194, s[22:23] offset:2560 nt
	global_load_dwordx2 v[92:93], v194, s[22:23] offset:3072 nt
	global_load_dwordx2 v[94:95], v194, s[22:23] offset:3584 nt
	s_add_i32 s0, s6, 6
	s_add_i32 s0, s6, 6
	s_lshr_b32 s8, s0, 11
	s_cmp_lt_u32 s0, 0x4000
	s_cselect_b32 s8, s8, 8
	s_cmp_eq_u32 s8, s7
	s_cbranch_scc1 .Lp6_np6
; __device__ __forceinline__ float bf_lo(unsigned w) { return __uint_as_float(w << 16); }
; __device__ __forceinline__ float bf_hi(unsigned w) { return __uint_as_float(w & 0xffff0000u); }
; __device__ __forceinline__ void modulate_store(const f32x4 (&v)[8], float rstd, const float* pn, const float* modr, bf16_t* orow, int lane) {
; #pragma unroll
;     for (int j = 0; j < 8; ++j) { const int col = 4 * lane + 256 * j;
;         const f32x4 g = *(const f32x4*)(pn + col), sh = *(const f32x4*)(modr + col), sc = *(const f32x4*)(modr + DM + col);
;         const f32x4 hh = v[j] * rstd * g * (sc + 1.f) + sh;
; __global__ void __launch_bounds__(NWAVES * 64, 2) mk_fwd(Args args) {
;     ...
;                 const float* m0 = mod + (size_t)r * 6144;
; #pragma unroll
;                 for (int j = 0; j < 8; ++j) { const int col = 4 * F.lane + 256 * j; const f32x4 gt = *(const f32x4*)(m0 + 2 * DM + col), pn = *(const f32x4*)(post_norm + col);
;                     const f32x4 y4 = (f32x4){bf_lo(yw[q][j].x), bf_hi(yw[q][j].x), bf_lo(yw[q][j].y), bf_hi(yw[q][j].y)};
;                     v[q][j] = v[q][j] + gt * (y4 * rsy * pn);
;                     if (lat) *(f32x4*)(args.out + (size_t)row * DM + col) = v[q][j]; }
;                 const float rstd = __builtin_amdgcn_rsqf(sumsq8(v[q]) * (1.f / DM) + EPS);
;                 modulate_store(v[q], rstd, pre_norm + DM, mod + (size_t)(9 + r) * 6144, H + (size_t)row * DM, F.lane); }
	s_mov_b32 s7, s8
	s_add_i32 s1, s8, 9
	s_mul_i32 s1, s1, 0x6000
	s_add_u32 s44, s84, s1
	s_addc_u32 s45, s85, 0
	s_add_u32 s44, s44, 0x2000
	s_addc_u32 s45, s45, 0
	s_add_i32 s1, s8, 9
	s_mul_i32 s1, s1, 0x6000
	s_add_u32 s36, s84, s1
	s_addc_u32 s37, s85, 0
	s_add_u32 s38, s80, 0x2000
	s_addc_u32 s39, s81, 0
	s_mul_i32 s1, s8, 0x6000
	s_add_u32 s34, s84, s1
	s_addc_u32 s35, s85, 0
	s_add_u32 s34, s34, 0x4000
	s_addc_u32 s35, s35, 0
	global_load_dwordx4 v[96:99], v192, s[34:35] offset:0
	global_load_dwordx4 v[200:203], v192, s[82:83] offset:0
	global_load_dwordx4 v[100:103], v192, s[34:35] offset:1024
	global_load_dwordx4 v[204:207], v192, s[82:83] offset:1024
	global_load_dwordx4 v[104:107], v192, s[34:35] offset:2048
	global_load_dwordx4 v[208:211], v192, s[82:83] offset:2048
	global_load_dwordx4 v[108:111], v192, s[34:35] offset:3072
	global_load_dwordx4 v[212:215], v192, s[82:83] offset:3072
	s_waitcnt vmcnt(0)
	v_mul_f32_e32 v96, v96, v200
	v_mul_f32_e32 v97, v97, v201
	v_mul_f32_e32 v98, v98, v202
	v_mul_f32_e32 v99, v99, v203
	v_mul_f32_e32 v100, v100, v204
	v_mul_f32_e32 v101, v101, v205
	v_mul_f32_e32 v102, v102, v206
	v_mul_f32_e32 v103, v103, v207
	v_mul_f32_e32 v104, v104, v208
	v_mul_f32_e32 v105, v105, v209
	v_mul_f32_e32 v106, v106, v210
	v_mul_f32_e32 v107, v107, v211
	v_mul_f32_e32 v108, v108, v212
	v_mul_f32_e32 v109, v109, v213
	v_mul_f32_e32 v110, v110, v214
	v_mul_f32_e32 v111, v111, v215
	global_load_dwordx4 v[128:131], v192, s[38:39] offset:0
	global_load_dwordx4 v[200:203], v192, s[44:45] offset:0
	global_load_dwordx4 v[160:163], v192, s[36:37] offset:0
	global_load_dwordx4 v[132:135], v192, s[38:39] offset:1024
	global_load_dwordx4 v[204:207], v192, s[44:45] offset:1024
	global_load_dwordx4 v[164:167], v192, s[36:37] offset:1024
	global_load_dwordx4 v[136:139], v192, s[38:39] offset:2048
	global_load_dwordx4 v[208:211], v192, s[44:45] offset:2048
	global_load_dwordx4 v[168:171], v192, s[36:37] offset:2048
	global_load_dwordx4 v[140:143], v192, s[38:39] offset:3072
	global_load_dwordx4 v[212:215], v192, s[44:45] offset:3072
	global_load_dwordx4 v[172:175], v192, s[36:37] offset:3072
	s_waitcnt vmcnt(0)
	v_add_f32_e32 v200, 1.0, v200
	v_add_f32_e32 v201, 1.0, v201
	v_add_f32_e32 v202, 1.0, v202
	v_add_f32_e32 v203, 1.0, v203
	v_mul_f32_e32 v128, v128, v200
	v_mul_f32_e32 v129, v129, v201
	v_mul_f32_e32 v130, v130, v202
	v_mul_f32_e32 v131, v131, v203
	v_add_f32_e32 v204, 1.0, v204
	v_add_f32_e32 v205, 1.0, v205
	v_add_f32_e32 v206, 1.0, v206
	v_add_f32_e32 v207, 1.0, v207
	v_mul_f32_e32 v132, v132, v204
	v_mul_f32_e32 v133, v133, v205
	v_mul_f32_e32 v134, v134, v206
	v_mul_f32_e32 v135, v135, v207
	v_add_f32_e32 v208, 1.0, v208
	v_add_f32_e32 v209, 1.0, v209
	v_add_f32_e32 v210, 1.0, v210
	v_add_f32_e32 v211, 1.0, v211
	v_mul_f32_e32 v136, v136, v208
	v_mul_f32_e32 v137, v137, v209
	v_mul_f32_e32 v138, v138, v210
	v_mul_f32_e32 v139, v139, v211
	v_add_f32_e32 v212, 1.0, v212
	v_add_f32_e32 v213, 1.0, v213
	v_add_f32_e32 v214, 1.0, v214
	v_add_f32_e32 v215, 1.0, v215
	v_mul_f32_e32 v140, v140, v212
	v_mul_f32_e32 v141, v141, v213
	v_mul_f32_e32 v142, v142, v214
	v_mul_f32_e32 v143, v143, v215
	global_load_dwordx4 v[112:115], v193, s[34:35] offset:0
	global_load_dwordx4 v[200:203], v193, s[82:83] offset:0
	global_load_dwordx4 v[116:119], v193, s[34:35] offset:1024
	global_load_dwordx4 v[204:207], v193, s[82:83] offset:1024
	global_load_dwordx4 v[120:123], v193, s[34:35] offset:2048
	global_load_dwordx4 v[208:211], v193, s[82:83] offset:2048
	global_load_dwordx4 v[124:127], v193, s[34:35] offset:3072
	global_load_dwordx4 v[212:215], v193, s[82:83] offset:3072
	s_waitcnt vmcnt(0)
	v_mul_f32_e32 v112, v112, v200
	v_mul_f32_e32 v113, v113, v201
	v_mul_f32_e32 v114, v114, v202
	v_mul_f32_e32 v115, v115, v203
	v_mul_f32_e32 v116, v116, v204
	v_mul_f32_e32 v117, v117, v205
	v_mul_f32_e32 v118, v118, v206
	v_mul_f32_e32 v119, v119, v207
	v_mul_f32_e32 v120, v120, v208
	v_mul_f32_e32 v121, v121, v209
	v_mul_f32_e32 v122, v122, v210
	v_mul_f32_e32 v123, v123, v211
	v_mul_f32_e32 v124, v124, v212
	v_mul_f32_e32 v125, v125, v213
	v_mul_f32_e32 v126, v126, v214
	v_mul_f32_e32 v127, v127, v215
	global_load_dwordx4 v[144:147], v193, s[38:39] offset:0
	global_load_dwordx4 v[200:203], v193, s[44:45] offset:0
	global_load_dwordx4 v[176:179], v193, s[36:37] offset:0
	global_load_dwordx4 v[148:151], v193, s[38:39] offset:1024
	global_load_dwordx4 v[204:207], v193, s[44:45] offset:1024
	global_load_dwordx4 v[180:183], v193, s[36:37] offset:1024
	global_load_dwordx4 v[152:155], v193, s[38:39] offset:2048
	global_load_dwordx4 v[208:211], v193, s[44:45] offset:2048
	global_load_dwordx4 v[184:187], v193, s[36:37] offset:2048
	global_load_dwordx4 v[156:159], v193, s[38:39] offset:3072
	global_load_dwordx4 v[212:215], v193, s[44:45] offset:3072
	global_load_dwordx4 v[188:191], v193, s[36:37] offset:3072
	s_waitcnt vmcnt(0)
	v_add_f32_e32 v200, 1.0, v200
	v_add_f32_e32 v201, 1.0, v201
	v_add_f32_e32 v202, 1.0, v202
	v_add_f32_e32 v203, 1.0, v203
	v_mul_f32_e32 v144, v144, v200
	v_mul_f32_e32 v145, v145, v201
	v_mul_f32_e32 v146, v146, v202
	v_mul_f32_e32 v147, v147, v203
	v_add_f32_e32 v204, 1.0, v204
	v_add_f32_e32 v205, 1.0, v205
	v_add_f32_e32 v206, 1.0, v206
	v_add_f32_e32 v207, 1.0, v207
	v_mul_f32_e32 v148, v148, v204
	v_mul_f32_e32 v149, v149, v205
	v_mul_f32_e32 v150, v150, v206
	v_mul_f32_e32 v151, v151, v207
	v_add_f32_e32 v208, 1.0, v208
	v_add_f32_e32 v209, 1.0, v209
	v_add_f32_e32 v210, 1.0, v210
	v_add_f32_e32 v211, 1.0, v211
	v_mul_f32_e32 v152, v152, v208
	v_mul_f32_e32 v153, v153, v209
	v_mul_f32_e32 v154, v154, v210
	v_mul_f32_e32 v155, v155, v211
	v_add_f32_e32 v212, 1.0, v212
	v_add_f32_e32 v213, 1.0, v213
	v_add_f32_e32 v214, 1.0, v214
	v_add_f32_e32 v215, 1.0, v215
	v_mul_f32_e32 v156, v156, v212
	v_mul_f32_e32 v157, v157, v213
	v_mul_f32_e32 v158, v158, v214
	v_mul_f32_e32 v159, v159, v215
; __device__ __forceinline__ float bf_lo(unsigned w) { return __uint_as_float(w << 16); }
; __device__ __forceinline__ float bf_hi(unsigned w) { return __uint_as_float(w & 0xffff0000u); }
; __global__ void __launch_bounds__(NWAVES * 64, 2) mk_fwd(Args args) {
;     ...
;             for (int q = 0; q < 3; ++q) { const int row = row0 + q; const bool lat = row < ML; const int r = lat ? row / SEQ : 8;
;                 float sy = 0.f;
; #pragma unroll
;                 for (int j = 0; j < 8; ++j) { const float a = bf_lo(yw[q][j].x), b = bf_hi(yw[q][j].x), c2 = bf_lo(yw[q][j].y), d = bf_hi(yw[q][j].y); sy += (a * a + b * b) + (c2 * c2 + d * d); }
;                 const float rsy = __builtin_amdgcn_rsqf(wave_sum(sy) * (1.f / DM) + EPS);
;                 const float* m0 = mod + (size_t)r * 6144;
; #pragma unroll
;                 for (int j = 0; j < 8; ++j) { const int col = 4 * F.lane + 256 * j; const f32x4 gt = *(const f32x4*)(m0 + 2 * DM + col), pn = *(const f32x4*)(post_norm + col);
;                     const f32x4 y4 = (f32x4){bf_lo(yw[q][j].x), bf_hi(yw[q][j].x), bf_lo(yw[q][j].y), bf_hi(yw[q][j].y)};
;                     v[q][j] = v[q][j] + gt * (y4 * rsy * pn);
.Lp6_np6:
	s_waitcnt vmcnt(24)
	v_lshlrev_b32_e32 v216, 16, v32
	v_and_b32_e32 v217, 0xffff0000, v32
	v_lshlrev_b32_e32 v218, 16, v33
	v_and_b32_e32 v219, 0xffff0000, v33
	v_mul_f32_e32 v222, v216, v216
	v_mul_f32_e32 v223, v217, v217
	v_fmac_f32_e32 v222, v218, v218
	v_fmac_f32_e32 v223, v219, v219
	v_lshlrev_b32_e32 v216, 16, v34
	v_and_b32_e32 v217, 0xffff0000, v34
	v_lshlrev_b32_e32 v218, 16, v35
	v_and_b32_e32 v219, 0xffff0000, v35
	v_fmac_f32_e32 v222, v216, v216
	v_fmac_f32_e32 v223, v217, v217
	v_fmac_f32_e32 v222, v218, v218
	v_fmac_f32_e32 v223, v219, v219
	v_lshlrev_b32_e32 v216, 16, v36
	v_and_b32_e32 v217, 0xffff0000, v36
	v_lshlrev_b32_e32 v218, 16, v37
	v_and_b32_e32 v219, 0xffff0000, v37
	v_fmac_f32_e32 v222, v216, v216
	v_fmac_f32_e32 v223, v217, v217
	v_fmac_f32_e32 v222, v218, v218
	v_fmac_f32_e32 v223, v219, v219
	v_lshlrev_b32_e32 v216, 16, v38
	v_and_b32_e32 v217, 0xffff0000, v38
	v_lshlrev_b32_e32 v218, 16, v39
	v_and_b32_e32 v219, 0xffff0000, v39
	v_fmac_f32_e32 v222, v216, v216
	v_fmac_f32_e32 v223, v217, v217
	v_fmac_f32_e32 v222, v218, v218
	v_fmac_f32_e32 v223, v219, v219
	v_lshlrev_b32_e32 v216, 16, v40
	v_and_b32_e32 v217, 0xffff0000, v40
	v_lshlrev_b32_e32 v218, 16, v41
	v_and_b32_e32 v219, 0xffff0000, v41
	v_fmac_f32_e32 v222, v216, v216
	v_fmac_f32_e32 v223, v217, v217
	v_fmac_f32_e32 v222, v218, v218
	v_fmac_f32_e32 v223, v219, v219
	v_lshlrev_b32_e32 v216, 16, v42
	v_and_b32_e32 v217, 0xffff0000, v42
	v_lshlrev_b32_e32 v218, 16, v43
	v_and_b32_e32 v219, 0xffff0000, v43
	v_fmac_f32_e32 v222, v216, v216
	v_fmac_f32_e32 v223, v217, v217
	v_fmac_f32_e32 v222, v218, v218
	v_fmac_f32_e32 v223, v219, v219
	v_lshlrev_b32_e32 v216, 16, v44
	v_and_b32_e32 v217, 0xffff0000, v44
	v_lshlrev_b32_e32 v218, 16, v45
	v_and_b32_e32 v219, 0xffff0000, v45
	v_fmac_f32_e32 v222, v216, v216
	v_fmac_f32_e32 v223, v217, v217
	v_fmac_f32_e32 v222, v218, v218
	v_fmac_f32_e32 v223, v219, v219
	v_lshlrev_b32_e32 v216, 16, v46
	v_and_b32_e32 v217, 0xffff0000, v46
	v_lshlrev_b32_e32 v218, 16, v47
	v_and_b32_e32 v219, 0xffff0000, v47
	v_fmac_f32_e32 v222, v216, v216
	v_fmac_f32_e32 v223, v217, v217
	v_fmac_f32_e32 v222, v218, v218
	v_fmac_f32_e32 v223, v219, v219
	v_add_f32_e32 v222, v222, v223
	s_nop 1
	v_add_f32_dpp v224, v222, v222 quad_perm:[1,0,3,2] row_mask:0xf bank_mask:0xf
	s_nop 1
	v_add_f32_dpp v224, v224, v224 quad_perm:[2,3,0,1] row_mask:0xf bank_mask:0xf
	s_nop 1
	v_add_f32_dpp v224, v224, v224 row_half_mirror row_mask:0xf bank_mask:0xf
	s_nop 1
	v_add_f32_dpp v224, v224, v224 row_mirror row_mask:0xf bank_mask:0xf
	s_nop 1
	v_readlane_b32 s40, v224, 0
	v_readlane_b32 s41, v224, 16
	v_readlane_b32 s42, v224, 32
	v_readlane_b32 s43, v224, 48
	s_nop 1
	v_mov_b32_e32 v225, s40
	v_add_f32_e32 v225, s41, v225
	v_add_f32_e32 v225, s42, v225
	v_add_f32_e32 v225, s43, v225
	v_fmamk_f32 v225, v225, 0x3a000000, v195
	v_rsq_f32_e32 v225, v225
	s_nop 0
	v_lshlrev_b32_e32 v216, 16, v32
	v_and_b32_e32 v217, 0xffff0000, v32
	v_lshlrev_b32_e32 v218, 16, v33
	v_and_b32_e32 v219, 0xffff0000, v33
	v_mul_f32_e32 v216, v225, v216
	v_mul_f32_e32 v217, v225, v217
	v_mul_f32_e32 v218, v225, v218
	v_mul_f32_e32 v219, v225, v219
	v_fmac_f32_e32 v0, v96, v216
	v_fmac_f32_e32 v1, v97, v217
	v_fmac_f32_e32 v2, v98, v218
	v_fmac_f32_e32 v3, v99, v219
	v_lshlrev_b32_e32 v216, 16, v34
	v_and_b32_e32 v217, 0xffff0000, v34
	v_lshlrev_b32_e32 v218, 16, v35
	v_and_b32_e32 v219, 0xffff0000, v35
	v_mul_f32_e32 v216, v225, v216
	v_mul_f32_e32 v217, v225, v217
	v_mul_f32_e32 v218, v225, v218
	v_mul_f32_e32 v219, v225, v219
	v_fmac_f32_e32 v4, v100, v216
	v_fmac_f32_e32 v5, v101, v217
	v_fmac_f32_e32 v6, v102, v218
	v_fmac_f32_e32 v7, v103, v219
	v_lshlrev_b32_e32 v216, 16, v36
	v_and_b32_e32 v217, 0xffff0000, v36
	v_lshlrev_b32_e32 v218, 16, v37
	v_and_b32_e32 v219, 0xffff0000, v37
	v_mul_f32_e32 v216, v225, v216
	v_mul_f32_e32 v217, v225, v217
	v_mul_f32_e32 v218, v225, v218
	v_mul_f32_e32 v219, v225, v219
	v_fmac_f32_e32 v8, v104, v216
	v_fmac_f32_e32 v9, v105, v217
	v_fmac_f32_e32 v10, v106, v218
	v_fmac_f32_e32 v11, v107, v219
	v_lshlrev_b32_e32 v216, 16, v38
	v_and_b32_e32 v217, 0xffff0000, v38
	v_lshlrev_b32_e32 v218, 16, v39
	v_and_b32_e32 v219, 0xffff0000, v39
	v_mul_f32_e32 v216, v225, v216
	v_mul_f32_e32 v217, v225, v217
	v_mul_f32_e32 v218, v225, v218
	v_mul_f32_e32 v219, v225, v219
	v_fmac_f32_e32 v12, v108, v216
	v_fmac_f32_e32 v13, v109, v217
	v_fmac_f32_e32 v14, v110, v218
	v_fmac_f32_e32 v15, v111, v219
	v_lshlrev_b32_e32 v216, 16, v40
	v_and_b32_e32 v217, 0xffff0000, v40
	v_lshlrev_b32_e32 v218, 16, v41
	v_and_b32_e32 v219, 0xffff0000, v41
	v_mul_f32_e32 v216, v225, v216
	v_mul_f32_e32 v217, v225, v217
	v_mul_f32_e32 v218, v225, v218
	v_mul_f32_e32 v219, v225, v219
	v_fmac_f32_e32 v16, v112, v216
	v_fmac_f32_e32 v17, v113, v217
	v_fmac_f32_e32 v18, v114, v218
	v_fmac_f32_e32 v19, v115, v219
	v_lshlrev_b32_e32 v216, 16, v42
	v_and_b32_e32 v217, 0xffff0000, v42
	v_lshlrev_b32_e32 v218, 16, v43
	v_and_b32_e32 v219, 0xffff0000, v43
	v_mul_f32_e32 v216, v225, v216
	v_mul_f32_e32 v217, v225, v217
	v_mul_f32_e32 v218, v225, v218
	v_mul_f32_e32 v219, v225, v219
	v_fmac_f32_e32 v20, v116, v216
	v_fmac_f32_e32 v21, v117, v217
	v_fmac_f32_e32 v22, v118, v218
	v_fmac_f32_e32 v23, v119, v219
	v_lshlrev_b32_e32 v216, 16, v44
	v_and_b32_e32 v217, 0xffff0000, v44
	v_lshlrev_b32_e32 v218, 16, v45
	v_and_b32_e32 v219, 0xffff0000, v45
	v_mul_f32_e32 v216, v225, v216
	v_mul_f32_e32 v217, v225, v217
	v_mul_f32_e32 v218, v225, v218
	v_mul_f32_e32 v219, v225, v219
	v_fmac_f32_e32 v24, v120, v216
	v_fmac_f32_e32 v25, v121, v217
	v_fmac_f32_e32 v26, v122, v218
; __device__ __forceinline__ float bf_lo(unsigned w) { return __uint_as_float(w << 16); }
; __device__ __forceinline__ float sumsq8(const f32x4 (&v)[8]) {
;     float s = 0.f;
; #pragma unroll
;     for (int j = 0; j < 8; ++j) s += (v[j][0] * v[j][0] + v[j][1] * v[j][1]) + (v[j][2] * v[j][2] + v[j][3] * v[j][3]);
;     return wave_sum(s);
; }
; __device__ __forceinline__ void modulate_store(const f32x4 (&v)[8], float rstd, const float* pn, const float* modr, bf16_t* orow, int lane) {
; #pragma unroll
;     for (int j = 0; j < 8; ++j) { const int col = 4 * lane + 256 * j;
; __global__ void __launch_bounds__(NWAVES * 64, 2) mk_fwd(Args args) {
;     ...
;         for (int row0 = F.gw * 3; row0 < MT; row0 += F.NGW * 3) {
;             f32x4 v[3][8]; u32x2 yw[3][8];
; #pragma unroll
;             for (int q = 0; q < 3; ++q) { const int row = row0 + q; const float* src = row < ML ? x + (size_t)row * DM : ctx + (size_t)(row - ML) * DM; load_row_f32(src, F.lane, v[q]);
;                 const bf16_t* yr = Y + (size_t)row * DM;
; #pragma unroll
;                 for (int j = 0; j < 8; ++j) yw[q][j] = *(const u32x2*)(yr + 4 * F.lane + 256 * j); }
; #pragma unroll
;             for (int q = 0; q < 3; ++q) { const int row = row0 + q; const bool lat = row < ML; const int r = lat ? row / SEQ : 8;
;                 float sy = 0.f;
; #pragma unroll
;                 for (int j = 0; j < 8; ++j) { const float a = bf_lo(yw[q][j].x), b = bf_hi(yw[q][j].x), c2 = bf_lo(yw[q][j].y), d = bf_hi(yw[q][j].y); sy += (a * a + b * b) + (c2 * c2 + d * d); }
;                 const float rsy = __builtin_amdgcn_rsqf(wave_sum(sy) * (1.f / DM) + EPS);
;                 const float* m0 = mod + (size_t)r * 6144;
; #pragma unroll
;                 for (int j = 0; j < 8; ++j) { const int col = 4 * F.lane + 256 * j; const f32x4 gt = *(const f32x4*)(m0 + 2 * DM + col), pn = *(const f32x4*)(post_norm + col);
;                     const f32x4 y4 = (f32x4){bf_lo(yw[q][j].x), bf_hi(yw[q][j].x), bf_lo(yw[q][j].y), bf_hi(yw[q][j].y)};
;                     v[q][j] = v[q][j] + gt * (y4 * rsy * pn);
;                     if (lat) *(f32x4*)(args.out + (size_t)row * DM + col) = v[q][j]; }
;                 const float rstd = __builtin_amdgcn_rsqf(sumsq8(v[q]) * (1.f / DM) + EPS);
;                 modulate_store(v[q], rstd, pre_norm + DM, mod + (size_t)(9 + r) * 6144, H + (size_t)row * DM, F.lane); }
	v_fmac_f32_e32 v27, v123, v219
	v_lshlrev_b32_e32 v216, 16, v46
	v_and_b32_e32 v217, 0xffff0000, v46
	v_lshlrev_b32_e32 v218, 16, v47
	v_and_b32_e32 v219, 0xffff0000, v47
	v_mul_f32_e32 v216, v225, v216
	v_mul_f32_e32 v217, v225, v217
	v_mul_f32_e32 v218, v225, v218
	v_mul_f32_e32 v219, v225, v219
	v_fmac_f32_e32 v28, v124, v216
	v_fmac_f32_e32 v29, v125, v217
	v_fmac_f32_e32 v30, v126, v218
	v_fmac_f32_e32 v31, v127, v219
	v_mul_f32_e32 v222, v0, v0
	v_mul_f32_e32 v223, v1, v1
	v_fmac_f32_e32 v222, v2, v2
	v_fmac_f32_e32 v223, v3, v3
	v_fmac_f32_e32 v222, v4, v4
	v_fmac_f32_e32 v223, v5, v5
	v_fmac_f32_e32 v222, v6, v6
	v_fmac_f32_e32 v223, v7, v7
	v_fmac_f32_e32 v222, v8, v8
	v_fmac_f32_e32 v223, v9, v9
	v_fmac_f32_e32 v222, v10, v10
	v_fmac_f32_e32 v223, v11, v11
	v_fmac_f32_e32 v222, v12, v12
	v_fmac_f32_e32 v223, v13, v13
	v_fmac_f32_e32 v222, v14, v14
	v_fmac_f32_e32 v223, v15, v15
	v_fmac_f32_e32 v222, v16, v16
	v_fmac_f32_e32 v223, v17, v17
	v_fmac_f32_e32 v222, v18, v18
	v_fmac_f32_e32 v223, v19, v19
	v_fmac_f32_e32 v222, v20, v20
	v_fmac_f32_e32 v223, v21, v21
	v_fmac_f32_e32 v222, v22, v22
	v_fmac_f32_e32 v223, v23, v23
	v_fmac_f32_e32 v222, v24, v24
	v_fmac_f32_e32 v223, v25, v25
	v_fmac_f32_e32 v222, v26, v26
	v_fmac_f32_e32 v223, v27, v27
	v_fmac_f32_e32 v222, v28, v28
	v_fmac_f32_e32 v223, v29, v29
	v_fmac_f32_e32 v222, v30, v30
	v_fmac_f32_e32 v223, v31, v31
	v_add_f32_e32 v222, v222, v223
	s_nop 1
	v_add_f32_dpp v224, v222, v222 quad_perm:[1,0,3,2] row_mask:0xf bank_mask:0xf
	s_nop 1
	v_add_f32_dpp v224, v224, v224 quad_perm:[2,3,0,1] row_mask:0xf bank_mask:0xf
	s_nop 1
	v_add_f32_dpp v224, v224, v224 row_half_mirror row_mask:0xf bank_mask:0xf
	s_nop 1
	v_add_f32_dpp v224, v224, v224 row_mirror row_mask:0xf bank_mask:0xf
	s_nop 1
	v_readlane_b32 s40, v224, 0
	v_readlane_b32 s41, v224, 16
	v_readlane_b32 s42, v224, 32
	v_readlane_b32 s43, v224, 48
	s_nop 1
	v_mov_b32_e32 v225, s40
	v_add_f32_e32 v225, s41, v225
	v_add_f32_e32 v225, s42, v225
	v_add_f32_e32 v225, s43, v225
	v_fmamk_f32 v225, v225, 0x3a000000, v195
	v_rsq_f32_e32 v225, v225
	s_nop 0
	s_add_i32 s0, s6, 6
	s_lshl_b32 s1, s0, 12
	s_add_u32 s26, s84, s1
	s_addc_u32 s27, s85, 0
	s_add_u32 s26, s26, 0x4000000
	s_addc_u32 s27, s27, 0
	v_mul_f32_e32 v216, v225, v0
	v_mul_f32_e32 v217, v225, v1
	v_mul_f32_e32 v218, v225, v2
	v_mul_f32_e32 v219, v225, v3
	v_fma_f32 v216, v216, v128, v160
	v_fma_f32 v217, v217, v129, v161
	v_fma_f32 v218, v218, v130, v162
	v_fma_f32 v219, v219, v131, v163
	v_cvt_pk_bf16_f32 v196, v216, v217
	v_cvt_pk_bf16_f32 v197, v218, v219
	global_store_dwordx2 v194, v[196:197], s[26:27] offset:0
	v_mul_f32_e32 v216, v225, v4
	v_mul_f32_e32 v217, v225, v5
	v_mul_f32_e32 v218, v225, v6
	v_mul_f32_e32 v219, v225, v7
	v_fma_f32 v216, v216, v132, v164
	v_fma_f32 v217, v217, v133, v165
	v_fma_f32 v218, v218, v134, v166
	v_fma_f32 v219, v219, v135, v167
	v_cvt_pk_bf16_f32 v220, v216, v217
	v_cvt_pk_bf16_f32 v221, v218, v219
	global_store_dwordx2 v194, v[220:221], s[26:27] offset:512
	v_mul_f32_e32 v216, v225, v8
	v_mul_f32_e32 v217, v225, v9
	v_mul_f32_e32 v218, v225, v10
	v_mul_f32_e32 v219, v225, v11
	v_fma_f32 v216, v216, v136, v168
	v_fma_f32 v217, v217, v137, v169
	v_fma_f32 v218, v218, v138, v170
	v_fma_f32 v219, v219, v139, v171
	v_cvt_pk_bf16_f32 v196, v216, v217
	v_cvt_pk_bf16_f32 v197, v218, v219
	global_store_dwordx2 v194, v[196:197], s[26:27] offset:1024
	v_mul_f32_e32 v216, v225, v12
	v_mul_f32_e32 v217, v225, v13
	v_mul_f32_e32 v218, v225, v14
	v_mul_f32_e32 v219, v225, v15
	v_fma_f32 v216, v216, v140, v172
	v_fma_f32 v217, v217, v141, v173
	v_fma_f32 v218, v218, v142, v174
	v_fma_f32 v219, v219, v143, v175
	v_cvt_pk_bf16_f32 v220, v216, v217
	v_cvt_pk_bf16_f32 v221, v218, v219
	global_store_dwordx2 v194, v[220:221], s[26:27] offset:1536
	v_mul_f32_e32 v216, v225, v16
	v_mul_f32_e32 v217, v225, v17
	v_mul_f32_e32 v218, v225, v18
	v_mul_f32_e32 v219, v225, v19
	v_fma_f32 v216, v216, v144, v176
	v_fma_f32 v217, v217, v145, v177
	v_fma_f32 v218, v218, v146, v178
	v_fma_f32 v219, v219, v147, v179
	v_cvt_pk_bf16_f32 v196, v216, v217
	v_cvt_pk_bf16_f32 v197, v218, v219
	global_store_dwordx2 v194, v[196:197], s[26:27] offset:2048
	v_mul_f32_e32 v216, v225, v20
	v_mul_f32_e32 v217, v225, v21
	v_mul_f32_e32 v218, v225, v22
	v_mul_f32_e32 v219, v225, v23
	v_fma_f32 v216, v216, v148, v180
	v_fma_f32 v217, v217, v149, v181
	v_fma_f32 v218, v218, v150, v182
	v_fma_f32 v219, v219, v151, v183
	v_cvt_pk_bf16_f32 v220, v216, v217
	v_cvt_pk_bf16_f32 v221, v218, v219
	global_store_dwordx2 v194, v[220:221], s[26:27] offset:2560
	v_mul_f32_e32 v216, v225, v24
	v_mul_f32_e32 v217, v225, v25
	v_mul_f32_e32 v218, v225, v26
	v_mul_f32_e32 v219, v225, v27
	v_fma_f32 v216, v216, v152, v184
	v_fma_f32 v217, v217, v153, v185
	v_fma_f32 v218, v218, v154, v186
	v_fma_f32 v219, v219, v155, v187
	v_cvt_pk_bf16_f32 v196, v216, v217
	v_cvt_pk_bf16_f32 v197, v218, v219
	global_store_dwordx2 v194, v[196:197], s[26:27] offset:3072
	v_mul_f32_e32 v216, v225, v28
	v_mul_f32_e32 v217, v225, v29
	v_mul_f32_e32 v218, v225, v30
	v_mul_f32_e32 v219, v225, v31
	v_fma_f32 v216, v216, v156, v188
	v_fma_f32 v217, v217, v157, v189
	v_fma_f32 v218, v218, v158, v190
	v_fma_f32 v219, v219, v159, v191
	v_cvt_pk_bf16_f32 v220, v216, v217
	v_cvt_pk_bf16_f32 v221, v218, v219
	global_store_dwordx2 v194, v[220:221], s[26:27] offset:3584
	s_add_i32 s0, s6, 8
	s_cmp_lt_u32 s0, 0x4000
	s_cselect_b32 s10, s68, s72
	s_cselect_b32 s11, s69, s73
	s_cselect_b32 s1, 0, 0x4000
	s_sub_i32 s1, s0, s1
	s_lshl_b32 s1, s1, 13
	s_add_u32 s10, s10, s1
	s_addc_u32 s11, s11, 0
	s_add_i32 s0, s6, 8
	s_lshl_b32 s1, s0, 12
	s_add_u32 s22, s84, s1
	s_addc_u32 s23, s85, 0
	s_add_u32 s22, s22, 0x11800000
	s_addc_u32 s23, s23, 0
	global_load_dwordx4 v[0:3], v192, s[10:11] offset:0 nt
	global_load_dwordx4 v[4:7], v192, s[10:11] offset:1024 nt
	global_load_dwordx4 v[8:11], v192, s[10:11] offset:2048 nt
	global_load_dwordx4 v[12:15], v192, s[10:11] offset:3072 nt
	global_load_dwordx4 v[16:19], v193, s[10:11] offset:0 nt
	global_load_dwordx4 v[20:23], v193, s[10:11] offset:1024 nt
	global_load_dwordx4 v[24:27], v193, s[10:11] offset:2048 nt
	global_load_dwordx4 v[28:31], v193, s[10:11] offset:3072 nt
	global_load_dwordx2 v[32:33], v194, s[22:23] offset:0 nt
	global_load_dwordx2 v[34:35], v194, s[22:23] offset:512 nt
	global_load_dwordx2 v[36:37], v194, s[22:23] offset:1024 nt
	global_load_dwordx2 v[38:39], v194, s[22:23] offset:1536 nt
	global_load_dwordx2 v[40:41], v194, s[22:23] offset:2048 nt
	global_load_dwordx2 v[42:43], v194, s[22:23] offset:2560 nt
	global_load_dwordx2 v[44:45], v194, s[22:23] offset:3072 nt
	global_load_dwordx2 v[46:47], v194, s[22:23] offset:3584 nt
	s_add_i32 s0, s6, 7
	s_add_i32 s0, s6, 7
	s_lshr_b32 s8, s0, 11
	s_cmp_lt_u32 s0, 0x4000
	s_cselect_b32 s8, s8, 8
	s_cmp_eq_u32 s8, s7
	s_cbranch_scc1 .Lp6_np7
; __device__ __forceinline__ float bf_lo(unsigned w) { return __uint_as_float(w << 16); }
; __device__ __forceinline__ float bf_hi(unsigned w) { return __uint_as_float(w & 0xffff0000u); }
; __device__ __forceinline__ void modulate_store(const f32x4 (&v)[8], float rstd, const float* pn, const float* modr, bf16_t* orow, int lane) {
; #pragma unroll
;     for (int j = 0; j < 8; ++j) { const int col = 4 * lane + 256 * j;
;         const f32x4 g = *(const f32x4*)(pn + col), sh = *(const f32x4*)(modr + col), sc = *(const f32x4*)(modr + DM + col);
;         const f32x4 hh = v[j] * rstd * g * (sc + 1.f) + sh;
; __global__ void __launch_bounds__(NWAVES * 64, 2) mk_fwd(Args args) {
;     ...
;                 const float* m0 = mod + (size_t)r * 6144;
; #pragma unroll
;                 for (int j = 0; j < 8; ++j) { const int col = 4 * F.lane + 256 * j; const f32x4 gt = *(const f32x4*)(m0 + 2 * DM + col), pn = *(const f32x4*)(post_norm + col);
;                     const f32x4 y4 = (f32x4){bf_lo(yw[q][j].x), bf_hi(yw[q][j].x), bf_lo(yw[q][j].y), bf_hi(yw[q][j].y)};
;                     v[q][j] = v[q][j] + gt * (y4 * rsy * pn);
;                     if (lat) *(f32x4*)(args.out + (size_t)row * DM + col) = v[q][j]; }
;                 const float rstd = __builtin_amdgcn_rsqf(sumsq8(v[q]) * (1.f / DM) + EPS);
;                 modulate_store(v[q], rstd, pre_norm + DM, mod + (size_t)(9 + r) * 6144, H + (size_t)row * DM, F.lane); }
	s_mov_b32 s7, s8
	s_add_i32 s1, s8, 9
	s_mul_i32 s1, s1, 0x6000
	s_add_u32 s44, s84, s1
	s_addc_u32 s45, s85, 0
	s_add_u32 s44, s44, 0x2000
	s_addc_u32 s45, s45, 0
	s_add_i32 s1, s8, 9
	s_mul_i32 s1, s1, 0x6000
	s_add_u32 s36, s84, s1
	s_addc_u32 s37, s85, 0
	s_add_u32 s38, s80, 0x2000
	s_addc_u32 s39, s81, 0
	s_mul_i32 s1, s8, 0x6000
	s_add_u32 s34, s84, s1
	s_addc_u32 s35, s85, 0
	s_add_u32 s34, s34, 0x4000
	s_addc_u32 s35, s35, 0
	global_load_dwordx4 v[96:99], v192, s[34:35] offset:0
	global_load_dwordx4 v[200:203], v192, s[82:83] offset:0
	global_load_dwordx4 v[100:103], v192, s[34:35] offset:1024
	global_load_dwordx4 v[204:207], v192, s[82:83] offset:1024
	global_load_dwordx4 v[104:107], v192, s[34:35] offset:2048
	global_load_dwordx4 v[208:211], v192, s[82:83] offset:2048
	global_load_dwordx4 v[108:111], v192, s[34:35] offset:3072
	global_load_dwordx4 v[212:215], v192, s[82:83] offset:3072
	s_waitcnt vmcnt(0)
	v_mul_f32_e32 v96, v96, v200
	v_mul_f32_e32 v97, v97, v201
	v_mul_f32_e32 v98, v98, v202
	v_mul_f32_e32 v99, v99, v203
	v_mul_f32_e32 v100, v100, v204
	v_mul_f32_e32 v101, v101, v205
	v_mul_f32_e32 v102, v102, v206
	v_mul_f32_e32 v103, v103, v207
	v_mul_f32_e32 v104, v104, v208
	v_mul_f32_e32 v105, v105, v209
	v_mul_f32_e32 v106, v106, v210
	v_mul_f32_e32 v107, v107, v211
	v_mul_f32_e32 v108, v108, v212
	v_mul_f32_e32 v109, v109, v213
	v_mul_f32_e32 v110, v110, v214
	v_mul_f32_e32 v111, v111, v215
	global_load_dwordx4 v[128:131], v192, s[38:39] offset:0
	global_load_dwordx4 v[200:203], v192, s[44:45] offset:0
	global_load_dwordx4 v[160:163], v192, s[36:37] offset:0
	global_load_dwordx4 v[132:135], v192, s[38:39] offset:1024
	global_load_dwordx4 v[204:207], v192, s[44:45] offset:1024
	global_load_dwordx4 v[164:167], v192, s[36:37] offset:1024
	global_load_dwordx4 v[136:139], v192, s[38:39] offset:2048
	global_load_dwordx4 v[208:211], v192, s[44:45] offset:2048
	global_load_dwordx4 v[168:171], v192, s[36:37] offset:2048
	global_load_dwordx4 v[140:143], v192, s[38:39] offset:3072
	global_load_dwordx4 v[212:215], v192, s[44:45] offset:3072
	global_load_dwordx4 v[172:175], v192, s[36:37] offset:3072
	s_waitcnt vmcnt(0)
	v_add_f32_e32 v200, 1.0, v200
	v_add_f32_e32 v201, 1.0, v201
	v_add_f32_e32 v202, 1.0, v202
	v_add_f32_e32 v203, 1.0, v203
	v_mul_f32_e32 v128, v128, v200
	v_mul_f32_e32 v129, v129, v201
	v_mul_f32_e32 v130, v130, v202
	v_mul_f32_e32 v131, v131, v203
	v_add_f32_e32 v204, 1.0, v204
	v_add_f32_e32 v205, 1.0, v205
	v_add_f32_e32 v206, 1.0, v206
	v_add_f32_e32 v207, 1.0, v207
	v_mul_f32_e32 v132, v132, v204
	v_mul_f32_e32 v133, v133, v205
	v_mul_f32_e32 v134, v134, v206
	v_mul_f32_e32 v135, v135, v207
	v_add_f32_e32 v208, 1.0, v208
	v_add_f32_e32 v209, 1.0, v209
	v_add_f32_e32 v210, 1.0, v210
	v_add_f32_e32 v211, 1.0, v211
	v_mul_f32_e32 v136, v136, v208
	v_mul_f32_e32 v137, v137, v209
	v_mul_f32_e32 v138, v138, v210
	v_mul_f32_e32 v139, v139, v211
	v_add_f32_e32 v212, 1.0, v212
	v_add_f32_e32 v213, 1.0, v213
	v_add_f32_e32 v214, 1.0, v214
	v_add_f32_e32 v215, 1.0, v215
	v_mul_f32_e32 v140, v140, v212
	v_mul_f32_e32 v141, v141, v213
	v_mul_f32_e32 v142, v142, v214
	v_mul_f32_e32 v143, v143, v215
	global_load_dwordx4 v[112:115], v193, s[34:35] offset:0
	global_load_dwordx4 v[200:203], v193, s[82:83] offset:0
	global_load_dwordx4 v[116:119], v193, s[34:35] offset:1024
	global_load_dwordx4 v[204:207], v193, s[82:83] offset:1024
	global_load_dwordx4 v[120:123], v193, s[34:35] offset:2048
	global_load_dwordx4 v[208:211], v193, s[82:83] offset:2048
	global_load_dwordx4 v[124:127], v193, s[34:35] offset:3072
	global_load_dwordx4 v[212:215], v193, s[82:83] offset:3072
	s_waitcnt vmcnt(0)
	v_mul_f32_e32 v112, v112, v200
	v_mul_f32_e32 v113, v113, v201
	v_mul_f32_e32 v114, v114, v202
	v_mul_f32_e32 v115, v115, v203
	v_mul_f32_e32 v116, v116, v204
	v_mul_f32_e32 v117, v117, v205
	v_mul_f32_e32 v118, v118, v206
	v_mul_f32_e32 v119, v119, v207
	v_mul_f32_e32 v120, v120, v208
	v_mul_f32_e32 v121, v121, v209
	v_mul_f32_e32 v122, v122, v210
	v_mul_f32_e32 v123, v123, v211
	v_mul_f32_e32 v124, v124, v212
	v_mul_f32_e32 v125, v125, v213
	v_mul_f32_e32 v126, v126, v214
	v_mul_f32_e32 v127, v127, v215
	global_load_dwordx4 v[144:147], v193, s[38:39] offset:0
	global_load_dwordx4 v[200:203], v193, s[44:45] offset:0
	global_load_dwordx4 v[176:179], v193, s[36:37] offset:0
	global_load_dwordx4 v[148:151], v193, s[38:39] offset:1024
	global_load_dwordx4 v[204:207], v193, s[44:45] offset:1024
	global_load_dwordx4 v[180:183], v193, s[36:37] offset:1024
	global_load_dwordx4 v[152:155], v193, s[38:39] offset:2048
	global_load_dwordx4 v[208:211], v193, s[44:45] offset:2048
	global_load_dwordx4 v[184:187], v193, s[36:37] offset:2048
	global_load_dwordx4 v[156:159], v193, s[38:39] offset:3072
	global_load_dwordx4 v[212:215], v193, s[44:45] offset:3072
	global_load_dwordx4 v[188:191], v193, s[36:37] offset:3072
	s_waitcnt vmcnt(0)
	v_add_f32_e32 v200, 1.0, v200
	v_add_f32_e32 v201, 1.0, v201
	v_add_f32_e32 v202, 1.0, v202
	v_add_f32_e32 v203, 1.0, v203
	v_mul_f32_e32 v144, v144, v200
	v_mul_f32_e32 v145, v145, v201
	v_mul_f32_e32 v146, v146, v202
	v_mul_f32_e32 v147, v147, v203
	v_add_f32_e32 v204, 1.0, v204
	v_add_f32_e32 v205, 1.0, v205
	v_add_f32_e32 v206, 1.0, v206
	v_add_f32_e32 v207, 1.0, v207
	v_mul_f32_e32 v148, v148, v204
	v_mul_f32_e32 v149, v149, v205
	v_mul_f32_e32 v150, v150, v206
	v_mul_f32_e32 v151, v151, v207
	v_add_f32_e32 v208, 1.0, v208
	v_add_f32_e32 v209, 1.0, v209
	v_add_f32_e32 v210, 1.0, v210
	v_add_f32_e32 v211, 1.0, v211
	v_mul_f32_e32 v152, v152, v208
	v_mul_f32_e32 v153, v153, v209
	v_mul_f32_e32 v154, v154, v210
	v_mul_f32_e32 v155, v155, v211
	v_add_f32_e32 v212, 1.0, v212
	v_add_f32_e32 v213, 1.0, v213
	v_add_f32_e32 v214, 1.0, v214
	v_add_f32_e32 v215, 1.0, v215
	v_mul_f32_e32 v156, v156, v212
	v_mul_f32_e32 v157, v157, v213
	v_mul_f32_e32 v158, v158, v214
	v_mul_f32_e32 v159, v159, v215

; #define FRESH() int gtid; do { int t_ = threadIdx.x; asm volatile("" : "+v"(t_)); F.tid = t_; F.lane = t_ & 63; gtid = blockIdx.x * (NWAVES * 64) + t_; (void)gtid; } while (0)
; __global__ void __launch_bounds__(NWAVES * 64, 2) mk_fwd(Args args) {
;     ...
;     if (IN(11)) { FRESH();
;         const int per = (ML + F.NGW - 1) / F.NGW, per2 = (per + 1) & ~1, rbeg = F.gw * per2;
;         int rcur = -1; f32x4 PA[8];
;         for (int row0 = rbeg; row0 < rbeg + per2 && row0 < ML; row0 += 2) {
;             f32x4 v[2][8]; u32x2 yw[2][8];
; #pragma unroll
;             for (int q = 0; q < 2; ++q) { const int row = row0 + q; load_row_f32(args.out + (size_t)row * DM, F.lane, v[q]);
;                 const bf16_t* yr = Y + (size_t)row * DM;
; #pragma unroll
;                 for (int j = 0; j < 8; ++j) yw[q][j] = *(const u32x2*)(yr + 4 * F.lane + 256 * j); }
; #pragma unroll
;             for (int q = 0; q < 2; ++q) { const int row = row0 + q; const int r = row / SEQ;
;                 if (r != rcur) { const float* m1 = mod + (size_t)(9 + r) * 6144; rcur = r;
; #pragma unroll
;                     for (int j = 0; j < 8; ++j) { const int col = 4 * F.lane + 256 * j; PA[j] = *(const f32x4*)(m1 + 2 * DM + col) * *(const f32x4*)(post_norm + DM + col); } }
.LBB0_1288:
	s_cmp_gt_i32 s86, 11
	s_cselect_b64 s[2:3], -1, 0
	s_xor_b64 s[0:1], s[0:1], -1
	s_or_b64 s[0:1], s[2:3], s[0:1]
	s_and_b64 vcc, exec, s[0:1]
	s_cbranch_vccnz .LBB0_1296
	s_cmpk_lg_i32 s63, 0x100
	s_cbranch_scc1 .Lp11_generic
	v_and_b32_e32 v194, 63, v198
	v_lshlrev_b32_e32 v192, 4, v194
	v_add_u32_e32 v193, 0x1000, v192
	v_lshlrev_b32_e32 v194, 3, v194
	v_mov_b32_e32 v195, 0x358637bd
	s_lshr_b32 s0, s33, 8
	s_mul_i32 s1, s0, 0x6000
	s_add_u32 s8, s84, s1
	s_addc_u32 s9, s85, 0
	s_add_u32 s8, s8, 0x4000
	s_addc_u32 s9, s9, 0
	s_add_u32 s10, s8, 0x36000
	s_addc_u32 s11, s9, 0
	s_add_u32 s12, s82, 0x2000
	s_addc_u32 s13, s83, 0
	s_lshl_b32 s0, s33, 16
	s_add_u32 s14, s68, s0
	s_addc_u32 s15, s69, 0
	s_add_u32 s18, s94, s0
	s_addc_u32 s19, s95, 0
	s_lshl_b32 s0, s33, 15
	s_add_u32 s16, s84, s0
	s_addc_u32 s17, s85, 0
	s_add_u32 s22, s16, 0x8800000
	s_addc_u32 s23, s17, 0
	s_add_u32 s16, s16, 0x11800000
	s_addc_u32 s17, s17, 0
	global_load_dwordx4 v[128:131], v192, s[8:9] offset:0
	global_load_dwordx4 v[132:135], v192, s[8:9] offset:1024
	global_load_dwordx4 v[136:139], v192, s[8:9] offset:2048
	global_load_dwordx4 v[140:143], v192, s[8:9] offset:3072
	global_load_dwordx4 v[144:147], v193, s[8:9] offset:0
	global_load_dwordx4 v[148:151], v193, s[8:9] offset:1024
	global_load_dwordx4 v[152:155], v193, s[8:9] offset:2048
	global_load_dwordx4 v[156:159], v193, s[8:9] offset:3072
	global_load_dwordx4 v[32:35], v192, s[82:83] offset:0
	global_load_dwordx4 v[36:39], v192, s[82:83] offset:1024
	global_load_dwordx4 v[40:43], v192, s[82:83] offset:2048
	global_load_dwordx4 v[44:47], v192, s[82:83] offset:3072
	global_load_dwordx4 v[48:51], v193, s[82:83] offset:0
	global_load_dwordx4 v[52:55], v193, s[82:83] offset:1024
	global_load_dwordx4 v[56:59], v193, s[82:83] offset:2048
	global_load_dwordx4 v[60:63], v193, s[82:83] offset:3072
	global_load_dwordx4 v[160:163], v192, s[10:11] offset:0
	global_load_dwordx4 v[164:167], v192, s[10:11] offset:1024
	global_load_dwordx4 v[168:171], v192, s[10:11] offset:2048
	global_load_dwordx4 v[172:175], v192, s[10:11] offset:3072
	global_load_dwordx4 v[176:179], v193, s[10:11] offset:0
	global_load_dwordx4 v[180:183], v193, s[10:11] offset:1024
	global_load_dwordx4 v[184:187], v193, s[10:11] offset:2048
	global_load_dwordx4 v[188:191], v193, s[10:11] offset:3072
	global_load_dwordx4 v[96:99], v192, s[12:13] offset:0
	global_load_dwordx4 v[100:103], v192, s[12:13] offset:1024
	global_load_dwordx4 v[104:107], v192, s[12:13] offset:2048
	global_load_dwordx4 v[108:111], v192, s[12:13] offset:3072
	global_load_dwordx4 v[112:115], v193, s[12:13] offset:0
	global_load_dwordx4 v[116:119], v193, s[12:13] offset:1024
	global_load_dwordx4 v[120:123], v193, s[12:13] offset:2048
	global_load_dwordx4 v[124:127], v193, s[12:13] offset:3072
	s_waitcnt vmcnt(0)
	v_mul_f32_e32 v128, v128, v32
	v_mul_f32_e32 v129, v129, v33
	v_mul_f32_e32 v130, v130, v34
	v_mul_f32_e32 v131, v131, v35
	v_mul_f32_e32 v132, v132, v36
	v_mul_f32_e32 v133, v133, v37
	v_mul_f32_e32 v134, v134, v38
	v_mul_f32_e32 v135, v135, v39
	v_mul_f32_e32 v136, v136, v40
	v_mul_f32_e32 v137, v137, v41
	v_mul_f32_e32 v138, v138, v42
	v_mul_f32_e32 v139, v139, v43
	v_mul_f32_e32 v140, v140, v44
	v_mul_f32_e32 v141, v141, v45
	v_mul_f32_e32 v142, v142, v46
	v_mul_f32_e32 v143, v143, v47
	v_mul_f32_e32 v144, v144, v48
	v_mul_f32_e32 v145, v145, v49
	v_mul_f32_e32 v146, v146, v50
	v_mul_f32_e32 v147, v147, v51
	v_mul_f32_e32 v148, v148, v52
	v_mul_f32_e32 v149, v149, v53
	v_mul_f32_e32 v150, v150, v54
	v_mul_f32_e32 v151, v151, v55
	v_mul_f32_e32 v152, v152, v56
	v_mul_f32_e32 v153, v153, v57
	v_mul_f32_e32 v154, v154, v58
	v_mul_f32_e32 v155, v155, v59
	v_mul_f32_e32 v156, v156, v60
	v_mul_f32_e32 v157, v157, v61
	v_mul_f32_e32 v158, v158, v62
	v_mul_f32_e32 v159, v159, v63
	v_mul_f32_e32 v160, v160, v96
	v_mul_f32_e32 v161, v161, v97
	v_mul_f32_e32 v162, v162, v98
	v_mul_f32_e32 v163, v163, v99
	v_mul_f32_e32 v164, v164, v100
	v_mul_f32_e32 v165, v165, v101
	v_mul_f32_e32 v166, v166, v102
	v_mul_f32_e32 v167, v167, v103
	v_mul_f32_e32 v168, v168, v104
	v_mul_f32_e32 v169, v169, v105
	v_mul_f32_e32 v170, v170, v106
	v_mul_f32_e32 v171, v171, v107
	v_mul_f32_e32 v172, v172, v108
	v_mul_f32_e32 v173, v173, v109
	v_mul_f32_e32 v174, v174, v110
	v_mul_f32_e32 v175, v175, v111
	v_mul_f32_e32 v176, v176, v112
	v_mul_f32_e32 v177, v177, v113
	v_mul_f32_e32 v178, v178, v114
	v_mul_f32_e32 v179, v179, v115
	v_mul_f32_e32 v180, v180, v116
	v_mul_f32_e32 v181, v181, v117
	v_mul_f32_e32 v182, v182, v118
	v_mul_f32_e32 v183, v183, v119
	v_mul_f32_e32 v184, v184, v120
	v_mul_f32_e32 v185, v185, v121
	v_mul_f32_e32 v186, v186, v122
	v_mul_f32_e32 v187, v187, v123
	v_mul_f32_e32 v188, v188, v124
	v_mul_f32_e32 v189, v189, v125
	v_mul_f32_e32 v190, v190, v126
	v_mul_f32_e32 v191, v191, v127
	global_load_dwordx4 v[0:3], v192, s[14:15] offset:0 nt
	global_load_dwordx4 v[4:7], v192, s[14:15] offset:1024 nt
	global_load_dwordx4 v[8:11], v192, s[14:15] offset:2048 nt
	global_load_dwordx4 v[12:15], v192, s[14:15] offset:3072 nt
	global_load_dwordx4 v[16:19], v193, s[14:15] offset:0 nt
	global_load_dwordx4 v[20:23], v193, s[14:15] offset:1024 nt
	global_load_dwordx4 v[24:27], v193, s[14:15] offset:2048 nt
	global_load_dwordx4 v[28:31], v193, s[14:15] offset:3072 nt
	global_load_dwordx2 v[64:65], v194, s[16:17] offset:0 nt
	global_load_dwordx2 v[66:67], v194, s[16:17] offset:512 nt
	global_load_dwordx2 v[68:69], v194, s[16:17] offset:1024 nt
	global_load_dwordx2 v[70:71], v194, s[16:17] offset:1536 nt
	global_load_dwordx2 v[72:73], v194, s[16:17] offset:2048 nt
; __device__ __forceinline__ float bf_lo(unsigned w) { return __uint_as_float(w << 16); }
; __device__ __forceinline__ float bf_hi(unsigned w) { return __uint_as_float(w & 0xffff0000u); }
; __global__ void __launch_bounds__(NWAVES * 64, 2) mk_fwd(Args args) {
;     ...
;         for (int row0 = rbeg; row0 < rbeg + per2 && row0 < ML; row0 += 2) {
;             f32x4 v[2][8]; u32x2 yw[2][8];
; #pragma unroll
;             for (int q = 0; q < 2; ++q) { const int row = row0 + q; load_row_f32(args.out + (size_t)row * DM, F.lane, v[q]);
;                 const bf16_t* yr = Y + (size_t)row * DM;
; #pragma unroll
;                 for (int j = 0; j < 8; ++j) yw[q][j] = *(const u32x2*)(yr + 4 * F.lane + 256 * j); }
; #pragma unroll
;             for (int q = 0; q < 2; ++q) { const int row = row0 + q; const int r = row / SEQ;
;                 if (r != rcur) { const float* m1 = mod + (size_t)(9 + r) * 6144; rcur = r;
; #pragma unroll
;                     for (int j = 0; j < 8; ++j) { const int col = 4 * F.lane + 256 * j; PA[j] = *(const f32x4*)(m1 + 2 * DM + col) * *(const f32x4*)(post_norm + DM + col); } }
;                 float sy = 0.f;
; #pragma unroll
;                 for (int j = 0; j < 8; ++j) { const float a = bf_lo(yw[q][j].x), b = bf_hi(yw[q][j].x), c2 = bf_lo(yw[q][j].y), d = bf_hi(yw[q][j].y); sy += (a * a + b * b) + (c2 * c2 + d * d); }
	global_load_dwordx2 v[74:75], v194, s[16:17] offset:2560 nt
	global_load_dwordx2 v[76:77], v194, s[16:17] offset:3072 nt
	global_load_dwordx2 v[78:79], v194, s[16:17] offset:3584 nt
	global_load_dwordx2 v[96:97], v194, s[22:23] offset:0 nt
	global_load_dwordx2 v[98:99], v194, s[22:23] offset:512 nt
	global_load_dwordx2 v[100:101], v194, s[22:23] offset:1024 nt
	global_load_dwordx2 v[102:103], v194, s[22:23] offset:1536 nt
	global_load_dwordx2 v[104:105], v194, s[22:23] offset:2048 nt
	global_load_dwordx2 v[106:107], v194, s[22:23] offset:2560 nt
	global_load_dwordx2 v[108:109], v194, s[22:23] offset:3072 nt
	global_load_dwordx2 v[110:111], v194, s[22:23] offset:3584 nt
	s_add_u32 s14, s14, 0x2000
	s_addc_u32 s15, s15, 0
	s_add_u32 s16, s16, 0x1000
	s_addc_u32 s17, s17, 0
	s_add_u32 s22, s22, 0x1000
	s_addc_u32 s23, s23, 0
	global_load_dwordx4 v[32:35], v192, s[14:15] offset:0 nt
	global_load_dwordx4 v[36:39], v192, s[14:15] offset:1024 nt
	global_load_dwordx4 v[40:43], v192, s[14:15] offset:2048 nt
	global_load_dwordx4 v[44:47], v192, s[14:15] offset:3072 nt
	global_load_dwordx4 v[48:51], v193, s[14:15] offset:0 nt
	global_load_dwordx4 v[52:55], v193, s[14:15] offset:1024 nt
	global_load_dwordx4 v[56:59], v193, s[14:15] offset:2048 nt
	global_load_dwordx4 v[60:63], v193, s[14:15] offset:3072 nt
	global_load_dwordx2 v[80:81], v194, s[16:17] offset:0 nt
	global_load_dwordx2 v[82:83], v194, s[16:17] offset:512 nt
	global_load_dwordx2 v[84:85], v194, s[16:17] offset:1024 nt
	global_load_dwordx2 v[86:87], v194, s[16:17] offset:1536 nt
	global_load_dwordx2 v[88:89], v194, s[16:17] offset:2048 nt
	global_load_dwordx2 v[90:91], v194, s[16:17] offset:2560 nt
	global_load_dwordx2 v[92:93], v194, s[16:17] offset:3072 nt
	global_load_dwordx2 v[94:95], v194, s[16:17] offset:3584 nt
	global_load_dwordx2 v[112:113], v194, s[22:23] offset:0 nt
	global_load_dwordx2 v[114:115], v194, s[22:23] offset:512 nt
	global_load_dwordx2 v[116:117], v194, s[22:23] offset:1024 nt
	global_load_dwordx2 v[118:119], v194, s[22:23] offset:1536 nt
	global_load_dwordx2 v[120:121], v194, s[22:23] offset:2048 nt
	global_load_dwordx2 v[122:123], v194, s[22:23] offset:2560 nt
	global_load_dwordx2 v[124:125], v194, s[22:23] offset:3072 nt
	global_load_dwordx2 v[126:127], v194, s[22:23] offset:3584 nt
	s_add_u32 s14, s14, 0x2000
	s_addc_u32 s15, s15, 0
	s_add_u32 s16, s16, 0x1000
	s_addc_u32 s17, s17, 0
	s_add_u32 s22, s22, 0x1000
	s_addc_u32 s23, s23, 0
	s_waitcnt vmcnt(24)
	v_lshlrev_b32_e32 v200, 16, v64
	v_and_b32_e32 v201, 0xffff0000, v64
	v_lshlrev_b32_e32 v202, 16, v65
	v_and_b32_e32 v203, 0xffff0000, v65
	v_mul_f32_e32 v208, v200, v200
	v_mul_f32_e32 v209, v201, v201
	v_fmac_f32_e32 v208, v202, v202
	v_fmac_f32_e32 v209, v203, v203
	v_lshlrev_b32_e32 v204, 16, v96
	v_and_b32_e32 v205, 0xffff0000, v96
	v_lshlrev_b32_e32 v206, 16, v97
	v_and_b32_e32 v207, 0xffff0000, v97
	v_mul_f32_e32 v210, v204, v204
	v_mul_f32_e32 v211, v205, v205
	v_fmac_f32_e32 v210, v206, v206
	v_fmac_f32_e32 v211, v207, v207
	v_lshlrev_b32_e32 v200, 16, v66
	v_and_b32_e32 v201, 0xffff0000, v66
	v_lshlrev_b32_e32 v202, 16, v67
	v_and_b32_e32 v203, 0xffff0000, v67
	v_fmac_f32_e32 v208, v200, v200
	v_fmac_f32_e32 v209, v201, v201
	v_fmac_f32_e32 v208, v202, v202
	v_fmac_f32_e32 v209, v203, v203
	v_lshlrev_b32_e32 v204, 16, v98
	v_and_b32_e32 v205, 0xffff0000, v98
	v_lshlrev_b32_e32 v206, 16, v99
	v_and_b32_e32 v207, 0xffff0000, v99
	v_fmac_f32_e32 v210, v204, v204
	v_fmac_f32_e32 v211, v205, v205
	v_fmac_f32_e32 v210, v206, v206
	v_fmac_f32_e32 v211, v207, v207
	v_lshlrev_b32_e32 v200, 16, v68
	v_and_b32_e32 v201, 0xffff0000, v68
	v_lshlrev_b32_e32 v202, 16, v69
	v_and_b32_e32 v203, 0xffff0000, v69
	v_fmac_f32_e32 v208, v200, v200
	v_fmac_f32_e32 v209, v201, v201
	v_fmac_f32_e32 v208, v202, v202
	v_fmac_f32_e32 v209, v203, v203
	v_lshlrev_b32_e32 v204, 16, v100
	v_and_b32_e32 v205, 0xffff0000, v100
	v_lshlrev_b32_e32 v206, 16, v101
	v_and_b32_e32 v207, 0xffff0000, v101
	v_fmac_f32_e32 v210, v204, v204
	v_fmac_f32_e32 v211, v205, v205
	v_fmac_f32_e32 v210, v206, v206
	v_fmac_f32_e32 v211, v207, v207
	v_lshlrev_b32_e32 v200, 16, v70
	v_and_b32_e32 v201, 0xffff0000, v70
	v_lshlrev_b32_e32 v202, 16, v71
	v_and_b32_e32 v203, 0xffff0000, v71
	v_fmac_f32_e32 v208, v200, v200
	v_fmac_f32_e32 v209, v201, v201
	v_fmac_f32_e32 v208, v202, v202
	v_fmac_f32_e32 v209, v203, v203
	v_lshlrev_b32_e32 v204, 16, v102
	v_and_b32_e32 v205, 0xffff0000, v102
	v_lshlrev_b32_e32 v206, 16, v103
	v_and_b32_e32 v207, 0xffff0000, v103
	v_fmac_f32_e32 v210, v204, v204
	v_fmac_f32_e32 v211, v205, v205
	v_fmac_f32_e32 v210, v206, v206
	v_fmac_f32_e32 v211, v207, v207
	v_lshlrev_b32_e32 v200, 16, v72
	v_and_b32_e32 v201, 0xffff0000, v72
	v_lshlrev_b32_e32 v202, 16, v73
	v_and_b32_e32 v203, 0xffff0000, v73
	v_fmac_f32_e32 v208, v200, v200
	v_fmac_f32_e32 v209, v201, v201
	v_fmac_f32_e32 v208, v202, v202
	v_fmac_f32_e32 v209, v203, v203
	v_lshlrev_b32_e32 v204, 16, v104
	v_and_b32_e32 v205, 0xffff0000, v104
	v_lshlrev_b32_e32 v206, 16, v105
	v_and_b32_e32 v207, 0xffff0000, v105
	v_fmac_f32_e32 v210, v204, v204
	v_fmac_f32_e32 v211, v205, v205
	v_fmac_f32_e32 v210, v206, v206
	v_fmac_f32_e32 v211, v207, v207
	v_lshlrev_b32_e32 v200, 16, v74
	v_and_b32_e32 v201, 0xffff0000, v74
	v_lshlrev_b32_e32 v202, 16, v75
	v_and_b32_e32 v203, 0xffff0000, v75
	v_fmac_f32_e32 v208, v200, v200
	v_fmac_f32_e32 v209, v201, v201
	v_fmac_f32_e32 v208, v202, v202
	v_fmac_f32_e32 v209, v203, v203
	v_lshlrev_b32_e32 v204, 16, v106
	v_and_b32_e32 v205, 0xffff0000, v106
	v_lshlrev_b32_e32 v206, 16, v107
	v_and_b32_e32 v207, 0xffff0000, v107
	v_fmac_f32_e32 v210, v204, v204
; __device__ __forceinline__ float bf_lo(unsigned w) { return __uint_as_float(w << 16); }
; __device__ __forceinline__ float bf_hi(unsigned w) { return __uint_as_float(w & 0xffff0000u); }
; __global__ void __launch_bounds__(NWAVES * 64, 2) mk_fwd(Args args) {
;     ...
;                 float sy = 0.f;
; #pragma unroll
;                 for (int j = 0; j < 8; ++j) { const float a = bf_lo(yw[q][j].x), b = bf_hi(yw[q][j].x), c2 = bf_lo(yw[q][j].y), d = bf_hi(yw[q][j].y); sy += (a * a + b * b) + (c2 * c2 + d * d); }
;                 const float rsy = __builtin_amdgcn_rsqf(wave_sum(sy) * (1.f / DM) + EPS);
; #pragma unroll
;                 for (int j = 0; j < 8; ++j) { const int col = 4 * F.lane + 256 * j;
;                     const f32x4 y4 = (f32x4){bf_lo(yw[q][j].x), bf_hi(yw[q][j].x), bf_lo(yw[q][j].y), bf_hi(yw[q][j].y)};
;                     *(f32x4*)(args.out + (size_t)row * DM + col) = v[q][j] + PA[j] * (y4 * rsy); }
	v_fmac_f32_e32 v211, v205, v205
	v_fmac_f32_e32 v210, v206, v206
	v_fmac_f32_e32 v211, v207, v207
	v_lshlrev_b32_e32 v200, 16, v76
	v_and_b32_e32 v201, 0xffff0000, v76
	v_lshlrev_b32_e32 v202, 16, v77
	v_and_b32_e32 v203, 0xffff0000, v77
	v_fmac_f32_e32 v208, v200, v200
	v_fmac_f32_e32 v209, v201, v201
	v_fmac_f32_e32 v208, v202, v202
	v_fmac_f32_e32 v209, v203, v203
	v_lshlrev_b32_e32 v204, 16, v108
	v_and_b32_e32 v205, 0xffff0000, v108
	v_lshlrev_b32_e32 v206, 16, v109
	v_and_b32_e32 v207, 0xffff0000, v109
	v_fmac_f32_e32 v210, v204, v204
	v_fmac_f32_e32 v211, v205, v205
	v_fmac_f32_e32 v210, v206, v206
	v_fmac_f32_e32 v211, v207, v207
	v_lshlrev_b32_e32 v200, 16, v78
	v_and_b32_e32 v201, 0xffff0000, v78
	v_lshlrev_b32_e32 v202, 16, v79
	v_and_b32_e32 v203, 0xffff0000, v79
	v_fmac_f32_e32 v208, v200, v200
	v_fmac_f32_e32 v209, v201, v201
	v_fmac_f32_e32 v208, v202, v202
	v_fmac_f32_e32 v209, v203, v203
	v_lshlrev_b32_e32 v204, 16, v110
	v_and_b32_e32 v205, 0xffff0000, v110
	v_lshlrev_b32_e32 v206, 16, v111
	v_and_b32_e32 v207, 0xffff0000, v111
	v_fmac_f32_e32 v210, v204, v204
	v_fmac_f32_e32 v211, v205, v205
	v_fmac_f32_e32 v210, v206, v206
	v_fmac_f32_e32 v211, v207, v207
	v_add_f32_e32 v208, v208, v209
	v_add_f32_e32 v210, v210, v211
	s_nop 0
	v_add_f32_dpp v212, v208, v208 quad_perm:[1,0,3,2] row_mask:0xf bank_mask:0xf
	v_add_f32_dpp v213, v210, v210 quad_perm:[1,0,3,2] row_mask:0xf bank_mask:0xf
	s_nop 0
	v_add_f32_dpp v212, v212, v212 quad_perm:[2,3,0,1] row_mask:0xf bank_mask:0xf
	v_add_f32_dpp v213, v213, v213 quad_perm:[2,3,0,1] row_mask:0xf bank_mask:0xf
	s_nop 0
	v_add_f32_dpp v212, v212, v212 row_half_mirror row_mask:0xf bank_mask:0xf
	v_add_f32_dpp v213, v213, v213 row_half_mirror row_mask:0xf bank_mask:0xf
	s_nop 0
	v_add_f32_dpp v212, v212, v212 row_mirror row_mask:0xf bank_mask:0xf
	v_add_f32_dpp v213, v213, v213 row_mirror row_mask:0xf bank_mask:0xf
	s_nop 0
	v_readlane_b32 s4, v212, 0
	v_readlane_b32 s5, v212, 16
	v_readlane_b32 s6, v212, 32
	v_readlane_b32 s7, v212, 48
	v_readlane_b32 s24, v213, 0
	v_readlane_b32 s25, v213, 16
	v_readlane_b32 s26, v213, 32
	v_readlane_b32 s27, v213, 48
	s_nop 1
	v_mov_b32_e32 v214, s4
	v_mov_b32_e32 v215, s24
	v_add_f32_e32 v214, s5, v214
	v_add_f32_e32 v215, s25, v215
	v_add_f32_e32 v214, s6, v214
	v_add_f32_e32 v215, s26, v215
	v_add_f32_e32 v214, s7, v214
	v_add_f32_e32 v215, s27, v215
	v_fmamk_f32 v214, v214, 0x3a000000, v195
	v_fmamk_f32 v215, v215, 0x3a000000, v195
	v_rsq_f32_e32 v214, v214
	v_rsq_f32_e32 v215, v215
	s_nop 0
	v_lshlrev_b32_e32 v200, 16, v64
	v_and_b32_e32 v201, 0xffff0000, v64
	v_lshlrev_b32_e32 v202, 16, v65
	v_and_b32_e32 v203, 0xffff0000, v65
	v_lshlrev_b32_e32 v204, 16, v96
	v_and_b32_e32 v205, 0xffff0000, v96
	v_lshlrev_b32_e32 v206, 16, v97
	v_and_b32_e32 v207, 0xffff0000, v97
	v_mul_f32_e32 v200, v214, v200
	v_mul_f32_e32 v201, v214, v201
	v_mul_f32_e32 v202, v214, v202
	v_mul_f32_e32 v203, v214, v203
	v_mul_f32_e32 v204, v215, v204
	v_mul_f32_e32 v205, v215, v205
	v_mul_f32_e32 v206, v215, v206
	v_mul_f32_e32 v207, v215, v207
	v_fmac_f32_e32 v0, v128, v200
	v_fmac_f32_e32 v1, v129, v201
	v_fmac_f32_e32 v2, v130, v202
	v_fmac_f32_e32 v3, v131, v203
	v_fmac_f32_e32 v0, v160, v204
	v_fmac_f32_e32 v1, v161, v205
	v_fmac_f32_e32 v2, v162, v206
	v_fmac_f32_e32 v3, v163, v207
	global_store_dwordx4 v192, v[0:3], s[18:19] offset:0 nt
	v_lshlrev_b32_e32 v200, 16, v66
	v_and_b32_e32 v201, 0xffff0000, v66
	v_lshlrev_b32_e32 v202, 16, v67
	v_and_b32_e32 v203, 0xffff0000, v67
	v_lshlrev_b32_e32 v204, 16, v98
	v_and_b32_e32 v205, 0xffff0000, v98
	v_lshlrev_b32_e32 v206, 16, v99
	v_and_b32_e32 v207, 0xffff0000, v99
	v_mul_f32_e32 v200, v214, v200
	v_mul_f32_e32 v201, v214, v201
	v_mul_f32_e32 v202, v214, v202
	v_mul_f32_e32 v203, v214, v203
	v_mul_f32_e32 v204, v215, v204
	v_mul_f32_e32 v205, v215, v205
	v_mul_f32_e32 v206, v215, v206
	v_mul_f32_e32 v207, v215, v207
	v_fmac_f32_e32 v4, v132, v200
	v_fmac_f32_e32 v5, v133, v201
	v_fmac_f32_e32 v6, v134, v202
	v_fmac_f32_e32 v7, v135, v203
	v_fmac_f32_e32 v4, v164, v204
	v_fmac_f32_e32 v5, v165, v205
	v_fmac_f32_e32 v6, v166, v206
	v_fmac_f32_e32 v7, v167, v207
	global_store_dwordx4 v192, v[4:7], s[18:19] offset:1024 nt
	v_lshlrev_b32_e32 v200, 16, v68
	v_and_b32_e32 v201, 0xffff0000, v68
	v_lshlrev_b32_e32 v202, 16, v69
	v_and_b32_e32 v203, 0xffff0000, v69
	v_lshlrev_b32_e32 v204, 16, v100
	v_and_b32_e32 v205, 0xffff0000, v100
	v_lshlrev_b32_e32 v206, 16, v101
	v_and_b32_e32 v207, 0xffff0000, v101
	v_mul_f32_e32 v200, v214, v200
	v_mul_f32_e32 v201, v214, v201
	v_mul_f32_e32 v202, v214, v202
	v_mul_f32_e32 v203, v214, v203
	v_mul_f32_e32 v204, v215, v204
	v_mul_f32_e32 v205, v215, v205
	v_mul_f32_e32 v206, v215, v206
	v_mul_f32_e32 v207, v215, v207
	v_fmac_f32_e32 v8, v136, v200
	v_fmac_f32_e32 v9, v137, v201
	v_fmac_f32_e32 v10, v138, v202
	v_fmac_f32_e32 v11, v139, v203
	v_fmac_f32_e32 v8, v168, v204
	v_fmac_f32_e32 v9, v169, v205
	v_fmac_f32_e32 v10, v170, v206
	v_fmac_f32_e32 v11, v171, v207
	global_store_dwordx4 v192, v[8:11], s[18:19] offset:2048 nt
	v_lshlrev_b32_e32 v200, 16, v70
	v_and_b32_e32 v201, 0xffff0000, v70
	v_lshlrev_b32_e32 v202, 16, v71
	v_and_b32_e32 v203, 0xffff0000, v71
	v_lshlrev_b32_e32 v204, 16, v102
	v_and_b32_e32 v205, 0xffff0000, v102
	v_lshlrev_b32_e32 v206, 16, v103
	v_and_b32_e32 v207, 0xffff0000, v103
	v_mul_f32_e32 v200, v214, v200
	v_mul_f32_e32 v201, v214, v201
	v_mul_f32_e32 v202, v214, v202
	v_mul_f32_e32 v203, v214, v203
	v_mul_f32_e32 v204, v215, v204
	v_mul_f32_e32 v205, v215, v205
	v_mul_f32_e32 v206, v215, v206
	v_mul_f32_e32 v207, v215, v207
	v_fmac_f32_e32 v12, v140, v200
; __device__ __forceinline__ float bf_lo(unsigned w) { return __uint_as_float(w << 16); }
; __device__ __forceinline__ float bf_hi(unsigned w) { return __uint_as_float(w & 0xffff0000u); }
; __global__ void __launch_bounds__(NWAVES * 64, 2) mk_fwd(Args args) {
;     ...
;         for (int row0 = rbeg; row0 < rbeg + per2 && row0 < ML; row0 += 2) {
;             f32x4 v[2][8]; u32x2 yw[2][8];
; #pragma unroll
;             for (int q = 0; q < 2; ++q) { const int row = row0 + q; load_row_f32(args.out + (size_t)row * DM, F.lane, v[q]);
;                 const bf16_t* yr = Y + (size_t)row * DM;
; #pragma unroll
;                 for (int j = 0; j < 8; ++j) yw[q][j] = *(const u32x2*)(yr + 4 * F.lane + 256 * j); }
;     ...
;                 const float rsy = __builtin_amdgcn_rsqf(wave_sum(sy) * (1.f / DM) + EPS);
; #pragma unroll
;                 for (int j = 0; j < 8; ++j) { const int col = 4 * F.lane + 256 * j;
;                     const f32x4 y4 = (f32x4){bf_lo(yw[q][j].x), bf_hi(yw[q][j].x), bf_lo(yw[q][j].y), bf_hi(yw[q][j].y)};
;                     *(f32x4*)(args.out + (size_t)row * DM + col) = v[q][j] + PA[j] * (y4 * rsy); }
	v_fmac_f32_e32 v13, v141, v201
	v_fmac_f32_e32 v14, v142, v202
	v_fmac_f32_e32 v15, v143, v203
	v_fmac_f32_e32 v12, v172, v204
	v_fmac_f32_e32 v13, v173, v205
	v_fmac_f32_e32 v14, v174, v206
	v_fmac_f32_e32 v15, v175, v207
	global_store_dwordx4 v192, v[12:15], s[18:19] offset:3072 nt
	v_lshlrev_b32_e32 v200, 16, v72
	v_and_b32_e32 v201, 0xffff0000, v72
	v_lshlrev_b32_e32 v202, 16, v73
	v_and_b32_e32 v203, 0xffff0000, v73
	v_lshlrev_b32_e32 v204, 16, v104
	v_and_b32_e32 v205, 0xffff0000, v104
	v_lshlrev_b32_e32 v206, 16, v105
	v_and_b32_e32 v207, 0xffff0000, v105
	v_mul_f32_e32 v200, v214, v200
	v_mul_f32_e32 v201, v214, v201
	v_mul_f32_e32 v202, v214, v202
	v_mul_f32_e32 v203, v214, v203
	v_mul_f32_e32 v204, v215, v204
	v_mul_f32_e32 v205, v215, v205
	v_mul_f32_e32 v206, v215, v206
	v_mul_f32_e32 v207, v215, v207
	v_fmac_f32_e32 v16, v144, v200
	v_fmac_f32_e32 v17, v145, v201
	v_fmac_f32_e32 v18, v146, v202
	v_fmac_f32_e32 v19, v147, v203
	v_fmac_f32_e32 v16, v176, v204
	v_fmac_f32_e32 v17, v177, v205
	v_fmac_f32_e32 v18, v178, v206
	v_fmac_f32_e32 v19, v179, v207
	global_store_dwordx4 v193, v[16:19], s[18:19] offset:0 nt
	v_lshlrev_b32_e32 v200, 16, v74
	v_and_b32_e32 v201, 0xffff0000, v74
	v_lshlrev_b32_e32 v202, 16, v75
	v_and_b32_e32 v203, 0xffff0000, v75
	v_lshlrev_b32_e32 v204, 16, v106
	v_and_b32_e32 v205, 0xffff0000, v106
	v_lshlrev_b32_e32 v206, 16, v107
	v_and_b32_e32 v207, 0xffff0000, v107
	v_mul_f32_e32 v200, v214, v200
	v_mul_f32_e32 v201, v214, v201
	v_mul_f32_e32 v202, v214, v202
	v_mul_f32_e32 v203, v214, v203
	v_mul_f32_e32 v204, v215, v204
	v_mul_f32_e32 v205, v215, v205
	v_mul_f32_e32 v206, v215, v206
	v_mul_f32_e32 v207, v215, v207
	v_fmac_f32_e32 v20, v148, v200
	v_fmac_f32_e32 v21, v149, v201
	v_fmac_f32_e32 v22, v150, v202
	v_fmac_f32_e32 v23, v151, v203
	v_fmac_f32_e32 v20, v180, v204
	v_fmac_f32_e32 v21, v181, v205
	v_fmac_f32_e32 v22, v182, v206
	v_fmac_f32_e32 v23, v183, v207
	global_store_dwordx4 v193, v[20:23], s[18:19] offset:1024 nt
	v_lshlrev_b32_e32 v200, 16, v76
	v_and_b32_e32 v201, 0xffff0000, v76
	v_lshlrev_b32_e32 v202, 16, v77
	v_and_b32_e32 v203, 0xffff0000, v77
	v_lshlrev_b32_e32 v204, 16, v108
	v_and_b32_e32 v205, 0xffff0000, v108
	v_lshlrev_b32_e32 v206, 16, v109
	v_and_b32_e32 v207, 0xffff0000, v109
	v_mul_f32_e32 v200, v214, v200
	v_mul_f32_e32 v201, v214, v201
	v_mul_f32_e32 v202, v214, v202
	v_mul_f32_e32 v203, v214, v203
	v_mul_f32_e32 v204, v215, v204
	v_mul_f32_e32 v205, v215, v205
	v_mul_f32_e32 v206, v215, v206
	v_mul_f32_e32 v207, v215, v207
	v_fmac_f32_e32 v24, v152, v200
	v_fmac_f32_e32 v25, v153, v201
	v_fmac_f32_e32 v26, v154, v202
	v_fmac_f32_e32 v27, v155, v203
	v_fmac_f32_e32 v24, v184, v204
	v_fmac_f32_e32 v25, v185, v205
	v_fmac_f32_e32 v26, v186, v206
	v_fmac_f32_e32 v27, v187, v207
	global_store_dwordx4 v193, v[24:27], s[18:19] offset:2048 nt
	v_lshlrev_b32_e32 v200, 16, v78
	v_and_b32_e32 v201, 0xffff0000, v78
	v_lshlrev_b32_e32 v202, 16, v79
	v_and_b32_e32 v203, 0xffff0000, v79
	v_lshlrev_b32_e32 v204, 16, v110
	v_and_b32_e32 v205, 0xffff0000, v110
	v_lshlrev_b32_e32 v206, 16, v111
	v_and_b32_e32 v207, 0xffff0000, v111
	v_mul_f32_e32 v200, v214, v200
	v_mul_f32_e32 v201, v214, v201
	v_mul_f32_e32 v202, v214, v202
	v_mul_f32_e32 v203, v214, v203
	v_mul_f32_e32 v204, v215, v204
	v_mul_f32_e32 v205, v215, v205
	v_mul_f32_e32 v206, v215, v206
	v_mul_f32_e32 v207, v215, v207
	v_fmac_f32_e32 v28, v156, v200
	v_fmac_f32_e32 v29, v157, v201
	v_fmac_f32_e32 v30, v158, v202
	v_fmac_f32_e32 v31, v159, v203
	v_fmac_f32_e32 v28, v188, v204
	v_fmac_f32_e32 v29, v189, v205
	v_fmac_f32_e32 v30, v190, v206
	v_fmac_f32_e32 v31, v191, v207
	global_store_dwordx4 v193, v[28:31], s[18:19] offset:3072 nt
	s_add_u32 s18, s18, 0x2000
	s_addc_u32 s19, s19, 0
	global_load_dwordx4 v[0:3], v192, s[14:15] offset:0 nt
	global_load_dwordx4 v[4:7], v192, s[14:15] offset:1024 nt
	global_load_dwordx4 v[8:11], v192, s[14:15] offset:2048 nt
	global_load_dwordx4 v[12:15], v192, s[14:15] offset:3072 nt
	global_load_dwordx4 v[16:19], v193, s[14:15] offset:0 nt
	global_load_dwordx4 v[20:23], v193, s[14:15] offset:1024 nt
	global_load_dwordx4 v[24:27], v193, s[14:15] offset:2048 nt
	global_load_dwordx4 v[28:31], v193, s[14:15] offset:3072 nt
	global_load_dwordx2 v[64:65], v194, s[16:17] offset:0 nt
	global_load_dwordx2 v[66:67], v194, s[16:17] offset:512 nt
	global_load_dwordx2 v[68:69], v194, s[16:17] offset:1024 nt
	global_load_dwordx2 v[70:71], v194, s[16:17] offset:1536 nt
	global_load_dwordx2 v[72:73], v194, s[16:17] offset:2048 nt
	global_load_dwordx2 v[74:75], v194, s[16:17] offset:2560 nt
	global_load_dwordx2 v[76:77], v194, s[16:17] offset:3072 nt
	global_load_dwordx2 v[78:79], v194, s[16:17] offset:3584 nt
	global_load_dwordx2 v[96:97], v194, s[22:23] offset:0 nt
	global_load_dwordx2 v[98:99], v194, s[22:23] offset:512 nt
	global_load_dwordx2 v[100:101], v194, s[22:23] offset:1024 nt
	global_load_dwordx2 v[102:103], v194, s[22:23] offset:1536 nt
	global_load_dwordx2 v[104:105], v194, s[22:23] offset:2048 nt
	global_load_dwordx2 v[106:107], v194, s[22:23] offset:2560 nt
	global_load_dwordx2 v[108:109], v194, s[22:23] offset:3072 nt
	global_load_dwordx2 v[110:111], v194, s[22:23] offset:3584 nt
	s_add_u32 s14, s14, 0x2000
	s_addc_u32 s15, s15, 0
	s_add_u32 s16, s16, 0x1000
	s_addc_u32 s17, s17, 0
	s_add_u32 s22, s22, 0x1000
	s_addc_u32 s23, s23, 0
	s_waitcnt vmcnt(32)
; __device__ __forceinline__ float bf_lo(unsigned w) { return __uint_as_float(w << 16); }
; __device__ __forceinline__ float bf_hi(unsigned w) { return __uint_as_float(w & 0xffff0000u); }
; __global__ void __launch_bounds__(NWAVES * 64, 2) mk_fwd(Args args) {
;     ...
;                 float sy = 0.f;
; #pragma unroll
;                 for (int j = 0; j < 8; ++j) { const float a = bf_lo(yw[q][j].x), b = bf_hi(yw[q][j].x), c2 = bf_lo(yw[q][j].y), d = bf_hi(yw[q][j].y); sy += (a * a + b * b) + (c2 * c2 + d * d); }
;                 const float rsy = __builtin_amdgcn_rsqf(wave_sum(sy) * (1.f / DM) + EPS);
	v_lshlrev_b32_e32 v200, 16, v80
	v_and_b32_e32 v201, 0xffff0000, v80
	v_lshlrev_b32_e32 v202, 16, v81
	v_and_b32_e32 v203, 0xffff0000, v81
	v_mul_f32_e32 v208, v200, v200
	v_mul_f32_e32 v209, v201, v201
	v_fmac_f32_e32 v208, v202, v202
	v_fmac_f32_e32 v209, v203, v203
	v_lshlrev_b32_e32 v204, 16, v112
	v_and_b32_e32 v205, 0xffff0000, v112
	v_lshlrev_b32_e32 v206, 16, v113
	v_and_b32_e32 v207, 0xffff0000, v113
	v_mul_f32_e32 v210, v204, v204
	v_mul_f32_e32 v211, v205, v205
	v_fmac_f32_e32 v210, v206, v206
	v_fmac_f32_e32 v211, v207, v207
	v_lshlrev_b32_e32 v200, 16, v82
	v_and_b32_e32 v201, 0xffff0000, v82
	v_lshlrev_b32_e32 v202, 16, v83
	v_and_b32_e32 v203, 0xffff0000, v83
	v_fmac_f32_e32 v208, v200, v200
	v_fmac_f32_e32 v209, v201, v201
	v_fmac_f32_e32 v208, v202, v202
	v_fmac_f32_e32 v209, v203, v203
	v_lshlrev_b32_e32 v204, 16, v114
	v_and_b32_e32 v205, 0xffff0000, v114
	v_lshlrev_b32_e32 v206, 16, v115
	v_and_b32_e32 v207, 0xffff0000, v115
	v_fmac_f32_e32 v210, v204, v204
	v_fmac_f32_e32 v211, v205, v205
	v_fmac_f32_e32 v210, v206, v206
	v_fmac_f32_e32 v211, v207, v207
	v_lshlrev_b32_e32 v200, 16, v84
	v_and_b32_e32 v201, 0xffff0000, v84
	v_lshlrev_b32_e32 v202, 16, v85
	v_and_b32_e32 v203, 0xffff0000, v85
	v_fmac_f32_e32 v208, v200, v200
	v_fmac_f32_e32 v209, v201, v201
	v_fmac_f32_e32 v208, v202, v202
	v_fmac_f32_e32 v209, v203, v203
	v_lshlrev_b32_e32 v204, 16, v116
	v_and_b32_e32 v205, 0xffff0000, v116
	v_lshlrev_b32_e32 v206, 16, v117
	v_and_b32_e32 v207, 0xffff0000, v117
	v_fmac_f32_e32 v210, v204, v204
	v_fmac_f32_e32 v211, v205, v205
	v_fmac_f32_e32 v210, v206, v206
	v_fmac_f32_e32 v211, v207, v207
	v_lshlrev_b32_e32 v200, 16, v86
	v_and_b32_e32 v201, 0xffff0000, v86
	v_lshlrev_b32_e32 v202, 16, v87
	v_and_b32_e32 v203, 0xffff0000, v87
	v_fmac_f32_e32 v208, v200, v200
	v_fmac_f32_e32 v209, v201, v201
	v_fmac_f32_e32 v208, v202, v202
	v_fmac_f32_e32 v209, v203, v203
	v_lshlrev_b32_e32 v204, 16, v118
	v_and_b32_e32 v205, 0xffff0000, v118
	v_lshlrev_b32_e32 v206, 16, v119
	v_and_b32_e32 v207, 0xffff0000, v119
	v_fmac_f32_e32 v210, v204, v204
	v_fmac_f32_e32 v211, v205, v205
	v_fmac_f32_e32 v210, v206, v206
	v_fmac_f32_e32 v211, v207, v207
	v_lshlrev_b32_e32 v200, 16, v88
	v_and_b32_e32 v201, 0xffff0000, v88
	v_lshlrev_b32_e32 v202, 16, v89
	v_and_b32_e32 v203, 0xffff0000, v89
	v_fmac_f32_e32 v208, v200, v200
	v_fmac_f32_e32 v209, v201, v201
	v_fmac_f32_e32 v208, v202, v202
	v_fmac_f32_e32 v209, v203, v203
	v_lshlrev_b32_e32 v204, 16, v120
	v_and_b32_e32 v205, 0xffff0000, v120
	v_lshlrev_b32_e32 v206, 16, v121
	v_and_b32_e32 v207, 0xffff0000, v121
	v_fmac_f32_e32 v210, v204, v204
	v_fmac_f32_e32 v211, v205, v205
	v_fmac_f32_e32 v210, v206, v206
	v_fmac_f32_e32 v211, v207, v207
	v_lshlrev_b32_e32 v200, 16, v90
	v_and_b32_e32 v201, 0xffff0000, v90
	v_lshlrev_b32_e32 v202, 16, v91
	v_and_b32_e32 v203, 0xffff0000, v91
	v_fmac_f32_e32 v208, v200, v200
	v_fmac_f32_e32 v209, v201, v201
	v_fmac_f32_e32 v208, v202, v202
	v_fmac_f32_e32 v209, v203, v203
	v_lshlrev_b32_e32 v204, 16, v122
	v_and_b32_e32 v205, 0xffff0000, v122
	v_lshlrev_b32_e32 v206, 16, v123
	v_and_b32_e32 v207, 0xffff0000, v123
	v_fmac_f32_e32 v210, v204, v204
	v_fmac_f32_e32 v211, v205, v205
	v_fmac_f32_e32 v210, v206, v206
	v_fmac_f32_e32 v211, v207, v207
	v_lshlrev_b32_e32 v200, 16, v92
	v_and_b32_e32 v201, 0xffff0000, v92
	v_lshlrev_b32_e32 v202, 16, v93
	v_and_b32_e32 v203, 0xffff0000, v93
	v_fmac_f32_e32 v208, v200, v200
	v_fmac_f32_e32 v209, v201, v201
	v_fmac_f32_e32 v208, v202, v202
	v_fmac_f32_e32 v209, v203, v203
	v_lshlrev_b32_e32 v204, 16, v124
	v_and_b32_e32 v205, 0xffff0000, v124
	v_lshlrev_b32_e32 v206, 16, v125
	v_and_b32_e32 v207, 0xffff0000, v125
	v_fmac_f32_e32 v210, v204, v204
	v_fmac_f32_e32 v211, v205, v205
	v_fmac_f32_e32 v210, v206, v206
	v_fmac_f32_e32 v211, v207, v207
	v_lshlrev_b32_e32 v200, 16, v94
	v_and_b32_e32 v201, 0xffff0000, v94
	v_lshlrev_b32_e32 v202, 16, v95
	v_and_b32_e32 v203, 0xffff0000, v95
	v_fmac_f32_e32 v208, v200, v200
	v_fmac_f32_e32 v209, v201, v201
	v_fmac_f32_e32 v208, v202, v202
	v_fmac_f32_e32 v209, v203, v203
	v_lshlrev_b32_e32 v204, 16, v126
	v_and_b32_e32 v205, 0xffff0000, v126
	v_lshlrev_b32_e32 v206, 16, v127
	v_and_b32_e32 v207, 0xffff0000, v127
	v_fmac_f32_e32 v210, v204, v204
	v_fmac_f32_e32 v211, v205, v205
	v_fmac_f32_e32 v210, v206, v206
	v_fmac_f32_e32 v211, v207, v207
	v_add_f32_e32 v208, v208, v209
	v_add_f32_e32 v210, v210, v211
	s_nop 0
	v_add_f32_dpp v212, v208, v208 quad_perm:[1,0,3,2] row_mask:0xf bank_mask:0xf
	v_add_f32_dpp v213, v210, v210 quad_perm:[1,0,3,2] row_mask:0xf bank_mask:0xf
	s_nop 0
	v_add_f32_dpp v212, v212, v212 quad_perm:[2,3,0,1] row_mask:0xf bank_mask:0xf
	v_add_f32_dpp v213, v213, v213 quad_perm:[2,3,0,1] row_mask:0xf bank_mask:0xf
	s_nop 0
	v_add_f32_dpp v212, v212, v212 row_half_mirror row_mask:0xf bank_mask:0xf
	v_add_f32_dpp v213, v213, v213 row_half_mirror row_mask:0xf bank_mask:0xf
	s_nop 0
	v_add_f32_dpp v212, v212, v212 row_mirror row_mask:0xf bank_mask:0xf
	v_add_f32_dpp v213, v213, v213 row_mirror row_mask:0xf bank_mask:0xf
	s_nop 0
	v_readlane_b32 s4, v212, 0
	v_readlane_b32 s5, v212, 16
	v_readlane_b32 s6, v212, 32
	v_readlane_b32 s7, v212, 48
	v_readlane_b32 s24, v213, 0
	v_readlane_b32 s25, v213, 16
	v_readlane_b32 s26, v213, 32
	v_readlane_b32 s27, v213, 48
	s_nop 1
	v_mov_b32_e32 v214, s4
	v_mov_b32_e32 v215, s24
	v_add_f32_e32 v214, s5, v214
	v_add_f32_e32 v215, s25, v215
	v_add_f32_e32 v214, s6, v214
	v_add_f32_e32 v215, s26, v215
	v_add_f32_e32 v214, s7, v214
	v_add_f32_e32 v215, s27, v215
	v_fmamk_f32 v214, v214, 0x3a000000, v195
	v_fmamk_f32 v215, v215, 0x3a000000, v195
; __device__ __forceinline__ float bf_lo(unsigned w) { return __uint_as_float(w << 16); }
; __device__ __forceinline__ float bf_hi(unsigned w) { return __uint_as_float(w & 0xffff0000u); }
; __global__ void __launch_bounds__(NWAVES * 64, 2) mk_fwd(Args args) {
;     ...
;                 const float rsy = __builtin_amdgcn_rsqf(wave_sum(sy) * (1.f / DM) + EPS);
; #pragma unroll
;                 for (int j = 0; j < 8; ++j) { const int col = 4 * F.lane + 256 * j;
;                     const f32x4 y4 = (f32x4){bf_lo(yw[q][j].x), bf_hi(yw[q][j].x), bf_lo(yw[q][j].y), bf_hi(yw[q][j].y)};
;                     *(f32x4*)(args.out + (size_t)row * DM + col) = v[q][j] + PA[j] * (y4 * rsy); }
	v_rsq_f32_e32 v214, v214
	v_rsq_f32_e32 v215, v215
	s_nop 0
	v_lshlrev_b32_e32 v200, 16, v80
	v_and_b32_e32 v201, 0xffff0000, v80
	v_lshlrev_b32_e32 v202, 16, v81
	v_and_b32_e32 v203, 0xffff0000, v81
	v_lshlrev_b32_e32 v204, 16, v112
	v_and_b32_e32 v205, 0xffff0000, v112
	v_lshlrev_b32_e32 v206, 16, v113
	v_and_b32_e32 v207, 0xffff0000, v113
	v_mul_f32_e32 v200, v214, v200
	v_mul_f32_e32 v201, v214, v201
	v_mul_f32_e32 v202, v214, v202
	v_mul_f32_e32 v203, v214, v203
	v_mul_f32_e32 v204, v215, v204
	v_mul_f32_e32 v205, v215, v205
	v_mul_f32_e32 v206, v215, v206
	v_mul_f32_e32 v207, v215, v207
	v_fmac_f32_e32 v32, v128, v200
	v_fmac_f32_e32 v33, v129, v201
	v_fmac_f32_e32 v34, v130, v202
	v_fmac_f32_e32 v35, v131, v203
	v_fmac_f32_e32 v32, v160, v204
	v_fmac_f32_e32 v33, v161, v205
	v_fmac_f32_e32 v34, v162, v206
	v_fmac_f32_e32 v35, v163, v207
	global_store_dwordx4 v192, v[32:35], s[18:19] offset:0 nt
	v_lshlrev_b32_e32 v200, 16, v82
	v_and_b32_e32 v201, 0xffff0000, v82
	v_lshlrev_b32_e32 v202, 16, v83
	v_and_b32_e32 v203, 0xffff0000, v83
	v_lshlrev_b32_e32 v204, 16, v114
	v_and_b32_e32 v205, 0xffff0000, v114
	v_lshlrev_b32_e32 v206, 16, v115
	v_and_b32_e32 v207, 0xffff0000, v115
	v_mul_f32_e32 v200, v214, v200
	v_mul_f32_e32 v201, v214, v201
	v_mul_f32_e32 v202, v214, v202
	v_mul_f32_e32 v203, v214, v203
	v_mul_f32_e32 v204, v215, v204
	v_mul_f32_e32 v205, v215, v205
	v_mul_f32_e32 v206, v215, v206
	v_mul_f32_e32 v207, v215, v207
	v_fmac_f32_e32 v36, v132, v200
	v_fmac_f32_e32 v37, v133, v201
	v_fmac_f32_e32 v38, v134, v202
	v_fmac_f32_e32 v39, v135, v203
	v_fmac_f32_e32 v36, v164, v204
	v_fmac_f32_e32 v37, v165, v205
	v_fmac_f32_e32 v38, v166, v206
	v_fmac_f32_e32 v39, v167, v207
	global_store_dwordx4 v192, v[36:39], s[18:19] offset:1024 nt
	v_lshlrev_b32_e32 v200, 16, v84
	v_and_b32_e32 v201, 0xffff0000, v84
	v_lshlrev_b32_e32 v202, 16, v85
	v_and_b32_e32 v203, 0xffff0000, v85
	v_lshlrev_b32_e32 v204, 16, v116
	v_and_b32_e32 v205, 0xffff0000, v116
	v_lshlrev_b32_e32 v206, 16, v117
	v_and_b32_e32 v207, 0xffff0000, v117
	v_mul_f32_e32 v200, v214, v200
	v_mul_f32_e32 v201, v214, v201
	v_mul_f32_e32 v202, v214, v202
	v_mul_f32_e32 v203, v214, v203
	v_mul_f32_e32 v204, v215, v204
	v_mul_f32_e32 v205, v215, v205
	v_mul_f32_e32 v206, v215, v206
	v_mul_f32_e32 v207, v215, v207
	v_fmac_f32_e32 v40, v136, v200
	v_fmac_f32_e32 v41, v137, v201
	v_fmac_f32_e32 v42, v138, v202
	v_fmac_f32_e32 v43, v139, v203
	v_fmac_f32_e32 v40, v168, v204
	v_fmac_f32_e32 v41, v169, v205
	v_fmac_f32_e32 v42, v170, v206
	v_fmac_f32_e32 v43, v171, v207
	global_store_dwordx4 v192, v[40:43], s[18:19] offset:2048 nt
	v_lshlrev_b32_e32 v200, 16, v86
	v_and_b32_e32 v201, 0xffff0000, v86
	v_lshlrev_b32_e32 v202, 16, v87
	v_and_b32_e32 v203, 0xffff0000, v87
	v_lshlrev_b32_e32 v204, 16, v118
	v_and_b32_e32 v205, 0xffff0000, v118
	v_lshlrev_b32_e32 v206, 16, v119
	v_and_b32_e32 v207, 0xffff0000, v119
	v_mul_f32_e32 v200, v214, v200
	v_mul_f32_e32 v201, v214, v201
	v_mul_f32_e32 v202, v214, v202
	v_mul_f32_e32 v203, v214, v203
	v_mul_f32_e32 v204, v215, v204
	v_mul_f32_e32 v205, v215, v205
	v_mul_f32_e32 v206, v215, v206
	v_mul_f32_e32 v207, v215, v207
	v_fmac_f32_e32 v44, v140, v200
	v_fmac_f32_e32 v45, v141, v201
	v_fmac_f32_e32 v46, v142, v202
	v_fmac_f32_e32 v47, v143, v203
	v_fmac_f32_e32 v44, v172, v204
	v_fmac_f32_e32 v45, v173, v205
	v_fmac_f32_e32 v46, v174, v206
	v_fmac_f32_e32 v47, v175, v207
	global_store_dwordx4 v192, v[44:47], s[18:19] offset:3072 nt
	v_lshlrev_b32_e32 v200, 16, v88
	v_and_b32_e32 v201, 0xffff0000, v88
	v_lshlrev_b32_e32 v202, 16, v89
	v_and_b32_e32 v203, 0xffff0000, v89
	v_lshlrev_b32_e32 v204, 16, v120
	v_and_b32_e32 v205, 0xffff0000, v120
	v_lshlrev_b32_e32 v206, 16, v121
	v_and_b32_e32 v207, 0xffff0000, v121
	v_mul_f32_e32 v200, v214, v200
	v_mul_f32_e32 v201, v214, v201
	v_mul_f32_e32 v202, v214, v202
	v_mul_f32_e32 v203, v214, v203
	v_mul_f32_e32 v204, v215, v204
	v_mul_f32_e32 v205, v215, v205
	v_mul_f32_e32 v206, v215, v206
	v_mul_f32_e32 v207, v215, v207
	v_fmac_f32_e32 v48, v144, v200
	v_fmac_f32_e32 v49, v145, v201
	v_fmac_f32_e32 v50, v146, v202
	v_fmac_f32_e32 v51, v147, v203
	v_fmac_f32_e32 v48, v176, v204
	v_fmac_f32_e32 v49, v177, v205
	v_fmac_f32_e32 v50, v178, v206
	v_fmac_f32_e32 v51, v179, v207
	global_store_dwordx4 v193, v[48:51], s[18:19] offset:0 nt
	v_lshlrev_b32_e32 v200, 16, v90
	v_and_b32_e32 v201, 0xffff0000, v90
	v_lshlrev_b32_e32 v202, 16, v91
	v_and_b32_e32 v203, 0xffff0000, v91
	v_lshlrev_b32_e32 v204, 16, v122
	v_and_b32_e32 v205, 0xffff0000, v122
	v_lshlrev_b32_e32 v206, 16, v123
	v_and_b32_e32 v207, 0xffff0000, v123
	v_mul_f32_e32 v200, v214, v200
	v_mul_f32_e32 v201, v214, v201
	v_mul_f32_e32 v202, v214, v202
	v_mul_f32_e32 v203, v214, v203
	v_mul_f32_e32 v204, v215, v204
	v_mul_f32_e32 v205, v215, v205
	v_mul_f32_e32 v206, v215, v206
	v_mul_f32_e32 v207, v215, v207
	v_fmac_f32_e32 v52, v148, v200
	v_fmac_f32_e32 v53, v149, v201
	v_fmac_f32_e32 v54, v150, v202
	v_fmac_f32_e32 v55, v151, v203
	v_fmac_f32_e32 v52, v180, v204
	v_fmac_f32_e32 v53, v181, v205
	v_fmac_f32_e32 v54, v182, v206
	v_fmac_f32_e32 v55, v183, v207
	global_store_dwordx4 v193, v[52:55], s[18:19] offset:1024 nt
	v_lshlrev_b32_e32 v200, 16, v92
	v_and_b32_e32 v201, 0xffff0000, v92
	v_lshlrev_b32_e32 v202, 16, v93
	v_and_b32_e32 v203, 0xffff0000, v93
	v_lshlrev_b32_e32 v204, 16, v124
	v_and_b32_e32 v205, 0xffff0000, v124
	v_lshlrev_b32_e32 v206, 16, v125
	v_and_b32_e32 v207, 0xffff0000, v125
	v_mul_f32_e32 v200, v214, v200
	v_mul_f32_e32 v201, v214, v201
	v_mul_f32_e32 v202, v214, v202
	v_mul_f32_e32 v203, v214, v203
	v_mul_f32_e32 v204, v215, v204
; __device__ __forceinline__ float bf_lo(unsigned w) { return __uint_as_float(w << 16); }
; __device__ __forceinline__ float bf_hi(unsigned w) { return __uint_as_float(w & 0xffff0000u); }
; __global__ void __launch_bounds__(NWAVES * 64, 2) mk_fwd(Args args) {
;     ...
;         for (int row0 = rbeg; row0 < rbeg + per2 && row0 < ML; row0 += 2) {
;             f32x4 v[2][8]; u32x2 yw[2][8];
; #pragma unroll
;             for (int q = 0; q < 2; ++q) { const int row = row0 + q; load_row_f32(args.out + (size_t)row * DM, F.lane, v[q]);
;                 const bf16_t* yr = Y + (size_t)row * DM;
; #pragma unroll
;                 for (int j = 0; j < 8; ++j) yw[q][j] = *(const u32x2*)(yr + 4 * F.lane + 256 * j); }
; #pragma unroll
;             for (int q = 0; q < 2; ++q) { const int row = row0 + q; const int r = row / SEQ;
;                 if (r != rcur) { const float* m1 = mod + (size_t)(9 + r) * 6144; rcur = r;
; #pragma unroll
;                     for (int j = 0; j < 8; ++j) { const int col = 4 * F.lane + 256 * j; PA[j] = *(const f32x4*)(m1 + 2 * DM + col) * *(const f32x4*)(post_norm + DM + col); } }
;                 float sy = 0.f;
; #pragma unroll
;                 for (int j = 0; j < 8; ++j) { const float a = bf_lo(yw[q][j].x), b = bf_hi(yw[q][j].x), c2 = bf_lo(yw[q][j].y), d = bf_hi(yw[q][j].y); sy += (a * a + b * b) + (c2 * c2 + d * d); }
;                 const float rsy = __builtin_amdgcn_rsqf(wave_sum(sy) * (1.f / DM) + EPS);
; #pragma unroll
;                 for (int j = 0; j < 8; ++j) { const int col = 4 * F.lane + 256 * j;
;                     const f32x4 y4 = (f32x4){bf_lo(yw[q][j].x), bf_hi(yw[q][j].x), bf_lo(yw[q][j].y), bf_hi(yw[q][j].y)};
;                     *(f32x4*)(args.out + (size_t)row * DM + col) = v[q][j] + PA[j] * (y4 * rsy); }
	v_mul_f32_e32 v205, v215, v205
	v_mul_f32_e32 v206, v215, v206
	v_mul_f32_e32 v207, v215, v207
	v_fmac_f32_e32 v56, v152, v200
	v_fmac_f32_e32 v57, v153, v201
	v_fmac_f32_e32 v58, v154, v202
	v_fmac_f32_e32 v59, v155, v203
	v_fmac_f32_e32 v56, v184, v204
	v_fmac_f32_e32 v57, v185, v205
	v_fmac_f32_e32 v58, v186, v206
	v_fmac_f32_e32 v59, v187, v207
	global_store_dwordx4 v193, v[56:59], s[18:19] offset:2048 nt
	v_lshlrev_b32_e32 v200, 16, v94
	v_and_b32_e32 v201, 0xffff0000, v94
	v_lshlrev_b32_e32 v202, 16, v95
	v_and_b32_e32 v203, 0xffff0000, v95
	v_lshlrev_b32_e32 v204, 16, v126
	v_and_b32_e32 v205, 0xffff0000, v126
	v_lshlrev_b32_e32 v206, 16, v127
	v_and_b32_e32 v207, 0xffff0000, v127
	v_mul_f32_e32 v200, v214, v200
	v_mul_f32_e32 v201, v214, v201
	v_mul_f32_e32 v202, v214, v202
	v_mul_f32_e32 v203, v214, v203
	v_mul_f32_e32 v204, v215, v204
	v_mul_f32_e32 v205, v215, v205
	v_mul_f32_e32 v206, v215, v206
	v_mul_f32_e32 v207, v215, v207
	v_fmac_f32_e32 v60, v156, v200
	v_fmac_f32_e32 v61, v157, v201
	v_fmac_f32_e32 v62, v158, v202
	v_fmac_f32_e32 v63, v159, v203
	v_fmac_f32_e32 v60, v188, v204
	v_fmac_f32_e32 v61, v189, v205
	v_fmac_f32_e32 v62, v190, v206
	v_fmac_f32_e32 v63, v191, v207
	global_store_dwordx4 v193, v[60:63], s[18:19] offset:3072 nt
	s_add_u32 s18, s18, 0x2000
	s_addc_u32 s19, s19, 0
	global_load_dwordx4 v[32:35], v192, s[14:15] offset:0 nt
	global_load_dwordx4 v[36:39], v192, s[14:15] offset:1024 nt
	global_load_dwordx4 v[40:43], v192, s[14:15] offset:2048 nt
	global_load_dwordx4 v[44:47], v192, s[14:15] offset:3072 nt
	global_load_dwordx4 v[48:51], v193, s[14:15] offset:0 nt
	global_load_dwordx4 v[52:55], v193, s[14:15] offset:1024 nt
	global_load_dwordx4 v[56:59], v193, s[14:15] offset:2048 nt
	global_load_dwordx4 v[60:63], v193, s[14:15] offset:3072 nt
	global_load_dwordx2 v[80:81], v194, s[16:17] offset:0 nt
	global_load_dwordx2 v[82:83], v194, s[16:17] offset:512 nt
	global_load_dwordx2 v[84:85], v194, s[16:17] offset:1024 nt
	global_load_dwordx2 v[86:87], v194, s[16:17] offset:1536 nt
	global_load_dwordx2 v[88:89], v194, s[16:17] offset:2048 nt
	global_load_dwordx2 v[90:91], v194, s[16:17] offset:2560 nt
	global_load_dwordx2 v[92:93], v194, s[16:17] offset:3072 nt
	global_load_dwordx2 v[94:95], v194, s[16:17] offset:3584 nt
	global_load_dwordx2 v[112:113], v194, s[22:23] offset:0 nt
	global_load_dwordx2 v[114:115], v194, s[22:23] offset:512 nt
	global_load_dwordx2 v[116:117], v194, s[22:23] offset:1024 nt
	global_load_dwordx2 v[118:119], v194, s[22:23] offset:1536 nt
	global_load_dwordx2 v[120:121], v194, s[22:23] offset:2048 nt
	global_load_dwordx2 v[122:123], v194, s[22:23] offset:2560 nt
	global_load_dwordx2 v[124:125], v194, s[22:23] offset:3072 nt
	global_load_dwordx2 v[126:127], v194, s[22:23] offset:3584 nt
	s_add_u32 s14, s14, 0x2000
	s_addc_u32 s15, s15, 0
	s_add_u32 s16, s16, 0x1000
	s_addc_u32 s17, s17, 0
	s_add_u32 s22, s22, 0x1000
	s_addc_u32 s23, s23, 0
	s_waitcnt vmcnt(32)
	v_lshlrev_b32_e32 v200, 16, v64
	v_and_b32_e32 v201, 0xffff0000, v64
	v_lshlrev_b32_e32 v202, 16, v65
	v_and_b32_e32 v203, 0xffff0000, v65
	v_mul_f32_e32 v208, v200, v200
	v_mul_f32_e32 v209, v201, v201
	v_fmac_f32_e32 v208, v202, v202
	v_fmac_f32_e32 v209, v203, v203
	v_lshlrev_b32_e32 v204, 16, v96
	v_and_b32_e32 v205, 0xffff0000, v96
	v_lshlrev_b32_e32 v206, 16, v97
	v_and_b32_e32 v207, 0xffff0000, v97
	v_mul_f32_e32 v210, v204, v204
	v_mul_f32_e32 v211, v205, v205
	v_fmac_f32_e32 v210, v206, v206
	v_fmac_f32_e32 v211, v207, v207
	v_lshlrev_b32_e32 v200, 16, v66
	v_and_b32_e32 v201, 0xffff0000, v66
	v_lshlrev_b32_e32 v202, 16, v67
	v_and_b32_e32 v203, 0xffff0000, v67
	v_fmac_f32_e32 v208, v200, v200
	v_fmac_f32_e32 v209, v201, v201
	v_fmac_f32_e32 v208, v202, v202
	v_fmac_f32_e32 v209, v203, v203
	v_lshlrev_b32_e32 v204, 16, v98
	v_and_b32_e32 v205, 0xffff0000, v98
	v_lshlrev_b32_e32 v206, 16, v99
	v_and_b32_e32 v207, 0xffff0000, v99
	v_fmac_f32_e32 v210, v204, v204
	v_fmac_f32_e32 v211, v205, v205
	v_fmac_f32_e32 v210, v206, v206
	v_fmac_f32_e32 v211, v207, v207
	v_lshlrev_b32_e32 v200, 16, v68
	v_and_b32_e32 v201, 0xffff0000, v68
	v_lshlrev_b32_e32 v202, 16, v69
	v_and_b32_e32 v203, 0xffff0000, v69
	v_fmac_f32_e32 v208, v200, v200
	v_fmac_f32_e32 v209, v201, v201
	v_fmac_f32_e32 v208, v202, v202
	v_fmac_f32_e32 v209, v203, v203
	v_lshlrev_b32_e32 v204, 16, v100
	v_and_b32_e32 v205, 0xffff0000, v100
	v_lshlrev_b32_e32 v206, 16, v101
	v_and_b32_e32 v207, 0xffff0000, v101
	v_fmac_f32_e32 v210, v204, v204
	v_fmac_f32_e32 v211, v205, v205
	v_fmac_f32_e32 v210, v206, v206
	v_fmac_f32_e32 v211, v207, v207
	v_lshlrev_b32_e32 v200, 16, v70
	v_and_b32_e32 v201, 0xffff0000, v70
	v_lshlrev_b32_e32 v202, 16, v71
	v_and_b32_e32 v203, 0xffff0000, v71
	v_fmac_f32_e32 v208, v200, v200
	v_fmac_f32_e32 v209, v201, v201
	v_fmac_f32_e32 v208, v202, v202
	v_fmac_f32_e32 v209, v203, v203
	v_lshlrev_b32_e32 v204, 16, v102
	v_and_b32_e32 v205, 0xffff0000, v102
	v_lshlrev_b32_e32 v206, 16, v103
	v_and_b32_e32 v207, 0xffff0000, v103
	v_fmac_f32_e32 v210, v204, v204
	v_fmac_f32_e32 v211, v205, v205
	v_fmac_f32_e32 v210, v206, v206
	v_fmac_f32_e32 v211, v207, v207
	v_lshlrev_b32_e32 v200, 16, v72
	v_and_b32_e32 v201, 0xffff0000, v72
	v_lshlrev_b32_e32 v202, 16, v73
	v_and_b32_e32 v203, 0xffff0000, v73
	v_fmac_f32_e32 v208, v200, v200
	v_fmac_f32_e32 v209, v201, v201
	v_fmac_f32_e32 v208, v202, v202
	v_fmac_f32_e32 v209, v203, v203
	v_lshlrev_b32_e32 v204, 16, v104
	v_and_b32_e32 v205, 0xffff0000, v104
	v_lshlrev_b32_e32 v206, 16, v105
	v_and_b32_e32 v207, 0xffff0000, v105
	v_fmac_f32_e32 v210, v204, v204
	v_fmac_f32_e32 v211, v205, v205
; __device__ __forceinline__ float bf_lo(unsigned w) { return __uint_as_float(w << 16); }
; __device__ __forceinline__ float bf_hi(unsigned w) { return __uint_as_float(w & 0xffff0000u); }
; __global__ void __launch_bounds__(NWAVES * 64, 2) mk_fwd(Args args) {
;     ...
;                 float sy = 0.f;
; #pragma unroll
;                 for (int j = 0; j < 8; ++j) { const float a = bf_lo(yw[q][j].x), b = bf_hi(yw[q][j].x), c2 = bf_lo(yw[q][j].y), d = bf_hi(yw[q][j].y); sy += (a * a + b * b) + (c2 * c2 + d * d); }
;                 const float rsy = __builtin_amdgcn_rsqf(wave_sum(sy) * (1.f / DM) + EPS);
; #pragma unroll
;                 for (int j = 0; j < 8; ++j) { const int col = 4 * F.lane + 256 * j;
;                     const f32x4 y4 = (f32x4){bf_lo(yw[q][j].x), bf_hi(yw[q][j].x), bf_lo(yw[q][j].y), bf_hi(yw[q][j].y)};
;                     *(f32x4*)(args.out + (size_t)row * DM + col) = v[q][j] + PA[j] * (y4 * rsy); }
	v_fmac_f32_e32 v210, v206, v206
	v_fmac_f32_e32 v211, v207, v207
	v_lshlrev_b32_e32 v200, 16, v74
	v_and_b32_e32 v201, 0xffff0000, v74
	v_lshlrev_b32_e32 v202, 16, v75
	v_and_b32_e32 v203, 0xffff0000, v75
	v_fmac_f32_e32 v208, v200, v200
	v_fmac_f32_e32 v209, v201, v201
	v_fmac_f32_e32 v208, v202, v202
	v_fmac_f32_e32 v209, v203, v203
	v_lshlrev_b32_e32 v204, 16, v106
	v_and_b32_e32 v205, 0xffff0000, v106
	v_lshlrev_b32_e32 v206, 16, v107
	v_and_b32_e32 v207, 0xffff0000, v107
	v_fmac_f32_e32 v210, v204, v204
	v_fmac_f32_e32 v211, v205, v205
	v_fmac_f32_e32 v210, v206, v206
	v_fmac_f32_e32 v211, v207, v207
	v_lshlrev_b32_e32 v200, 16, v76
	v_and_b32_e32 v201, 0xffff0000, v76
	v_lshlrev_b32_e32 v202, 16, v77
	v_and_b32_e32 v203, 0xffff0000, v77
	v_fmac_f32_e32 v208, v200, v200
	v_fmac_f32_e32 v209, v201, v201
	v_fmac_f32_e32 v208, v202, v202
	v_fmac_f32_e32 v209, v203, v203
	v_lshlrev_b32_e32 v204, 16, v108
	v_and_b32_e32 v205, 0xffff0000, v108
	v_lshlrev_b32_e32 v206, 16, v109
	v_and_b32_e32 v207, 0xffff0000, v109
	v_fmac_f32_e32 v210, v204, v204
	v_fmac_f32_e32 v211, v205, v205
	v_fmac_f32_e32 v210, v206, v206
	v_fmac_f32_e32 v211, v207, v207
	v_lshlrev_b32_e32 v200, 16, v78
	v_and_b32_e32 v201, 0xffff0000, v78
	v_lshlrev_b32_e32 v202, 16, v79
	v_and_b32_e32 v203, 0xffff0000, v79
	v_fmac_f32_e32 v208, v200, v200
	v_fmac_f32_e32 v209, v201, v201
	v_fmac_f32_e32 v208, v202, v202
	v_fmac_f32_e32 v209, v203, v203
	v_lshlrev_b32_e32 v204, 16, v110
	v_and_b32_e32 v205, 0xffff0000, v110
	v_lshlrev_b32_e32 v206, 16, v111
	v_and_b32_e32 v207, 0xffff0000, v111
	v_fmac_f32_e32 v210, v204, v204
	v_fmac_f32_e32 v211, v205, v205
	v_fmac_f32_e32 v210, v206, v206
	v_fmac_f32_e32 v211, v207, v207
	v_add_f32_e32 v208, v208, v209
	v_add_f32_e32 v210, v210, v211
	s_nop 0
	v_add_f32_dpp v212, v208, v208 quad_perm:[1,0,3,2] row_mask:0xf bank_mask:0xf
	v_add_f32_dpp v213, v210, v210 quad_perm:[1,0,3,2] row_mask:0xf bank_mask:0xf
	s_nop 0
	v_add_f32_dpp v212, v212, v212 quad_perm:[2,3,0,1] row_mask:0xf bank_mask:0xf
	v_add_f32_dpp v213, v213, v213 quad_perm:[2,3,0,1] row_mask:0xf bank_mask:0xf
	s_nop 0
	v_add_f32_dpp v212, v212, v212 row_half_mirror row_mask:0xf bank_mask:0xf
	v_add_f32_dpp v213, v213, v213 row_half_mirror row_mask:0xf bank_mask:0xf
	s_nop 0
	v_add_f32_dpp v212, v212, v212 row_mirror row_mask:0xf bank_mask:0xf
	v_add_f32_dpp v213, v213, v213 row_mirror row_mask:0xf bank_mask:0xf
	s_nop 0
	v_readlane_b32 s4, v212, 0
	v_readlane_b32 s5, v212, 16
	v_readlane_b32 s6, v212, 32
	v_readlane_b32 s7, v212, 48
	v_readlane_b32 s24, v213, 0
	v_readlane_b32 s25, v213, 16
	v_readlane_b32 s26, v213, 32
	v_readlane_b32 s27, v213, 48
	s_nop 1
	v_mov_b32_e32 v214, s4
	v_mov_b32_e32 v215, s24
	v_add_f32_e32 v214, s5, v214
	v_add_f32_e32 v215, s25, v215
	v_add_f32_e32 v214, s6, v214
	v_add_f32_e32 v215, s26, v215
	v_add_f32_e32 v214, s7, v214
	v_add_f32_e32 v215, s27, v215
	v_fmamk_f32 v214, v214, 0x3a000000, v195
	v_fmamk_f32 v215, v215, 0x3a000000, v195
	v_rsq_f32_e32 v214, v214
	v_rsq_f32_e32 v215, v215
	s_nop 0
	v_lshlrev_b32_e32 v200, 16, v64
	v_and_b32_e32 v201, 0xffff0000, v64
	v_lshlrev_b32_e32 v202, 16, v65
	v_and_b32_e32 v203, 0xffff0000, v65
	v_lshlrev_b32_e32 v204, 16, v96
	v_and_b32_e32 v205, 0xffff0000, v96
	v_lshlrev_b32_e32 v206, 16, v97
	v_and_b32_e32 v207, 0xffff0000, v97
	v_mul_f32_e32 v200, v214, v200
	v_mul_f32_e32 v201, v214, v201
	v_mul_f32_e32 v202, v214, v202
	v_mul_f32_e32 v203, v214, v203
	v_mul_f32_e32 v204, v215, v204
	v_mul_f32_e32 v205, v215, v205
	v_mul_f32_e32 v206, v215, v206
	v_mul_f32_e32 v207, v215, v207
	v_fmac_f32_e32 v0, v128, v200
	v_fmac_f32_e32 v1, v129, v201
	v_fmac_f32_e32 v2, v130, v202
	v_fmac_f32_e32 v3, v131, v203
	v_fmac_f32_e32 v0, v160, v204
	v_fmac_f32_e32 v1, v161, v205
	v_fmac_f32_e32 v2, v162, v206
	v_fmac_f32_e32 v3, v163, v207
	global_store_dwordx4 v192, v[0:3], s[18:19] offset:0 nt
	v_lshlrev_b32_e32 v200, 16, v66
	v_and_b32_e32 v201, 0xffff0000, v66
	v_lshlrev_b32_e32 v202, 16, v67
	v_and_b32_e32 v203, 0xffff0000, v67
	v_lshlrev_b32_e32 v204, 16, v98
	v_and_b32_e32 v205, 0xffff0000, v98
	v_lshlrev_b32_e32 v206, 16, v99
	v_and_b32_e32 v207, 0xffff0000, v99
	v_mul_f32_e32 v200, v214, v200
	v_mul_f32_e32 v201, v214, v201
	v_mul_f32_e32 v202, v214, v202
	v_mul_f32_e32 v203, v214, v203
	v_mul_f32_e32 v204, v215, v204
	v_mul_f32_e32 v205, v215, v205
	v_mul_f32_e32 v206, v215, v206
	v_mul_f32_e32 v207, v215, v207
	v_fmac_f32_e32 v4, v132, v200
	v_fmac_f32_e32 v5, v133, v201
	v_fmac_f32_e32 v6, v134, v202
	v_fmac_f32_e32 v7, v135, v203
	v_fmac_f32_e32 v4, v164, v204
	v_fmac_f32_e32 v5, v165, v205
	v_fmac_f32_e32 v6, v166, v206
	v_fmac_f32_e32 v7, v167, v207
	global_store_dwordx4 v192, v[4:7], s[18:19] offset:1024 nt
	v_lshlrev_b32_e32 v200, 16, v68
	v_and_b32_e32 v201, 0xffff0000, v68
	v_lshlrev_b32_e32 v202, 16, v69
	v_and_b32_e32 v203, 0xffff0000, v69
	v_lshlrev_b32_e32 v204, 16, v100
	v_and_b32_e32 v205, 0xffff0000, v100
	v_lshlrev_b32_e32 v206, 16, v101
	v_and_b32_e32 v207, 0xffff0000, v101
	v_mul_f32_e32 v200, v214, v200
	v_mul_f32_e32 v201, v214, v201
	v_mul_f32_e32 v202, v214, v202
	v_mul_f32_e32 v203, v214, v203
	v_mul_f32_e32 v204, v215, v204
	v_mul_f32_e32 v205, v215, v205
	v_mul_f32_e32 v206, v215, v206
	v_mul_f32_e32 v207, v215, v207
	v_fmac_f32_e32 v8, v136, v200
	v_fmac_f32_e32 v9, v137, v201
	v_fmac_f32_e32 v10, v138, v202
	v_fmac_f32_e32 v11, v139, v203
	v_fmac_f32_e32 v8, v168, v204
	v_fmac_f32_e32 v9, v169, v205
	v_fmac_f32_e32 v10, v170, v206
	v_fmac_f32_e32 v11, v171, v207
	global_store_dwordx4 v192, v[8:11], s[18:19] offset:2048 nt
	v_lshlrev_b32_e32 v200, 16, v70
	v_and_b32_e32 v201, 0xffff0000, v70
; __device__ __forceinline__ float bf_lo(unsigned w) { return __uint_as_float(w << 16); }
; __device__ __forceinline__ float bf_hi(unsigned w) { return __uint_as_float(w & 0xffff0000u); }
; __global__ void __launch_bounds__(NWAVES * 64, 2) mk_fwd(Args args) {
;     ...
;         for (int row0 = rbeg; row0 < rbeg + per2 && row0 < ML; row0 += 2) {
;             f32x4 v[2][8]; u32x2 yw[2][8];
; #pragma unroll
;             for (int q = 0; q < 2; ++q) { const int row = row0 + q; load_row_f32(args.out + (size_t)row * DM, F.lane, v[q]);
;                 const bf16_t* yr = Y + (size_t)row * DM;
; #pragma unroll
;                 for (int j = 0; j < 8; ++j) yw[q][j] = *(const u32x2*)(yr + 4 * F.lane + 256 * j); }
;     ...
;                 for (int j = 0; j < 8; ++j) { const int col = 4 * F.lane + 256 * j;
;                     const f32x4 y4 = (f32x4){bf_lo(yw[q][j].x), bf_hi(yw[q][j].x), bf_lo(yw[q][j].y), bf_hi(yw[q][j].y)};
;                     *(f32x4*)(args.out + (size_t)row * DM + col) = v[q][j] + PA[j] * (y4 * rsy); }
	v_lshlrev_b32_e32 v202, 16, v71
	v_and_b32_e32 v203, 0xffff0000, v71
	v_lshlrev_b32_e32 v204, 16, v102
	v_and_b32_e32 v205, 0xffff0000, v102
	v_lshlrev_b32_e32 v206, 16, v103
	v_and_b32_e32 v207, 0xffff0000, v103
	v_mul_f32_e32 v200, v214, v200
	v_mul_f32_e32 v201, v214, v201
	v_mul_f32_e32 v202, v214, v202
	v_mul_f32_e32 v203, v214, v203
	v_mul_f32_e32 v204, v215, v204
	v_mul_f32_e32 v205, v215, v205
	v_mul_f32_e32 v206, v215, v206
	v_mul_f32_e32 v207, v215, v207
	v_fmac_f32_e32 v12, v140, v200
	v_fmac_f32_e32 v13, v141, v201
	v_fmac_f32_e32 v14, v142, v202
	v_fmac_f32_e32 v15, v143, v203
	v_fmac_f32_e32 v12, v172, v204
	v_fmac_f32_e32 v13, v173, v205
	v_fmac_f32_e32 v14, v174, v206
	v_fmac_f32_e32 v15, v175, v207
	global_store_dwordx4 v192, v[12:15], s[18:19] offset:3072 nt
	v_lshlrev_b32_e32 v200, 16, v72
	v_and_b32_e32 v201, 0xffff0000, v72
	v_lshlrev_b32_e32 v202, 16, v73
	v_and_b32_e32 v203, 0xffff0000, v73
	v_lshlrev_b32_e32 v204, 16, v104
	v_and_b32_e32 v205, 0xffff0000, v104
	v_lshlrev_b32_e32 v206, 16, v105
	v_and_b32_e32 v207, 0xffff0000, v105
	v_mul_f32_e32 v200, v214, v200
	v_mul_f32_e32 v201, v214, v201
	v_mul_f32_e32 v202, v214, v202
	v_mul_f32_e32 v203, v214, v203
	v_mul_f32_e32 v204, v215, v204
	v_mul_f32_e32 v205, v215, v205
	v_mul_f32_e32 v206, v215, v206
	v_mul_f32_e32 v207, v215, v207
	v_fmac_f32_e32 v16, v144, v200
	v_fmac_f32_e32 v17, v145, v201
	v_fmac_f32_e32 v18, v146, v202
	v_fmac_f32_e32 v19, v147, v203
	v_fmac_f32_e32 v16, v176, v204
	v_fmac_f32_e32 v17, v177, v205
	v_fmac_f32_e32 v18, v178, v206
	v_fmac_f32_e32 v19, v179, v207
	global_store_dwordx4 v193, v[16:19], s[18:19] offset:0 nt
	v_lshlrev_b32_e32 v200, 16, v74
	v_and_b32_e32 v201, 0xffff0000, v74
	v_lshlrev_b32_e32 v202, 16, v75
	v_and_b32_e32 v203, 0xffff0000, v75
	v_lshlrev_b32_e32 v204, 16, v106
	v_and_b32_e32 v205, 0xffff0000, v106
	v_lshlrev_b32_e32 v206, 16, v107
	v_and_b32_e32 v207, 0xffff0000, v107
	v_mul_f32_e32 v200, v214, v200
	v_mul_f32_e32 v201, v214, v201
	v_mul_f32_e32 v202, v214, v202
	v_mul_f32_e32 v203, v214, v203
	v_mul_f32_e32 v204, v215, v204
	v_mul_f32_e32 v205, v215, v205
	v_mul_f32_e32 v206, v215, v206
	v_mul_f32_e32 v207, v215, v207
	v_fmac_f32_e32 v20, v148, v200
	v_fmac_f32_e32 v21, v149, v201
	v_fmac_f32_e32 v22, v150, v202
	v_fmac_f32_e32 v23, v151, v203
	v_fmac_f32_e32 v20, v180, v204
	v_fmac_f32_e32 v21, v181, v205
	v_fmac_f32_e32 v22, v182, v206
	v_fmac_f32_e32 v23, v183, v207
	global_store_dwordx4 v193, v[20:23], s[18:19] offset:1024 nt
	v_lshlrev_b32_e32 v200, 16, v76
	v_and_b32_e32 v201, 0xffff0000, v76
	v_lshlrev_b32_e32 v202, 16, v77
	v_and_b32_e32 v203, 0xffff0000, v77
	v_lshlrev_b32_e32 v204, 16, v108
	v_and_b32_e32 v205, 0xffff0000, v108
	v_lshlrev_b32_e32 v206, 16, v109
	v_and_b32_e32 v207, 0xffff0000, v109
	v_mul_f32_e32 v200, v214, v200
	v_mul_f32_e32 v201, v214, v201
	v_mul_f32_e32 v202, v214, v202
	v_mul_f32_e32 v203, v214, v203
	v_mul_f32_e32 v204, v215, v204
	v_mul_f32_e32 v205, v215, v205
	v_mul_f32_e32 v206, v215, v206
	v_mul_f32_e32 v207, v215, v207
	v_fmac_f32_e32 v24, v152, v200
	v_fmac_f32_e32 v25, v153, v201
	v_fmac_f32_e32 v26, v154, v202
	v_fmac_f32_e32 v27, v155, v203
	v_fmac_f32_e32 v24, v184, v204
	v_fmac_f32_e32 v25, v185, v205
	v_fmac_f32_e32 v26, v186, v206
	v_fmac_f32_e32 v27, v187, v207
	global_store_dwordx4 v193, v[24:27], s[18:19] offset:2048 nt
	v_lshlrev_b32_e32 v200, 16, v78
	v_and_b32_e32 v201, 0xffff0000, v78
	v_lshlrev_b32_e32 v202, 16, v79
	v_and_b32_e32 v203, 0xffff0000, v79
	v_lshlrev_b32_e32 v204, 16, v110
	v_and_b32_e32 v205, 0xffff0000, v110
	v_lshlrev_b32_e32 v206, 16, v111
	v_and_b32_e32 v207, 0xffff0000, v111
	v_mul_f32_e32 v200, v214, v200
	v_mul_f32_e32 v201, v214, v201
	v_mul_f32_e32 v202, v214, v202
	v_mul_f32_e32 v203, v214, v203
	v_mul_f32_e32 v204, v215, v204
	v_mul_f32_e32 v205, v215, v205
	v_mul_f32_e32 v206, v215, v206
	v_mul_f32_e32 v207, v215, v207
	v_fmac_f32_e32 v28, v156, v200
	v_fmac_f32_e32 v29, v157, v201
	v_fmac_f32_e32 v30, v158, v202
	v_fmac_f32_e32 v31, v159, v203
	v_fmac_f32_e32 v28, v188, v204
	v_fmac_f32_e32 v29, v189, v205
	v_fmac_f32_e32 v30, v190, v206
	v_fmac_f32_e32 v31, v191, v207
	global_store_dwordx4 v193, v[28:31], s[18:19] offset:3072 nt
	s_add_u32 s18, s18, 0x2000
	s_addc_u32 s19, s19, 0
	global_load_dwordx4 v[0:3], v192, s[14:15] offset:0 nt
	global_load_dwordx4 v[4:7], v192, s[14:15] offset:1024 nt
	global_load_dwordx4 v[8:11], v192, s[14:15] offset:2048 nt
	global_load_dwordx4 v[12:15], v192, s[14:15] offset:3072 nt
	global_load_dwordx4 v[16:19], v193, s[14:15] offset:0 nt
	global_load_dwordx4 v[20:23], v193, s[14:15] offset:1024 nt
	global_load_dwordx4 v[24:27], v193, s[14:15] offset:2048 nt
	global_load_dwordx4 v[28:31], v193, s[14:15] offset:3072 nt
	global_load_dwordx2 v[64:65], v194, s[16:17] offset:0 nt
	global_load_dwordx2 v[66:67], v194, s[16:17] offset:512 nt
	global_load_dwordx2 v[68:69], v194, s[16:17] offset:1024 nt
	global_load_dwordx2 v[70:71], v194, s[16:17] offset:1536 nt
	global_load_dwordx2 v[72:73], v194, s[16:17] offset:2048 nt
	global_load_dwordx2 v[74:75], v194, s[16:17] offset:2560 nt
	global_load_dwordx2 v[76:77], v194, s[16:17] offset:3072 nt
	global_load_dwordx2 v[78:79], v194, s[16:17] offset:3584 nt
	global_load_dwordx2 v[96:97], v194, s[22:23] offset:0 nt
	global_load_dwordx2 v[98:99], v194, s[22:23] offset:512 nt
	global_load_dwordx2 v[100:101], v194, s[22:23] offset:1024 nt
	global_load_dwordx2 v[102:103], v194, s[22:23] offset:1536 nt
	global_load_dwordx2 v[104:105], v194, s[22:23] offset:2048 nt
	global_load_dwordx2 v[106:107], v194, s[22:23] offset:2560 nt
	global_load_dwordx2 v[108:109], v194, s[22:23] offset:3072 nt
	global_load_dwordx2 v[110:111], v194, s[22:23] offset:3584 nt
	s_add_u32 s14, s14, 0x2000
	s_addc_u32 s15, s15, 0
	s_add_u32 s16, s16, 0x1000
	s_addc_u32 s17, s17, 0
	s_add_u32 s22, s22, 0x1000
	s_addc_u32 s23, s23, 0
	s_waitcnt vmcnt(32)
; __device__ __forceinline__ float bf_lo(unsigned w) { return __uint_as_float(w << 16); }
; __device__ __forceinline__ float bf_hi(unsigned w) { return __uint_as_float(w & 0xffff0000u); }
; __global__ void __launch_bounds__(NWAVES * 64, 2) mk_fwd(Args args) {
;     ...
;                 float sy = 0.f;
; #pragma unroll
;                 for (int j = 0; j < 8; ++j) { const float a = bf_lo(yw[q][j].x), b = bf_hi(yw[q][j].x), c2 = bf_lo(yw[q][j].y), d = bf_hi(yw[q][j].y); sy += (a * a + b * b) + (c2 * c2 + d * d); }
;                 const float rsy = __builtin_amdgcn_rsqf(wave_sum(sy) * (1.f / DM) + EPS);
	v_lshlrev_b32_e32 v200, 16, v80
	v_and_b32_e32 v201, 0xffff0000, v80
	v_lshlrev_b32_e32 v202, 16, v81
	v_and_b32_e32 v203, 0xffff0000, v81
	v_mul_f32_e32 v208, v200, v200
	v_mul_f32_e32 v209, v201, v201
	v_fmac_f32_e32 v208, v202, v202
	v_fmac_f32_e32 v209, v203, v203
	v_lshlrev_b32_e32 v204, 16, v112
	v_and_b32_e32 v205, 0xffff0000, v112
	v_lshlrev_b32_e32 v206, 16, v113
	v_and_b32_e32 v207, 0xffff0000, v113
	v_mul_f32_e32 v210, v204, v204
	v_mul_f32_e32 v211, v205, v205
	v_fmac_f32_e32 v210, v206, v206
	v_fmac_f32_e32 v211, v207, v207
	v_lshlrev_b32_e32 v200, 16, v82
	v_and_b32_e32 v201, 0xffff0000, v82
	v_lshlrev_b32_e32 v202, 16, v83
	v_and_b32_e32 v203, 0xffff0000, v83
	v_fmac_f32_e32 v208, v200, v200
	v_fmac_f32_e32 v209, v201, v201
	v_fmac_f32_e32 v208, v202, v202
	v_fmac_f32_e32 v209, v203, v203
	v_lshlrev_b32_e32 v204, 16, v114
	v_and_b32_e32 v205, 0xffff0000, v114
	v_lshlrev_b32_e32 v206, 16, v115
	v_and_b32_e32 v207, 0xffff0000, v115
	v_fmac_f32_e32 v210, v204, v204
	v_fmac_f32_e32 v211, v205, v205
	v_fmac_f32_e32 v210, v206, v206
	v_fmac_f32_e32 v211, v207, v207
	v_lshlrev_b32_e32 v200, 16, v84
	v_and_b32_e32 v201, 0xffff0000, v84
	v_lshlrev_b32_e32 v202, 16, v85
	v_and_b32_e32 v203, 0xffff0000, v85
	v_fmac_f32_e32 v208, v200, v200
	v_fmac_f32_e32 v209, v201, v201
	v_fmac_f32_e32 v208, v202, v202
	v_fmac_f32_e32 v209, v203, v203
	v_lshlrev_b32_e32 v204, 16, v116
	v_and_b32_e32 v205, 0xffff0000, v116
	v_lshlrev_b32_e32 v206, 16, v117
	v_and_b32_e32 v207, 0xffff0000, v117
	v_fmac_f32_e32 v210, v204, v204
	v_fmac_f32_e32 v211, v205, v205
	v_fmac_f32_e32 v210, v206, v206
	v_fmac_f32_e32 v211, v207, v207
	v_lshlrev_b32_e32 v200, 16, v86
	v_and_b32_e32 v201, 0xffff0000, v86
	v_lshlrev_b32_e32 v202, 16, v87
	v_and_b32_e32 v203, 0xffff0000, v87
	v_fmac_f32_e32 v208, v200, v200
	v_fmac_f32_e32 v209, v201, v201
	v_fmac_f32_e32 v208, v202, v202
	v_fmac_f32_e32 v209, v203, v203
	v_lshlrev_b32_e32 v204, 16, v118
	v_and_b32_e32 v205, 0xffff0000, v118
	v_lshlrev_b32_e32 v206, 16, v119
	v_and_b32_e32 v207, 0xffff0000, v119
	v_fmac_f32_e32 v210, v204, v204
	v_fmac_f32_e32 v211, v205, v205
	v_fmac_f32_e32 v210, v206, v206
	v_fmac_f32_e32 v211, v207, v207
	v_lshlrev_b32_e32 v200, 16, v88
	v_and_b32_e32 v201, 0xffff0000, v88
	v_lshlrev_b32_e32 v202, 16, v89
	v_and_b32_e32 v203, 0xffff0000, v89
	v_fmac_f32_e32 v208, v200, v200
	v_fmac_f32_e32 v209, v201, v201
	v_fmac_f32_e32 v208, v202, v202
	v_fmac_f32_e32 v209, v203, v203
	v_lshlrev_b32_e32 v204, 16, v120
	v_and_b32_e32 v205, 0xffff0000, v120
	v_lshlrev_b32_e32 v206, 16, v121
	v_and_b32_e32 v207, 0xffff0000, v121
	v_fmac_f32_e32 v210, v204, v204
	v_fmac_f32_e32 v211, v205, v205
	v_fmac_f32_e32 v210, v206, v206
	v_fmac_f32_e32 v211, v207, v207
	v_lshlrev_b32_e32 v200, 16, v90
	v_and_b32_e32 v201, 0xffff0000, v90
	v_lshlrev_b32_e32 v202, 16, v91
	v_and_b32_e32 v203, 0xffff0000, v91
	v_fmac_f32_e32 v208, v200, v200
	v_fmac_f32_e32 v209, v201, v201
	v_fmac_f32_e32 v208, v202, v202
	v_fmac_f32_e32 v209, v203, v203
	v_lshlrev_b32_e32 v204, 16, v122
	v_and_b32_e32 v205, 0xffff0000, v122
	v_lshlrev_b32_e32 v206, 16, v123
	v_and_b32_e32 v207, 0xffff0000, v123
	v_fmac_f32_e32 v210, v204, v204
	v_fmac_f32_e32 v211, v205, v205
	v_fmac_f32_e32 v210, v206, v206
	v_fmac_f32_e32 v211, v207, v207
	v_lshlrev_b32_e32 v200, 16, v92
	v_and_b32_e32 v201, 0xffff0000, v92
	v_lshlrev_b32_e32 v202, 16, v93
	v_and_b32_e32 v203, 0xffff0000, v93
	v_fmac_f32_e32 v208, v200, v200
	v_fmac_f32_e32 v209, v201, v201
	v_fmac_f32_e32 v208, v202, v202
	v_fmac_f32_e32 v209, v203, v203
	v_lshlrev_b32_e32 v204, 16, v124
	v_and_b32_e32 v205, 0xffff0000, v124
	v_lshlrev_b32_e32 v206, 16, v125
	v_and_b32_e32 v207, 0xffff0000, v125
	v_fmac_f32_e32 v210, v204, v204
	v_fmac_f32_e32 v211, v205, v205
	v_fmac_f32_e32 v210, v206, v206
	v_fmac_f32_e32 v211, v207, v207
	v_lshlrev_b32_e32 v200, 16, v94
	v_and_b32_e32 v201, 0xffff0000, v94
	v_lshlrev_b32_e32 v202, 16, v95
	v_and_b32_e32 v203, 0xffff0000, v95
	v_fmac_f32_e32 v208, v200, v200
	v_fmac_f32_e32 v209, v201, v201
	v_fmac_f32_e32 v208, v202, v202
	v_fmac_f32_e32 v209, v203, v203
	v_lshlrev_b32_e32 v204, 16, v126
	v_and_b32_e32 v205, 0xffff0000, v126
	v_lshlrev_b32_e32 v206, 16, v127
	v_and_b32_e32 v207, 0xffff0000, v127
	v_fmac_f32_e32 v210, v204, v204
	v_fmac_f32_e32 v211, v205, v205
	v_fmac_f32_e32 v210, v206, v206
	v_fmac_f32_e32 v211, v207, v207
	v_add_f32_e32 v208, v208, v209
	v_add_f32_e32 v210, v210, v211
	s_nop 0
	v_add_f32_dpp v212, v208, v208 quad_perm:[1,0,3,2] row_mask:0xf bank_mask:0xf
	v_add_f32_dpp v213, v210, v210 quad_perm:[1,0,3,2] row_mask:0xf bank_mask:0xf
	s_nop 0
	v_add_f32_dpp v212, v212, v212 quad_perm:[2,3,0,1] row_mask:0xf bank_mask:0xf
	v_add_f32_dpp v213, v213, v213 quad_perm:[2,3,0,1] row_mask:0xf bank_mask:0xf
	s_nop 0
	v_add_f32_dpp v212, v212, v212 row_half_mirror row_mask:0xf bank_mask:0xf
	v_add_f32_dpp v213, v213, v213 row_half_mirror row_mask:0xf bank_mask:0xf
	s_nop 0
	v_add_f32_dpp v212, v212, v212 row_mirror row_mask:0xf bank_mask:0xf
	v_add_f32_dpp v213, v213, v213 row_mirror row_mask:0xf bank_mask:0xf
	s_nop 0
	v_readlane_b32 s4, v212, 0
	v_readlane_b32 s5, v212, 16
	v_readlane_b32 s6, v212, 32
	v_readlane_b32 s7, v212, 48
	v_readlane_b32 s24, v213, 0
	v_readlane_b32 s25, v213, 16
	v_readlane_b32 s26, v213, 32
	v_readlane_b32 s27, v213, 48
	s_nop 1
	v_mov_b32_e32 v214, s4
	v_mov_b32_e32 v215, s24
	v_add_f32_e32 v214, s5, v214
	v_add_f32_e32 v215, s25, v215
	v_add_f32_e32 v214, s6, v214
	v_add_f32_e32 v215, s26, v215
	v_add_f32_e32 v214, s7, v214
	v_add_f32_e32 v215, s27, v215
	v_fmamk_f32 v214, v214, 0x3a000000, v195
	v_fmamk_f32 v215, v215, 0x3a000000, v195
; __device__ __forceinline__ float bf_lo(unsigned w) { return __uint_as_float(w << 16); }
; __device__ __forceinline__ float bf_hi(unsigned w) { return __uint_as_float(w & 0xffff0000u); }
; __global__ void __launch_bounds__(NWAVES * 64, 2) mk_fwd(Args args) {
;     ...
;                 const float rsy = __builtin_amdgcn_rsqf(wave_sum(sy) * (1.f / DM) + EPS);
; #pragma unroll
;                 for (int j = 0; j < 8; ++j) { const int col = 4 * F.lane + 256 * j;
;                     const f32x4 y4 = (f32x4){bf_lo(yw[q][j].x), bf_hi(yw[q][j].x), bf_lo(yw[q][j].y), bf_hi(yw[q][j].y)};
;                     *(f32x4*)(args.out + (size_t)row * DM + col) = v[q][j] + PA[j] * (y4 * rsy); }
	v_rsq_f32_e32 v214, v214
	v_rsq_f32_e32 v215, v215
	s_nop 0
	v_lshlrev_b32_e32 v200, 16, v80
	v_and_b32_e32 v201, 0xffff0000, v80
	v_lshlrev_b32_e32 v202, 16, v81
	v_and_b32_e32 v203, 0xffff0000, v81
	v_lshlrev_b32_e32 v204, 16, v112
	v_and_b32_e32 v205, 0xffff0000, v112
	v_lshlrev_b32_e32 v206, 16, v113
	v_and_b32_e32 v207, 0xffff0000, v113
	v_mul_f32_e32 v200, v214, v200
	v_mul_f32_e32 v201, v214, v201
	v_mul_f32_e32 v202, v214, v202
	v_mul_f32_e32 v203, v214, v203
	v_mul_f32_e32 v204, v215, v204
	v_mul_f32_e32 v205, v215, v205
	v_mul_f32_e32 v206, v215, v206
	v_mul_f32_e32 v207, v215, v207
	v_fmac_f32_e32 v32, v128, v200
	v_fmac_f32_e32 v33, v129, v201
	v_fmac_f32_e32 v34, v130, v202
	v_fmac_f32_e32 v35, v131, v203
	v_fmac_f32_e32 v32, v160, v204
	v_fmac_f32_e32 v33, v161, v205
	v_fmac_f32_e32 v34, v162, v206
	v_fmac_f32_e32 v35, v163, v207
	global_store_dwordx4 v192, v[32:35], s[18:19] offset:0 nt
	v_lshlrev_b32_e32 v200, 16, v82
	v_and_b32_e32 v201, 0xffff0000, v82
	v_lshlrev_b32_e32 v202, 16, v83
	v_and_b32_e32 v203, 0xffff0000, v83
	v_lshlrev_b32_e32 v204, 16, v114
	v_and_b32_e32 v205, 0xffff0000, v114
	v_lshlrev_b32_e32 v206, 16, v115
	v_and_b32_e32 v207, 0xffff0000, v115
	v_mul_f32_e32 v200, v214, v200
	v_mul_f32_e32 v201, v214, v201
	v_mul_f32_e32 v202, v214, v202
	v_mul_f32_e32 v203, v214, v203
	v_mul_f32_e32 v204, v215, v204
	v_mul_f32_e32 v205, v215, v205
	v_mul_f32_e32 v206, v215, v206
	v_mul_f32_e32 v207, v215, v207
	v_fmac_f32_e32 v36, v132, v200
	v_fmac_f32_e32 v37, v133, v201
	v_fmac_f32_e32 v38, v134, v202
	v_fmac_f32_e32 v39, v135, v203
	v_fmac_f32_e32 v36, v164, v204
	v_fmac_f32_e32 v37, v165, v205
	v_fmac_f32_e32 v38, v166, v206
	v_fmac_f32_e32 v39, v167, v207
	global_store_dwordx4 v192, v[36:39], s[18:19] offset:1024 nt
	v_lshlrev_b32_e32 v200, 16, v84
	v_and_b32_e32 v201, 0xffff0000, v84
	v_lshlrev_b32_e32 v202, 16, v85
	v_and_b32_e32 v203, 0xffff0000, v85
	v_lshlrev_b32_e32 v204, 16, v116
	v_and_b32_e32 v205, 0xffff0000, v116
	v_lshlrev_b32_e32 v206, 16, v117
	v_and_b32_e32 v207, 0xffff0000, v117
	v_mul_f32_e32 v200, v214, v200
	v_mul_f32_e32 v201, v214, v201
	v_mul_f32_e32 v202, v214, v202
	v_mul_f32_e32 v203, v214, v203
	v_mul_f32_e32 v204, v215, v204
	v_mul_f32_e32 v205, v215, v205
	v_mul_f32_e32 v206, v215, v206
	v_mul_f32_e32 v207, v215, v207
	v_fmac_f32_e32 v40, v136, v200
	v_fmac_f32_e32 v41, v137, v201
	v_fmac_f32_e32 v42, v138, v202
	v_fmac_f32_e32 v43, v139, v203
	v_fmac_f32_e32 v40, v168, v204
	v_fmac_f32_e32 v41, v169, v205
	v_fmac_f32_e32 v42, v170, v206
	v_fmac_f32_e32 v43, v171, v207
	global_store_dwordx4 v192, v[40:43], s[18:19] offset:2048 nt
	v_lshlrev_b32_e32 v200, 16, v86
	v_and_b32_e32 v201, 0xffff0000, v86
	v_lshlrev_b32_e32 v202, 16, v87
	v_and_b32_e32 v203, 0xffff0000, v87
	v_lshlrev_b32_e32 v204, 16, v118
	v_and_b32_e32 v205, 0xffff0000, v118
	v_lshlrev_b32_e32 v206, 16, v119
	v_and_b32_e32 v207, 0xffff0000, v119
	v_mul_f32_e32 v200, v214, v200
	v_mul_f32_e32 v201, v214, v201
	v_mul_f32_e32 v202, v214, v202
	v_mul_f32_e32 v203, v214, v203
	v_mul_f32_e32 v204, v215, v204
	v_mul_f32_e32 v205, v215, v205
	v_mul_f32_e32 v206, v215, v206
	v_mul_f32_e32 v207, v215, v207
	v_fmac_f32_e32 v44, v140, v200
	v_fmac_f32_e32 v45, v141, v201
	v_fmac_f32_e32 v46, v142, v202
	v_fmac_f32_e32 v47, v143, v203
	v_fmac_f32_e32 v44, v172, v204
	v_fmac_f32_e32 v45, v173, v205
	v_fmac_f32_e32 v46, v174, v206
	v_fmac_f32_e32 v47, v175, v207
	global_store_dwordx4 v192, v[44:47], s[18:19] offset:3072 nt
	v_lshlrev_b32_e32 v200, 16, v88
	v_and_b32_e32 v201, 0xffff0000, v88
	v_lshlrev_b32_e32 v202, 16, v89
	v_and_b32_e32 v203, 0xffff0000, v89
	v_lshlrev_b32_e32 v204, 16, v120
	v_and_b32_e32 v205, 0xffff0000, v120
	v_lshlrev_b32_e32 v206, 16, v121
	v_and_b32_e32 v207, 0xffff0000, v121
	v_mul_f32_e32 v200, v214, v200
	v_mul_f32_e32 v201, v214, v201
	v_mul_f32_e32 v202, v214, v202
	v_mul_f32_e32 v203, v214, v203
	v_mul_f32_e32 v204, v215, v204
	v_mul_f32_e32 v205, v215, v205
	v_mul_f32_e32 v206, v215, v206
	v_mul_f32_e32 v207, v215, v207
	v_fmac_f32_e32 v48, v144, v200
	v_fmac_f32_e32 v49, v145, v201
	v_fmac_f32_e32 v50, v146, v202
	v_fmac_f32_e32 v51, v147, v203
	v_fmac_f32_e32 v48, v176, v204
	v_fmac_f32_e32 v49, v177, v205
	v_fmac_f32_e32 v50, v178, v206
	v_fmac_f32_e32 v51, v179, v207
	global_store_dwordx4 v193, v[48:51], s[18:19] offset:0 nt
	v_lshlrev_b32_e32 v200, 16, v90
	v_and_b32_e32 v201, 0xffff0000, v90
	v_lshlrev_b32_e32 v202, 16, v91
	v_and_b32_e32 v203, 0xffff0000, v91
	v_lshlrev_b32_e32 v204, 16, v122
	v_and_b32_e32 v205, 0xffff0000, v122
	v_lshlrev_b32_e32 v206, 16, v123
	v_and_b32_e32 v207, 0xffff0000, v123
	v_mul_f32_e32 v200, v214, v200
	v_mul_f32_e32 v201, v214, v201
	v_mul_f32_e32 v202, v214, v202
	v_mul_f32_e32 v203, v214, v203
	v_mul_f32_e32 v204, v215, v204
	v_mul_f32_e32 v205, v215, v205
	v_mul_f32_e32 v206, v215, v206
	v_mul_f32_e32 v207, v215, v207
	v_fmac_f32_e32 v52, v148, v200
	v_fmac_f32_e32 v53, v149, v201
	v_fmac_f32_e32 v54, v150, v202
	v_fmac_f32_e32 v55, v151, v203
	v_fmac_f32_e32 v52, v180, v204
	v_fmac_f32_e32 v53, v181, v205
	v_fmac_f32_e32 v54, v182, v206
	v_fmac_f32_e32 v55, v183, v207
	global_store_dwordx4 v193, v[52:55], s[18:19] offset:1024 nt
	v_lshlrev_b32_e32 v200, 16, v92
	v_and_b32_e32 v201, 0xffff0000, v92
	v_lshlrev_b32_e32 v202, 16, v93
	v_and_b32_e32 v203, 0xffff0000, v93
	v_lshlrev_b32_e32 v204, 16, v124
	v_and_b32_e32 v205, 0xffff0000, v124
	v_lshlrev_b32_e32 v206, 16, v125
	v_and_b32_e32 v207, 0xffff0000, v125
	v_mul_f32_e32 v200, v214, v200
	v_mul_f32_e32 v201, v214, v201
	v_mul_f32_e32 v202, v214, v202
	v_mul_f32_e32 v203, v214, v203
	v_mul_f32_e32 v204, v215, v204
; __device__ __forceinline__ float bf_lo(unsigned w) { return __uint_as_float(w << 16); }
; __device__ __forceinline__ float bf_hi(unsigned w) { return __uint_as_float(w & 0xffff0000u); }
; __global__ void __launch_bounds__(NWAVES * 64, 2) mk_fwd(Args args) {
;     ...
;         for (int row0 = rbeg; row0 < rbeg + per2 && row0 < ML; row0 += 2) {
;             f32x4 v[2][8]; u32x2 yw[2][8];
; #pragma unroll
;             for (int q = 0; q < 2; ++q) { const int row = row0 + q; load_row_f32(args.out + (size_t)row * DM, F.lane, v[q]);
;                 const bf16_t* yr = Y + (size_t)row * DM;
; #pragma unroll
;                 for (int j = 0; j < 8; ++j) yw[q][j] = *(const u32x2*)(yr + 4 * F.lane + 256 * j); }
; #pragma unroll
;             for (int q = 0; q < 2; ++q) { const int row = row0 + q; const int r = row / SEQ;
;                 if (r != rcur) { const float* m1 = mod + (size_t)(9 + r) * 6144; rcur = r;
; #pragma unroll
;                     for (int j = 0; j < 8; ++j) { const int col = 4 * F.lane + 256 * j; PA[j] = *(const f32x4*)(m1 + 2 * DM + col) * *(const f32x4*)(post_norm + DM + col); } }
;                 float sy = 0.f;
; #pragma unroll
;                 for (int j = 0; j < 8; ++j) { const float a = bf_lo(yw[q][j].x), b = bf_hi(yw[q][j].x), c2 = bf_lo(yw[q][j].y), d = bf_hi(yw[q][j].y); sy += (a * a + b * b) + (c2 * c2 + d * d); }
;     ...
;                 for (int j = 0; j < 8; ++j) { const int col = 4 * F.lane + 256 * j;
;                     const f32x4 y4 = (f32x4){bf_lo(yw[q][j].x), bf_hi(yw[q][j].x), bf_lo(yw[q][j].y), bf_hi(yw[q][j].y)};
;                     *(f32x4*)(args.out + (size_t)row * DM + col) = v[q][j] + PA[j] * (y4 * rsy); }
	v_mul_f32_e32 v205, v215, v205
	v_mul_f32_e32 v206, v215, v206
	v_mul_f32_e32 v207, v215, v207
	v_fmac_f32_e32 v56, v152, v200
	v_fmac_f32_e32 v57, v153, v201
	v_fmac_f32_e32 v58, v154, v202
	v_fmac_f32_e32 v59, v155, v203
	v_fmac_f32_e32 v56, v184, v204
	v_fmac_f32_e32 v57, v185, v205
	v_fmac_f32_e32 v58, v186, v206
	v_fmac_f32_e32 v59, v187, v207
	global_store_dwordx4 v193, v[56:59], s[18:19] offset:2048 nt
	v_lshlrev_b32_e32 v200, 16, v94
	v_and_b32_e32 v201, 0xffff0000, v94
	v_lshlrev_b32_e32 v202, 16, v95
	v_and_b32_e32 v203, 0xffff0000, v95
	v_lshlrev_b32_e32 v204, 16, v126
	v_and_b32_e32 v205, 0xffff0000, v126
	v_lshlrev_b32_e32 v206, 16, v127
	v_and_b32_e32 v207, 0xffff0000, v127
	v_mul_f32_e32 v200, v214, v200
	v_mul_f32_e32 v201, v214, v201
	v_mul_f32_e32 v202, v214, v202
	v_mul_f32_e32 v203, v214, v203
	v_mul_f32_e32 v204, v215, v204
	v_mul_f32_e32 v205, v215, v205
	v_mul_f32_e32 v206, v215, v206
	v_mul_f32_e32 v207, v215, v207
	v_fmac_f32_e32 v60, v156, v200
	v_fmac_f32_e32 v61, v157, v201
	v_fmac_f32_e32 v62, v158, v202
	v_fmac_f32_e32 v63, v159, v203
	v_fmac_f32_e32 v60, v188, v204
	v_fmac_f32_e32 v61, v189, v205
	v_fmac_f32_e32 v62, v190, v206
	v_fmac_f32_e32 v63, v191, v207
	global_store_dwordx4 v193, v[60:63], s[18:19] offset:3072 nt
	s_add_u32 s18, s18, 0x2000
	s_addc_u32 s19, s19, 0
	global_load_dwordx4 v[32:35], v192, s[14:15] offset:0 nt
	global_load_dwordx4 v[36:39], v192, s[14:15] offset:1024 nt
	global_load_dwordx4 v[40:43], v192, s[14:15] offset:2048 nt
	global_load_dwordx4 v[44:47], v192, s[14:15] offset:3072 nt
	global_load_dwordx4 v[48:51], v193, s[14:15] offset:0 nt
	global_load_dwordx4 v[52:55], v193, s[14:15] offset:1024 nt
	global_load_dwordx4 v[56:59], v193, s[14:15] offset:2048 nt
	global_load_dwordx4 v[60:63], v193, s[14:15] offset:3072 nt
	global_load_dwordx2 v[80:81], v194, s[16:17] offset:0 nt
	global_load_dwordx2 v[82:83], v194, s[16:17] offset:512 nt
	global_load_dwordx2 v[84:85], v194, s[16:17] offset:1024 nt
	global_load_dwordx2 v[86:87], v194, s[16:17] offset:1536 nt
	global_load_dwordx2 v[88:89], v194, s[16:17] offset:2048 nt
	global_load_dwordx2 v[90:91], v194, s[16:17] offset:2560 nt
	global_load_dwordx2 v[92:93], v194, s[16:17] offset:3072 nt
	global_load_dwordx2 v[94:95], v194, s[16:17] offset:3584 nt
	global_load_dwordx2 v[112:113], v194, s[22:23] offset:0 nt
	global_load_dwordx2 v[114:115], v194, s[22:23] offset:512 nt
	global_load_dwordx2 v[116:117], v194, s[22:23] offset:1024 nt
	global_load_dwordx2 v[118:119], v194, s[22:23] offset:1536 nt
	global_load_dwordx2 v[120:121], v194, s[22:23] offset:2048 nt
	global_load_dwordx2 v[122:123], v194, s[22:23] offset:2560 nt
	global_load_dwordx2 v[124:125], v194, s[22:23] offset:3072 nt
	global_load_dwordx2 v[126:127], v194, s[22:23] offset:3584 nt
	s_add_u32 s14, s14, 0x2000
	s_addc_u32 s15, s15, 0
	s_add_u32 s16, s16, 0x1000
	s_addc_u32 s17, s17, 0
	s_add_u32 s22, s22, 0x1000
	s_addc_u32 s23, s23, 0
	s_waitcnt vmcnt(32)
	v_lshlrev_b32_e32 v200, 16, v64
	v_and_b32_e32 v201, 0xffff0000, v64
	v_lshlrev_b32_e32 v202, 16, v65
	v_and_b32_e32 v203, 0xffff0000, v65
	v_mul_f32_e32 v208, v200, v200
	v_mul_f32_e32 v209, v201, v201
	v_fmac_f32_e32 v208, v202, v202
	v_fmac_f32_e32 v209, v203, v203
	v_lshlrev_b32_e32 v204, 16, v96
	v_and_b32_e32 v205, 0xffff0000, v96
	v_lshlrev_b32_e32 v206, 16, v97
	v_and_b32_e32 v207, 0xffff0000, v97
	v_mul_f32_e32 v210, v204, v204
	v_mul_f32_e32 v211, v205, v205
	v_fmac_f32_e32 v210, v206, v206
	v_fmac_f32_e32 v211, v207, v207
	v_lshlrev_b32_e32 v200, 16, v66
	v_and_b32_e32 v201, 0xffff0000, v66
	v_lshlrev_b32_e32 v202, 16, v67
	v_and_b32_e32 v203, 0xffff0000, v67
	v_fmac_f32_e32 v208, v200, v200
	v_fmac_f32_e32 v209, v201, v201
	v_fmac_f32_e32 v208, v202, v202
	v_fmac_f32_e32 v209, v203, v203
	v_lshlrev_b32_e32 v204, 16, v98
	v_and_b32_e32 v205, 0xffff0000, v98
	v_lshlrev_b32_e32 v206, 16, v99
	v_and_b32_e32 v207, 0xffff0000, v99
	v_fmac_f32_e32 v210, v204, v204
	v_fmac_f32_e32 v211, v205, v205
	v_fmac_f32_e32 v210, v206, v206
	v_fmac_f32_e32 v211, v207, v207
	v_lshlrev_b32_e32 v200, 16, v68
	v_and_b32_e32 v201, 0xffff0000, v68
	v_lshlrev_b32_e32 v202, 16, v69
	v_and_b32_e32 v203, 0xffff0000, v69
	v_fmac_f32_e32 v208, v200, v200
	v_fmac_f32_e32 v209, v201, v201
	v_fmac_f32_e32 v208, v202, v202
	v_fmac_f32_e32 v209, v203, v203
	v_lshlrev_b32_e32 v204, 16, v100
	v_and_b32_e32 v205, 0xffff0000, v100
	v_lshlrev_b32_e32 v206, 16, v101
	v_and_b32_e32 v207, 0xffff0000, v101
	v_fmac_f32_e32 v210, v204, v204
	v_fmac_f32_e32 v211, v205, v205
	v_fmac_f32_e32 v210, v206, v206
	v_fmac_f32_e32 v211, v207, v207
	v_lshlrev_b32_e32 v200, 16, v70
	v_and_b32_e32 v201, 0xffff0000, v70
	v_lshlrev_b32_e32 v202, 16, v71
	v_and_b32_e32 v203, 0xffff0000, v71
	v_fmac_f32_e32 v208, v200, v200
	v_fmac_f32_e32 v209, v201, v201
	v_fmac_f32_e32 v208, v202, v202
	v_fmac_f32_e32 v209, v203, v203
	v_lshlrev_b32_e32 v204, 16, v102
	v_and_b32_e32 v205, 0xffff0000, v102
	v_lshlrev_b32_e32 v206, 16, v103
	v_and_b32_e32 v207, 0xffff0000, v103
	v_fmac_f32_e32 v210, v204, v204
	v_fmac_f32_e32 v211, v205, v205
	v_fmac_f32_e32 v210, v206, v206
	v_fmac_f32_e32 v211, v207, v207
	v_lshlrev_b32_e32 v200, 16, v72
	v_and_b32_e32 v201, 0xffff0000, v72
	v_lshlrev_b32_e32 v202, 16, v73
	v_and_b32_e32 v203, 0xffff0000, v73
	v_fmac_f32_e32 v208, v200, v200
	v_fmac_f32_e32 v209, v201, v201
	v_fmac_f32_e32 v208, v202, v202
	v_fmac_f32_e32 v209, v203, v203
	v_lshlrev_b32_e32 v204, 16, v104
	v_and_b32_e32 v205, 0xffff0000, v104
	v_lshlrev_b32_e32 v206, 16, v105
	v_and_b32_e32 v207, 0xffff0000, v105
	v_fmac_f32_e32 v210, v204, v204
	v_fmac_f32_e32 v211, v205, v205
; __device__ __forceinline__ float bf_lo(unsigned w) { return __uint_as_float(w << 16); }
; __device__ __forceinline__ float bf_hi(unsigned w) { return __uint_as_float(w & 0xffff0000u); }
; __global__ void __launch_bounds__(NWAVES * 64, 2) mk_fwd(Args args) {
;     ...
;                 float sy = 0.f;
; #pragma unroll
;                 for (int j = 0; j < 8; ++j) { const float a = bf_lo(yw[q][j].x), b = bf_hi(yw[q][j].x), c2 = bf_lo(yw[q][j].y), d = bf_hi(yw[q][j].y); sy += (a * a + b * b) + (c2 * c2 + d * d); }
;                 const float rsy = __builtin_amdgcn_rsqf(wave_sum(sy) * (1.f / DM) + EPS);
; #pragma unroll
;                 for (int j = 0; j < 8; ++j) { const int col = 4 * F.lane + 256 * j;
;                     const f32x4 y4 = (f32x4){bf_lo(yw[q][j].x), bf_hi(yw[q][j].x), bf_lo(yw[q][j].y), bf_hi(yw[q][j].y)};
;                     *(f32x4*)(args.out + (size_t)row * DM + col) = v[q][j] + PA[j] * (y4 * rsy); }
	v_fmac_f32_e32 v210, v206, v206
	v_fmac_f32_e32 v211, v207, v207
	v_lshlrev_b32_e32 v200, 16, v74
	v_and_b32_e32 v201, 0xffff0000, v74
	v_lshlrev_b32_e32 v202, 16, v75
	v_and_b32_e32 v203, 0xffff0000, v75
	v_fmac_f32_e32 v208, v200, v200
	v_fmac_f32_e32 v209, v201, v201
	v_fmac_f32_e32 v208, v202, v202
	v_fmac_f32_e32 v209, v203, v203
	v_lshlrev_b32_e32 v204, 16, v106
	v_and_b32_e32 v205, 0xffff0000, v106
	v_lshlrev_b32_e32 v206, 16, v107
	v_and_b32_e32 v207, 0xffff0000, v107
	v_fmac_f32_e32 v210, v204, v204
	v_fmac_f32_e32 v211, v205, v205
	v_fmac_f32_e32 v210, v206, v206
	v_fmac_f32_e32 v211, v207, v207
	v_lshlrev_b32_e32 v200, 16, v76
	v_and_b32_e32 v201, 0xffff0000, v76
	v_lshlrev_b32_e32 v202, 16, v77
	v_and_b32_e32 v203, 0xffff0000, v77
	v_fmac_f32_e32 v208, v200, v200
	v_fmac_f32_e32 v209, v201, v201
	v_fmac_f32_e32 v208, v202, v202
	v_fmac_f32_e32 v209, v203, v203
	v_lshlrev_b32_e32 v204, 16, v108
	v_and_b32_e32 v205, 0xffff0000, v108
	v_lshlrev_b32_e32 v206, 16, v109
	v_and_b32_e32 v207, 0xffff0000, v109
	v_fmac_f32_e32 v210, v204, v204
	v_fmac_f32_e32 v211, v205, v205
	v_fmac_f32_e32 v210, v206, v206
	v_fmac_f32_e32 v211, v207, v207
	v_lshlrev_b32_e32 v200, 16, v78
	v_and_b32_e32 v201, 0xffff0000, v78
	v_lshlrev_b32_e32 v202, 16, v79
	v_and_b32_e32 v203, 0xffff0000, v79
	v_fmac_f32_e32 v208, v200, v200
	v_fmac_f32_e32 v209, v201, v201
	v_fmac_f32_e32 v208, v202, v202
	v_fmac_f32_e32 v209, v203, v203
	v_lshlrev_b32_e32 v204, 16, v110
	v_and_b32_e32 v205, 0xffff0000, v110
	v_lshlrev_b32_e32 v206, 16, v111
	v_and_b32_e32 v207, 0xffff0000, v111
	v_fmac_f32_e32 v210, v204, v204
	v_fmac_f32_e32 v211, v205, v205
	v_fmac_f32_e32 v210, v206, v206
	v_fmac_f32_e32 v211, v207, v207
	v_add_f32_e32 v208, v208, v209
	v_add_f32_e32 v210, v210, v211
	s_nop 0
	v_add_f32_dpp v212, v208, v208 quad_perm:[1,0,3,2] row_mask:0xf bank_mask:0xf
	v_add_f32_dpp v213, v210, v210 quad_perm:[1,0,3,2] row_mask:0xf bank_mask:0xf
	s_nop 0
	v_add_f32_dpp v212, v212, v212 quad_perm:[2,3,0,1] row_mask:0xf bank_mask:0xf
	v_add_f32_dpp v213, v213, v213 quad_perm:[2,3,0,1] row_mask:0xf bank_mask:0xf
	s_nop 0
	v_add_f32_dpp v212, v212, v212 row_half_mirror row_mask:0xf bank_mask:0xf
	v_add_f32_dpp v213, v213, v213 row_half_mirror row_mask:0xf bank_mask:0xf
	s_nop 0
	v_add_f32_dpp v212, v212, v212 row_mirror row_mask:0xf bank_mask:0xf
	v_add_f32_dpp v213, v213, v213 row_mirror row_mask:0xf bank_mask:0xf
	s_nop 0
	v_readlane_b32 s4, v212, 0
	v_readlane_b32 s5, v212, 16
	v_readlane_b32 s6, v212, 32
	v_readlane_b32 s7, v212, 48
	v_readlane_b32 s24, v213, 0
	v_readlane_b32 s25, v213, 16
	v_readlane_b32 s26, v213, 32
	v_readlane_b32 s27, v213, 48
	s_nop 1
	v_mov_b32_e32 v214, s4
	v_mov_b32_e32 v215, s24
	v_add_f32_e32 v214, s5, v214
	v_add_f32_e32 v215, s25, v215
	v_add_f32_e32 v214, s6, v214
	v_add_f32_e32 v215, s26, v215
	v_add_f32_e32 v214, s7, v214
	v_add_f32_e32 v215, s27, v215
	v_fmamk_f32 v214, v214, 0x3a000000, v195
	v_fmamk_f32 v215, v215, 0x3a000000, v195
	v_rsq_f32_e32 v214, v214
	v_rsq_f32_e32 v215, v215
	s_nop 0
	v_lshlrev_b32_e32 v200, 16, v64
	v_and_b32_e32 v201, 0xffff0000, v64
	v_lshlrev_b32_e32 v202, 16, v65
	v_and_b32_e32 v203, 0xffff0000, v65
	v_lshlrev_b32_e32 v204, 16, v96
	v_and_b32_e32 v205, 0xffff0000, v96
	v_lshlrev_b32_e32 v206, 16, v97
	v_and_b32_e32 v207, 0xffff0000, v97
	v_mul_f32_e32 v200, v214, v200
	v_mul_f32_e32 v201, v214, v201
	v_mul_f32_e32 v202, v214, v202
	v_mul_f32_e32 v203, v214, v203
	v_mul_f32_e32 v204, v215, v204
	v_mul_f32_e32 v205, v215, v205
	v_mul_f32_e32 v206, v215, v206
	v_mul_f32_e32 v207, v215, v207
	v_fmac_f32_e32 v0, v128, v200
	v_fmac_f32_e32 v1, v129, v201
	v_fmac_f32_e32 v2, v130, v202
	v_fmac_f32_e32 v3, v131, v203
	v_fmac_f32_e32 v0, v160, v204
	v_fmac_f32_e32 v1, v161, v205
	v_fmac_f32_e32 v2, v162, v206
	v_fmac_f32_e32 v3, v163, v207
	global_store_dwordx4 v192, v[0:3], s[18:19] offset:0 nt
	v_lshlrev_b32_e32 v200, 16, v66
	v_and_b32_e32 v201, 0xffff0000, v66
	v_lshlrev_b32_e32 v202, 16, v67
	v_and_b32_e32 v203, 0xffff0000, v67
	v_lshlrev_b32_e32 v204, 16, v98
	v_and_b32_e32 v205, 0xffff0000, v98
	v_lshlrev_b32_e32 v206, 16, v99
	v_and_b32_e32 v207, 0xffff0000, v99
	v_mul_f32_e32 v200, v214, v200
	v_mul_f32_e32 v201, v214, v201
	v_mul_f32_e32 v202, v214, v202
	v_mul_f32_e32 v203, v214, v203
	v_mul_f32_e32 v204, v215, v204
	v_mul_f32_e32 v205, v215, v205
	v_mul_f32_e32 v206, v215, v206
	v_mul_f32_e32 v207, v215, v207
	v_fmac_f32_e32 v4, v132, v200
	v_fmac_f32_e32 v5, v133, v201
	v_fmac_f32_e32 v6, v134, v202
	v_fmac_f32_e32 v7, v135, v203
	v_fmac_f32_e32 v4, v164, v204
	v_fmac_f32_e32 v5, v165, v205
	v_fmac_f32_e32 v6, v166, v206
	v_fmac_f32_e32 v7, v167, v207
	global_store_dwordx4 v192, v[4:7], s[18:19] offset:1024 nt
	v_lshlrev_b32_e32 v200, 16, v68
	v_and_b32_e32 v201, 0xffff0000, v68
	v_lshlrev_b32_e32 v202, 16, v69
	v_and_b32_e32 v203, 0xffff0000, v69
	v_lshlrev_b32_e32 v204, 16, v100
	v_and_b32_e32 v205, 0xffff0000, v100
	v_lshlrev_b32_e32 v206, 16, v101
	v_and_b32_e32 v207, 0xffff0000, v101
	v_mul_f32_e32 v200, v214, v200
	v_mul_f32_e32 v201, v214, v201
	v_mul_f32_e32 v202, v214, v202
	v_mul_f32_e32 v203, v214, v203
	v_mul_f32_e32 v204, v215, v204
	v_mul_f32_e32 v205, v215, v205
	v_mul_f32_e32 v206, v215, v206
	v_mul_f32_e32 v207, v215, v207
	v_fmac_f32_e32 v8, v136, v200
	v_fmac_f32_e32 v9, v137, v201
	v_fmac_f32_e32 v10, v138, v202
	v_fmac_f32_e32 v11, v139, v203
	v_fmac_f32_e32 v8, v168, v204
	v_fmac_f32_e32 v9, v169, v205
	v_fmac_f32_e32 v10, v170, v206
	v_fmac_f32_e32 v11, v171, v207
	global_store_dwordx4 v192, v[8:11], s[18:19] offset:2048 nt
	v_lshlrev_b32_e32 v200, 16, v70
	v_and_b32_e32 v201, 0xffff0000, v70
; __device__ __forceinline__ float bf_lo(unsigned w) { return __uint_as_float(w << 16); }
; __device__ __forceinline__ float bf_hi(unsigned w) { return __uint_as_float(w & 0xffff0000u); }
; __global__ void __launch_bounds__(NWAVES * 64, 2) mk_fwd(Args args) {
;     ...
;         for (int row0 = rbeg; row0 < rbeg + per2 && row0 < ML; row0 += 2) {
;             f32x4 v[2][8]; u32x2 yw[2][8];
; #pragma unroll
;             for (int q = 0; q < 2; ++q) { const int row = row0 + q; load_row_f32(args.out + (size_t)row * DM, F.lane, v[q]);
;                 const bf16_t* yr = Y + (size_t)row * DM;
; #pragma unroll
;                 for (int j = 0; j < 8; ++j) yw[q][j] = *(const u32x2*)(yr + 4 * F.lane + 256 * j); }
;     ...
;                 for (int j = 0; j < 8; ++j) { const int col = 4 * F.lane + 256 * j;
;                     const f32x4 y4 = (f32x4){bf_lo(yw[q][j].x), bf_hi(yw[q][j].x), bf_lo(yw[q][j].y), bf_hi(yw[q][j].y)};
;                     *(f32x4*)(args.out + (size_t)row * DM + col) = v[q][j] + PA[j] * (y4 * rsy); }
	v_lshlrev_b32_e32 v202, 16, v71
	v_and_b32_e32 v203, 0xffff0000, v71
	v_lshlrev_b32_e32 v204, 16, v102
	v_and_b32_e32 v205, 0xffff0000, v102
	v_lshlrev_b32_e32 v206, 16, v103
	v_and_b32_e32 v207, 0xffff0000, v103
	v_mul_f32_e32 v200, v214, v200
	v_mul_f32_e32 v201, v214, v201
	v_mul_f32_e32 v202, v214, v202
	v_mul_f32_e32 v203, v214, v203
	v_mul_f32_e32 v204, v215, v204
	v_mul_f32_e32 v205, v215, v205
	v_mul_f32_e32 v206, v215, v206
	v_mul_f32_e32 v207, v215, v207
	v_fmac_f32_e32 v12, v140, v200
	v_fmac_f32_e32 v13, v141, v201
	v_fmac_f32_e32 v14, v142, v202
	v_fmac_f32_e32 v15, v143, v203
	v_fmac_f32_e32 v12, v172, v204
	v_fmac_f32_e32 v13, v173, v205
	v_fmac_f32_e32 v14, v174, v206
	v_fmac_f32_e32 v15, v175, v207
	global_store_dwordx4 v192, v[12:15], s[18:19] offset:3072 nt
	v_lshlrev_b32_e32 v200, 16, v72
	v_and_b32_e32 v201, 0xffff0000, v72
	v_lshlrev_b32_e32 v202, 16, v73
	v_and_b32_e32 v203, 0xffff0000, v73
	v_lshlrev_b32_e32 v204, 16, v104
	v_and_b32_e32 v205, 0xffff0000, v104
	v_lshlrev_b32_e32 v206, 16, v105
	v_and_b32_e32 v207, 0xffff0000, v105
	v_mul_f32_e32 v200, v214, v200
	v_mul_f32_e32 v201, v214, v201
	v_mul_f32_e32 v202, v214, v202
	v_mul_f32_e32 v203, v214, v203
	v_mul_f32_e32 v204, v215, v204
	v_mul_f32_e32 v205, v215, v205
	v_mul_f32_e32 v206, v215, v206
	v_mul_f32_e32 v207, v215, v207
	v_fmac_f32_e32 v16, v144, v200
	v_fmac_f32_e32 v17, v145, v201
	v_fmac_f32_e32 v18, v146, v202
	v_fmac_f32_e32 v19, v147, v203
	v_fmac_f32_e32 v16, v176, v204
	v_fmac_f32_e32 v17, v177, v205
	v_fmac_f32_e32 v18, v178, v206
	v_fmac_f32_e32 v19, v179, v207
	global_store_dwordx4 v193, v[16:19], s[18:19] offset:0 nt
	v_lshlrev_b32_e32 v200, 16, v74
	v_and_b32_e32 v201, 0xffff0000, v74
	v_lshlrev_b32_e32 v202, 16, v75
	v_and_b32_e32 v203, 0xffff0000, v75
	v_lshlrev_b32_e32 v204, 16, v106
	v_and_b32_e32 v205, 0xffff0000, v106
	v_lshlrev_b32_e32 v206, 16, v107
	v_and_b32_e32 v207, 0xffff0000, v107
	v_mul_f32_e32 v200, v214, v200
	v_mul_f32_e32 v201, v214, v201
	v_mul_f32_e32 v202, v214, v202
	v_mul_f32_e32 v203, v214, v203
	v_mul_f32_e32 v204, v215, v204
	v_mul_f32_e32 v205, v215, v205
	v_mul_f32_e32 v206, v215, v206
	v_mul_f32_e32 v207, v215, v207
	v_fmac_f32_e32 v20, v148, v200
	v_fmac_f32_e32 v21, v149, v201
	v_fmac_f32_e32 v22, v150, v202
	v_fmac_f32_e32 v23, v151, v203
	v_fmac_f32_e32 v20, v180, v204
	v_fmac_f32_e32 v21, v181, v205
	v_fmac_f32_e32 v22, v182, v206
	v_fmac_f32_e32 v23, v183, v207
	global_store_dwordx4 v193, v[20:23], s[18:19] offset:1024 nt
	v_lshlrev_b32_e32 v200, 16, v76
	v_and_b32_e32 v201, 0xffff0000, v76
	v_lshlrev_b32_e32 v202, 16, v77
	v_and_b32_e32 v203, 0xffff0000, v77
	v_lshlrev_b32_e32 v204, 16, v108
	v_and_b32_e32 v205, 0xffff0000, v108
	v_lshlrev_b32_e32 v206, 16, v109
	v_and_b32_e32 v207, 0xffff0000, v109
	v_mul_f32_e32 v200, v214, v200
	v_mul_f32_e32 v201, v214, v201
	v_mul_f32_e32 v202, v214, v202
	v_mul_f32_e32 v203, v214, v203
	v_mul_f32_e32 v204, v215, v204
	v_mul_f32_e32 v205, v215, v205
	v_mul_f32_e32 v206, v215, v206
	v_mul_f32_e32 v207, v215, v207
	v_fmac_f32_e32 v24, v152, v200
	v_fmac_f32_e32 v25, v153, v201
	v_fmac_f32_e32 v26, v154, v202
	v_fmac_f32_e32 v27, v155, v203
	v_fmac_f32_e32 v24, v184, v204
	v_fmac_f32_e32 v25, v185, v205
	v_fmac_f32_e32 v26, v186, v206
	v_fmac_f32_e32 v27, v187, v207
	global_store_dwordx4 v193, v[24:27], s[18:19] offset:2048 nt
	v_lshlrev_b32_e32 v200, 16, v78
	v_and_b32_e32 v201, 0xffff0000, v78
	v_lshlrev_b32_e32 v202, 16, v79
	v_and_b32_e32 v203, 0xffff0000, v79
	v_lshlrev_b32_e32 v204, 16, v110
	v_and_b32_e32 v205, 0xffff0000, v110
	v_lshlrev_b32_e32 v206, 16, v111
	v_and_b32_e32 v207, 0xffff0000, v111
	v_mul_f32_e32 v200, v214, v200
	v_mul_f32_e32 v201, v214, v201
	v_mul_f32_e32 v202, v214, v202
	v_mul_f32_e32 v203, v214, v203
	v_mul_f32_e32 v204, v215, v204
	v_mul_f32_e32 v205, v215, v205
	v_mul_f32_e32 v206, v215, v206
	v_mul_f32_e32 v207, v215, v207
	v_fmac_f32_e32 v28, v156, v200
	v_fmac_f32_e32 v29, v157, v201
	v_fmac_f32_e32 v30, v158, v202
	v_fmac_f32_e32 v31, v159, v203
	v_fmac_f32_e32 v28, v188, v204
	v_fmac_f32_e32 v29, v189, v205
	v_fmac_f32_e32 v30, v190, v206
	v_fmac_f32_e32 v31, v191, v207
	global_store_dwordx4 v193, v[28:31], s[18:19] offset:3072 nt
	s_add_u32 s18, s18, 0x2000
	s_addc_u32 s19, s19, 0
	global_load_dwordx4 v[0:3], v192, s[14:15] offset:0 nt
	global_load_dwordx4 v[4:7], v192, s[14:15] offset:1024 nt
	global_load_dwordx4 v[8:11], v192, s[14:15] offset:2048 nt
	global_load_dwordx4 v[12:15], v192, s[14:15] offset:3072 nt
	global_load_dwordx4 v[16:19], v193, s[14:15] offset:0 nt
	global_load_dwordx4 v[20:23], v193, s[14:15] offset:1024 nt
	global_load_dwordx4 v[24:27], v193, s[14:15] offset:2048 nt
	global_load_dwordx4 v[28:31], v193, s[14:15] offset:3072 nt
	global_load_dwordx2 v[64:65], v194, s[16:17] offset:0 nt
	global_load_dwordx2 v[66:67], v194, s[16:17] offset:512 nt
	global_load_dwordx2 v[68:69], v194, s[16:17] offset:1024 nt
	global_load_dwordx2 v[70:71], v194, s[16:17] offset:1536 nt
	global_load_dwordx2 v[72:73], v194, s[16:17] offset:2048 nt
	global_load_dwordx2 v[74:75], v194, s[16:17] offset:2560 nt
	global_load_dwordx2 v[76:77], v194, s[16:17] offset:3072 nt
	global_load_dwordx2 v[78:79], v194, s[16:17] offset:3584 nt
	global_load_dwordx2 v[96:97], v194, s[22:23] offset:0 nt
	global_load_dwordx2 v[98:99], v194, s[22:23] offset:512 nt
	global_load_dwordx2 v[100:101], v194, s[22:23] offset:1024 nt
	global_load_dwordx2 v[102:103], v194, s[22:23] offset:1536 nt
	global_load_dwordx2 v[104:105], v194, s[22:23] offset:2048 nt
	global_load_dwordx2 v[106:107], v194, s[22:23] offset:2560 nt
	global_load_dwordx2 v[108:109], v194, s[22:23] offset:3072 nt
	global_load_dwordx2 v[110:111], v194, s[22:23] offset:3584 nt
	s_add_u32 s14, s14, 0x2000
	s_addc_u32 s15, s15, 0
	s_add_u32 s16, s16, 0x1000
	s_addc_u32 s17, s17, 0
	s_add_u32 s22, s22, 0x1000
	s_addc_u32 s23, s23, 0
	s_waitcnt vmcnt(32)
; __device__ __forceinline__ float bf_lo(unsigned w) { return __uint_as_float(w << 16); }
; __device__ __forceinline__ float bf_hi(unsigned w) { return __uint_as_float(w & 0xffff0000u); }
; __global__ void __launch_bounds__(NWAVES * 64, 2) mk_fwd(Args args) {
;     ...
;                 float sy = 0.f;
; #pragma unroll
;                 for (int j = 0; j < 8; ++j) { const float a = bf_lo(yw[q][j].x), b = bf_hi(yw[q][j].x), c2 = bf_lo(yw[q][j].y), d = bf_hi(yw[q][j].y); sy += (a * a + b * b) + (c2 * c2 + d * d); }
;                 const float rsy = __builtin_amdgcn_rsqf(wave_sum(sy) * (1.f / DM) + EPS);
	v_lshlrev_b32_e32 v200, 16, v80
	v_and_b32_e32 v201, 0xffff0000, v80
	v_lshlrev_b32_e32 v202, 16, v81
	v_and_b32_e32 v203, 0xffff0000, v81
	v_mul_f32_e32 v208, v200, v200
	v_mul_f32_e32 v209, v201, v201
	v_fmac_f32_e32 v208, v202, v202
	v_fmac_f32_e32 v209, v203, v203
	v_lshlrev_b32_e32 v204, 16, v112
	v_and_b32_e32 v205, 0xffff0000, v112
	v_lshlrev_b32_e32 v206, 16, v113
	v_and_b32_e32 v207, 0xffff0000, v113
	v_mul_f32_e32 v210, v204, v204
	v_mul_f32_e32 v211, v205, v205
	v_fmac_f32_e32 v210, v206, v206
	v_fmac_f32_e32 v211, v207, v207
	v_lshlrev_b32_e32 v200, 16, v82
	v_and_b32_e32 v201, 0xffff0000, v82
	v_lshlrev_b32_e32 v202, 16, v83
	v_and_b32_e32 v203, 0xffff0000, v83
	v_fmac_f32_e32 v208, v200, v200
	v_fmac_f32_e32 v209, v201, v201
	v_fmac_f32_e32 v208, v202, v202
	v_fmac_f32_e32 v209, v203, v203
	v_lshlrev_b32_e32 v204, 16, v114
	v_and_b32_e32 v205, 0xffff0000, v114
	v_lshlrev_b32_e32 v206, 16, v115
	v_and_b32_e32 v207, 0xffff0000, v115
	v_fmac_f32_e32 v210, v204, v204
	v_fmac_f32_e32 v211, v205, v205
	v_fmac_f32_e32 v210, v206, v206
	v_fmac_f32_e32 v211, v207, v207
	v_lshlrev_b32_e32 v200, 16, v84
	v_and_b32_e32 v201, 0xffff0000, v84
	v_lshlrev_b32_e32 v202, 16, v85
	v_and_b32_e32 v203, 0xffff0000, v85
	v_fmac_f32_e32 v208, v200, v200
	v_fmac_f32_e32 v209, v201, v201
	v_fmac_f32_e32 v208, v202, v202
	v_fmac_f32_e32 v209, v203, v203
	v_lshlrev_b32_e32 v204, 16, v116
	v_and_b32_e32 v205, 0xffff0000, v116
	v_lshlrev_b32_e32 v206, 16, v117
	v_and_b32_e32 v207, 0xffff0000, v117
	v_fmac_f32_e32 v210, v204, v204
	v_fmac_f32_e32 v211, v205, v205
	v_fmac_f32_e32 v210, v206, v206
	v_fmac_f32_e32 v211, v207, v207
	v_lshlrev_b32_e32 v200, 16, v86
	v_and_b32_e32 v201, 0xffff0000, v86
	v_lshlrev_b32_e32 v202, 16, v87
	v_and_b32_e32 v203, 0xffff0000, v87
	v_fmac_f32_e32 v208, v200, v200
	v_fmac_f32_e32 v209, v201, v201
	v_fmac_f32_e32 v208, v202, v202
	v_fmac_f32_e32 v209, v203, v203
	v_lshlrev_b32_e32 v204, 16, v118
	v_and_b32_e32 v205, 0xffff0000, v118
	v_lshlrev_b32_e32 v206, 16, v119
	v_and_b32_e32 v207, 0xffff0000, v119
	v_fmac_f32_e32 v210, v204, v204
	v_fmac_f32_e32 v211, v205, v205
	v_fmac_f32_e32 v210, v206, v206
	v_fmac_f32_e32 v211, v207, v207
	v_lshlrev_b32_e32 v200, 16, v88
	v_and_b32_e32 v201, 0xffff0000, v88
	v_lshlrev_b32_e32 v202, 16, v89
	v_and_b32_e32 v203, 0xffff0000, v89
	v_fmac_f32_e32 v208, v200, v200
	v_fmac_f32_e32 v209, v201, v201
	v_fmac_f32_e32 v208, v202, v202
	v_fmac_f32_e32 v209, v203, v203
	v_lshlrev_b32_e32 v204, 16, v120
	v_and_b32_e32 v205, 0xffff0000, v120
	v_lshlrev_b32_e32 v206, 16, v121
	v_and_b32_e32 v207, 0xffff0000, v121
	v_fmac_f32_e32 v210, v204, v204
	v_fmac_f32_e32 v211, v205, v205
	v_fmac_f32_e32 v210, v206, v206
	v_fmac_f32_e32 v211, v207, v207
	v_lshlrev_b32_e32 v200, 16, v90
	v_and_b32_e32 v201, 0xffff0000, v90
	v_lshlrev_b32_e32 v202, 16, v91
	v_and_b32_e32 v203, 0xffff0000, v91
	v_fmac_f32_e32 v208, v200, v200
	v_fmac_f32_e32 v209, v201, v201
	v_fmac_f32_e32 v208, v202, v202
	v_fmac_f32_e32 v209, v203, v203
	v_lshlrev_b32_e32 v204, 16, v122
	v_and_b32_e32 v205, 0xffff0000, v122
	v_lshlrev_b32_e32 v206, 16, v123
	v_and_b32_e32 v207, 0xffff0000, v123
	v_fmac_f32_e32 v210, v204, v204
	v_fmac_f32_e32 v211, v205, v205
	v_fmac_f32_e32 v210, v206, v206
	v_fmac_f32_e32 v211, v207, v207
	v_lshlrev_b32_e32 v200, 16, v92
	v_and_b32_e32 v201, 0xffff0000, v92
	v_lshlrev_b32_e32 v202, 16, v93
	v_and_b32_e32 v203, 0xffff0000, v93
	v_fmac_f32_e32 v208, v200, v200
	v_fmac_f32_e32 v209, v201, v201
	v_fmac_f32_e32 v208, v202, v202
	v_fmac_f32_e32 v209, v203, v203
	v_lshlrev_b32_e32 v204, 16, v124
	v_and_b32_e32 v205, 0xffff0000, v124
	v_lshlrev_b32_e32 v206, 16, v125
	v_and_b32_e32 v207, 0xffff0000, v125
	v_fmac_f32_e32 v210, v204, v204
	v_fmac_f32_e32 v211, v205, v205
	v_fmac_f32_e32 v210, v206, v206
	v_fmac_f32_e32 v211, v207, v207
	v_lshlrev_b32_e32 v200, 16, v94
	v_and_b32_e32 v201, 0xffff0000, v94
	v_lshlrev_b32_e32 v202, 16, v95
	v_and_b32_e32 v203, 0xffff0000, v95
	v_fmac_f32_e32 v208, v200, v200
	v_fmac_f32_e32 v209, v201, v201
	v_fmac_f32_e32 v208, v202, v202
	v_fmac_f32_e32 v209, v203, v203
	v_lshlrev_b32_e32 v204, 16, v126
	v_and_b32_e32 v205, 0xffff0000, v126
	v_lshlrev_b32_e32 v206, 16, v127
	v_and_b32_e32 v207, 0xffff0000, v127
	v_fmac_f32_e32 v210, v204, v204
	v_fmac_f32_e32 v211, v205, v205
	v_fmac_f32_e32 v210, v206, v206
	v_fmac_f32_e32 v211, v207, v207
	v_add_f32_e32 v208, v208, v209
	v_add_f32_e32 v210, v210, v211
	s_nop 0
	v_add_f32_dpp v212, v208, v208 quad_perm:[1,0,3,2] row_mask:0xf bank_mask:0xf
	v_add_f32_dpp v213, v210, v210 quad_perm:[1,0,3,2] row_mask:0xf bank_mask:0xf
	s_nop 0
	v_add_f32_dpp v212, v212, v212 quad_perm:[2,3,0,1] row_mask:0xf bank_mask:0xf
	v_add_f32_dpp v213, v213, v213 quad_perm:[2,3,0,1] row_mask:0xf bank_mask:0xf
	s_nop 0
	v_add_f32_dpp v212, v212, v212 row_half_mirror row_mask:0xf bank_mask:0xf
	v_add_f32_dpp v213, v213, v213 row_half_mirror row_mask:0xf bank_mask:0xf
	s_nop 0
	v_add_f32_dpp v212, v212, v212 row_mirror row_mask:0xf bank_mask:0xf
	v_add_f32_dpp v213, v213, v213 row_mirror row_mask:0xf bank_mask:0xf
	s_nop 0
	v_readlane_b32 s4, v212, 0
	v_readlane_b32 s5, v212, 16
	v_readlane_b32 s6, v212, 32
	v_readlane_b32 s7, v212, 48
	v_readlane_b32 s24, v213, 0
	v_readlane_b32 s25, v213, 16
	v_readlane_b32 s26, v213, 32
	v_readlane_b32 s27, v213, 48
	s_nop 1
	v_mov_b32_e32 v214, s4
	v_mov_b32_e32 v215, s24
	v_add_f32_e32 v214, s5, v214
	v_add_f32_e32 v215, s25, v215
	v_add_f32_e32 v214, s6, v214
	v_add_f32_e32 v215, s26, v215
	v_add_f32_e32 v214, s7, v214
	v_add_f32_e32 v215, s27, v215
	v_fmamk_f32 v214, v214, 0x3a000000, v195
	v_fmamk_f32 v215, v215, 0x3a000000, v195
; __device__ __forceinline__ float bf_lo(unsigned w) { return __uint_as_float(w << 16); }
; __device__ __forceinline__ float bf_hi(unsigned w) { return __uint_as_float(w & 0xffff0000u); }
; __global__ void __launch_bounds__(NWAVES * 64, 2) mk_fwd(Args args) {
;     ...
;                 const float rsy = __builtin_amdgcn_rsqf(wave_sum(sy) * (1.f / DM) + EPS);
; #pragma unroll
;                 for (int j = 0; j < 8; ++j) { const int col = 4 * F.lane + 256 * j;
;                     const f32x4 y4 = (f32x4){bf_lo(yw[q][j].x), bf_hi(yw[q][j].x), bf_lo(yw[q][j].y), bf_hi(yw[q][j].y)};
;                     *(f32x4*)(args.out + (size_t)row * DM + col) = v[q][j] + PA[j] * (y4 * rsy); }
	v_rsq_f32_e32 v214, v214
	v_rsq_f32_e32 v215, v215
	s_nop 0
	v_lshlrev_b32_e32 v200, 16, v80
	v_and_b32_e32 v201, 0xffff0000, v80
	v_lshlrev_b32_e32 v202, 16, v81
	v_and_b32_e32 v203, 0xffff0000, v81
	v_lshlrev_b32_e32 v204, 16, v112
	v_and_b32_e32 v205, 0xffff0000, v112
	v_lshlrev_b32_e32 v206, 16, v113
	v_and_b32_e32 v207, 0xffff0000, v113
	v_mul_f32_e32 v200, v214, v200
	v_mul_f32_e32 v201, v214, v201
	v_mul_f32_e32 v202, v214, v202
	v_mul_f32_e32 v203, v214, v203
	v_mul_f32_e32 v204, v215, v204
	v_mul_f32_e32 v205, v215, v205
	v_mul_f32_e32 v206, v215, v206
	v_mul_f32_e32 v207, v215, v207
	v_fmac_f32_e32 v32, v128, v200
	v_fmac_f32_e32 v33, v129, v201
	v_fmac_f32_e32 v34, v130, v202
	v_fmac_f32_e32 v35, v131, v203
	v_fmac_f32_e32 v32, v160, v204
	v_fmac_f32_e32 v33, v161, v205
	v_fmac_f32_e32 v34, v162, v206
	v_fmac_f32_e32 v35, v163, v207
	global_store_dwordx4 v192, v[32:35], s[18:19] offset:0 nt
	v_lshlrev_b32_e32 v200, 16, v82
	v_and_b32_e32 v201, 0xffff0000, v82
	v_lshlrev_b32_e32 v202, 16, v83
	v_and_b32_e32 v203, 0xffff0000, v83
	v_lshlrev_b32_e32 v204, 16, v114
	v_and_b32_e32 v205, 0xffff0000, v114
	v_lshlrev_b32_e32 v206, 16, v115
	v_and_b32_e32 v207, 0xffff0000, v115
	v_mul_f32_e32 v200, v214, v200
	v_mul_f32_e32 v201, v214, v201
	v_mul_f32_e32 v202, v214, v202
	v_mul_f32_e32 v203, v214, v203
	v_mul_f32_e32 v204, v215, v204
	v_mul_f32_e32 v205, v215, v205
	v_mul_f32_e32 v206, v215, v206
	v_mul_f32_e32 v207, v215, v207
	v_fmac_f32_e32 v36, v132, v200
	v_fmac_f32_e32 v37, v133, v201
	v_fmac_f32_e32 v38, v134, v202
	v_fmac_f32_e32 v39, v135, v203
	v_fmac_f32_e32 v36, v164, v204
	v_fmac_f32_e32 v37, v165, v205
	v_fmac_f32_e32 v38, v166, v206
	v_fmac_f32_e32 v39, v167, v207
	global_store_dwordx4 v192, v[36:39], s[18:19] offset:1024 nt
	v_lshlrev_b32_e32 v200, 16, v84
	v_and_b32_e32 v201, 0xffff0000, v84
	v_lshlrev_b32_e32 v202, 16, v85
	v_and_b32_e32 v203, 0xffff0000, v85
	v_lshlrev_b32_e32 v204, 16, v116
	v_and_b32_e32 v205, 0xffff0000, v116
	v_lshlrev_b32_e32 v206, 16, v117
	v_and_b32_e32 v207, 0xffff0000, v117
	v_mul_f32_e32 v200, v214, v200
	v_mul_f32_e32 v201, v214, v201
	v_mul_f32_e32 v202, v214, v202
	v_mul_f32_e32 v203, v214, v203
	v_mul_f32_e32 v204, v215, v204
	v_mul_f32_e32 v205, v215, v205
	v_mul_f32_e32 v206, v215, v206
	v_mul_f32_e32 v207, v215, v207
	v_fmac_f32_e32 v40, v136, v200
	v_fmac_f32_e32 v41, v137, v201
	v_fmac_f32_e32 v42, v138, v202
	v_fmac_f32_e32 v43, v139, v203
	v_fmac_f32_e32 v40, v168, v204
	v_fmac_f32_e32 v41, v169, v205
	v_fmac_f32_e32 v42, v170, v206
	v_fmac_f32_e32 v43, v171, v207
	global_store_dwordx4 v192, v[40:43], s[18:19] offset:2048 nt
	v_lshlrev_b32_e32 v200, 16, v86
	v_and_b32_e32 v201, 0xffff0000, v86
	v_lshlrev_b32_e32 v202, 16, v87
	v_and_b32_e32 v203, 0xffff0000, v87
	v_lshlrev_b32_e32 v204, 16, v118
	v_and_b32_e32 v205, 0xffff0000, v118
	v_lshlrev_b32_e32 v206, 16, v119
	v_and_b32_e32 v207, 0xffff0000, v119
	v_mul_f32_e32 v200, v214, v200
	v_mul_f32_e32 v201, v214, v201
	v_mul_f32_e32 v202, v214, v202
	v_mul_f32_e32 v203, v214, v203
	v_mul_f32_e32 v204, v215, v204
	v_mul_f32_e32 v205, v215, v205
	v_mul_f32_e32 v206, v215, v206
	v_mul_f32_e32 v207, v215, v207
	v_fmac_f32_e32 v44, v140, v200
	v_fmac_f32_e32 v45, v141, v201
	v_fmac_f32_e32 v46, v142, v202
	v_fmac_f32_e32 v47, v143, v203
	v_fmac_f32_e32 v44, v172, v204
	v_fmac_f32_e32 v45, v173, v205
	v_fmac_f32_e32 v46, v174, v206
	v_fmac_f32_e32 v47, v175, v207
	global_store_dwordx4 v192, v[44:47], s[18:19] offset:3072 nt
	v_lshlrev_b32_e32 v200, 16, v88
	v_and_b32_e32 v201, 0xffff0000, v88
	v_lshlrev_b32_e32 v202, 16, v89
	v_and_b32_e32 v203, 0xffff0000, v89
	v_lshlrev_b32_e32 v204, 16, v120
	v_and_b32_e32 v205, 0xffff0000, v120
	v_lshlrev_b32_e32 v206, 16, v121
	v_and_b32_e32 v207, 0xffff0000, v121
	v_mul_f32_e32 v200, v214, v200
	v_mul_f32_e32 v201, v214, v201
	v_mul_f32_e32 v202, v214, v202
	v_mul_f32_e32 v203, v214, v203
	v_mul_f32_e32 v204, v215, v204
	v_mul_f32_e32 v205, v215, v205
	v_mul_f32_e32 v206, v215, v206
	v_mul_f32_e32 v207, v215, v207
	v_fmac_f32_e32 v48, v144, v200
	v_fmac_f32_e32 v49, v145, v201
	v_fmac_f32_e32 v50, v146, v202
	v_fmac_f32_e32 v51, v147, v203
	v_fmac_f32_e32 v48, v176, v204
	v_fmac_f32_e32 v49, v177, v205
	v_fmac_f32_e32 v50, v178, v206
	v_fmac_f32_e32 v51, v179, v207
	global_store_dwordx4 v193, v[48:51], s[18:19] offset:0 nt
	v_lshlrev_b32_e32 v200, 16, v90
	v_and_b32_e32 v201, 0xffff0000, v90
	v_lshlrev_b32_e32 v202, 16, v91
	v_and_b32_e32 v203, 0xffff0000, v91
	v_lshlrev_b32_e32 v204, 16, v122
	v_and_b32_e32 v205, 0xffff0000, v122
	v_lshlrev_b32_e32 v206, 16, v123
	v_and_b32_e32 v207, 0xffff0000, v123
	v_mul_f32_e32 v200, v214, v200
	v_mul_f32_e32 v201, v214, v201
	v_mul_f32_e32 v202, v214, v202
	v_mul_f32_e32 v203, v214, v203
	v_mul_f32_e32 v204, v215, v204
	v_mul_f32_e32 v205, v215, v205
	v_mul_f32_e32 v206, v215, v206
	v_mul_f32_e32 v207, v215, v207
	v_fmac_f32_e32 v52, v148, v200
	v_fmac_f32_e32 v53, v149, v201
	v_fmac_f32_e32 v54, v150, v202
	v_fmac_f32_e32 v55, v151, v203
	v_fmac_f32_e32 v52, v180, v204
	v_fmac_f32_e32 v53, v181, v205
	v_fmac_f32_e32 v54, v182, v206
	v_fmac_f32_e32 v55, v183, v207
	global_store_dwordx4 v193, v[52:55], s[18:19] offset:1024 nt
	v_lshlrev_b32_e32 v200, 16, v92
	v_and_b32_e32 v201, 0xffff0000, v92
	v_lshlrev_b32_e32 v202, 16, v93
	v_and_b32_e32 v203, 0xffff0000, v93
	v_lshlrev_b32_e32 v204, 16, v124
	v_and_b32_e32 v205, 0xffff0000, v124
	v_lshlrev_b32_e32 v206, 16, v125
	v_and_b32_e32 v207, 0xffff0000, v125
	v_mul_f32_e32 v200, v214, v200
	v_mul_f32_e32 v201, v214, v201
	v_mul_f32_e32 v202, v214, v202
	v_mul_f32_e32 v203, v214, v203
	v_mul_f32_e32 v204, v215, v204
; __device__ __forceinline__ float bf_lo(unsigned w) { return __uint_as_float(w << 16); }
; __device__ __forceinline__ float bf_hi(unsigned w) { return __uint_as_float(w & 0xffff0000u); }
; __global__ void __launch_bounds__(NWAVES * 64, 2) mk_fwd(Args args) {
;     ...
;             for (int q = 0; q < 2; ++q) { const int row = row0 + q; load_row_f32(args.out + (size_t)row * DM, F.lane, v[q]);
;                 const bf16_t* yr = Y + (size_t)row * DM;
; #pragma unroll
;                 for (int j = 0; j < 8; ++j) yw[q][j] = *(const u32x2*)(yr + 4 * F.lane + 256 * j); }
; #pragma unroll
;             for (int q = 0; q < 2; ++q) { const int row = row0 + q; const int r = row / SEQ;
;                 if (r != rcur) { const float* m1 = mod + (size_t)(9 + r) * 6144; rcur = r;
; #pragma unroll
;                     for (int j = 0; j < 8; ++j) { const int col = 4 * F.lane + 256 * j; PA[j] = *(const f32x4*)(m1 + 2 * DM + col) * *(const f32x4*)(post_norm + DM + col); } }
;                 float sy = 0.f;
; #pragma unroll
;                 for (int j = 0; j < 8; ++j) { const float a = bf_lo(yw[q][j].x), b = bf_hi(yw[q][j].x), c2 = bf_lo(yw[q][j].y), d = bf_hi(yw[q][j].y); sy += (a * a + b * b) + (c2 * c2 + d * d); }
;                 const float rsy = __builtin_amdgcn_rsqf(wave_sum(sy) * (1.f / DM) + EPS);
; #pragma unroll
;                 for (int j = 0; j < 8; ++j) { const int col = 4 * F.lane + 256 * j;
;                     const f32x4 y4 = (f32x4){bf_lo(yw[q][j].x), bf_hi(yw[q][j].x), bf_lo(yw[q][j].y), bf_hi(yw[q][j].y)};
;                     *(f32x4*)(args.out + (size_t)row * DM + col) = v[q][j] + PA[j] * (y4 * rsy); }
	v_mul_f32_e32 v205, v215, v205
	v_mul_f32_e32 v206, v215, v206
	v_mul_f32_e32 v207, v215, v207
	v_fmac_f32_e32 v56, v152, v200
	v_fmac_f32_e32 v57, v153, v201
	v_fmac_f32_e32 v58, v154, v202
	v_fmac_f32_e32 v59, v155, v203
	v_fmac_f32_e32 v56, v184, v204
	v_fmac_f32_e32 v57, v185, v205
	v_fmac_f32_e32 v58, v186, v206
	v_fmac_f32_e32 v59, v187, v207
	global_store_dwordx4 v193, v[56:59], s[18:19] offset:2048 nt
	v_lshlrev_b32_e32 v200, 16, v94
	v_and_b32_e32 v201, 0xffff0000, v94
	v_lshlrev_b32_e32 v202, 16, v95
	v_and_b32_e32 v203, 0xffff0000, v95
	v_lshlrev_b32_e32 v204, 16, v126
	v_and_b32_e32 v205, 0xffff0000, v126
	v_lshlrev_b32_e32 v206, 16, v127
	v_and_b32_e32 v207, 0xffff0000, v127
	v_mul_f32_e32 v200, v214, v200
	v_mul_f32_e32 v201, v214, v201
	v_mul_f32_e32 v202, v214, v202
	v_mul_f32_e32 v203, v214, v203
	v_mul_f32_e32 v204, v215, v204
	v_mul_f32_e32 v205, v215, v205
	v_mul_f32_e32 v206, v215, v206
	v_mul_f32_e32 v207, v215, v207
	v_fmac_f32_e32 v60, v156, v200
	v_fmac_f32_e32 v61, v157, v201
	v_fmac_f32_e32 v62, v158, v202
	v_fmac_f32_e32 v63, v159, v203
	v_fmac_f32_e32 v60, v188, v204
	v_fmac_f32_e32 v61, v189, v205
	v_fmac_f32_e32 v62, v190, v206
	v_fmac_f32_e32 v63, v191, v207
	global_store_dwordx4 v193, v[60:63], s[18:19] offset:3072 nt
	s_add_u32 s18, s18, 0x2000
	s_addc_u32 s19, s19, 0
	global_load_dwordx4 v[32:35], v192, s[14:15] offset:0 nt
	global_load_dwordx4 v[36:39], v192, s[14:15] offset:1024 nt
	global_load_dwordx4 v[40:43], v192, s[14:15] offset:2048 nt
	global_load_dwordx4 v[44:47], v192, s[14:15] offset:3072 nt
	global_load_dwordx4 v[48:51], v193, s[14:15] offset:0 nt
	global_load_dwordx4 v[52:55], v193, s[14:15] offset:1024 nt
	global_load_dwordx4 v[56:59], v193, s[14:15] offset:2048 nt
	global_load_dwordx4 v[60:63], v193, s[14:15] offset:3072 nt
	global_load_dwordx2 v[80:81], v194, s[16:17] offset:0 nt
	global_load_dwordx2 v[82:83], v194, s[16:17] offset:512 nt
	global_load_dwordx2 v[84:85], v194, s[16:17] offset:1024 nt
	global_load_dwordx2 v[86:87], v194, s[16:17] offset:1536 nt
	global_load_dwordx2 v[88:89], v194, s[16:17] offset:2048 nt
	global_load_dwordx2 v[90:91], v194, s[16:17] offset:2560 nt
	global_load_dwordx2 v[92:93], v194, s[16:17] offset:3072 nt
	global_load_dwordx2 v[94:95], v194, s[16:17] offset:3584 nt
	global_load_dwordx2 v[112:113], v194, s[22:23] offset:0 nt
	global_load_dwordx2 v[114:115], v194, s[22:23] offset:512 nt
	global_load_dwordx2 v[116:117], v194, s[22:23] offset:1024 nt
	global_load_dwordx2 v[118:119], v194, s[22:23] offset:1536 nt
	global_load_dwordx2 v[120:121], v194, s[22:23] offset:2048 nt
	global_load_dwordx2 v[122:123], v194, s[22:23] offset:2560 nt
	global_load_dwordx2 v[124:125], v194, s[22:23] offset:3072 nt
	global_load_dwordx2 v[126:127], v194, s[22:23] offset:3584 nt
	s_add_u32 s14, s14, 0x2000
	s_addc_u32 s15, s15, 0
	s_add_u32 s16, s16, 0x1000
	s_addc_u32 s17, s17, 0
	s_add_u32 s22, s22, 0x1000
	s_addc_u32 s23, s23, 0
	s_waitcnt vmcnt(32)
	v_lshlrev_b32_e32 v200, 16, v64
	v_and_b32_e32 v201, 0xffff0000, v64
	v_lshlrev_b32_e32 v202, 16, v65
	v_and_b32_e32 v203, 0xffff0000, v65
	v_mul_f32_e32 v208, v200, v200
	v_mul_f32_e32 v209, v201, v201
	v_fmac_f32_e32 v208, v202, v202
	v_fmac_f32_e32 v209, v203, v203
	v_lshlrev_b32_e32 v204, 16, v96
	v_and_b32_e32 v205, 0xffff0000, v96
	v_lshlrev_b32_e32 v206, 16, v97
	v_and_b32_e32 v207, 0xffff0000, v97
	v_mul_f32_e32 v210, v204, v204
	v_mul_f32_e32 v211, v205, v205
	v_fmac_f32_e32 v210, v206, v206
	v_fmac_f32_e32 v211, v207, v207
	v_lshlrev_b32_e32 v200, 16, v66
	v_and_b32_e32 v201, 0xffff0000, v66
	v_lshlrev_b32_e32 v202, 16, v67
	v_and_b32_e32 v203, 0xffff0000, v67
	v_fmac_f32_e32 v208, v200, v200
	v_fmac_f32_e32 v209, v201, v201
	v_fmac_f32_e32 v208, v202, v202
	v_fmac_f32_e32 v209, v203, v203
	v_lshlrev_b32_e32 v204, 16, v98
	v_and_b32_e32 v205, 0xffff0000, v98
	v_lshlrev_b32_e32 v206, 16, v99
	v_and_b32_e32 v207, 0xffff0000, v99
	v_fmac_f32_e32 v210, v204, v204
	v_fmac_f32_e32 v211, v205, v205
	v_fmac_f32_e32 v210, v206, v206
	v_fmac_f32_e32 v211, v207, v207
	v_lshlrev_b32_e32 v200, 16, v68
	v_and_b32_e32 v201, 0xffff0000, v68
	v_lshlrev_b32_e32 v202, 16, v69
	v_and_b32_e32 v203, 0xffff0000, v69
	v_fmac_f32_e32 v208, v200, v200
	v_fmac_f32_e32 v209, v201, v201
	v_fmac_f32_e32 v208, v202, v202
	v_fmac_f32_e32 v209, v203, v203
	v_lshlrev_b32_e32 v204, 16, v100
	v_and_b32_e32 v205, 0xffff0000, v100
	v_lshlrev_b32_e32 v206, 16, v101
	v_and_b32_e32 v207, 0xffff0000, v101
	v_fmac_f32_e32 v210, v204, v204
	v_fmac_f32_e32 v211, v205, v205
	v_fmac_f32_e32 v210, v206, v206
	v_fmac_f32_e32 v211, v207, v207
	v_lshlrev_b32_e32 v200, 16, v70
	v_and_b32_e32 v201, 0xffff0000, v70
	v_lshlrev_b32_e32 v202, 16, v71
	v_and_b32_e32 v203, 0xffff0000, v71
	v_fmac_f32_e32 v208, v200, v200
	v_fmac_f32_e32 v209, v201, v201
	v_fmac_f32_e32 v208, v202, v202
	v_fmac_f32_e32 v209, v203, v203
	v_lshlrev_b32_e32 v204, 16, v102
	v_and_b32_e32 v205, 0xffff0000, v102
	v_lshlrev_b32_e32 v206, 16, v103
	v_and_b32_e32 v207, 0xffff0000, v103
	v_fmac_f32_e32 v210, v204, v204
	v_fmac_f32_e32 v211, v205, v205
	v_fmac_f32_e32 v210, v206, v206
	v_fmac_f32_e32 v211, v207, v207
	v_lshlrev_b32_e32 v200, 16, v72
	v_and_b32_e32 v201, 0xffff0000, v72
	v_lshlrev_b32_e32 v202, 16, v73
	v_and_b32_e32 v203, 0xffff0000, v73
	v_fmac_f32_e32 v208, v200, v200
	v_fmac_f32_e32 v209, v201, v201
	v_fmac_f32_e32 v208, v202, v202
	v_fmac_f32_e32 v209, v203, v203
	v_lshlrev_b32_e32 v204, 16, v104
	v_and_b32_e32 v205, 0xffff0000, v104
	v_lshlrev_b32_e32 v206, 16, v105
	v_and_b32_e32 v207, 0xffff0000, v105
	v_fmac_f32_e32 v210, v204, v204
	v_fmac_f32_e32 v211, v205, v205
; __device__ __forceinline__ float bf_lo(unsigned w) { return __uint_as_float(w << 16); }
; __device__ __forceinline__ float bf_hi(unsigned w) { return __uint_as_float(w & 0xffff0000u); }
; __global__ void __launch_bounds__(NWAVES * 64, 2) mk_fwd(Args args) {
;     ...
;                 float sy = 0.f;
; #pragma unroll
;                 for (int j = 0; j < 8; ++j) { const float a = bf_lo(yw[q][j].x), b = bf_hi(yw[q][j].x), c2 = bf_lo(yw[q][j].y), d = bf_hi(yw[q][j].y); sy += (a * a + b * b) + (c2 * c2 + d * d); }
;                 const float rsy = __builtin_amdgcn_rsqf(wave_sum(sy) * (1.f / DM) + EPS);
; #pragma unroll
;                 for (int j = 0; j < 8; ++j) { const int col = 4 * F.lane + 256 * j;
;                     const f32x4 y4 = (f32x4){bf_lo(yw[q][j].x), bf_hi(yw[q][j].x), bf_lo(yw[q][j].y), bf_hi(yw[q][j].y)};
;                     *(f32x4*)(args.out + (size_t)row * DM + col) = v[q][j] + PA[j] * (y4 * rsy); }
	v_fmac_f32_e32 v210, v206, v206
	v_fmac_f32_e32 v211, v207, v207
	v_lshlrev_b32_e32 v200, 16, v74
	v_and_b32_e32 v201, 0xffff0000, v74
	v_lshlrev_b32_e32 v202, 16, v75
	v_and_b32_e32 v203, 0xffff0000, v75
	v_fmac_f32_e32 v208, v200, v200
	v_fmac_f32_e32 v209, v201, v201
	v_fmac_f32_e32 v208, v202, v202
	v_fmac_f32_e32 v209, v203, v203
	v_lshlrev_b32_e32 v204, 16, v106
	v_and_b32_e32 v205, 0xffff0000, v106
	v_lshlrev_b32_e32 v206, 16, v107
	v_and_b32_e32 v207, 0xffff0000, v107
	v_fmac_f32_e32 v210, v204, v204
	v_fmac_f32_e32 v211, v205, v205
	v_fmac_f32_e32 v210, v206, v206
	v_fmac_f32_e32 v211, v207, v207
	v_lshlrev_b32_e32 v200, 16, v76
	v_and_b32_e32 v201, 0xffff0000, v76
	v_lshlrev_b32_e32 v202, 16, v77
	v_and_b32_e32 v203, 0xffff0000, v77
	v_fmac_f32_e32 v208, v200, v200
	v_fmac_f32_e32 v209, v201, v201
	v_fmac_f32_e32 v208, v202, v202
	v_fmac_f32_e32 v209, v203, v203
	v_lshlrev_b32_e32 v204, 16, v108
	v_and_b32_e32 v205, 0xffff0000, v108
	v_lshlrev_b32_e32 v206, 16, v109
	v_and_b32_e32 v207, 0xffff0000, v109
	v_fmac_f32_e32 v210, v204, v204
	v_fmac_f32_e32 v211, v205, v205
	v_fmac_f32_e32 v210, v206, v206
	v_fmac_f32_e32 v211, v207, v207
	v_lshlrev_b32_e32 v200, 16, v78
	v_and_b32_e32 v201, 0xffff0000, v78
	v_lshlrev_b32_e32 v202, 16, v79
	v_and_b32_e32 v203, 0xffff0000, v79
	v_fmac_f32_e32 v208, v200, v200
	v_fmac_f32_e32 v209, v201, v201
	v_fmac_f32_e32 v208, v202, v202
	v_fmac_f32_e32 v209, v203, v203
	v_lshlrev_b32_e32 v204, 16, v110
	v_and_b32_e32 v205, 0xffff0000, v110
	v_lshlrev_b32_e32 v206, 16, v111
	v_and_b32_e32 v207, 0xffff0000, v111
	v_fmac_f32_e32 v210, v204, v204
	v_fmac_f32_e32 v211, v205, v205
	v_fmac_f32_e32 v210, v206, v206
	v_fmac_f32_e32 v211, v207, v207
	v_add_f32_e32 v208, v208, v209
	v_add_f32_e32 v210, v210, v211
	s_nop 0
	v_add_f32_dpp v212, v208, v208 quad_perm:[1,0,3,2] row_mask:0xf bank_mask:0xf
	v_add_f32_dpp v213, v210, v210 quad_perm:[1,0,3,2] row_mask:0xf bank_mask:0xf
	s_nop 0
	v_add_f32_dpp v212, v212, v212 quad_perm:[2,3,0,1] row_mask:0xf bank_mask:0xf
	v_add_f32_dpp v213, v213, v213 quad_perm:[2,3,0,1] row_mask:0xf bank_mask:0xf
	s_nop 0
	v_add_f32_dpp v212, v212, v212 row_half_mirror row_mask:0xf bank_mask:0xf
	v_add_f32_dpp v213, v213, v213 row_half_mirror row_mask:0xf bank_mask:0xf
	s_nop 0
	v_add_f32_dpp v212, v212, v212 row_mirror row_mask:0xf bank_mask:0xf
	v_add_f32_dpp v213, v213, v213 row_mirror row_mask:0xf bank_mask:0xf
	s_nop 0
	v_readlane_b32 s4, v212, 0
	v_readlane_b32 s5, v212, 16
	v_readlane_b32 s6, v212, 32
	v_readlane_b32 s7, v212, 48
	v_readlane_b32 s24, v213, 0
	v_readlane_b32 s25, v213, 16
	v_readlane_b32 s26, v213, 32
	v_readlane_b32 s27, v213, 48
	s_nop 1
	v_mov_b32_e32 v214, s4
	v_mov_b32_e32 v215, s24
	v_add_f32_e32 v214, s5, v214
	v_add_f32_e32 v215, s25, v215
	v_add_f32_e32 v214, s6, v214
	v_add_f32_e32 v215, s26, v215
	v_add_f32_e32 v214, s7, v214
	v_add_f32_e32 v215, s27, v215
	v_fmamk_f32 v214, v214, 0x3a000000, v195
	v_fmamk_f32 v215, v215, 0x3a000000, v195
	v_rsq_f32_e32 v214, v214
	v_rsq_f32_e32 v215, v215
	s_nop 0
	v_lshlrev_b32_e32 v200, 16, v64
	v_and_b32_e32 v201, 0xffff0000, v64
	v_lshlrev_b32_e32 v202, 16, v65
	v_and_b32_e32 v203, 0xffff0000, v65
	v_lshlrev_b32_e32 v204, 16, v96
	v_and_b32_e32 v205, 0xffff0000, v96
	v_lshlrev_b32_e32 v206, 16, v97
	v_and_b32_e32 v207, 0xffff0000, v97
	v_mul_f32_e32 v200, v214, v200
	v_mul_f32_e32 v201, v214, v201
	v_mul_f32_e32 v202, v214, v202
	v_mul_f32_e32 v203, v214, v203
	v_mul_f32_e32 v204, v215, v204
	v_mul_f32_e32 v205, v215, v205
	v_mul_f32_e32 v206, v215, v206
	v_mul_f32_e32 v207, v215, v207
	v_fmac_f32_e32 v0, v128, v200
	v_fmac_f32_e32 v1, v129, v201
	v_fmac_f32_e32 v2, v130, v202
	v_fmac_f32_e32 v3, v131, v203
	v_fmac_f32_e32 v0, v160, v204
	v_fmac_f32_e32 v1, v161, v205
	v_fmac_f32_e32 v2, v162, v206
	v_fmac_f32_e32 v3, v163, v207
	global_store_dwordx4 v192, v[0:3], s[18:19] offset:0 nt
	v_lshlrev_b32_e32 v200, 16, v66
	v_and_b32_e32 v201, 0xffff0000, v66
	v_lshlrev_b32_e32 v202, 16, v67
	v_and_b32_e32 v203, 0xffff0000, v67
	v_lshlrev_b32_e32 v204, 16, v98
	v_and_b32_e32 v205, 0xffff0000, v98
	v_lshlrev_b32_e32 v206, 16, v99
	v_and_b32_e32 v207, 0xffff0000, v99
	v_mul_f32_e32 v200, v214, v200
	v_mul_f32_e32 v201, v214, v201
	v_mul_f32_e32 v202, v214, v202
	v_mul_f32_e32 v203, v214, v203
	v_mul_f32_e32 v204, v215, v204
	v_mul_f32_e32 v205, v215, v205
	v_mul_f32_e32 v206, v215, v206
	v_mul_f32_e32 v207, v215, v207
	v_fmac_f32_e32 v4, v132, v200
	v_fmac_f32_e32 v5, v133, v201
	v_fmac_f32_e32 v6, v134, v202
	v_fmac_f32_e32 v7, v135, v203
	v_fmac_f32_e32 v4, v164, v204
	v_fmac_f32_e32 v5, v165, v205
	v_fmac_f32_e32 v6, v166, v206
	v_fmac_f32_e32 v7, v167, v207
	global_store_dwordx4 v192, v[4:7], s[18:19] offset:1024 nt
	v_lshlrev_b32_e32 v200, 16, v68
	v_and_b32_e32 v201, 0xffff0000, v68
	v_lshlrev_b32_e32 v202, 16, v69
	v_and_b32_e32 v203, 0xffff0000, v69
	v_lshlrev_b32_e32 v204, 16, v100
	v_and_b32_e32 v205, 0xffff0000, v100
	v_lshlrev_b32_e32 v206, 16, v101
	v_and_b32_e32 v207, 0xffff0000, v101
	v_mul_f32_e32 v200, v214, v200
	v_mul_f32_e32 v201, v214, v201
	v_mul_f32_e32 v202, v214, v202
	v_mul_f32_e32 v203, v214, v203
	v_mul_f32_e32 v204, v215, v204
	v_mul_f32_e32 v205, v215, v205
	v_mul_f32_e32 v206, v215, v206
	v_mul_f32_e32 v207, v215, v207
	v_fmac_f32_e32 v8, v136, v200
	v_fmac_f32_e32 v9, v137, v201
	v_fmac_f32_e32 v10, v138, v202
	v_fmac_f32_e32 v11, v139, v203
	v_fmac_f32_e32 v8, v168, v204
	v_fmac_f32_e32 v9, v169, v205
	v_fmac_f32_e32 v10, v170, v206
	v_fmac_f32_e32 v11, v171, v207
	global_store_dwordx4 v192, v[8:11], s[18:19] offset:2048 nt
	v_lshlrev_b32_e32 v200, 16, v70
	v_and_b32_e32 v201, 0xffff0000, v70
; __device__ __forceinline__ float bf_lo(unsigned w) { return __uint_as_float(w << 16); }
; __device__ __forceinline__ float bf_hi(unsigned w) { return __uint_as_float(w & 0xffff0000u); }
; __global__ void __launch_bounds__(NWAVES * 64, 2) mk_fwd(Args args) {
;     ...
;                 for (int j = 0; j < 8; ++j) { const int col = 4 * F.lane + 256 * j;
;                     const f32x4 y4 = (f32x4){bf_lo(yw[q][j].x), bf_hi(yw[q][j].x), bf_lo(yw[q][j].y), bf_hi(yw[q][j].y)};
;                     *(f32x4*)(args.out + (size_t)row * DM + col) = v[q][j] + PA[j] * (y4 * rsy); }
	v_lshlrev_b32_e32 v202, 16, v71
	v_and_b32_e32 v203, 0xffff0000, v71
	v_lshlrev_b32_e32 v204, 16, v102
	v_and_b32_e32 v205, 0xffff0000, v102
	v_lshlrev_b32_e32 v206, 16, v103
	v_and_b32_e32 v207, 0xffff0000, v103
	v_mul_f32_e32 v200, v214, v200
	v_mul_f32_e32 v201, v214, v201
	v_mul_f32_e32 v202, v214, v202
	v_mul_f32_e32 v203, v214, v203
	v_mul_f32_e32 v204, v215, v204
	v_mul_f32_e32 v205, v215, v205
	v_mul_f32_e32 v206, v215, v206
	v_mul_f32_e32 v207, v215, v207
	v_fmac_f32_e32 v12, v140, v200
	v_fmac_f32_e32 v13, v141, v201
	v_fmac_f32_e32 v14, v142, v202
	v_fmac_f32_e32 v15, v143, v203
	v_fmac_f32_e32 v12, v172, v204
	v_fmac_f32_e32 v13, v173, v205
	v_fmac_f32_e32 v14, v174, v206
	v_fmac_f32_e32 v15, v175, v207
	global_store_dwordx4 v192, v[12:15], s[18:19] offset:3072 nt
	v_lshlrev_b32_e32 v200, 16, v72
	v_and_b32_e32 v201, 0xffff0000, v72
	v_lshlrev_b32_e32 v202, 16, v73
	v_and_b32_e32 v203, 0xffff0000, v73
	v_lshlrev_b32_e32 v204, 16, v104
	v_and_b32_e32 v205, 0xffff0000, v104
	v_lshlrev_b32_e32 v206, 16, v105
	v_and_b32_e32 v207, 0xffff0000, v105
	v_mul_f32_e32 v200, v214, v200
	v_mul_f32_e32 v201, v214, v201
	v_mul_f32_e32 v202, v214, v202
	v_mul_f32_e32 v203, v214, v203
	v_mul_f32_e32 v204, v215, v204
	v_mul_f32_e32 v205, v215, v205
	v_mul_f32_e32 v206, v215, v206
	v_mul_f32_e32 v207, v215, v207
	v_fmac_f32_e32 v16, v144, v200
	v_fmac_f32_e32 v17, v145, v201
	v_fmac_f32_e32 v18, v146, v202
	v_fmac_f32_e32 v19, v147, v203
	v_fmac_f32_e32 v16, v176, v204
	v_fmac_f32_e32 v17, v177, v205
	v_fmac_f32_e32 v18, v178, v206
	v_fmac_f32_e32 v19, v179, v207
	global_store_dwordx4 v193, v[16:19], s[18:19] offset:0 nt
	v_lshlrev_b32_e32 v200, 16, v74
	v_and_b32_e32 v201, 0xffff0000, v74
	v_lshlrev_b32_e32 v202, 16, v75
	v_and_b32_e32 v203, 0xffff0000, v75
	v_lshlrev_b32_e32 v204, 16, v106
	v_and_b32_e32 v205, 0xffff0000, v106
	v_lshlrev_b32_e32 v206, 16, v107
	v_and_b32_e32 v207, 0xffff0000, v107
	v_mul_f32_e32 v200, v214, v200
	v_mul_f32_e32 v201, v214, v201
	v_mul_f32_e32 v202, v214, v202
	v_mul_f32_e32 v203, v214, v203
	v_mul_f32_e32 v204, v215, v204
	v_mul_f32_e32 v205, v215, v205
	v_mul_f32_e32 v206, v215, v206
	v_mul_f32_e32 v207, v215, v207
	v_fmac_f32_e32 v20, v148, v200
	v_fmac_f32_e32 v21, v149, v201
	v_fmac_f32_e32 v22, v150, v202
	v_fmac_f32_e32 v23, v151, v203
	v_fmac_f32_e32 v20, v180, v204
	v_fmac_f32_e32 v21, v181, v205
	v_fmac_f32_e32 v22, v182, v206
	v_fmac_f32_e32 v23, v183, v207
	global_store_dwordx4 v193, v[20:23], s[18:19] offset:1024 nt
	v_lshlrev_b32_e32 v200, 16, v76
	v_and_b32_e32 v201, 0xffff0000, v76
	v_lshlrev_b32_e32 v202, 16, v77
	v_and_b32_e32 v203, 0xffff0000, v77
	v_lshlrev_b32_e32 v204, 16, v108
	v_and_b32_e32 v205, 0xffff0000, v108
	v_lshlrev_b32_e32 v206, 16, v109
	v_and_b32_e32 v207, 0xffff0000, v109
	v_mul_f32_e32 v200, v214, v200
	v_mul_f32_e32 v201, v214, v201
	v_mul_f32_e32 v202, v214, v202
	v_mul_f32_e32 v203, v214, v203
	v_mul_f32_e32 v204, v215, v204
	v_mul_f32_e32 v205, v215, v205
	v_mul_f32_e32 v206, v215, v206
	v_mul_f32_e32 v207, v215, v207
	v_fmac_f32_e32 v24, v152, v200
	v_fmac_f32_e32 v25, v153, v201
	v_fmac_f32_e32 v26, v154, v202
	v_fmac_f32_e32 v27, v155, v203
	v_fmac_f32_e32 v24, v184, v204
	v_fmac_f32_e32 v25, v185, v205
	v_fmac_f32_e32 v26, v186, v206
	v_fmac_f32_e32 v27, v187, v207
	global_store_dwordx4 v193, v[24:27], s[18:19] offset:2048 nt
	v_lshlrev_b32_e32 v200, 16, v78
	v_and_b32_e32 v201, 0xffff0000, v78
	v_lshlrev_b32_e32 v202, 16, v79
	v_and_b32_e32 v203, 0xffff0000, v79
	v_lshlrev_b32_e32 v204, 16, v110
	v_and_b32_e32 v205, 0xffff0000, v110
	v_lshlrev_b32_e32 v206, 16, v111
	v_and_b32_e32 v207, 0xffff0000, v111
	v_mul_f32_e32 v200, v214, v200
	v_mul_f32_e32 v201, v214, v201
	v_mul_f32_e32 v202, v214, v202
	v_mul_f32_e32 v203, v214, v203
	v_mul_f32_e32 v204, v215, v204
	v_mul_f32_e32 v205, v215, v205
	v_mul_f32_e32 v206, v215, v206
	v_mul_f32_e32 v207, v215, v207
	v_fmac_f32_e32 v28, v156, v200
	v_fmac_f32_e32 v29, v157, v201
	v_fmac_f32_e32 v30, v158, v202
	v_fmac_f32_e32 v31, v159, v203
	v_fmac_f32_e32 v28, v188, v204
	v_fmac_f32_e32 v29, v189, v205
	v_fmac_f32_e32 v30, v190, v206
	v_fmac_f32_e32 v31, v191, v207
	global_store_dwordx4 v193, v[28:31], s[18:19] offset:3072 nt
	s_add_u32 s18, s18, 0x2000
	s_addc_u32 s19, s19, 0
	s_waitcnt vmcnt(8)
; __device__ __forceinline__ float bf_lo(unsigned w) { return __uint_as_float(w << 16); }
; __device__ __forceinline__ float bf_hi(unsigned w) { return __uint_as_float(w & 0xffff0000u); }
; __global__ void __launch_bounds__(NWAVES * 64, 2) mk_fwd(Args args) {
;     ...
;                 for (int j = 0; j < 8; ++j) { const float a = bf_lo(yw[q][j].x), b = bf_hi(yw[q][j].x), c2 = bf_lo(yw[q][j].y), d = bf_hi(yw[q][j].y); sy += (a * a + b * b) + (c2 * c2 + d * d); }
;                 const float rsy = __builtin_amdgcn_rsqf(wave_sum(sy) * (1.f / DM) + EPS);
	v_lshlrev_b32_e32 v200, 16, v80
	v_and_b32_e32 v201, 0xffff0000, v80
	v_lshlrev_b32_e32 v202, 16, v81
	v_and_b32_e32 v203, 0xffff0000, v81
	v_mul_f32_e32 v208, v200, v200
	v_mul_f32_e32 v209, v201, v201
	v_fmac_f32_e32 v208, v202, v202
	v_fmac_f32_e32 v209, v203, v203
	v_lshlrev_b32_e32 v204, 16, v112
	v_and_b32_e32 v205, 0xffff0000, v112
	v_lshlrev_b32_e32 v206, 16, v113
	v_and_b32_e32 v207, 0xffff0000, v113
	v_mul_f32_e32 v210, v204, v204
	v_mul_f32_e32 v211, v205, v205
	v_fmac_f32_e32 v210, v206, v206
	v_fmac_f32_e32 v211, v207, v207
	v_lshlrev_b32_e32 v200, 16, v82
	v_and_b32_e32 v201, 0xffff0000, v82
	v_lshlrev_b32_e32 v202, 16, v83
	v_and_b32_e32 v203, 0xffff0000, v83
	v_fmac_f32_e32 v208, v200, v200
	v_fmac_f32_e32 v209, v201, v201
	v_fmac_f32_e32 v208, v202, v202
	v_fmac_f32_e32 v209, v203, v203
	v_lshlrev_b32_e32 v204, 16, v114
	v_and_b32_e32 v205, 0xffff0000, v114
	v_lshlrev_b32_e32 v206, 16, v115
	v_and_b32_e32 v207, 0xffff0000, v115
	v_fmac_f32_e32 v210, v204, v204
	v_fmac_f32_e32 v211, v205, v205
	v_fmac_f32_e32 v210, v206, v206
	v_fmac_f32_e32 v211, v207, v207
	v_lshlrev_b32_e32 v200, 16, v84
	v_and_b32_e32 v201, 0xffff0000, v84
	v_lshlrev_b32_e32 v202, 16, v85
	v_and_b32_e32 v203, 0xffff0000, v85
	v_fmac_f32_e32 v208, v200, v200
	v_fmac_f32_e32 v209, v201, v201
	v_fmac_f32_e32 v208, v202, v202
	v_fmac_f32_e32 v209, v203, v203
	v_lshlrev_b32_e32 v204, 16, v116
	v_and_b32_e32 v205, 0xffff0000, v116
	v_lshlrev_b32_e32 v206, 16, v117
	v_and_b32_e32 v207, 0xffff0000, v117
	v_fmac_f32_e32 v210, v204, v204
	v_fmac_f32_e32 v211, v205, v205
	v_fmac_f32_e32 v210, v206, v206
	v_fmac_f32_e32 v211, v207, v207
	v_lshlrev_b32_e32 v200, 16, v86
	v_and_b32_e32 v201, 0xffff0000, v86
	v_lshlrev_b32_e32 v202, 16, v87
	v_and_b32_e32 v203, 0xffff0000, v87
	v_fmac_f32_e32 v208, v200, v200
	v_fmac_f32_e32 v209, v201, v201
	v_fmac_f32_e32 v208, v202, v202
	v_fmac_f32_e32 v209, v203, v203
	v_lshlrev_b32_e32 v204, 16, v118
	v_and_b32_e32 v205, 0xffff0000, v118
	v_lshlrev_b32_e32 v206, 16, v119
	v_and_b32_e32 v207, 0xffff0000, v119
	v_fmac_f32_e32 v210, v204, v204
	v_fmac_f32_e32 v211, v205, v205
	v_fmac_f32_e32 v210, v206, v206
	v_fmac_f32_e32 v211, v207, v207
	v_lshlrev_b32_e32 v200, 16, v88
	v_and_b32_e32 v201, 0xffff0000, v88
	v_lshlrev_b32_e32 v202, 16, v89
	v_and_b32_e32 v203, 0xffff0000, v89
	v_fmac_f32_e32 v208, v200, v200
	v_fmac_f32_e32 v209, v201, v201
	v_fmac_f32_e32 v208, v202, v202
	v_fmac_f32_e32 v209, v203, v203
	v_lshlrev_b32_e32 v204, 16, v120
	v_and_b32_e32 v205, 0xffff0000, v120
	v_lshlrev_b32_e32 v206, 16, v121
	v_and_b32_e32 v207, 0xffff0000, v121
	v_fmac_f32_e32 v210, v204, v204
	v_fmac_f32_e32 v211, v205, v205
	v_fmac_f32_e32 v210, v206, v206
	v_fmac_f32_e32 v211, v207, v207
	v_lshlrev_b32_e32 v200, 16, v90
	v_and_b32_e32 v201, 0xffff0000, v90
	v_lshlrev_b32_e32 v202, 16, v91
	v_and_b32_e32 v203, 0xffff0000, v91
	v_fmac_f32_e32 v208, v200, v200
	v_fmac_f32_e32 v209, v201, v201
	v_fmac_f32_e32 v208, v202, v202
	v_fmac_f32_e32 v209, v203, v203
	v_lshlrev_b32_e32 v204, 16, v122
	v_and_b32_e32 v205, 0xffff0000, v122
	v_lshlrev_b32_e32 v206, 16, v123
	v_and_b32_e32 v207, 0xffff0000, v123
	v_fmac_f32_e32 v210, v204, v204
	v_fmac_f32_e32 v211, v205, v205
	v_fmac_f32_e32 v210, v206, v206
	v_fmac_f32_e32 v211, v207, v207
	v_lshlrev_b32_e32 v200, 16, v92
	v_and_b32_e32 v201, 0xffff0000, v92
	v_lshlrev_b32_e32 v202, 16, v93
	v_and_b32_e32 v203, 0xffff0000, v93
	v_fmac_f32_e32 v208, v200, v200
	v_fmac_f32_e32 v209, v201, v201
	v_fmac_f32_e32 v208, v202, v202
	v_fmac_f32_e32 v209, v203, v203
	v_lshlrev_b32_e32 v204, 16, v124
	v_and_b32_e32 v205, 0xffff0000, v124
	v_lshlrev_b32_e32 v206, 16, v125
	v_and_b32_e32 v207, 0xffff0000, v125
	v_fmac_f32_e32 v210, v204, v204
	v_fmac_f32_e32 v211, v205, v205
	v_fmac_f32_e32 v210, v206, v206
	v_fmac_f32_e32 v211, v207, v207
	v_lshlrev_b32_e32 v200, 16, v94
	v_and_b32_e32 v201, 0xffff0000, v94
	v_lshlrev_b32_e32 v202, 16, v95
	v_and_b32_e32 v203, 0xffff0000, v95
	v_fmac_f32_e32 v208, v200, v200
	v_fmac_f32_e32 v209, v201, v201
	v_fmac_f32_e32 v208, v202, v202
	v_fmac_f32_e32 v209, v203, v203
	v_lshlrev_b32_e32 v204, 16, v126
	v_and_b32_e32 v205, 0xffff0000, v126
	v_lshlrev_b32_e32 v206, 16, v127
	v_and_b32_e32 v207, 0xffff0000, v127
	v_fmac_f32_e32 v210, v204, v204
	v_fmac_f32_e32 v211, v205, v205
	v_fmac_f32_e32 v210, v206, v206
	v_fmac_f32_e32 v211, v207, v207
	v_add_f32_e32 v208, v208, v209
	v_add_f32_e32 v210, v210, v211
	s_nop 0
	v_add_f32_dpp v212, v208, v208 quad_perm:[1,0,3,2] row_mask:0xf bank_mask:0xf
	v_add_f32_dpp v213, v210, v210 quad_perm:[1,0,3,2] row_mask:0xf bank_mask:0xf
	s_nop 0
	v_add_f32_dpp v212, v212, v212 quad_perm:[2,3,0,1] row_mask:0xf bank_mask:0xf
	v_add_f32_dpp v213, v213, v213 quad_perm:[2,3,0,1] row_mask:0xf bank_mask:0xf
	s_nop 0
	v_add_f32_dpp v212, v212, v212 row_half_mirror row_mask:0xf bank_mask:0xf
	v_add_f32_dpp v213, v213, v213 row_half_mirror row_mask:0xf bank_mask:0xf
	s_nop 0
	v_add_f32_dpp v212, v212, v212 row_mirror row_mask:0xf bank_mask:0xf
	v_add_f32_dpp v213, v213, v213 row_mirror row_mask:0xf bank_mask:0xf
	s_nop 0
	v_readlane_b32 s4, v212, 0
	v_readlane_b32 s5, v212, 16
	v_readlane_b32 s6, v212, 32
	v_readlane_b32 s7, v212, 48
	v_readlane_b32 s24, v213, 0
	v_readlane_b32 s25, v213, 16
	v_readlane_b32 s26, v213, 32
	v_readlane_b32 s27, v213, 48
	s_nop 1
	v_mov_b32_e32 v214, s4
	v_mov_b32_e32 v215, s24
	v_add_f32_e32 v214, s5, v214
	v_add_f32_e32 v215, s25, v215
	v_add_f32_e32 v214, s6, v214
	v_add_f32_e32 v215, s26, v215
	v_add_f32_e32 v214, s7, v214
	v_add_f32_e32 v215, s27, v215
	v_fmamk_f32 v214, v214, 0x3a000000, v195
	v_fmamk_f32 v215, v215, 0x3a000000, v195
; __device__ __forceinline__ float bf_lo(unsigned w) { return __uint_as_float(w << 16); }
; __device__ __forceinline__ float bf_hi(unsigned w) { return __uint_as_float(w & 0xffff0000u); }
; __global__ void __launch_bounds__(NWAVES * 64, 2) mk_fwd(Args args) {
;     ...
;                 const float rsy = __builtin_amdgcn_rsqf(wave_sum(sy) * (1.f / DM) + EPS);
; #pragma unroll
;                 for (int j = 0; j < 8; ++j) { const int col = 4 * F.lane + 256 * j;
;                     const f32x4 y4 = (f32x4){bf_lo(yw[q][j].x), bf_hi(yw[q][j].x), bf_lo(yw[q][j].y), bf_hi(yw[q][j].y)};
;                     *(f32x4*)(args.out + (size_t)row * DM + col) = v[q][j] + PA[j] * (y4 * rsy); }
	v_rsq_f32_e32 v214, v214
	v_rsq_f32_e32 v215, v215
	s_nop 0
	v_lshlrev_b32_e32 v200, 16, v80
	v_and_b32_e32 v201, 0xffff0000, v80
	v_lshlrev_b32_e32 v202, 16, v81
	v_and_b32_e32 v203, 0xffff0000, v81
	v_lshlrev_b32_e32 v204, 16, v112
	v_and_b32_e32 v205, 0xffff0000, v112
	v_lshlrev_b32_e32 v206, 16, v113
	v_and_b32_e32 v207, 0xffff0000, v113
	v_mul_f32_e32 v200, v214, v200
	v_mul_f32_e32 v201, v214, v201
	v_mul_f32_e32 v202, v214, v202
	v_mul_f32_e32 v203, v214, v203
	v_mul_f32_e32 v204, v215, v204
	v_mul_f32_e32 v205, v215, v205
	v_mul_f32_e32 v206, v215, v206
	v_mul_f32_e32 v207, v215, v207
	v_fmac_f32_e32 v32, v128, v200
	v_fmac_f32_e32 v33, v129, v201
	v_fmac_f32_e32 v34, v130, v202
	v_fmac_f32_e32 v35, v131, v203
	v_fmac_f32_e32 v32, v160, v204
	v_fmac_f32_e32 v33, v161, v205
	v_fmac_f32_e32 v34, v162, v206
	v_fmac_f32_e32 v35, v163, v207
	global_store_dwordx4 v192, v[32:35], s[18:19] offset:0 nt
	v_lshlrev_b32_e32 v200, 16, v82
	v_and_b32_e32 v201, 0xffff0000, v82
	v_lshlrev_b32_e32 v202, 16, v83
	v_and_b32_e32 v203, 0xffff0000, v83
	v_lshlrev_b32_e32 v204, 16, v114
	v_and_b32_e32 v205, 0xffff0000, v114
	v_lshlrev_b32_e32 v206, 16, v115
	v_and_b32_e32 v207, 0xffff0000, v115
	v_mul_f32_e32 v200, v214, v200
	v_mul_f32_e32 v201, v214, v201
	v_mul_f32_e32 v202, v214, v202
	v_mul_f32_e32 v203, v214, v203
	v_mul_f32_e32 v204, v215, v204
	v_mul_f32_e32 v205, v215, v205
	v_mul_f32_e32 v206, v215, v206
	v_mul_f32_e32 v207, v215, v207
	v_fmac_f32_e32 v36, v132, v200
	v_fmac_f32_e32 v37, v133, v201
	v_fmac_f32_e32 v38, v134, v202
	v_fmac_f32_e32 v39, v135, v203
	v_fmac_f32_e32 v36, v164, v204
	v_fmac_f32_e32 v37, v165, v205
	v_fmac_f32_e32 v38, v166, v206
	v_fmac_f32_e32 v39, v167, v207
	global_store_dwordx4 v192, v[36:39], s[18:19] offset:1024 nt
	v_lshlrev_b32_e32 v200, 16, v84
	v_and_b32_e32 v201, 0xffff0000, v84
	v_lshlrev_b32_e32 v202, 16, v85
	v_and_b32_e32 v203, 0xffff0000, v85
	v_lshlrev_b32_e32 v204, 16, v116
	v_and_b32_e32 v205, 0xffff0000, v116
	v_lshlrev_b32_e32 v206, 16, v117
	v_and_b32_e32 v207, 0xffff0000, v117
	v_mul_f32_e32 v200, v214, v200
	v_mul_f32_e32 v201, v214, v201
	v_mul_f32_e32 v202, v214, v202
	v_mul_f32_e32 v203, v214, v203
	v_mul_f32_e32 v204, v215, v204
	v_mul_f32_e32 v205, v215, v205
	v_mul_f32_e32 v206, v215, v206
	v_mul_f32_e32 v207, v215, v207
	v_fmac_f32_e32 v40, v136, v200
	v_fmac_f32_e32 v41, v137, v201
	v_fmac_f32_e32 v42, v138, v202
	v_fmac_f32_e32 v43, v139, v203
	v_fmac_f32_e32 v40, v168, v204
	v_fmac_f32_e32 v41, v169, v205
	v_fmac_f32_e32 v42, v170, v206
	v_fmac_f32_e32 v43, v171, v207
	global_store_dwordx4 v192, v[40:43], s[18:19] offset:2048 nt
	v_lshlrev_b32_e32 v200, 16, v86
	v_and_b32_e32 v201, 0xffff0000, v86
	v_lshlrev_b32_e32 v202, 16, v87
	v_and_b32_e32 v203, 0xffff0000, v87
	v_lshlrev_b32_e32 v204, 16, v118
	v_and_b32_e32 v205, 0xffff0000, v118
	v_lshlrev_b32_e32 v206, 16, v119
	v_and_b32_e32 v207, 0xffff0000, v119
	v_mul_f32_e32 v200, v214, v200
	v_mul_f32_e32 v201, v214, v201
	v_mul_f32_e32 v202, v214, v202
	v_mul_f32_e32 v203, v214, v203
	v_mul_f32_e32 v204, v215, v204
	v_mul_f32_e32 v205, v215, v205
	v_mul_f32_e32 v206, v215, v206
	v_mul_f32_e32 v207, v215, v207
	v_fmac_f32_e32 v44, v140, v200
	v_fmac_f32_e32 v45, v141, v201
	v_fmac_f32_e32 v46, v142, v202
	v_fmac_f32_e32 v47, v143, v203
	v_fmac_f32_e32 v44, v172, v204
	v_fmac_f32_e32 v45, v173, v205
	v_fmac_f32_e32 v46, v174, v206
	v_fmac_f32_e32 v47, v175, v207
	global_store_dwordx4 v192, v[44:47], s[18:19] offset:3072 nt
	v_lshlrev_b32_e32 v200, 16, v88
	v_and_b32_e32 v201, 0xffff0000, v88
	v_lshlrev_b32_e32 v202, 16, v89
	v_and_b32_e32 v203, 0xffff0000, v89
	v_lshlrev_b32_e32 v204, 16, v120
	v_and_b32_e32 v205, 0xffff0000, v120
	v_lshlrev_b32_e32 v206, 16, v121
	v_and_b32_e32 v207, 0xffff0000, v121
	v_mul_f32_e32 v200, v214, v200
	v_mul_f32_e32 v201, v214, v201
	v_mul_f32_e32 v202, v214, v202
	v_mul_f32_e32 v203, v214, v203
	v_mul_f32_e32 v204, v215, v204
	v_mul_f32_e32 v205, v215, v205
	v_mul_f32_e32 v206, v215, v206
	v_mul_f32_e32 v207, v215, v207
	v_fmac_f32_e32 v48, v144, v200
	v_fmac_f32_e32 v49, v145, v201
	v_fmac_f32_e32 v50, v146, v202
	v_fmac_f32_e32 v51, v147, v203
	v_fmac_f32_e32 v48, v176, v204
	v_fmac_f32_e32 v49, v177, v205
	v_fmac_f32_e32 v50, v178, v206
	v_fmac_f32_e32 v51, v179, v207
	global_store_dwordx4 v193, v[48:51], s[18:19] offset:0 nt
	v_lshlrev_b32_e32 v200, 16, v90
	v_and_b32_e32 v201, 0xffff0000, v90
	v_lshlrev_b32_e32 v202, 16, v91
	v_and_b32_e32 v203, 0xffff0000, v91
	v_lshlrev_b32_e32 v204, 16, v122
	v_and_b32_e32 v205, 0xffff0000, v122
	v_lshlrev_b32_e32 v206, 16, v123
	v_and_b32_e32 v207, 0xffff0000, v123
	v_mul_f32_e32 v200, v214, v200
	v_mul_f32_e32 v201, v214, v201
	v_mul_f32_e32 v202, v214, v202
	v_mul_f32_e32 v203, v214, v203
	v_mul_f32_e32 v204, v215, v204
	v_mul_f32_e32 v205, v215, v205
	v_mul_f32_e32 v206, v215, v206
	v_mul_f32_e32 v207, v215, v207
	v_fmac_f32_e32 v52, v148, v200
	v_fmac_f32_e32 v53, v149, v201
	v_fmac_f32_e32 v54, v150, v202
	v_fmac_f32_e32 v55, v151, v203
	v_fmac_f32_e32 v52, v180, v204
	v_fmac_f32_e32 v53, v181, v205
	v_fmac_f32_e32 v54, v182, v206
	v_fmac_f32_e32 v55, v183, v207
	global_store_dwordx4 v193, v[52:55], s[18:19] offset:1024 nt
	v_lshlrev_b32_e32 v200, 16, v92
	v_and_b32_e32 v201, 0xffff0000, v92
	v_lshlrev_b32_e32 v202, 16, v93
	v_and_b32_e32 v203, 0xffff0000, v93
	v_lshlrev_b32_e32 v204, 16, v124
	v_and_b32_e32 v205, 0xffff0000, v124
	v_lshlrev_b32_e32 v206, 16, v125
	v_and_b32_e32 v207, 0xffff0000, v125
	v_mul_f32_e32 v200, v214, v200
	v_mul_f32_e32 v201, v214, v201
	v_mul_f32_e32 v202, v214, v202
	v_mul_f32_e32 v203, v214, v203
	v_mul_f32_e32 v204, v215, v204
	v_mul_f32_e32 v205, v215, v205
	v_mul_f32_e32 v206, v215, v206
	v_mul_f32_e32 v207, v215, v207
	v_fmac_f32_e32 v56, v152, v200
	v_fmac_f32_e32 v57, v153, v201
	v_fmac_f32_e32 v58, v154, v202
	v_fmac_f32_e32 v59, v155, v203
	v_fmac_f32_e32 v56, v184, v204
	v_fmac_f32_e32 v57, v185, v205
	v_fmac_f32_e32 v58, v186, v206
	v_fmac_f32_e32 v59, v187, v207
	global_store_dwordx4 v193, v[56:59], s[18:19] offset:2048 nt
	v_lshlrev_b32_e32 v200, 16, v94
	v_and_b32_e32 v201, 0xffff0000, v94
	v_lshlrev_b32_e32 v202, 16, v95
	v_and_b32_e32 v203, 0xffff0000, v95
	v_lshlrev_b32_e32 v204, 16, v126
	v_and_b32_e32 v205, 0xffff0000, v126
	v_lshlrev_b32_e32 v206, 16, v127
	v_and_b32_e32 v207, 0xffff0000, v127
	v_mul_f32_e32 v200, v214, v200
	v_mul_f32_e32 v201, v214, v201
	v_mul_f32_e32 v202, v214, v202
	v_mul_f32_e32 v203, v214, v203
	v_mul_f32_e32 v204, v215, v204
	v_mul_f32_e32 v205, v215, v205
	v_mul_f32_e32 v206, v215, v206
	v_mul_f32_e32 v207, v215, v207
	v_fmac_f32_e32 v60, v156, v200
	v_fmac_f32_e32 v61, v157, v201
	v_fmac_f32_e32 v62, v158, v202
	v_fmac_f32_e32 v63, v159, v203
	v_fmac_f32_e32 v60, v188, v204
	v_fmac_f32_e32 v61, v189, v205
	v_fmac_f32_e32 v62, v190, v206
	v_fmac_f32_e32 v63, v191, v207
	global_store_dwordx4 v193, v[60:63], s[18:19] offset:3072 nt
	s_add_u32 s18, s18, 0x2000
	s_addc_u32 s19, s19, 0
	s_branch .LBB0_1296
